# v063 plus GEMM K-loops: 68 LDS-DMA loads addressed as SGPR base + 32-bit lane offset (saddr form) instead of a 64-bit VALU add per load
# speedup vs baseline: 1.0037x; 1.0011x over previous
; #define PG8_STAGE(bufoff, gbase, voff) do { _Pragma("unroll") for (int _i = 0; _i < 2; ++_i) \
;         __builtin_amdgcn_global_load_lds((const unsigned*)((const char*)(gbase) + (voff)[_i]), (PG8_LAS unsigned*)(lds + (bufoff) + ldsw + _i * 8192), 16, 0, 0); } while (0)
; #define PG8_WAIT_V(n) asm volatile("s_waitcnt vmcnt(" #n ")" ::: "memory")
; #define PG8_BAR __builtin_amdgcn_s_barrier()
; template <class Epi, class Sched, bool ALIGN_EPI = false, bool SP2 = false>
; __device__ __forceinline__ void gemm_phase(PG8_LAS unsigned char* lds, const Gemm g, const Sched& S, const Epi& E) {
;     ...
;         PG8_STAGE(PG8_SB(0, 0), cB, voffB); PG8_STAGE(PG8_SB(0, 1), cB + hstepB, voffB); PG8_STAGE(PG8_SA(0, 0), cA, voffA); PG8_STAGE(PG8_SA(0, 1), cA + hstepA, voffA);
;         if (wr == 1) PG8_BAR;
;         PG8_WAIT_V(2); PG8_BAR;
;         PG8_STAGE(PG8_SB(1, 0), cB + kstep, voffB); PG8_STAGE(PG8_SA(1, 0), cA + kstep, voffA); PG8_STAGE(PG8_SB(1, 1), cB + hstepB + kstep, voffB);
;         PG8_WAIT_V(6); PG8_BAR;
;     } else {
;         PG8_STAGE(PG8_SB(0, 0), cB, voffB); PG8_STAGE(PG8_SA(0, 0), cA, voffA); PG8_STAGE(PG8_SB(0, 1), cB + hstepB, voffB); PG8_STAGE(PG8_SA(0, 1), cA + hstepA, voffA);
;         if (wr == 1) PG8_BAR;
;         PG8_WAIT_V(4); PG8_BAR;
;         PG8_STAGE(PG8_SB(1, 0), cB + kstep, voffB); PG8_STAGE(PG8_SA(1, 0), cA + kstep, voffA); PG8_STAGE(PG8_SB(1, 1), cB + hstepB + kstep, voffB);
;         PG8_WAIT_V(6); PG8_BAR;
;     }
.LBB0_289:
	s_add_u32 s8, s34, 0x7800000
	s_addc_u32 s9, s35, 0
	s_add_u32 s10, s34, 0xfd00000
	s_addc_u32 s11, s35, 0
	s_add_u32 s59, s34, 0x12f00000
	s_mov_b64 s[12:13], 0x80
	s_addc_u32 s60, s35, 0
	s_and_b32 s5, s3, 3
	s_add_i32 m0, s53, 0x18000
	v_lshl_add_u64 v[6:7], v[6:7], 0, s[12:13]
	s_lshl_b32 s61, s4, 6
	s_lshl_b32 s14, s4, 13
	s_lshl_b32 s16, s5, 5
	s_lshl_b32 s15, s5, 12
	s_waitcnt vmcnt(2)
	s_barrier
	global_load_lds_dwordx4 v[6:7], off
	v_lshl_add_u64 v[4:5], v[4:5], 0, s[12:13]
	s_add_i32 m0, s53, 0x1a000
	s_add_i32 s62, s53, 0x8000
	s_add_i32 s63, s53, 0xa000
	global_load_lds_dwordx4 v[4:5], off
	v_lshl_add_u64 v[0:1], v[0:1], 0, s[12:13]
	s_mov_b32 m0, s62
	s_add_u32 s4, s26, 0x40080
	global_load_lds_dwordx4 v[0:1], off
	v_lshl_add_u64 v[0:1], v[2:3], 0, s[12:13]
	s_mov_b32 m0, s63
	s_addc_u32 s5, s27, 0
	global_load_lds_dwordx4 v[0:1], off
	s_add_i32 m0, s53, 0x1c000
	global_load_lds_dwordx4 v200, s[4:5]
	v_lshl_add_u64 v[0:1], s[4:5], 0, v[196:197]
	s_add_i32 m0, s53, 0x1e000
	v_and_b32_e32 v193, 15, v194
	global_load_lds_dwordx4 v[0:1], off
	v_lshlrev_b32_e32 v0, 1, v12
	v_lshlrev_b32_e32 v2, 2, v194
	v_lshlrev_b32_e32 v3, 6, v194
	s_movk_i32 s4, 0x3c0
	v_lshl_or_b32 v1, v193, 6, v0
	v_and_b32_e32 v2, 32, v2
	v_and_or_b32 v0, v3, s4, v0
	v_bitop3_b32 v1, v1, s14, v2 bitop3:0xde
	v_bitop3_b32 v207, s15, v0, v2 bitop3:0xf6
	v_lshlrev_b32_e32 v2, 8, v194
	v_and_b32_e32 v2, 0x38000, v2
	v_lshlrev_b32_e32 v3, 11, v11
	v_or3_b32 v2, v9, v2, v3
	s_or_b32 s68, s16, 0xfffff800
	v_add_u32_e32 v208, v2, v10
	v_lshlrev_b32_e32 v2, 4, v8
	s_waitcnt vmcnt(6)
	s_cmpk_lt_u32 s2, 0x100
	v_and_b32_e32 v2, 0x78000, v2
	v_or_b32_e32 v195, s61, v193
	s_cselect_b64 s[14:15], -1, 0
	s_bfe_u32 s69, s3, 0x10001
	v_or_b32_e32 v0, s16, v12
	v_readlane_b32 s2, v251, 13
	v_or3_b32 v2, v9, v2, v3
	s_add_i32 s73, 0, 0x10000
	s_add_i32 s74, 0, 0x14000
	s_mov_b32 s64, 0x18000
	s_mov_b32 s65, 0x8000
	v_and_or_b32 v206, s16, 32, v12
	v_or_b32_e32 v216, 16, v195
	v_or_b32_e32 v217, 32, v195
	v_or_b32_e32 v218, 48, v195
	s_ashr_i32 s70, s2, 31
	s_mov_b32 s71, s2
	s_mov_b32 s72, 0x38000
	v_mov_b32_e32 v209, v205
	v_add_u32_e32 v210, v2, v10
	v_mov_b32_e32 v211, v205
	v_mov_b64_e32 v[212:213], 0x600
	v_mov_b64_e32 v[214:215], 0x5ff
	v_add_u32_e32 v219, s73, v207
	v_add_u32_e32 v220, s74, v207
	v_add_u32_e32 v221, 0, v1
	s_mov_b32 s75, 0x8080
	s_mov_b32 s76, 0x20000
	s_mov_b32 s77, 0x28000
	s_mov_b32 s78, 0x30000
	s_movk_i32 s79, 0x1080
	v_lshlrev_b32_e32 v204, 1, v0
	v_mov_b32_e32 v222, 0x8080
	v_mov_b32_e32 v223, 0x3e38aa3b
	s_barrier
	v_readlane_b32 s3, v251, 14
	s_branch .LBB0_292

; #define PG8_STAGE(bufoff, gbase, voff) do { _Pragma("unroll") for (int _i = 0; _i < 2; ++_i) \
;         __builtin_amdgcn_global_load_lds((const unsigned*)((const char*)(gbase) + (voff)[_i]), (PG8_LAS unsigned*)(lds + (bufoff) + ldsw + _i * 8192), 16, 0, 0); } while (0)
; #define PG8_LDA(dst, b, h) do { _Pragma("unroll") for (int m = 0; m < 4; ++m) _Pragma("unroll") for (int k = 0; k < 2; ++k) dst[m][k] = *(const PG8_LAS bf16x8*)(lds + PG8_SA(b, h) + aoff + m * 2048 + k * 1024); } while (0)
; #define PG8_LDB(dst, b, h) do { _Pragma("unroll") for (int n = 0; n < 2; ++n) _Pragma("unroll") for (int k = 0; k < 2; ++k) dst[n][k] = *(const PG8_LAS bf16x8*)(lds + PG8_SB(b, h) + boff + n * 2048 + k * 1024); } while (0)
; #define PG8_MMA(ai, bj, At, Bt) do { __builtin_amdgcn_s_setprio(1); _Pragma("unroll") for (int m = 0; m < 4; ++m) _Pragma("unroll") for (int n = 0; n < 2; ++n) _Pragma("unroll") for (int k = 0; k < 2; ++k) \
;         acc[ai][bj][m][n] = __builtin_amdgcn_mfma_f32_16x16x32_bf16(Bt[n][k], At[m][k], acc[ai][bj][m][n], 0, 0, 0); __builtin_amdgcn_s_setprio(0); } while (0)
; #define PG8_WAIT_V(n) asm volatile("s_waitcnt vmcnt(" #n ")" ::: "memory")
; #define PG8_WAIT_L(n) asm volatile("s_waitcnt lgkmcnt(" #n ")" ::: "memory")
; #define PG8_BAR __builtin_amdgcn_s_barrier()
; #define PG8_SCHED __builtin_amdgcn_sched_barrier(0)
; template <class Epi, class Sched, bool ALIGN_EPI = false, bool SP2 = false>
; __device__ __forceinline__ void gemm_phase(PG8_LAS unsigned char* lds, const Gemm g, const Sched& S, const Epi& E) {
;     ...
;             PG8_LDB(B0, 0, 0); PG8_LDB(B1, 0, 1); PG8_SCHED; PG8_LDA(At, 0, 0); PG8_STAGE(PG8_SA(1, 1), a1 + hstepA, voffA);
;             PG8_WAIT_V(8); PG8_WAIT_L(0); PG8_BAR; PG8_MMA(0, 0, At, B0); PG8_MMA(0, 1, At, B1); PG8_BAR; PG8_SCHED;
;             PG8_LDA(At, 0, 1); PG8_STAGE(PG8_SB(0, 0), b2, voffB); PG8_STAGE(PG8_SB(0, 1), b2 + hstepB, voffB); PG8_STAGE(PG8_SA(0, 0), a2, voffA);
;             PG8_WAIT_V(8); PG8_WAIT_L(0); PG8_BAR; PG8_MMA(1, 0, At, B0); PG8_MMA(1, 1, At, B1); PG8_BAR; PG8_SCHED;
.LBB0_295:
	ds_read_b128 v[128:131], v219
	ds_read_b128 v[132:135], v219 offset:1024
	ds_read_b128 v[136:139], v219 offset:2048
	ds_read_b128 v[140:143], v219 offset:3072
	ds_read_b128 v[144:147], v220
	ds_read_b128 v[148:151], v220 offset:1024
	ds_read_b128 v[152:155], v220 offset:2048
	ds_read_b128 v[156:159], v220 offset:3072
	s_add_u32 s26, s24, 0xfffc0080
	s_addc_u32 s27, s25, -1
	s_cmp_eq_u32 s84, 12
	s_cselect_b32 s29, s2, s27
	s_cselect_b32 s28, s3, s26
	s_cselect_b32 s27, s17, s83
	s_cselect_b32 s26, s23, s82
	v_lshl_add_u64 v[224:225], s[24:25], 0, v[208:209]
	s_add_i32 m0, s53, 0xc000
	ds_read_b128 v[160:163], v221
	ds_read_b128 v[164:167], v221 offset:1024
	ds_read_b128 v[168:171], v221 offset:2048
	ds_read_b128 v[172:175], v221 offset:3072
	ds_read_b128 v[176:179], v221 offset:4096
	ds_read_b128 v[180:183], v221 offset:5120
	ds_read_b128 v[184:187], v221 offset:6144
	ds_read_b128 v[188:191], v221 offset:7168
	global_load_lds_dwordx4 v[224:225], off
	s_add_i32 m0, s53, 0xe000
	s_nop 0
	global_load_lds_dwordx4 v210, s[24:25]
	s_waitcnt vmcnt(8)
	s_waitcnt lgkmcnt(0)
	s_barrier
	s_setprio 1
	s_waitcnt lgkmcnt(0)
	v_mfma_f32_16x16x32_bf16 v[124:127], v[128:131], v[160:163], v[124:127]
	v_mfma_f32_16x16x32_bf16 v[120:123], v[136:139], v[160:163], v[120:123]
	v_mfma_f32_16x16x32_bf16 v[116:119], v[128:131], v[168:171], v[116:119]
	v_mfma_f32_16x16x32_bf16 v[108:111], v[136:139], v[168:171], v[108:111]
	v_mfma_f32_16x16x32_bf16 v[100:103], v[128:131], v[176:179], v[100:103]
	v_mfma_f32_16x16x32_bf16 v[92:95], v[136:139], v[176:179], v[92:95]
	v_mfma_f32_16x16x32_bf16 v[84:87], v[128:131], v[184:187], v[84:87]
	v_mfma_f32_16x16x32_bf16 v[76:79], v[136:139], v[184:187], v[76:79]
	v_mfma_f32_16x16x32_bf16 v[124:127], v[132:135], v[164:167], v[124:127]
	v_mfma_f32_16x16x32_bf16 v[120:123], v[140:143], v[164:167], v[120:123]
	v_mfma_f32_16x16x32_bf16 v[116:119], v[132:135], v[172:175], v[116:119]
	v_mfma_f32_16x16x32_bf16 v[108:111], v[140:143], v[172:175], v[108:111]
	v_mfma_f32_16x16x32_bf16 v[100:103], v[132:135], v[180:183], v[100:103]
	v_mfma_f32_16x16x32_bf16 v[92:95], v[140:143], v[180:183], v[92:95]
	v_mfma_f32_16x16x32_bf16 v[84:87], v[132:135], v[188:191], v[84:87]
	v_mfma_f32_16x16x32_bf16 v[76:79], v[140:143], v[188:191], v[76:79]
	s_setprio 0
	s_setprio 1
	v_mfma_f32_16x16x32_bf16 v[112:115], v[144:147], v[160:163], v[112:115]
	v_mfma_f32_16x16x32_bf16 v[104:107], v[152:155], v[160:163], v[104:107]
	v_mfma_f32_16x16x32_bf16 v[96:99], v[144:147], v[168:171], v[96:99]
	v_mfma_f32_16x16x32_bf16 v[88:91], v[152:155], v[168:171], v[88:91]
	v_mfma_f32_16x16x32_bf16 v[80:83], v[144:147], v[176:179], v[80:83]
	v_mfma_f32_16x16x32_bf16 v[72:75], v[152:155], v[176:179], v[72:75]
	v_mfma_f32_16x16x32_bf16 v[68:71], v[144:147], v[184:187], v[68:71]
	v_mfma_f32_16x16x32_bf16 v[64:67], v[152:155], v[184:187], v[64:67]
	v_mfma_f32_16x16x32_bf16 v[112:115], v[148:151], v[164:167], v[112:115]
	v_mfma_f32_16x16x32_bf16 v[104:107], v[156:159], v[164:167], v[104:107]
	v_mfma_f32_16x16x32_bf16 v[96:99], v[148:151], v[172:175], v[96:99]
	v_mfma_f32_16x16x32_bf16 v[88:91], v[156:159], v[172:175], v[88:91]
	v_mfma_f32_16x16x32_bf16 v[80:83], v[148:151], v[180:183], v[80:83]
	v_mfma_f32_16x16x32_bf16 v[72:75], v[156:159], v[180:183], v[72:75]
	v_mfma_f32_16x16x32_bf16 v[68:71], v[148:151], v[188:191], v[68:71]
	v_mfma_f32_16x16x32_bf16 v[64:67], v[156:159], v[188:191], v[64:67]
	s_setprio 0
	s_barrier
	s_add_i32 s85, s73, s44
	v_lshl_add_u64 v[224:225], s[26:27], 0, v[200:201]
	s_mov_b32 m0, s85
	ds_read_b128 v[160:163], v221 offset:16384
	ds_read_b128 v[164:167], v221 offset:17408
	ds_read_b128 v[168:171], v221 offset:18432
	ds_read_b128 v[172:175], v221 offset:19456
	ds_read_b128 v[176:179], v221 offset:20480
	ds_read_b128 v[180:183], v221 offset:21504
	ds_read_b128 v[184:187], v221 offset:22528
	ds_read_b128 v[188:191], v221 offset:23552
	global_load_lds_dwordx4 v[224:225], off
	s_add_i32 m0, s85, 0x2000
	s_add_u32 s86, s26, 0x40000
	v_lshl_add_u64 v[226:227], s[26:27], 0, v[196:197]
	s_addc_u32 s87, s27, 0
	s_add_i32 s85, s74, s44
	global_load_lds_dwordx4 v[226:227], off
	s_mov_b32 m0, s85
	v_lshl_add_u64 v[230:231], s[28:29], 0, v[198:199]
	global_load_lds_dwordx4 v200, s[86:87]
	s_add_i32 m0, s85, 0x2000
	s_nop 0
	global_load_lds_dwordx4 v196, s[86:87]
	v_lshl_add_u64 v[228:229], s[28:29], 0, v[202:203]
	s_mov_b32 m0, s53
	s_nop 0
	global_load_lds_dwordx4 v[228:229], off
	s_mov_b32 m0, s54
	s_nop 0
	global_load_lds_dwordx4 v[230:231], off
	s_waitcnt vmcnt(8)
	s_waitcnt lgkmcnt(0)
	s_barrier
; #define PG8_STAGE(bufoff, gbase, voff) do { _Pragma("unroll") for (int _i = 0; _i < 2; ++_i) \
;         __builtin_amdgcn_global_load_lds((const unsigned*)((const char*)(gbase) + (voff)[_i]), (PG8_LAS unsigned*)(lds + (bufoff) + ldsw + _i * 8192), 16, 0, 0); } while (0)
; #define PG8_LDA(dst, b, h) do { _Pragma("unroll") for (int m = 0; m < 4; ++m) _Pragma("unroll") for (int k = 0; k < 2; ++k) dst[m][k] = *(const PG8_LAS bf16x8*)(lds + PG8_SA(b, h) + aoff + m * 2048 + k * 1024); } while (0)
; #define PG8_LDB(dst, b, h) do { _Pragma("unroll") for (int n = 0; n < 2; ++n) _Pragma("unroll") for (int k = 0; k < 2; ++k) dst[n][k] = *(const PG8_LAS bf16x8*)(lds + PG8_SB(b, h) + boff + n * 2048 + k * 1024); } while (0)
; #define PG8_MMA(ai, bj, At, Bt) do { __builtin_amdgcn_s_setprio(1); _Pragma("unroll") for (int m = 0; m < 4; ++m) _Pragma("unroll") for (int n = 0; n < 2; ++n) _Pragma("unroll") for (int k = 0; k < 2; ++k) \
;         acc[ai][bj][m][n] = __builtin_amdgcn_mfma_f32_16x16x32_bf16(Bt[n][k], At[m][k], acc[ai][bj][m][n], 0, 0, 0); __builtin_amdgcn_s_setprio(0); } while (0)
; #define PG8_WAIT_V(n) asm volatile("s_waitcnt vmcnt(" #n ")" ::: "memory")
; #define PG8_WAIT_L(n) asm volatile("s_waitcnt lgkmcnt(" #n ")" ::: "memory")
; #define PG8_BAR __builtin_amdgcn_s_barrier()
; #define PG8_SCHED __builtin_amdgcn_sched_barrier(0)
; template <class Epi, class Sched, bool ALIGN_EPI = false, bool SP2 = false>
; __device__ __forceinline__ void gemm_phase(PG8_LAS unsigned char* lds, const Gemm g, const Sched& S, const Epi& E) {
;     ...
;             PG8_WAIT_V(8); PG8_WAIT_L(0); PG8_BAR; PG8_MMA(1, 0, At, B0); PG8_MMA(1, 1, At, B1); PG8_BAR; PG8_SCHED;
;             PG8_LDB(B0, 1, 0); PG8_LDB(B1, 1, 1); PG8_SCHED; PG8_LDA(At, 1, 0); PG8_STAGE(PG8_SA(0, 1), a2 + hstepA, voffA);
;             PG8_WAIT_V(8); PG8_WAIT_L(0); PG8_BAR; PG8_MMA(0, 0, At, B0); PG8_MMA(0, 1, At, B1); PG8_BAR; PG8_SCHED;
;             PG8_LDA(At, 1, 1); PG8_STAGE(PG8_SB(1, 0), b3, voffB); PG8_STAGE(PG8_SB(1, 1), b3 + hstepB, voffB); PG8_STAGE(PG8_SA(1, 0), a3, voffA);
	s_setprio 1
	s_waitcnt lgkmcnt(0)
	v_mfma_f32_16x16x32_bf16 v[60:63], v[128:131], v[160:163], v[60:63]
	v_mfma_f32_16x16x32_bf16 v[56:59], v[136:139], v[160:163], v[56:59]
	v_mfma_f32_16x16x32_bf16 v[52:55], v[128:131], v[168:171], v[52:55]
	v_mfma_f32_16x16x32_bf16 v[44:47], v[136:139], v[168:171], v[44:47]
	v_mfma_f32_16x16x32_bf16 v[36:39], v[128:131], v[176:179], v[36:39]
	v_mfma_f32_16x16x32_bf16 v[28:31], v[136:139], v[176:179], v[28:31]
	v_mfma_f32_16x16x32_bf16 v[20:23], v[128:131], v[184:187], v[20:23]
	v_mfma_f32_16x16x32_bf16 v[12:15], v[136:139], v[184:187], v[12:15]
	v_mfma_f32_16x16x32_bf16 v[60:63], v[132:135], v[164:167], v[60:63]
	v_mfma_f32_16x16x32_bf16 v[56:59], v[140:143], v[164:167], v[56:59]
	v_mfma_f32_16x16x32_bf16 v[52:55], v[132:135], v[172:175], v[52:55]
	v_mfma_f32_16x16x32_bf16 v[44:47], v[140:143], v[172:175], v[44:47]
	v_mfma_f32_16x16x32_bf16 v[36:39], v[132:135], v[180:183], v[36:39]
	v_mfma_f32_16x16x32_bf16 v[28:31], v[140:143], v[180:183], v[28:31]
	v_mfma_f32_16x16x32_bf16 v[20:23], v[132:135], v[188:191], v[20:23]
	v_mfma_f32_16x16x32_bf16 v[12:15], v[140:143], v[188:191], v[12:15]
	s_setprio 0
	s_setprio 1
	v_mfma_f32_16x16x32_bf16 v[48:51], v[144:147], v[160:163], v[48:51]
	v_mfma_f32_16x16x32_bf16 v[40:43], v[152:155], v[160:163], v[40:43]
	v_mfma_f32_16x16x32_bf16 v[32:35], v[144:147], v[168:171], v[32:35]
	v_mfma_f32_16x16x32_bf16 v[24:27], v[152:155], v[168:171], v[24:27]
	v_mfma_f32_16x16x32_bf16 v[16:19], v[144:147], v[176:179], v[16:19]
	v_mfma_f32_16x16x32_bf16 v[8:11], v[152:155], v[176:179], v[8:11]
	v_mfma_f32_16x16x32_bf16 v[4:7], v[144:147], v[184:187], v[4:7]
	v_mfma_f32_16x16x32_bf16 v[0:3], v[152:155], v[184:187], v[0:3]
	v_mfma_f32_16x16x32_bf16 v[48:51], v[148:151], v[164:167], v[48:51]
	v_mfma_f32_16x16x32_bf16 v[40:43], v[156:159], v[164:167], v[40:43]
	v_mfma_f32_16x16x32_bf16 v[32:35], v[148:151], v[172:175], v[32:35]
	v_mfma_f32_16x16x32_bf16 v[24:27], v[156:159], v[172:175], v[24:27]
	v_mfma_f32_16x16x32_bf16 v[16:19], v[148:151], v[180:183], v[16:19]
	v_mfma_f32_16x16x32_bf16 v[8:11], v[156:159], v[180:183], v[8:11]
	v_mfma_f32_16x16x32_bf16 v[4:7], v[148:151], v[188:191], v[4:7]
	v_mfma_f32_16x16x32_bf16 v[0:3], v[156:159], v[188:191], v[0:3]
	s_setprio 0
	s_barrier
	s_add_i32 s85, 0, 0x18000
	s_add_i32 s86, 0, 0x1c000
	v_add_u32_e32 v140, s85, v207
	v_add_u32_e32 v156, s86, v207
	ds_read_b128 v[128:131], v140
	ds_read_b128 v[132:135], v140 offset:1024
	ds_read_b128 v[136:139], v140 offset:2048
	ds_read_b128 v[140:143], v140 offset:3072
	ds_read_b128 v[144:147], v156
	ds_read_b128 v[148:151], v156 offset:1024
	ds_read_b128 v[152:155], v156 offset:2048
	ds_read_b128 v[156:159], v156 offset:3072
	s_add_u32 s28, s28, 0x40000
	s_addc_u32 s29, s29, 0
	s_mov_b32 m0, s55
	v_lshl_add_u64 v[232:233], s[28:29], 0, v[202:203]
	ds_read_b128 v[160:163], v221 offset:32768
	ds_read_b128 v[164:167], v221 offset:33792
	ds_read_b128 v[168:171], v221 offset:34816
	ds_read_b128 v[172:175], v221 offset:35840
	ds_read_b128 v[176:179], v221 offset:36864
	ds_read_b128 v[180:183], v221 offset:37888
	ds_read_b128 v[184:187], v221 offset:38912
	ds_read_b128 v[188:191], v221 offset:39936
	global_load_lds_dwordx4 v[232:233], off
	v_lshl_add_u64 v[232:233], s[28:29], 0, v[198:199]
	s_mov_b32 m0, s56
	s_nop 0
	global_load_lds_dwordx4 v[232:233], off
	s_waitcnt vmcnt(8)
	s_waitcnt lgkmcnt(0)
	s_barrier
	s_setprio 1
	s_waitcnt lgkmcnt(0)
	v_mfma_f32_16x16x32_bf16 v[124:127], v[128:131], v[160:163], v[124:127]
	v_mfma_f32_16x16x32_bf16 v[120:123], v[136:139], v[160:163], v[120:123]
	v_mfma_f32_16x16x32_bf16 v[116:119], v[128:131], v[168:171], v[116:119]
	v_mfma_f32_16x16x32_bf16 v[108:111], v[136:139], v[168:171], v[108:111]
	v_mfma_f32_16x16x32_bf16 v[100:103], v[128:131], v[176:179], v[100:103]
	v_mfma_f32_16x16x32_bf16 v[92:95], v[136:139], v[176:179], v[92:95]
	v_mfma_f32_16x16x32_bf16 v[84:87], v[128:131], v[184:187], v[84:87]
	v_mfma_f32_16x16x32_bf16 v[76:79], v[136:139], v[184:187], v[76:79]
	v_mfma_f32_16x16x32_bf16 v[124:127], v[132:135], v[164:167], v[124:127]
	v_mfma_f32_16x16x32_bf16 v[120:123], v[140:143], v[164:167], v[120:123]
	v_mfma_f32_16x16x32_bf16 v[116:119], v[132:135], v[172:175], v[116:119]
	v_mfma_f32_16x16x32_bf16 v[108:111], v[140:143], v[172:175], v[108:111]
	v_mfma_f32_16x16x32_bf16 v[100:103], v[132:135], v[180:183], v[100:103]
	v_mfma_f32_16x16x32_bf16 v[92:95], v[140:143], v[180:183], v[92:95]
	v_mfma_f32_16x16x32_bf16 v[84:87], v[132:135], v[188:191], v[84:87]
	v_mfma_f32_16x16x32_bf16 v[76:79], v[140:143], v[188:191], v[76:79]
	s_setprio 0
	s_setprio 1
	v_mfma_f32_16x16x32_bf16 v[112:115], v[144:147], v[160:163], v[112:115]
	v_mfma_f32_16x16x32_bf16 v[104:107], v[152:155], v[160:163], v[104:107]
	v_mfma_f32_16x16x32_bf16 v[96:99], v[144:147], v[168:171], v[96:99]
	v_mfma_f32_16x16x32_bf16 v[88:91], v[152:155], v[168:171], v[88:91]
	v_mfma_f32_16x16x32_bf16 v[80:83], v[144:147], v[176:179], v[80:83]
	v_mfma_f32_16x16x32_bf16 v[72:75], v[152:155], v[176:179], v[72:75]
	v_mfma_f32_16x16x32_bf16 v[68:71], v[144:147], v[184:187], v[68:71]
	v_mfma_f32_16x16x32_bf16 v[64:67], v[152:155], v[184:187], v[64:67]
	v_mfma_f32_16x16x32_bf16 v[112:115], v[148:151], v[164:167], v[112:115]
	v_mfma_f32_16x16x32_bf16 v[104:107], v[156:159], v[164:167], v[104:107]
	v_mfma_f32_16x16x32_bf16 v[96:99], v[148:151], v[172:175], v[96:99]
	v_mfma_f32_16x16x32_bf16 v[88:91], v[156:159], v[172:175], v[88:91]
	v_mfma_f32_16x16x32_bf16 v[80:83], v[148:151], v[180:183], v[80:83]
	v_mfma_f32_16x16x32_bf16 v[72:75], v[156:159], v[180:183], v[72:75]
	v_mfma_f32_16x16x32_bf16 v[68:71], v[148:151], v[188:191], v[68:71]
	v_mfma_f32_16x16x32_bf16 v[64:67], v[156:159], v[188:191], v[64:67]
	s_setprio 0
	s_barrier
; #define PG8_STAGE(bufoff, gbase, voff) do { _Pragma("unroll") for (int _i = 0; _i < 2; ++_i) \
;         __builtin_amdgcn_global_load_lds((const unsigned*)((const char*)(gbase) + (voff)[_i]), (PG8_LAS unsigned*)(lds + (bufoff) + ldsw + _i * 8192), 16, 0, 0); } while (0)
; #define PG8_LDA(dst, b, h) do { _Pragma("unroll") for (int m = 0; m < 4; ++m) _Pragma("unroll") for (int k = 0; k < 2; ++k) dst[m][k] = *(const PG8_LAS bf16x8*)(lds + PG8_SA(b, h) + aoff + m * 2048 + k * 1024); } while (0)
; #define PG8_MMA(ai, bj, At, Bt) do { __builtin_amdgcn_s_setprio(1); _Pragma("unroll") for (int m = 0; m < 4; ++m) _Pragma("unroll") for (int n = 0; n < 2; ++n) _Pragma("unroll") for (int k = 0; k < 2; ++k) \
;         acc[ai][bj][m][n] = __builtin_amdgcn_mfma_f32_16x16x32_bf16(Bt[n][k], At[m][k], acc[ai][bj][m][n], 0, 0, 0); __builtin_amdgcn_s_setprio(0); } while (0)
; #define PG8_WAIT_V(n) asm volatile("s_waitcnt vmcnt(" #n ")" ::: "memory")
; #define PG8_WAIT_L(n) asm volatile("s_waitcnt lgkmcnt(" #n ")" ::: "memory")
; #define PG8_BAR __builtin_amdgcn_s_barrier()
; #define PG8_SCHED __builtin_amdgcn_sched_barrier(0)
; template <class Epi, class Sched, bool ALIGN_EPI = false, bool SP2 = false>
; __device__ __forceinline__ void gemm_phase(PG8_LAS unsigned char* lds, const Gemm g, const Sched& S, const Epi& E) {
;     ...
;         for (int t = 0; t < nt; t += 2) {
;             const bool last = (t == nt - 2);
;             const char* a1 = cA + (size_t)(t + 1) * kstep;
;             const char* a2 = last ? nA : cA + (size_t)(t + 2) * kstep; const char* b2 = last ? nB : cB + (size_t)(t + 2) * kstep;
;     ...
;             PG8_WAIT_V(8); PG8_WAIT_L(0); PG8_BAR; PG8_MMA(0, 0, At, B0); PG8_MMA(0, 1, At, B1); PG8_BAR; PG8_SCHED;
;             PG8_LDA(At, 1, 1); PG8_STAGE(PG8_SB(1, 0), b3, voffB); PG8_STAGE(PG8_SB(1, 1), b3 + hstepB, voffB); PG8_STAGE(PG8_SA(1, 0), a3, voffA);
;             PG8_WAIT_V(8); PG8_WAIT_L(0); PG8_BAR; PG8_MMA(1, 0, At, B0); PG8_MMA(1, 1, At, B1); PG8_BAR; PG8_SCHED;
	s_add_i32 s28, s85, s44
	v_lshl_add_u64 v[224:225], v[224:225], 0, s[12:13]
	s_mov_b32 m0, s28
	ds_read_b128 v[160:163], v221 offset:49152
	ds_read_b128 v[164:167], v221 offset:50176
	ds_read_b128 v[168:171], v221 offset:51200
	ds_read_b128 v[172:175], v221 offset:52224
	ds_read_b128 v[176:179], v221 offset:53248
	ds_read_b128 v[180:183], v221 offset:54272
	ds_read_b128 v[184:187], v221 offset:55296
	ds_read_b128 v[188:191], v221 offset:56320
	global_load_lds_dwordx4 v[224:225], off
	s_add_i32 m0, s28, 0x2000
	s_add_u32 s26, s26, 0x40080
	v_lshl_add_u64 v[224:225], v[226:227], 0, s[12:13]
	s_addc_u32 s27, s27, 0
	s_add_i32 s28, s86, s44
	global_load_lds_dwordx4 v[224:225], off
	s_mov_b32 m0, s28
	s_nop 0
	global_load_lds_dwordx4 v200, s[26:27]
	s_add_i32 m0, s28, 0x2000
	s_nop 0
	global_load_lds_dwordx4 v196, s[26:27]
	v_lshl_add_u64 v[224:225], v[228:229], 0, s[12:13]
	s_mov_b32 m0, s62
	s_nop 0
	global_load_lds_dwordx4 v[224:225], off
	v_lshl_add_u64 v[224:225], v[230:231], 0, s[12:13]
	s_mov_b32 m0, s63
	s_nop 0
	global_load_lds_dwordx4 v[224:225], off
	s_waitcnt vmcnt(8)
	s_waitcnt lgkmcnt(0)
	s_barrier
	s_setprio 1
	s_waitcnt lgkmcnt(0)
	v_mfma_f32_16x16x32_bf16 v[60:63], v[128:131], v[160:163], v[60:63]
	v_mfma_f32_16x16x32_bf16 v[56:59], v[136:139], v[160:163], v[56:59]
	v_mfma_f32_16x16x32_bf16 v[52:55], v[128:131], v[168:171], v[52:55]
	v_mfma_f32_16x16x32_bf16 v[44:47], v[136:139], v[168:171], v[44:47]
	v_mfma_f32_16x16x32_bf16 v[36:39], v[128:131], v[176:179], v[36:39]
	v_mfma_f32_16x16x32_bf16 v[28:31], v[136:139], v[176:179], v[28:31]
	v_mfma_f32_16x16x32_bf16 v[20:23], v[128:131], v[184:187], v[20:23]
	v_mfma_f32_16x16x32_bf16 v[12:15], v[136:139], v[184:187], v[12:15]
	v_mfma_f32_16x16x32_bf16 v[60:63], v[132:135], v[164:167], v[60:63]
	v_mfma_f32_16x16x32_bf16 v[56:59], v[140:143], v[164:167], v[56:59]
	v_mfma_f32_16x16x32_bf16 v[52:55], v[132:135], v[172:175], v[52:55]
	v_mfma_f32_16x16x32_bf16 v[44:47], v[140:143], v[172:175], v[44:47]
	v_mfma_f32_16x16x32_bf16 v[36:39], v[132:135], v[180:183], v[36:39]
	v_mfma_f32_16x16x32_bf16 v[28:31], v[140:143], v[180:183], v[28:31]
	v_mfma_f32_16x16x32_bf16 v[20:23], v[132:135], v[188:191], v[20:23]
	v_mfma_f32_16x16x32_bf16 v[12:15], v[140:143], v[188:191], v[12:15]
	s_setprio 0
	s_setprio 1
	v_mfma_f32_16x16x32_bf16 v[48:51], v[144:147], v[160:163], v[48:51]
	v_mfma_f32_16x16x32_bf16 v[40:43], v[152:155], v[160:163], v[40:43]
	v_mfma_f32_16x16x32_bf16 v[32:35], v[144:147], v[168:171], v[32:35]
	v_mfma_f32_16x16x32_bf16 v[24:27], v[152:155], v[168:171], v[24:27]
	v_mfma_f32_16x16x32_bf16 v[16:19], v[144:147], v[176:179], v[16:19]
	v_mfma_f32_16x16x32_bf16 v[8:11], v[152:155], v[176:179], v[8:11]
	v_mfma_f32_16x16x32_bf16 v[4:7], v[144:147], v[184:187], v[4:7]
	v_mfma_f32_16x16x32_bf16 v[0:3], v[152:155], v[184:187], v[0:3]
	v_mfma_f32_16x16x32_bf16 v[48:51], v[148:151], v[164:167], v[48:51]
	v_mfma_f32_16x16x32_bf16 v[40:43], v[156:159], v[164:167], v[40:43]
	v_mfma_f32_16x16x32_bf16 v[32:35], v[148:151], v[172:175], v[32:35]
	v_mfma_f32_16x16x32_bf16 v[24:27], v[156:159], v[172:175], v[24:27]
	v_mfma_f32_16x16x32_bf16 v[16:19], v[148:151], v[180:183], v[16:19]
	v_mfma_f32_16x16x32_bf16 v[8:11], v[156:159], v[180:183], v[8:11]
	v_mfma_f32_16x16x32_bf16 v[4:7], v[148:151], v[188:191], v[4:7]
	v_mfma_f32_16x16x32_bf16 v[0:3], v[156:159], v[188:191], v[0:3]
	s_setprio 0
	s_barrier
	s_add_i32 s84, s84, 2
	s_add_u32 s24, s24, 0x100
	s_addc_u32 s25, s25, 0
	s_add_u32 s82, s82, 0x100
	s_addc_u32 s83, s83, 0
	s_cmp_gt_u32 s84, 13
	s_cbranch_scc0 .LBB0_295
	s_and_b64 vcc, exec, s[14:15]
	s_cbranch_vccz .LBB0_300
	s_barrier
	s_cmp_gt_i32 s81, 7
	s_mov_b64 s[2:3], -1
	s_cbranch_scc1 .LBB0_301

; #define PG8_STAGE(bufoff, gbase, voff) do { _Pragma("unroll") for (int _i = 0; _i < 2; ++_i) \
;         __builtin_amdgcn_global_load_lds((const unsigned*)((const char*)(gbase) + (voff)[_i]), (PG8_LAS unsigned*)(lds + (bufoff) + ldsw + _i * 8192), 16, 0, 0); } while (0)
; #define PG8_WAIT_V(n) asm volatile("s_waitcnt vmcnt(" #n ")" ::: "memory")
; #define PG8_BAR __builtin_amdgcn_s_barrier()
; template <class Epi, class Sched, bool ALIGN_EPI = false, bool SP2 = false>
; __device__ __forceinline__ void gemm_phase(PG8_LAS unsigned char* lds, const Gemm g, const Sched& S, const Epi& E) {
;     ...
;         PG8_STAGE(PG8_SB(0, 0), cB, voffB); PG8_STAGE(PG8_SB(0, 1), cB + hstepB, voffB); PG8_STAGE(PG8_SA(0, 0), cA, voffA); PG8_STAGE(PG8_SA(0, 1), cA + hstepA, voffA);
;         if (wr == 1) PG8_BAR;
;         PG8_WAIT_V(2); PG8_BAR;
;         PG8_STAGE(PG8_SB(1, 0), cB + kstep, voffB); PG8_STAGE(PG8_SA(1, 0), cA + kstep, voffA); PG8_STAGE(PG8_SB(1, 1), cB + hstepB + kstep, voffB);
;         PG8_WAIT_V(6); PG8_BAR;
;     } else {
;         PG8_STAGE(PG8_SB(0, 0), cB, voffB); PG8_STAGE(PG8_SA(0, 0), cA, voffA); PG8_STAGE(PG8_SB(0, 1), cB + hstepB, voffB); PG8_STAGE(PG8_SA(0, 1), cA + hstepA, voffA);
;         if (wr == 1) PG8_BAR;
;         PG8_WAIT_V(4); PG8_BAR;
;         PG8_STAGE(PG8_SB(1, 0), cB + kstep, voffB); PG8_STAGE(PG8_SA(1, 0), cA + kstep, voffA); PG8_STAGE(PG8_SB(1, 1), cB + hstepB + kstep, voffB);
;         PG8_WAIT_V(6); PG8_BAR;
;     }
.LBB0_380:
	s_add_u32 s64, s34, 0x18400000
	s_mov_b64 s[8:9], 0x80
	s_addc_u32 s65, s35, 0
	s_and_b32 s3, s3, 3
	s_add_i32 m0, s11, 0x18000
	v_lshl_add_u64 v[6:7], v[6:7], 0, s[8:9]
	s_lshl_b32 s13, s2, 13
	s_lshl_b32 s16, s3, 12
	s_waitcnt vmcnt(2)
	s_barrier
	global_load_lds_dwordx4 v[6:7], off
	v_lshl_add_u64 v[4:5], v[4:5], 0, s[8:9]
	s_add_i32 m0, s11, 0x1a000
	s_add_i32 s72, s11, 0x8000
	s_add_i32 s73, s11, 0xa000
	global_load_lds_dwordx4 v[4:5], off
	v_lshl_add_u64 v[0:1], v[0:1], 0, s[8:9]
	s_mov_b32 m0, s72
	s_add_u32 s14, s62, 0x80080
	global_load_lds_dwordx4 v[0:1], off
	v_lshl_add_u64 v[0:1], v[2:3], 0, s[8:9]
	s_mov_b32 m0, s73
	s_addc_u32 s15, s63, 0
	s_add_i32 s74, s11, 0x1c000
	global_load_lds_dwordx4 v[0:1], off
	s_mov_b32 m0, s74
	s_add_i32 s75, s11, 0x1e000
	global_load_lds_dwordx4 v66, s[14:15]
	v_lshl_add_u64 v[0:1], s[14:15], 0, v[70:71]
	s_mov_b32 m0, s75
	v_lshlrev_b32_e32 v2, 2, v194
	global_load_lds_dwordx4 v[0:1], off
	v_and_b32_e32 v0, 15, v194
	v_lshlrev_b32_e32 v1, 1, v8
	v_lshl_or_b32 v78, s2, 6, v0
	v_lshl_or_b32 v0, v0, 6, v1
	v_and_b32_e32 v2, 32, v2
	v_bitop3_b32 v3, v0, s13, v2 bitop3:0xde
	v_lshlrev_b32_e32 v0, 6, v194
	s_movk_i32 s2, 0x3c0
	v_and_or_b32 v0, v0, s2, v1
	s_cmpk_lt_u32 s12, 0x100
	v_bitop3_b32 v79, s16, v0, v2 bitop3:0xf6
	s_cselect_b64 s[12:13], -1, 0
	s_cmp_lt_u32 s3, 2
	v_lshl_or_b32 v0, s3, 5, v8
	v_readlane_b32 s2, v251, 13
	s_cselect_b64 s[14:15], -1, 0
	s_ashr_i32 s76, s2, 31
	s_waitcnt vmcnt(6)
	s_add_u32 s16, s96, s2
	s_addc_u32 s17, s5, s76
	s_add_i32 s78, 0, 0x10000
	s_sext_i32_i8 s22, s4
	s_mov_b32 s77, s2
	s_mov_b64 s[18:19], 0x100
	v_mov_b64_e32 v[74:75], 0x100
	v_mov_b64_e32 v[76:77], 0xff
	v_add_u32_e32 v80, s78, v79
	v_add_u32_e32 v81, 0, v3
	s_mov_b64 s[20:21], 0x180
	v_lshlrev_b32_e32 v72, 2, v0
	s_barrier
	v_readlane_b32 s3, v251, 14
	s_branch .LBB0_383

; #define PG8_STAGE(bufoff, gbase, voff) do { _Pragma("unroll") for (int _i = 0; _i < 2; ++_i) \
;         __builtin_amdgcn_global_load_lds((const unsigned*)((const char*)(gbase) + (voff)[_i]), (PG8_LAS unsigned*)(lds + (bufoff) + ldsw + _i * 8192), 16, 0, 0); } while (0)
; #define PG8_LDA(dst, b, h) do { _Pragma("unroll") for (int m = 0; m < 4; ++m) _Pragma("unroll") for (int k = 0; k < 2; ++k) dst[m][k] = *(const PG8_LAS bf16x8*)(lds + PG8_SA(b, h) + aoff + m * 2048 + k * 1024); } while (0)
; #define PG8_LDB(dst, b, h) do { _Pragma("unroll") for (int n = 0; n < 2; ++n) _Pragma("unroll") for (int k = 0; k < 2; ++k) dst[n][k] = *(const PG8_LAS bf16x8*)(lds + PG8_SB(b, h) + boff + n * 2048 + k * 1024); } while (0)
; #define PG8_WAIT_V(n) asm volatile("s_waitcnt vmcnt(" #n ")" ::: "memory")
; #define PG8_WAIT_L(n) asm volatile("s_waitcnt lgkmcnt(" #n ")" ::: "memory")
; #define PG8_BAR __builtin_amdgcn_s_barrier()
; template <class Epi, class Sched, bool ALIGN_EPI = false, bool SP2 = false>
; __device__ __forceinline__ void gemm_phase(PG8_LAS unsigned char* lds, const Gemm g, const Sched& S, const Epi& E) {
;     ...
;         const bool has_next = S.next(ui + 1, nxt);
;         const char* nA = has_next ? PG8_UA(nxt) : cA; const char* nB = has_next ? PG8_UB(nxt) : cB;
;         for (int t = 0; t < nt; t += 2) {
;             const bool last = (t == nt - 2);
;             const char* a1 = cA + (size_t)(t + 1) * kstep;
;             const char* a2 = last ? nA : cA + (size_t)(t + 2) * kstep; const char* b2 = last ? nB : cB + (size_t)(t + 2) * kstep;
;             const char* a3 = a2 + kstep; const char* b3 = b2 + kstep;
;             if (last && has_next) S.a_ready(nxt);
;             if constexpr (SP2) {
;             PG8_LDB(B0, 0, 0); PG8_LDB(B1, 0, 1); PG8_SCHED; PG8_LDA(At, 0, 0); PG8_STAGE(PG8_SA(1, 1), a1 + hstepA, voffA);
;             PG8_WAIT_V(8); PG8_WAIT_L(0); PG8_BAR; PG8_MMA(0, 0, At, B0); PG8_MMA(0, 1, At, B1); PG8_BAR; PG8_SCHED;
;             PG8_LDA(At, 0, 1); PG8_STAGE(PG8_SB(0, 0), b2, voffB); PG8_STAGE(PG8_SB(0, 1), b2 + hstepB, voffB); PG8_STAGE(PG8_SA(0, 0), a2, voffA);
;             PG8_WAIT_V(8); PG8_WAIT_L(0); PG8_BAR; PG8_MMA(1, 0, At, B0); PG8_MMA(1, 1, At, B1); PG8_BAR; PG8_SCHED;
;             PG8_LDB(B0, 1, 0); PG8_LDB(B1, 1, 1); PG8_SCHED; PG8_LDA(At, 1, 0); PG8_STAGE(PG8_SA(0, 1), a2 + hstepA, voffA);
.LBB0_389:
	s_ashr_i32 s27, s26, 31
	s_lshl_b64 s[2:3], s[26:27], 19
	s_add_u32 s23, s42, s2
	s_addc_u32 s27, s43, s3
	s_ashr_i32 s25, s24, 31
	s_lshl_b64 s[2:3], s[24:25], 9
	s_add_u32 s28, s23, s2
	s_addc_u32 s29, s27, s3
	s_and_b64 s[44:45], s[4:5], exec
	s_cselect_b32 s71, s29, s61
	s_cselect_b32 s70, s28, s60
	s_ashr_i32 s44, s26, 4
	s_ashr_i32 s45, s44, 31
	ds_read_b128 v[0:3], v80
	ds_read_b128 v[4:7], v80 offset:1024
	ds_read_b128 v[8:11], v80 offset:2048
	ds_read_b128 v[12:15], v80 offset:3072
	s_lshl_b64 s[44:45], s[44:45], 20
	s_add_u32 s23, s52, s44
	s_addc_u32 s25, s53, s45
	s_add_u32 s44, s23, s2
	s_addc_u32 s45, s25, s3
	s_and_b64 s[2:3], s[4:5], exec
	s_cselect_b32 s69, s45, s63
	s_cselect_b32 s68, s44, s62
	s_add_u32 s2, s60, 0x40080
	s_addc_u32 s3, s61, 0
	s_add_i32 s27, s11, 0xc000
	v_lshl_add_u64 v[48:49], s[2:3], 0, v[64:65]
	s_mov_b32 m0, s27
	ds_read_b128 v[16:19], v81
	ds_read_b128 v[20:23], v81 offset:1024
	ds_read_b128 v[24:27], v81 offset:2048
	ds_read_b128 v[28:31], v81 offset:3072
	ds_read_b128 v[32:35], v81 offset:4096
	ds_read_b128 v[36:39], v81 offset:5120
	ds_read_b128 v[40:43], v81 offset:6144
	ds_read_b128 v[44:47], v81 offset:7168
	global_load_lds_dwordx4 v[48:49], off
	v_lshl_add_u64 v[48:49], s[2:3], 0, v[68:69]
	s_add_i32 s2, s11, 0xe000
	s_mov_b32 m0, s2
	s_nop 0
	global_load_lds_dwordx4 v[48:49], off
	s_waitcnt vmcnt(8)
	s_waitcnt lgkmcnt(0)
	s_barrier
	s_setprio 1
	s_waitcnt lgkmcnt(0)
	v_mfma_f32_16x16x32_bf16 v[48:51], v[0:3], v[16:19], 0
	v_mfma_f32_16x16x32_bf16 v[16:19], v[8:11], v[16:19], 0
	v_mfma_f32_16x16x32_bf16 v[48:51], v[4:7], v[20:23], v[48:51]
	v_mfma_f32_16x16x32_bf16 v[16:19], v[12:15], v[20:23], v[16:19]
	v_mfma_f32_16x16x32_bf16 v[20:23], v[0:3], v[24:27], 0
	v_mfma_f32_16x16x32_bf16 v[24:27], v[8:11], v[24:27], 0
	v_mfma_f32_16x16x32_bf16 v[20:23], v[4:7], v[28:31], v[20:23]
	v_mfma_f32_16x16x32_bf16 v[24:27], v[12:15], v[28:31], v[24:27]
	v_mfma_f32_16x16x32_bf16 v[28:31], v[0:3], v[32:35], 0
	v_mfma_f32_16x16x32_bf16 v[32:35], v[8:11], v[32:35], 0
	v_mfma_f32_16x16x32_bf16 v[28:31], v[4:7], v[36:39], v[28:31]
	v_mfma_f32_16x16x32_bf16 v[32:35], v[12:15], v[36:39], v[32:35]
	v_mfma_f32_16x16x32_bf16 v[36:39], v[0:3], v[40:43], 0
	v_mfma_f32_16x16x32_bf16 v[40:43], v[8:11], v[40:43], 0
	v_mfma_f32_16x16x32_bf16 v[36:39], v[4:7], v[44:47], v[36:39]
	v_mfma_f32_16x16x32_bf16 v[40:43], v[12:15], v[44:47], v[40:43]
	s_setprio 0
	s_setprio 1
	s_setprio 0
	s_barrier
	s_add_i32 s25, s78, s54
	v_lshl_add_u64 v[130:131], s[62:63], 0, v[66:67]
	s_add_i32 s3, s25, 0x2000
	v_lshl_add_u64 v[98:99], v[130:131], 0, s[18:19]
	s_mov_b32 m0, s25
	v_lshl_add_u64 v[132:133], s[62:63], 0, v[70:71]
	s_add_u32 s80, s62, 0x80100
	ds_read_b128 v[44:47], v81 offset:16384
	ds_read_b128 v[52:55], v81 offset:17408
	ds_read_b128 v[56:59], v81 offset:18432
	ds_read_b128 v[60:63], v81 offset:19456
	ds_read_b128 v[82:85], v81 offset:20480
	ds_read_b128 v[86:89], v81 offset:21504
	ds_read_b128 v[90:93], v81 offset:22528
	ds_read_b128 v[94:97], v81 offset:23552
	global_load_lds_dwordx4 v[98:99], off
	v_lshl_add_u64 v[98:99], v[132:133], 0, s[18:19]
	s_mov_b32 m0, s3
	s_addc_u32 s81, s63, 0
	global_load_lds_dwordx4 v[98:99], off
	s_mov_b32 m0, s55
	v_lshl_add_u64 v[134:135], s[60:61], 0, v[64:65]
	global_load_lds_dwordx4 v66, s[80:81]
	s_mov_b32 m0, s56
	v_lshl_add_u64 v[136:137], s[60:61], 0, v[68:69]
	global_load_lds_dwordx4 v70, s[80:81]
	v_lshl_add_u64 v[98:99], v[134:135], 0, s[18:19]
	s_mov_b32 m0, s11
	s_nop 0
	global_load_lds_dwordx4 v[98:99], off
	v_lshl_add_u64 v[98:99], v[136:137], 0, s[18:19]
	s_mov_b32 m0, s57
	s_nop 0
	global_load_lds_dwordx4 v[98:99], off
	s_waitcnt vmcnt(8)
	s_waitcnt lgkmcnt(0)
	s_barrier
	s_setprio 1
	s_waitcnt lgkmcnt(0)
	v_mfma_f32_16x16x32_bf16 v[98:101], v[0:3], v[44:47], 0
	v_mfma_f32_16x16x32_bf16 v[44:47], v[8:11], v[44:47], 0
	v_mfma_f32_16x16x32_bf16 v[98:101], v[4:7], v[52:55], v[98:101]
	v_mfma_f32_16x16x32_bf16 v[44:47], v[12:15], v[52:55], v[44:47]
	v_mfma_f32_16x16x32_bf16 v[52:55], v[0:3], v[56:59], 0
	v_mfma_f32_16x16x32_bf16 v[56:59], v[8:11], v[56:59], 0
	v_mfma_f32_16x16x32_bf16 v[52:55], v[4:7], v[60:63], v[52:55]
	v_mfma_f32_16x16x32_bf16 v[56:59], v[12:15], v[60:63], v[56:59]
	v_mfma_f32_16x16x32_bf16 v[60:63], v[0:3], v[82:85], 0
	v_mfma_f32_16x16x32_bf16 v[0:3], v[0:3], v[90:93], 0
	v_mfma_f32_16x16x32_bf16 v[60:63], v[4:7], v[86:89], v[60:63]
	v_mfma_f32_16x16x32_bf16 v[0:3], v[4:7], v[94:97], v[0:3]
	v_mfma_f32_16x16x32_bf16 v[4:7], v[8:11], v[90:93], 0
	v_mfma_f32_16x16x32_bf16 v[82:85], v[8:11], v[82:85], 0
	v_mfma_f32_16x16x32_bf16 v[4:7], v[12:15], v[94:97], v[4:7]
	v_mfma_f32_16x16x32_bf16 v[82:85], v[12:15], v[86:89], v[82:85]
	s_setprio 0
	s_setprio 1
	s_setprio 0
	s_barrier
	s_add_i32 s79, 0, 0x18000
	v_add_u32_e32 v140, s79, v79
	ds_read_b128 v[8:11], v140
	ds_read_b128 v[12:15], v140 offset:1024
	ds_read_b128 v[86:89], v140 offset:2048
	ds_read_b128 v[90:93], v140 offset:3072
	s_add_u32 s80, s60, 0x40100
	s_addc_u32 s81, s61, 0
	s_mov_b32 m0, s58
	v_lshl_add_u64 v[138:139], s[80:81], 0, v[64:65]
	ds_read_b128 v[94:97], v81 offset:32768
	ds_read_b128 v[102:105], v81 offset:33792
	ds_read_b128 v[106:109], v81 offset:34816
	ds_read_b128 v[110:113], v81 offset:35840
	ds_read_b128 v[114:117], v81 offset:36864
	ds_read_b128 v[118:121], v81 offset:37888
	ds_read_b128 v[122:125], v81 offset:38912
	ds_read_b128 v[126:129], v81 offset:39936
	global_load_lds_dwordx4 v[138:139], off
	v_lshl_add_u64 v[138:139], s[80:81], 0, v[68:69]
	s_mov_b32 m0, s59
	s_nop 0
	global_load_lds_dwordx4 v[138:139], off
	s_waitcnt vmcnt(8)
	s_waitcnt lgkmcnt(0)
	s_barrier
; #define PG8_STAGE(bufoff, gbase, voff) do { _Pragma("unroll") for (int _i = 0; _i < 2; ++_i) \
;         __builtin_amdgcn_global_load_lds((const unsigned*)((const char*)(gbase) + (voff)[_i]), (PG8_LAS unsigned*)(lds + (bufoff) + ldsw + _i * 8192), 16, 0, 0); } while (0)
; #define PG8_LDA(dst, b, h) do { _Pragma("unroll") for (int m = 0; m < 4; ++m) _Pragma("unroll") for (int k = 0; k < 2; ++k) dst[m][k] = *(const PG8_LAS bf16x8*)(lds + PG8_SA(b, h) + aoff + m * 2048 + k * 1024); } while (0)
; #define PG8_LDB(dst, b, h) do { _Pragma("unroll") for (int n = 0; n < 2; ++n) _Pragma("unroll") for (int k = 0; k < 2; ++k) dst[n][k] = *(const PG8_LAS bf16x8*)(lds + PG8_SB(b, h) + boff + n * 2048 + k * 1024); } while (0)
; #define PG8_MMA(ai, bj, At, Bt) do { __builtin_amdgcn_s_setprio(1); _Pragma("unroll") for (int m = 0; m < 4; ++m) _Pragma("unroll") for (int n = 0; n < 2; ++n) _Pragma("unroll") for (int k = 0; k < 2; ++k) \
;         acc[ai][bj][m][n] = __builtin_amdgcn_mfma_f32_16x16x32_bf16(Bt[n][k], At[m][k], acc[ai][bj][m][n], 0, 0, 0); __builtin_amdgcn_s_setprio(0); } while (0)
; #define PG8_WAIT_V(n) asm volatile("s_waitcnt vmcnt(" #n ")" ::: "memory")
; #define PG8_WAIT_L(n) asm volatile("s_waitcnt lgkmcnt(" #n ")" ::: "memory")
; #define PG8_BAR __builtin_amdgcn_s_barrier()
; #define PG8_SCHED __builtin_amdgcn_sched_barrier(0)
; template <class Epi, class Sched, bool ALIGN_EPI = false, bool SP2 = false>
; __device__ __forceinline__ void gemm_phase(PG8_LAS unsigned char* lds, const Gemm g, const Sched& S, const Epi& E) {
;     ...
;             PG8_WAIT_V(8); PG8_WAIT_L(0); PG8_BAR; PG8_MMA(1, 0, At, B0); PG8_MMA(1, 1, At, B1); PG8_BAR; PG8_SCHED;
;             PG8_LDB(B0, 1, 0); PG8_LDB(B1, 1, 1); PG8_SCHED; PG8_LDA(At, 1, 0); PG8_STAGE(PG8_SA(0, 1), a2 + hstepA, voffA);
;             PG8_WAIT_V(8); PG8_WAIT_L(0); PG8_BAR; PG8_MMA(0, 0, At, B0); PG8_MMA(0, 1, At, B1); PG8_BAR; PG8_SCHED;
;             PG8_LDA(At, 1, 1); PG8_STAGE(PG8_SB(1, 0), b3, voffB); PG8_STAGE(PG8_SB(1, 1), b3 + hstepB, voffB); PG8_STAGE(PG8_SA(1, 0), a3, voffA);
;             PG8_WAIT_V(8); PG8_WAIT_L(0); PG8_BAR; PG8_MMA(1, 0, At, B0); PG8_MMA(1, 1, At, B1); PG8_BAR; PG8_SCHED;
	s_setprio 1
	s_waitcnt lgkmcnt(0)
	v_mfma_f32_16x16x32_bf16 v[48:51], v[8:11], v[94:97], v[48:51]
	v_mfma_f32_16x16x32_bf16 v[16:19], v[86:89], v[94:97], v[16:19]
	v_mfma_f32_16x16x32_bf16 v[20:23], v[8:11], v[106:109], v[20:23]
	v_mfma_f32_16x16x32_bf16 v[24:27], v[86:89], v[106:109], v[24:27]
	v_mfma_f32_16x16x32_bf16 v[28:31], v[8:11], v[114:117], v[28:31]
	v_mfma_f32_16x16x32_bf16 v[32:35], v[86:89], v[114:117], v[32:35]
	v_mfma_f32_16x16x32_bf16 v[36:39], v[8:11], v[122:125], v[36:39]
	v_mfma_f32_16x16x32_bf16 v[40:43], v[86:89], v[122:125], v[40:43]
	v_mfma_f32_16x16x32_bf16 v[48:51], v[12:15], v[102:105], v[48:51]
	v_mfma_f32_16x16x32_bf16 v[16:19], v[90:93], v[102:105], v[16:19]
	v_mfma_f32_16x16x32_bf16 v[20:23], v[12:15], v[110:113], v[20:23]
	v_mfma_f32_16x16x32_bf16 v[24:27], v[90:93], v[110:113], v[24:27]
	v_mfma_f32_16x16x32_bf16 v[28:31], v[12:15], v[118:121], v[28:31]
	v_mfma_f32_16x16x32_bf16 v[32:35], v[90:93], v[118:121], v[32:35]
	v_mfma_f32_16x16x32_bf16 v[36:39], v[12:15], v[126:129], v[36:39]
	v_mfma_f32_16x16x32_bf16 v[40:43], v[90:93], v[126:129], v[40:43]
	s_setprio 0
	s_setprio 1
	s_setprio 0
	s_barrier
	s_add_i32 s79, s79, s54
	s_add_i32 s23, s79, 0x2000
	v_lshl_add_u64 v[130:131], v[130:131], 0, s[20:21]
	s_mov_b32 m0, s79
	s_add_u32 s62, s62, 0x80180
	ds_read_b128 v[94:97], v81 offset:49152
	ds_read_b128 v[102:105], v81 offset:50176
	ds_read_b128 v[106:109], v81 offset:51200
	ds_read_b128 v[110:113], v81 offset:52224
	ds_read_b128 v[114:117], v81 offset:53248
	ds_read_b128 v[118:121], v81 offset:54272
	ds_read_b128 v[122:125], v81 offset:55296
	ds_read_b128 v[126:129], v81 offset:56320
	global_load_lds_dwordx4 v[130:131], off
	v_lshl_add_u64 v[130:131], v[132:133], 0, s[20:21]
	s_mov_b32 m0, s23
	s_addc_u32 s63, s63, 0
	global_load_lds_dwordx4 v[130:131], off
	s_mov_b32 m0, s74
	s_nop 0
	global_load_lds_dwordx4 v66, s[62:63]
	s_mov_b32 m0, s75
	s_nop 0
	global_load_lds_dwordx4 v70, s[62:63]
	v_lshl_add_u64 v[130:131], v[134:135], 0, s[20:21]
	s_mov_b32 m0, s72
	s_nop 0
	global_load_lds_dwordx4 v[130:131], off
	v_lshl_add_u64 v[130:131], v[136:137], 0, s[20:21]
	s_mov_b32 m0, s73
	s_nop 0
	global_load_lds_dwordx4 v[130:131], off
	s_waitcnt vmcnt(8)
	s_waitcnt lgkmcnt(0)
	s_barrier
	s_setprio 1
	s_waitcnt lgkmcnt(0)
	v_mfma_f32_16x16x32_bf16 v[44:47], v[86:89], v[94:97], v[44:47]
	v_mfma_f32_16x16x32_bf16 v[52:55], v[8:11], v[106:109], v[52:55]
	v_mfma_f32_16x16x32_bf16 v[56:59], v[86:89], v[106:109], v[56:59]
	v_mfma_f32_16x16x32_bf16 v[60:63], v[8:11], v[114:117], v[60:63]
	v_mfma_f32_16x16x32_bf16 v[0:3], v[8:11], v[122:125], v[0:3]
	v_mfma_f32_16x16x32_bf16 v[4:7], v[86:89], v[122:125], v[4:7]
	v_mfma_f32_16x16x32_bf16 v[98:101], v[8:11], v[94:97], v[98:101]
	v_mfma_f32_16x16x32_bf16 v[44:47], v[90:93], v[102:105], v[44:47]
	v_mfma_f32_16x16x32_bf16 v[52:55], v[12:15], v[110:113], v[52:55]
	v_mfma_f32_16x16x32_bf16 v[56:59], v[90:93], v[110:113], v[56:59]
	v_mfma_f32_16x16x32_bf16 v[60:63], v[12:15], v[118:121], v[60:63]
	v_mfma_f32_16x16x32_bf16 v[82:85], v[86:89], v[114:117], v[82:85]
	v_mfma_f32_16x16x32_bf16 v[0:3], v[12:15], v[126:129], v[0:3]
	v_mfma_f32_16x16x32_bf16 v[4:7], v[90:93], v[126:129], v[4:7]
	v_mfma_f32_16x16x32_bf16 v[98:101], v[12:15], v[102:105], v[98:101]
	v_mfma_f32_16x16x32_bf16 v[82:85], v[90:93], v[118:121], v[82:85]
	s_setprio 0
	s_setprio 1
	s_setprio 0
	s_barrier
	ds_read_b128 v[8:11], v80
	ds_read_b128 v[12:15], v80 offset:1024
	ds_read_b128 v[86:89], v80 offset:2048
	ds_read_b128 v[90:93], v80 offset:3072
	s_add_u32 s60, s60, 0x40180
	s_addc_u32 s61, s61, 0
	s_mov_b32 m0, s27
	v_lshl_add_u64 v[130:131], s[60:61], 0, v[64:65]
	ds_read_b128 v[94:97], v81
	ds_read_b128 v[102:105], v81 offset:1024
	ds_read_b128 v[106:109], v81 offset:2048
	ds_read_b128 v[110:113], v81 offset:3072
	ds_read_b128 v[114:117], v81 offset:4096
	ds_read_b128 v[118:121], v81 offset:5120
	ds_read_b128 v[122:125], v81 offset:6144
	ds_read_b128 v[126:129], v81 offset:7168
	global_load_lds_dwordx4 v[130:131], off
	s_mov_b32 m0, s2
	s_nop 0
	global_load_lds_dwordx4 v68, s[60:61]
	s_waitcnt vmcnt(8)
	s_waitcnt lgkmcnt(0)
	s_barrier
	s_setprio 1
	s_waitcnt lgkmcnt(0)
	v_mfma_f32_16x16x32_bf16 v[24:27], v[86:89], v[106:109], v[24:27]
	v_mfma_f32_16x16x32_bf16 v[48:51], v[8:11], v[94:97], v[48:51]
	v_mfma_f32_16x16x32_bf16 v[16:19], v[86:89], v[94:97], v[16:19]
	v_mfma_f32_16x16x32_bf16 v[94:97], v[90:93], v[110:113], v[24:27]
	v_mfma_f32_16x16x32_bf16 v[24:27], v[8:11], v[114:117], v[28:31]
	v_mfma_f32_16x16x32_bf16 v[48:51], v[12:15], v[102:105], v[48:51]
	v_mfma_f32_16x16x32_bf16 v[16:19], v[90:93], v[102:105], v[16:19]
	v_mfma_f32_16x16x32_bf16 v[102:105], v[12:15], v[118:121], v[24:27]
	v_mfma_f32_16x16x32_bf16 v[24:27], v[86:89], v[114:117], v[32:35]
	v_mfma_f32_16x16x32_bf16 v[32:35], v[90:93], v[118:121], v[24:27]
	v_mfma_f32_16x16x32_bf16 v[24:27], v[8:11], v[122:125], v[36:39]
	v_mfma_f32_16x16x32_bf16 v[20:23], v[8:11], v[106:109], v[20:23]
	v_mfma_f32_16x16x32_bf16 v[36:39], v[12:15], v[126:129], v[24:27]
	v_mfma_f32_16x16x32_bf16 v[24:27], v[86:89], v[122:125], v[40:43]
	v_mfma_f32_16x16x32_bf16 v[20:23], v[12:15], v[110:113], v[20:23]
	v_mfma_f32_16x16x32_bf16 v[40:43], v[90:93], v[126:129], v[24:27]
	s_setprio 0
	s_setprio 1
	s_setprio 0
	s_barrier
; #define PG8_STAGE(bufoff, gbase, voff) do { _Pragma("unroll") for (int _i = 0; _i < 2; ++_i) \
;         __builtin_amdgcn_global_load_lds((const unsigned*)((const char*)(gbase) + (voff)[_i]), (PG8_LAS unsigned*)(lds + (bufoff) + ldsw + _i * 8192), 16, 0, 0); } while (0)
; #define PG8_LDA(dst, b, h) do { _Pragma("unroll") for (int m = 0; m < 4; ++m) _Pragma("unroll") for (int k = 0; k < 2; ++k) dst[m][k] = *(const PG8_LAS bf16x8*)(lds + PG8_SA(b, h) + aoff + m * 2048 + k * 1024); } while (0)
; #define PG8_LDB(dst, b, h) do { _Pragma("unroll") for (int n = 0; n < 2; ++n) _Pragma("unroll") for (int k = 0; k < 2; ++k) dst[n][k] = *(const PG8_LAS bf16x8*)(lds + PG8_SB(b, h) + boff + n * 2048 + k * 1024); } while (0)
; #define PG8_MMA(ai, bj, At, Bt) do { __builtin_amdgcn_s_setprio(1); _Pragma("unroll") for (int m = 0; m < 4; ++m) _Pragma("unroll") for (int n = 0; n < 2; ++n) _Pragma("unroll") for (int k = 0; k < 2; ++k) \
;         acc[ai][bj][m][n] = __builtin_amdgcn_mfma_f32_16x16x32_bf16(Bt[n][k], At[m][k], acc[ai][bj][m][n], 0, 0, 0); __builtin_amdgcn_s_setprio(0); } while (0)
; #define PG8_WAIT_V(n) asm volatile("s_waitcnt vmcnt(" #n ")" ::: "memory")
; template <class Epi, class Sched, bool ALIGN_EPI = false, bool SP2 = false>
; __device__ __forceinline__ void gemm_phase(PG8_LAS unsigned char* lds, const Gemm g, const Sched& S, const Epi& E) {
;     ...
;             PG8_LDB(B0, 0, 0); PG8_LDB(B1, 0, 1); PG8_SCHED; PG8_LDA(At, 0, 0); PG8_STAGE(PG8_SA(1, 1), a1 + hstepA, voffA);
;             PG8_WAIT_V(8); PG8_WAIT_L(0); PG8_BAR; PG8_MMA(0, 0, At, B0); PG8_MMA(0, 1, At, B1); PG8_BAR; PG8_SCHED;
;             PG8_LDA(At, 0, 1); PG8_STAGE(PG8_SB(0, 0), b2, voffB); PG8_STAGE(PG8_SB(0, 1), b2 + hstepB, voffB); PG8_STAGE(PG8_SA(0, 0), a2, voffA);
;             PG8_WAIT_V(8); PG8_WAIT_L(0); PG8_BAR; PG8_MMA(1, 0, At, B0); PG8_MMA(1, 1, At, B1); PG8_BAR; PG8_SCHED;
;             PG8_LDB(B0, 1, 0); PG8_LDB(B1, 1, 1); PG8_SCHED; PG8_LDA(At, 1, 0); PG8_STAGE(PG8_SA(0, 1), a2 + hstepA, voffA);
;             PG8_WAIT_V(8); PG8_WAIT_L(0); PG8_BAR; PG8_MMA(0, 0, At, B0); PG8_MMA(0, 1, At, B1); PG8_BAR; PG8_SCHED;
;             PG8_LDA(At, 1, 1); PG8_STAGE(PG8_SB(1, 0), b3, voffB); PG8_STAGE(PG8_SB(1, 1), b3 + hstepB, voffB); PG8_STAGE(PG8_SA(1, 0), a3, voffA);
;             PG8_WAIT_V(8); PG8_WAIT_L(0); PG8_BAR; PG8_MMA(1, 0, At, B0); PG8_MMA(1, 1, At, B1); PG8_BAR; PG8_SCHED;
	s_mov_b32 m0, s25
	v_lshl_add_u64 v[142:143], s[68:69], 0, v[66:67]
	s_add_u32 s2, s68, 0x80000
	ds_read_b128 v[24:27], v81 offset:16384
	ds_read_b128 v[28:31], v81 offset:17408
	ds_read_b128 v[106:109], v81 offset:18432
	ds_read_b128 v[110:113], v81 offset:19456
	ds_read_b128 v[114:117], v81 offset:20480
	ds_read_b128 v[118:121], v81 offset:21504
	ds_read_b128 v[122:125], v81 offset:22528
	ds_read_b128 v[126:129], v81 offset:23552
	global_load_lds_dwordx4 v[142:143], off
	v_lshl_add_u64 v[144:145], s[68:69], 0, v[70:71]
	s_mov_b32 m0, s3
	s_addc_u32 s3, s69, 0
	global_load_lds_dwordx4 v[144:145], off
	s_mov_b32 m0, s55
	v_lshl_add_u64 v[146:147], s[70:71], 0, v[64:65]
	global_load_lds_dwordx4 v66, s[2:3]
	s_mov_b32 m0, s56
	v_lshl_add_u64 v[148:149], s[70:71], 0, v[68:69]
	global_load_lds_dwordx4 v70, s[2:3]
	s_mov_b32 m0, s11
	s_nop 0
	global_load_lds_dwordx4 v[146:147], off
	s_mov_b32 m0, s57
	s_nop 0
	global_load_lds_dwordx4 v[148:149], off
	s_waitcnt vmcnt(8)
	s_waitcnt lgkmcnt(0)
	s_barrier
	s_setprio 1
	s_waitcnt lgkmcnt(0)
	v_mfma_f32_16x16x32_bf16 v[98:101], v[8:11], v[24:27], v[98:101]
	v_mfma_f32_16x16x32_bf16 v[24:27], v[86:89], v[24:27], v[44:47]
	v_mfma_f32_16x16x32_bf16 v[44:47], v[90:93], v[28:31], v[24:27]
	v_mfma_f32_16x16x32_bf16 v[24:27], v[8:11], v[106:109], v[52:55]
	v_mfma_f32_16x16x32_bf16 v[52:55], v[12:15], v[110:113], v[24:27]
	v_mfma_f32_16x16x32_bf16 v[24:27], v[86:89], v[106:109], v[56:59]
	v_mfma_f32_16x16x32_bf16 v[106:109], v[90:93], v[110:113], v[24:27]
	v_mfma_f32_16x16x32_bf16 v[24:27], v[8:11], v[114:117], v[60:63]
	v_mfma_f32_16x16x32_bf16 v[0:3], v[8:11], v[122:125], v[0:3]
	v_mfma_f32_16x16x32_bf16 v[110:113], v[12:15], v[118:121], v[24:27]
	v_mfma_f32_16x16x32_bf16 v[24:27], v[86:89], v[114:117], v[82:85]
	v_mfma_f32_16x16x32_bf16 v[114:117], v[12:15], v[126:129], v[0:3]
	v_mfma_f32_16x16x32_bf16 v[0:3], v[86:89], v[122:125], v[4:7]
	v_mfma_f32_16x16x32_bf16 v[98:101], v[12:15], v[28:31], v[98:101]
	v_mfma_f32_16x16x32_bf16 v[82:85], v[90:93], v[118:121], v[24:27]
	v_mfma_f32_16x16x32_bf16 v[86:89], v[90:93], v[126:129], v[0:3]
	s_setprio 0
	s_setprio 1
	s_setprio 0
	s_barrier
	ds_read_b128 v[90:93], v140
	ds_read_b128 v[118:121], v140 offset:1024
	ds_read_b128 v[122:125], v140 offset:2048
	ds_read_b128 v[126:129], v140 offset:3072
	s_add_u32 s2, s70, 0x40000
	s_addc_u32 s3, s71, 0
	s_mov_b32 m0, s58
	v_lshl_add_u64 v[24:25], s[2:3], 0, v[64:65]
	ds_read_b128 v[0:3], v81 offset:32768
	ds_read_b128 v[4:7], v81 offset:33792
	ds_read_b128 v[8:11], v81 offset:34816
	ds_read_b128 v[12:15], v81 offset:35840
	ds_read_b128 v[56:59], v81 offset:36864
	ds_read_b128 v[60:63], v81 offset:37888
	ds_read_b128 v[130:133], v81 offset:38912
	ds_read_b128 v[134:137], v81 offset:39936
	global_load_lds_dwordx4 v[24:25], off
	v_lshl_add_u64 v[24:25], s[2:3], 0, v[68:69]
	s_mov_b32 m0, s59
	s_nop 0
	global_load_lds_dwordx4 v[24:25], off
	s_waitcnt vmcnt(8)
	s_waitcnt lgkmcnt(0)
	s_barrier
	s_setprio 1
	s_waitcnt lgkmcnt(0)
	v_mfma_f32_16x16x32_bf16 v[24:27], v[90:93], v[0:3], v[48:51]
	v_mfma_f32_16x16x32_bf16 v[0:3], v[122:125], v[0:3], v[16:19]
	v_mfma_f32_16x16x32_bf16 v[28:31], v[126:129], v[4:7], v[0:3]
	v_mfma_f32_16x16x32_bf16 v[0:3], v[90:93], v[8:11], v[20:23]
	v_mfma_f32_16x16x32_bf16 v[16:19], v[118:121], v[12:15], v[0:3]
	v_mfma_f32_16x16x32_bf16 v[0:3], v[122:125], v[8:11], v[94:97]
	v_mfma_f32_16x16x32_bf16 v[20:23], v[126:129], v[12:15], v[0:3]
	v_mfma_f32_16x16x32_bf16 v[0:3], v[90:93], v[56:59], v[102:105]
	v_mfma_f32_16x16x32_bf16 v[8:11], v[118:121], v[60:63], v[0:3]
	v_mfma_f32_16x16x32_bf16 v[0:3], v[122:125], v[56:59], v[32:35]
	v_mfma_f32_16x16x32_bf16 v[24:27], v[118:121], v[4:7], v[24:27]
	v_mfma_f32_16x16x32_bf16 v[12:15], v[126:129], v[60:63], v[0:3]
	v_mfma_f32_16x16x32_bf16 v[0:3], v[90:93], v[130:133], v[36:39]
	v_mfma_f32_16x16x32_bf16 v[4:7], v[122:125], v[130:133], v[40:43]
	v_mfma_f32_16x16x32_bf16 v[0:3], v[118:121], v[134:137], v[0:3]
	v_mfma_f32_16x16x32_bf16 v[4:7], v[126:129], v[134:137], v[4:7]
	s_setprio 0
	s_setprio 1
	s_setprio 0
	s_barrier
	s_mov_b32 m0, s79
	v_lshl_add_u64 v[48:49], v[142:143], 0, s[8:9]
	s_add_u32 s2, s68, 0x80080
	ds_read_b128 v[32:35], v81 offset:49152
	ds_read_b128 v[36:39], v81 offset:50176
	ds_read_b128 v[40:43], v81 offset:51200
	ds_read_b128 v[94:97], v81 offset:52224
	ds_read_b128 v[102:105], v81 offset:53248
	ds_read_b128 v[130:133], v81 offset:54272
	ds_read_b128 v[134:137], v81 offset:55296
	ds_read_b128 v[138:141], v81 offset:56320
	global_load_lds_dwordx4 v[48:49], off
	v_lshl_add_u64 v[48:49], v[144:145], 0, s[8:9]
	s_mov_b32 m0, s23
	s_addc_u32 s3, s69, 0
	global_load_lds_dwordx4 v[48:49], off
	s_mov_b32 m0, s74
	s_nop 0
	global_load_lds_dwordx4 v66, s[2:3]
	s_mov_b32 m0, s75
	s_nop 0
	global_load_lds_dwordx4 v70, s[2:3]
	v_lshl_add_u64 v[48:49], v[146:147], 0, s[8:9]
	s_mov_b32 m0, s72
	s_nop 0
	global_load_lds_dwordx4 v[48:49], off
	v_lshl_add_u64 v[48:49], v[148:149], 0, s[8:9]
	s_mov_b32 m0, s73
	s_nop 0
	global_load_lds_dwordx4 v[48:49], off
	s_waitcnt vmcnt(8)
	s_waitcnt lgkmcnt(0)
	s_barrier
	s_setprio 1
	s_waitcnt lgkmcnt(0)
	v_mfma_f32_16x16x32_bf16 v[48:51], v[90:93], v[32:35], v[98:101]
	v_mfma_f32_16x16x32_bf16 v[32:35], v[122:125], v[32:35], v[44:47]
	v_mfma_f32_16x16x32_bf16 v[60:63], v[126:129], v[36:39], v[32:35]
	v_mfma_f32_16x16x32_bf16 v[32:35], v[90:93], v[40:43], v[52:55]
	v_mfma_f32_16x16x32_bf16 v[56:59], v[118:121], v[36:39], v[48:51]
	v_mfma_f32_16x16x32_bf16 v[48:51], v[118:121], v[94:97], v[32:35]
	v_mfma_f32_16x16x32_bf16 v[32:35], v[122:125], v[40:43], v[106:109]
	v_mfma_f32_16x16x32_bf16 v[52:55], v[126:129], v[94:97], v[32:35]
	v_mfma_f32_16x16x32_bf16 v[32:35], v[90:93], v[102:105], v[110:113]
	v_mfma_f32_16x16x32_bf16 v[40:43], v[118:121], v[130:133], v[32:35]
	v_mfma_f32_16x16x32_bf16 v[32:35], v[122:125], v[102:105], v[82:85]
	v_mfma_f32_16x16x32_bf16 v[44:47], v[126:129], v[130:133], v[32:35]
	v_mfma_f32_16x16x32_bf16 v[32:35], v[90:93], v[134:137], v[114:117]
	v_mfma_f32_16x16x32_bf16 v[36:39], v[122:125], v[134:137], v[86:89]
	v_mfma_f32_16x16x32_bf16 v[32:35], v[118:121], v[138:141], v[32:35]
	v_mfma_f32_16x16x32_bf16 v[36:39], v[126:129], v[138:141], v[36:39]
	s_setprio 0
	s_setprio 1
	s_setprio 0
	s_barrier
	s_andn2_b64 vcc, exec, s[12:13]
	s_cbranch_vccnz .LBB0_391
	s_barrier

; #define PG8_STAGE(bufoff, gbase, voff) do { _Pragma("unroll") for (int _i = 0; _i < 2; ++_i) \
;         __builtin_amdgcn_global_load_lds((const unsigned*)((const char*)(gbase) + (voff)[_i]), (PG8_LAS unsigned*)(lds + (bufoff) + ldsw + _i * 8192), 16, 0, 0); } while (0)
; #define PG8_WAIT_V(n) asm volatile("s_waitcnt vmcnt(" #n ")" ::: "memory")
; #define PG8_BAR __builtin_amdgcn_s_barrier()
; template <class Epi, class Sched, bool ALIGN_EPI = false, bool SP2 = false>
; __device__ __forceinline__ void gemm_phase(PG8_LAS unsigned char* lds, const Gemm g, const Sched& S, const Epi& E) {
;     ...
;     f32x4 acc[2][2][4][2];
; #pragma unroll
;     for (int a = 0; a < 2; ++a)
; #pragma unroll
;         for (int b = 0; b < 2; ++b)
; #pragma unroll
;             for (int m = 0; m < 4; ++m)
; #pragma unroll
;                 for (int n = 0; n < 2; ++n) acc[a][b][m][n] = (f32x4){0.f, 0.f, 0.f, 0.f};
;     bf16x8 At[4][2], B0[2][2], B1[2][2];
;     const char* cA = PG8_UA(cur); const char* cB = PG8_UB(cur);
;     S.a_ready(cur);
;     if constexpr (SP2) {
;         PG8_STAGE(PG8_SB(0, 0), cB, voffB); PG8_STAGE(PG8_SB(0, 1), cB + hstepB, voffB); PG8_STAGE(PG8_SA(0, 0), cA, voffA); PG8_STAGE(PG8_SA(0, 1), cA + hstepA, voffA);
;         if (wr == 1) PG8_BAR;
;         PG8_WAIT_V(2); PG8_BAR;
;         PG8_STAGE(PG8_SB(1, 0), cB + kstep, voffB); PG8_STAGE(PG8_SA(1, 0), cA + kstep, voffA); PG8_STAGE(PG8_SB(1, 1), cB + hstepB + kstep, voffB);
;         PG8_WAIT_V(6); PG8_BAR;
;     } else {
;         PG8_STAGE(PG8_SB(0, 0), cB, voffB); PG8_STAGE(PG8_SA(0, 0), cA, voffA); PG8_STAGE(PG8_SB(0, 1), cB + hstepB, voffB); PG8_STAGE(PG8_SA(0, 1), cA + hstepA, voffA);
;         if (wr == 1) PG8_BAR;
;         PG8_WAIT_V(4); PG8_BAR;
;         PG8_STAGE(PG8_SB(1, 0), cB + kstep, voffB); PG8_STAGE(PG8_SA(1, 0), cA + kstep, voffA); PG8_STAGE(PG8_SB(1, 1), cB + hstepB + kstep, voffB);
;         PG8_WAIT_V(6); PG8_BAR;
;     }
.LBB0_884:
	v_lshlrev_b32_e32 v9, 2, v161
	s_and_b32 s41, s6, 3
	v_lshl_or_b32 v8, v161, 6, v166
	s_lshl_b32 s6, s2, 13
	v_and_b32_e32 v9, 32, v9
	v_bitop3_b32 v8, v8, s6, v9 bitop3:0xde
	s_mov_b64 s[6:7], 0x80
	s_add_i32 m0, s3, 0x18000
	v_lshl_add_u64 v[6:7], v[6:7], 0, s[6:7]
	s_waitcnt vmcnt(2)
	s_barrier
	global_load_lds_dwordx4 v[6:7], off
	v_lshl_add_u64 v[4:5], v[4:5], 0, s[6:7]
	s_add_i32 m0, s3, 0x1a000
	s_add_i32 s45, s3, 0x8000
	s_add_i32 s46, s3, 0xa000
	global_load_lds_dwordx4 v[4:5], off
	v_lshl_add_u64 v[2:3], v[2:3], 0, s[6:7]
	s_mov_b32 m0, s45
	s_add_u32 s24, s0, 0x40080
	global_load_lds_dwordx4 v[2:3], off
	v_lshl_add_u64 v[0:1], v[0:1], 0, s[6:7]
	s_mov_b32 m0, s46
	s_addc_u32 s25, s1, 0
	global_load_lds_dwordx4 v[0:1], off
	s_add_i32 m0, s3, 0x1c000
	global_load_lds_dwordx4 v146, s[24:25]
	v_lshl_add_u64 v[0:1], s[24:25], 0, v[150:151]
	s_add_i32 m0, s3, 0x1e000
	v_lshlrev_b32_e32 v2, 11, v164
	global_load_lds_dwordx4 v[0:1], off
	v_lshlrev_b32_e32 v0, 8, v194
	v_and_b32_e32 v0, 0x38000, v0
	s_add_u32 s18, s34, s18
	v_or3_b32 v0, v162, v0, v2
	s_addc_u32 s19, s35, s19
	v_add_u32_e32 v0, v0, v163
	v_mov_b32_e32 v1, v147
	v_lshl_add_u64 v[0:1], s[18:19], 0, v[0:1]
	s_mov_b64 s[24:25], 0x3840080
	v_lshl_add_u64 v[96:97], v[0:1], 0, s[24:25]
	v_lshlrev_b32_e32 v0, 4, v165
	s_add_u32 s20, s34, s20
	v_and_b32_e32 v0, 0x78000, v0
	s_addc_u32 s21, s35, s21
	v_or3_b32 v0, v162, v0, v2
	s_add_u32 s47, s20, 0x700100
	v_lshl_or_b32 v9, s41, 12, v167
	s_waitcnt vmcnt(6)
	v_add_u32_e32 v0, v0, v163
	v_mov_b32_e32 v1, v147
	s_addc_u32 s48, s21, 0
	s_add_i32 s52, 0, 0x10000
	s_add_i32 s54, 0, 0x14000
	s_add_i32 s56, 0, 0x18000
	s_add_i32 s58, 0, 0x1c000
	v_lshl_add_u64 v[0:1], s[18:19], 0, v[0:1]
	v_add_u32_e32 v100, s52, v9
	v_add_u32_e32 v101, s54, v9
	s_add_i32 s52, s52, s22
	s_add_i32 s54, s54, s22
	v_add_u32_e32 v103, s56, v9
	v_add_u32_e32 v104, s58, v9
	s_add_i32 s56, s56, s22
	s_add_i32 s58, s58, s22
	v_lshl_or_b32 v152, s2, 6, v161
	v_lshl_add_u64 v[98:99], v[0:1], 0, s[24:25]
	s_mov_b32 s49, -2
	s_mov_b64 s[20:21], 0
	v_add_u32_e32 v102, 0, v8
	s_add_i32 s50, s3, 0xc000
	s_add_i32 s51, s3, 0xe000
	s_add_i32 s53, s52, 0x2000
	s_add_i32 s55, s54, 0x2000
	s_add_i32 s57, s56, 0x2000
	s_add_i32 s59, s58, 0x2000
	v_mov_b32_e32 v0, v147
	v_mov_b32_e32 v1, v147
	v_mov_b32_e32 v2, v147
	v_mov_b32_e32 v3, v147
	v_mov_b32_e32 v4, v147
	v_mov_b32_e32 v5, v147
	v_mov_b32_e32 v6, v147
	v_mov_b32_e32 v7, v147
	v_mov_b32_e32 v16, v147
	v_mov_b32_e32 v17, v147
	v_mov_b32_e32 v18, v147
	v_mov_b32_e32 v19, v147
	v_mov_b32_e32 v20, v147
	v_mov_b32_e32 v21, v147
	v_mov_b32_e32 v22, v147
	v_mov_b32_e32 v23, v147
	v_mov_b32_e32 v32, v147
	v_mov_b32_e32 v33, v147
	v_mov_b32_e32 v34, v147
	v_mov_b32_e32 v35, v147
	v_mov_b32_e32 v36, v147
	v_mov_b32_e32 v37, v147
	v_mov_b32_e32 v38, v147
	v_mov_b32_e32 v39, v147
	v_mov_b32_e32 v48, v147
	v_mov_b32_e32 v49, v147
	v_mov_b32_e32 v50, v147
	v_mov_b32_e32 v51, v147
	v_mov_b32_e32 v52, v147
	v_mov_b32_e32 v53, v147
	v_mov_b32_e32 v54, v147
	v_mov_b32_e32 v55, v147
	v_mov_b32_e32 v8, v147
	v_mov_b32_e32 v9, v147
	v_mov_b32_e32 v10, v147
	v_mov_b32_e32 v11, v147
	v_mov_b32_e32 v12, v147
	v_mov_b32_e32 v13, v147
	v_mov_b32_e32 v14, v147
	v_mov_b32_e32 v15, v147
	v_mov_b32_e32 v24, v147
	v_mov_b32_e32 v25, v147
	v_mov_b32_e32 v26, v147
	v_mov_b32_e32 v27, v147
	v_mov_b32_e32 v28, v147
	v_mov_b32_e32 v29, v147
	v_mov_b32_e32 v30, v147
	v_mov_b32_e32 v31, v147
	v_mov_b32_e32 v40, v147
	v_mov_b32_e32 v41, v147
	v_mov_b32_e32 v42, v147
	v_mov_b32_e32 v43, v147
	v_mov_b32_e32 v44, v147
	v_mov_b32_e32 v45, v147
	v_mov_b32_e32 v46, v147
	v_mov_b32_e32 v47, v147
	v_mov_b32_e32 v56, v147
	v_mov_b32_e32 v57, v147
	v_mov_b32_e32 v58, v147
	v_mov_b32_e32 v59, v147
	v_mov_b32_e32 v60, v147
	v_mov_b32_e32 v61, v147
	v_mov_b32_e32 v62, v147
	v_mov_b32_e32 v63, v147
	v_mov_b32_e32 v64, v147
	v_mov_b32_e32 v65, v147
	v_mov_b32_e32 v66, v147
	v_mov_b32_e32 v67, v147
	v_mov_b32_e32 v68, v147
	v_mov_b32_e32 v69, v147
	v_mov_b32_e32 v70, v147
	v_mov_b32_e32 v71, v147
	v_mov_b32_e32 v80, v147
	v_mov_b32_e32 v81, v147
	v_mov_b32_e32 v82, v147
	v_mov_b32_e32 v83, v147
	v_mov_b32_e32 v84, v147
	v_mov_b32_e32 v85, v147
	v_mov_b32_e32 v86, v147
	v_mov_b32_e32 v87, v147
	v_mov_b32_e32 v112, v147
	v_mov_b32_e32 v113, v147
	v_mov_b32_e32 v114, v147
	v_mov_b32_e32 v115, v147
	v_mov_b32_e32 v116, v147
	v_mov_b32_e32 v117, v147
	v_mov_b32_e32 v118, v147
	v_mov_b32_e32 v119, v147
	v_mov_b32_e32 v128, v147
	v_mov_b32_e32 v129, v147
	v_mov_b32_e32 v130, v147
	v_mov_b32_e32 v131, v147
	v_mov_b32_e32 v132, v147
	v_mov_b32_e32 v133, v147
	v_mov_b32_e32 v134, v147
	v_mov_b32_e32 v135, v147
	v_mov_b32_e32 v72, v147
	v_mov_b32_e32 v73, v147
	v_mov_b32_e32 v74, v147
	v_mov_b32_e32 v75, v147
	v_mov_b32_e32 v76, v147
	v_mov_b32_e32 v77, v147
	v_mov_b32_e32 v78, v147
	v_mov_b32_e32 v79, v147
	v_mov_b32_e32 v88, v147
	v_mov_b32_e32 v89, v147
	v_mov_b32_e32 v90, v147
	v_mov_b32_e32 v91, v147
	v_mov_b32_e32 v92, v147
	v_mov_b32_e32 v93, v147
	v_mov_b32_e32 v94, v147
	v_mov_b32_e32 v95, v147
	v_mov_b32_e32 v120, v147
	v_mov_b32_e32 v121, v147
	v_mov_b32_e32 v122, v147
	v_mov_b32_e32 v123, v147
	v_mov_b32_e32 v124, v147
	v_mov_b32_e32 v125, v147
	v_mov_b32_e32 v126, v147
	v_mov_b32_e32 v127, v147
	v_mov_b32_e32 v136, v147
	v_mov_b32_e32 v137, v147
	v_mov_b32_e32 v138, v147
	v_mov_b32_e32 v139, v147
	v_mov_b32_e32 v140, v147
	v_mov_b32_e32 v141, v147
	v_mov_b32_e32 v142, v147
	v_mov_b32_e32 v143, v147
	s_barrier
; #define PG8_STAGE(bufoff, gbase, voff) do { _Pragma("unroll") for (int _i = 0; _i < 2; ++_i) \
;         __builtin_amdgcn_global_load_lds((const unsigned*)((const char*)(gbase) + (voff)[_i]), (PG8_LAS unsigned*)(lds + (bufoff) + ldsw + _i * 8192), 16, 0, 0); } while (0)
; #define PG8_LDA(dst, b, h) do { _Pragma("unroll") for (int m = 0; m < 4; ++m) _Pragma("unroll") for (int k = 0; k < 2; ++k) dst[m][k] = *(const PG8_LAS bf16x8*)(lds + PG8_SA(b, h) + aoff + m * 2048 + k * 1024); } while (0)
; #define PG8_LDB(dst, b, h) do { _Pragma("unroll") for (int n = 0; n < 2; ++n) _Pragma("unroll") for (int k = 0; k < 2; ++k) dst[n][k] = *(const PG8_LAS bf16x8*)(lds + PG8_SB(b, h) + boff + n * 2048 + k * 1024); } while (0)
; #define PG8_MMA(ai, bj, At, Bt) do { __builtin_amdgcn_s_setprio(1); _Pragma("unroll") for (int m = 0; m < 4; ++m) _Pragma("unroll") for (int n = 0; n < 2; ++n) _Pragma("unroll") for (int k = 0; k < 2; ++k) \
;         acc[ai][bj][m][n] = __builtin_amdgcn_mfma_f32_16x16x32_bf16(Bt[n][k], At[m][k], acc[ai][bj][m][n], 0, 0, 0); __builtin_amdgcn_s_setprio(0); } while (0)
; #define PG8_WAIT_V(n) asm volatile("s_waitcnt vmcnt(" #n ")" ::: "memory")
; #define PG8_WAIT_L(n) asm volatile("s_waitcnt lgkmcnt(" #n ")" ::: "memory")
; #define PG8_BAR __builtin_amdgcn_s_barrier()
; #define PG8_SCHED __builtin_amdgcn_sched_barrier(0)
; template <class Epi, class Sched, bool ALIGN_EPI = false, bool SP2 = false>
; __device__ __forceinline__ void gemm_phase(PG8_LAS unsigned char* lds, const Gemm g, const Sched& S, const Epi& E) {
;     ...
;             PG8_LDB(B0, 0, 0); PG8_LDB(B1, 0, 1); PG8_SCHED; PG8_LDA(At, 0, 0); PG8_STAGE(PG8_SA(1, 1), a1 + hstepA, voffA);
;             PG8_WAIT_V(8); PG8_WAIT_L(0); PG8_BAR; PG8_MMA(0, 0, At, B0); PG8_MMA(0, 1, At, B1); PG8_BAR; PG8_SCHED;
;             PG8_LDA(At, 0, 1); PG8_STAGE(PG8_SB(0, 0), b2, voffB); PG8_STAGE(PG8_SB(0, 1), b2 + hstepB, voffB); PG8_STAGE(PG8_SA(0, 0), a2, voffA);
;             PG8_WAIT_V(8); PG8_WAIT_L(0); PG8_BAR; PG8_MMA(1, 0, At, B0); PG8_MMA(1, 1, At, B1); PG8_BAR; PG8_SCHED;
.LBB0_885:
	ds_read_b128 v[106:109], v100
	ds_read_b128 v[154:157], v100 offset:1024
	ds_read_b128 v[168:171], v100 offset:2048
	ds_read_b128 v[172:175], v100 offset:3072
	ds_read_b128 v[176:179], v101
	ds_read_b128 v[180:183], v101 offset:1024
	ds_read_b128 v[184:187], v101 offset:2048
	ds_read_b128 v[188:191], v101 offset:3072
	s_add_u32 s22, s18, s20
	s_addc_u32 s23, s19, s21
	s_add_u32 s22, s22, 0x3800100
	s_addc_u32 s23, s23, 0
	s_add_u32 s60, s47, s20
	s_addc_u32 s61, s48, s21
	s_cmpk_eq_i32 s20, 0x700
	s_cselect_b32 s25, s5, s23
	s_cselect_b32 s24, s4, s22
	s_cselect_b32 s23, s1, s61
	s_cselect_b32 s22, s0, s60
	s_mov_b32 m0, s50
	v_lshl_add_u64 v[110:111], v[96:97], 0, s[20:21]
	ds_read_b128 v[196:199], v102
	ds_read_b128 v[200:203], v102 offset:1024
	ds_read_b128 v[204:207], v102 offset:2048
	ds_read_b128 v[208:211], v102 offset:3072
	ds_read_b128 v[212:215], v102 offset:4096
	ds_read_b128 v[216:219], v102 offset:5120
	ds_read_b128 v[220:223], v102 offset:6144
	ds_read_b128 v[224:227], v102 offset:7168
	global_load_lds_dwordx4 v[110:111], off
	v_lshl_add_u64 v[110:111], v[98:99], 0, s[20:21]
	s_mov_b32 m0, s51
	s_nop 0
	global_load_lds_dwordx4 v[110:111], off
	s_waitcnt vmcnt(8)
	s_waitcnt lgkmcnt(0)
	s_barrier
	s_setprio 1
	s_waitcnt lgkmcnt(0)
	v_mfma_f32_16x16x32_bf16 v[140:143], v[106:109], v[196:199], v[140:143]
	v_mfma_f32_16x16x32_bf16 v[136:139], v[168:171], v[196:199], v[136:139]
	v_mfma_f32_16x16x32_bf16 v[124:127], v[106:109], v[204:207], v[124:127]
	v_mfma_f32_16x16x32_bf16 v[120:123], v[168:171], v[204:207], v[120:123]
	v_mfma_f32_16x16x32_bf16 v[92:95], v[106:109], v[212:215], v[92:95]
	v_mfma_f32_16x16x32_bf16 v[88:91], v[168:171], v[212:215], v[88:91]
	v_mfma_f32_16x16x32_bf16 v[76:79], v[106:109], v[220:223], v[76:79]
	v_mfma_f32_16x16x32_bf16 v[72:75], v[168:171], v[220:223], v[72:75]
	v_mfma_f32_16x16x32_bf16 v[140:143], v[154:157], v[200:203], v[140:143]
	v_mfma_f32_16x16x32_bf16 v[136:139], v[172:175], v[200:203], v[136:139]
	v_mfma_f32_16x16x32_bf16 v[124:127], v[154:157], v[208:211], v[124:127]
	v_mfma_f32_16x16x32_bf16 v[120:123], v[172:175], v[208:211], v[120:123]
	v_mfma_f32_16x16x32_bf16 v[92:95], v[154:157], v[216:219], v[92:95]
	v_mfma_f32_16x16x32_bf16 v[88:91], v[172:175], v[216:219], v[88:91]
	v_mfma_f32_16x16x32_bf16 v[76:79], v[154:157], v[224:227], v[76:79]
	v_mfma_f32_16x16x32_bf16 v[72:75], v[172:175], v[224:227], v[72:75]
	s_setprio 0
	s_setprio 1
	v_mfma_f32_16x16x32_bf16 v[132:135], v[176:179], v[196:199], v[132:135]
	v_mfma_f32_16x16x32_bf16 v[128:131], v[184:187], v[196:199], v[128:131]
	v_mfma_f32_16x16x32_bf16 v[116:119], v[176:179], v[204:207], v[116:119]
	v_mfma_f32_16x16x32_bf16 v[110:113], v[184:187], v[204:207], v[112:115]
	v_mfma_f32_16x16x32_bf16 v[84:87], v[176:179], v[212:215], v[84:87]
	v_mfma_f32_16x16x32_bf16 v[80:83], v[184:187], v[212:215], v[80:83]
	v_mfma_f32_16x16x32_bf16 v[68:71], v[176:179], v[220:223], v[68:71]
	v_mfma_f32_16x16x32_bf16 v[64:67], v[184:187], v[220:223], v[64:67]
	v_mfma_f32_16x16x32_bf16 v[132:135], v[180:183], v[200:203], v[132:135]
	v_mfma_f32_16x16x32_bf16 v[128:131], v[188:191], v[200:203], v[128:131]
	v_mfma_f32_16x16x32_bf16 v[116:119], v[180:183], v[208:211], v[116:119]
	v_mfma_f32_16x16x32_bf16 v[110:113], v[188:191], v[208:211], v[110:113]
	v_mfma_f32_16x16x32_bf16 v[84:87], v[180:183], v[216:219], v[84:87]
	v_mfma_f32_16x16x32_bf16 v[80:83], v[188:191], v[216:219], v[80:83]
	v_mfma_f32_16x16x32_bf16 v[68:71], v[180:183], v[224:227], v[68:71]
	v_mfma_f32_16x16x32_bf16 v[64:67], v[188:191], v[224:227], v[64:67]
	s_setprio 0
	s_barrier
	s_mov_b32 m0, s52
	v_lshl_add_u64 v[158:159], s[22:23], 0, v[146:147]
	s_add_u32 s60, s22, 0x40000
	ds_read_b128 v[196:199], v102 offset:16384
	ds_read_b128 v[200:203], v102 offset:17408
	ds_read_b128 v[204:207], v102 offset:18432
	ds_read_b128 v[208:211], v102 offset:19456
	ds_read_b128 v[212:215], v102 offset:20480
	ds_read_b128 v[216:219], v102 offset:21504
	ds_read_b128 v[220:223], v102 offset:22528
	ds_read_b128 v[224:227], v102 offset:23552
	global_load_lds_dwordx4 v[158:159], off
	v_lshl_add_u64 v[228:229], s[22:23], 0, v[150:151]
	s_mov_b32 m0, s53
	s_addc_u32 s61, s23, 0
	global_load_lds_dwordx4 v[228:229], off
	s_mov_b32 m0, s54
	v_lshl_add_u64 v[230:231], s[24:25], 0, v[144:145]
	global_load_lds_dwordx4 v146, s[60:61]
	s_mov_b32 m0, s55
	v_lshl_add_u64 v[232:233], s[24:25], 0, v[148:149]
	global_load_lds_dwordx4 v150, s[60:61]
	s_mov_b32 m0, s3
	s_nop 0
	global_load_lds_dwordx4 v[230:231], off
	s_mov_b32 m0, s42
	s_nop 0
	global_load_lds_dwordx4 v[232:233], off
	s_waitcnt vmcnt(8)
	s_waitcnt lgkmcnt(0)
	s_barrier
; #define PG8_STAGE(bufoff, gbase, voff) do { _Pragma("unroll") for (int _i = 0; _i < 2; ++_i) \
;         __builtin_amdgcn_global_load_lds((const unsigned*)((const char*)(gbase) + (voff)[_i]), (PG8_LAS unsigned*)(lds + (bufoff) + ldsw + _i * 8192), 16, 0, 0); } while (0)
; #define PG8_LDA(dst, b, h) do { _Pragma("unroll") for (int m = 0; m < 4; ++m) _Pragma("unroll") for (int k = 0; k < 2; ++k) dst[m][k] = *(const PG8_LAS bf16x8*)(lds + PG8_SA(b, h) + aoff + m * 2048 + k * 1024); } while (0)
; #define PG8_LDB(dst, b, h) do { _Pragma("unroll") for (int n = 0; n < 2; ++n) _Pragma("unroll") for (int k = 0; k < 2; ++k) dst[n][k] = *(const PG8_LAS bf16x8*)(lds + PG8_SB(b, h) + boff + n * 2048 + k * 1024); } while (0)
; #define PG8_MMA(ai, bj, At, Bt) do { __builtin_amdgcn_s_setprio(1); _Pragma("unroll") for (int m = 0; m < 4; ++m) _Pragma("unroll") for (int n = 0; n < 2; ++n) _Pragma("unroll") for (int k = 0; k < 2; ++k) \
;         acc[ai][bj][m][n] = __builtin_amdgcn_mfma_f32_16x16x32_bf16(Bt[n][k], At[m][k], acc[ai][bj][m][n], 0, 0, 0); __builtin_amdgcn_s_setprio(0); } while (0)
; #define PG8_WAIT_V(n) asm volatile("s_waitcnt vmcnt(" #n ")" ::: "memory")
; #define PG8_WAIT_L(n) asm volatile("s_waitcnt lgkmcnt(" #n ")" ::: "memory")
; #define PG8_BAR __builtin_amdgcn_s_barrier()
; #define PG8_SCHED __builtin_amdgcn_sched_barrier(0)
; template <class Epi, class Sched, bool ALIGN_EPI = false, bool SP2 = false>
; __device__ __forceinline__ void gemm_phase(PG8_LAS unsigned char* lds, const Gemm g, const Sched& S, const Epi& E) {
;     ...
;             PG8_WAIT_V(8); PG8_WAIT_L(0); PG8_BAR; PG8_MMA(1, 0, At, B0); PG8_MMA(1, 1, At, B1); PG8_BAR; PG8_SCHED;
;             PG8_LDB(B0, 1, 0); PG8_LDB(B1, 1, 1); PG8_SCHED; PG8_LDA(At, 1, 0); PG8_STAGE(PG8_SA(0, 1), a2 + hstepA, voffA);
;             PG8_WAIT_V(8); PG8_WAIT_L(0); PG8_BAR; PG8_MMA(0, 0, At, B0); PG8_MMA(0, 1, At, B1); PG8_BAR; PG8_SCHED;
;             PG8_LDA(At, 1, 1); PG8_STAGE(PG8_SB(1, 0), b3, voffB); PG8_STAGE(PG8_SB(1, 1), b3 + hstepB, voffB); PG8_STAGE(PG8_SA(1, 0), a3, voffA);
	s_setprio 1
	s_waitcnt lgkmcnt(0)
	v_mfma_f32_16x16x32_bf16 v[60:63], v[106:109], v[196:199], v[60:63]
	v_mfma_f32_16x16x32_bf16 v[56:59], v[168:171], v[196:199], v[56:59]
	v_mfma_f32_16x16x32_bf16 v[44:47], v[106:109], v[204:207], v[44:47]
	v_mfma_f32_16x16x32_bf16 v[40:43], v[168:171], v[204:207], v[40:43]
	v_mfma_f32_16x16x32_bf16 v[28:31], v[106:109], v[212:215], v[28:31]
	v_mfma_f32_16x16x32_bf16 v[24:27], v[168:171], v[212:215], v[24:27]
	v_mfma_f32_16x16x32_bf16 v[12:15], v[106:109], v[220:223], v[12:15]
	v_mfma_f32_16x16x32_bf16 v[8:11], v[168:171], v[220:223], v[8:11]
	v_mfma_f32_16x16x32_bf16 v[60:63], v[154:157], v[200:203], v[60:63]
	v_mfma_f32_16x16x32_bf16 v[56:59], v[172:175], v[200:203], v[56:59]
	v_mfma_f32_16x16x32_bf16 v[44:47], v[154:157], v[208:211], v[44:47]
	v_mfma_f32_16x16x32_bf16 v[40:43], v[172:175], v[208:211], v[40:43]
	v_mfma_f32_16x16x32_bf16 v[28:31], v[154:157], v[216:219], v[28:31]
	v_mfma_f32_16x16x32_bf16 v[24:27], v[172:175], v[216:219], v[24:27]
	v_mfma_f32_16x16x32_bf16 v[12:15], v[154:157], v[224:227], v[12:15]
	v_mfma_f32_16x16x32_bf16 v[8:11], v[172:175], v[224:227], v[8:11]
	s_setprio 0
	s_setprio 1
	v_mfma_f32_16x16x32_bf16 v[52:55], v[176:179], v[196:199], v[52:55]
	v_mfma_f32_16x16x32_bf16 v[48:51], v[184:187], v[196:199], v[48:51]
	v_mfma_f32_16x16x32_bf16 v[36:39], v[176:179], v[204:207], v[36:39]
	v_mfma_f32_16x16x32_bf16 v[32:35], v[184:187], v[204:207], v[32:35]
	v_mfma_f32_16x16x32_bf16 v[20:23], v[176:179], v[212:215], v[20:23]
	v_mfma_f32_16x16x32_bf16 v[16:19], v[184:187], v[212:215], v[16:19]
	v_mfma_f32_16x16x32_bf16 v[4:7], v[176:179], v[220:223], v[4:7]
	v_mfma_f32_16x16x32_bf16 v[0:3], v[184:187], v[220:223], v[0:3]
	v_mfma_f32_16x16x32_bf16 v[52:55], v[180:183], v[200:203], v[52:55]
	v_mfma_f32_16x16x32_bf16 v[48:51], v[188:191], v[200:203], v[48:51]
	v_mfma_f32_16x16x32_bf16 v[36:39], v[180:183], v[208:211], v[36:39]
	v_mfma_f32_16x16x32_bf16 v[32:35], v[188:191], v[208:211], v[32:35]
	v_mfma_f32_16x16x32_bf16 v[20:23], v[180:183], v[216:219], v[20:23]
	v_mfma_f32_16x16x32_bf16 v[16:19], v[188:191], v[216:219], v[16:19]
	v_mfma_f32_16x16x32_bf16 v[4:7], v[180:183], v[224:227], v[4:7]
	v_mfma_f32_16x16x32_bf16 v[0:3], v[188:191], v[224:227], v[0:3]
	s_setprio 0
	s_barrier
	ds_read_b128 v[106:109], v103
	ds_read_b128 v[154:157], v103 offset:1024
	ds_read_b128 v[168:171], v103 offset:2048
	ds_read_b128 v[172:175], v103 offset:3072
	ds_read_b128 v[176:179], v104
	ds_read_b128 v[180:183], v104 offset:1024
	ds_read_b128 v[184:187], v104 offset:2048
	ds_read_b128 v[188:191], v104 offset:3072
	s_add_u32 s24, s24, 0x40000
	s_addc_u32 s25, s25, 0
	s_mov_b32 m0, s43
	v_lshl_add_u64 v[114:115], s[24:25], 0, v[144:145]
	ds_read_b128 v[196:199], v102 offset:32768
	ds_read_b128 v[200:203], v102 offset:33792
	ds_read_b128 v[204:207], v102 offset:34816
	ds_read_b128 v[208:211], v102 offset:35840
	ds_read_b128 v[212:215], v102 offset:36864
	ds_read_b128 v[216:219], v102 offset:37888
	ds_read_b128 v[220:223], v102 offset:38912
	ds_read_b128 v[224:227], v102 offset:39936
	global_load_lds_dwordx4 v[114:115], off
	v_lshl_add_u64 v[114:115], s[24:25], 0, v[148:149]
	s_mov_b32 m0, s44
	s_nop 0
	global_load_lds_dwordx4 v[114:115], off
	s_waitcnt vmcnt(8)
	s_waitcnt lgkmcnt(0)
	s_barrier
	s_setprio 1
	s_waitcnt lgkmcnt(0)
	v_mfma_f32_16x16x32_bf16 v[140:143], v[106:109], v[196:199], v[140:143]
	v_mfma_f32_16x16x32_bf16 v[136:139], v[168:171], v[196:199], v[136:139]
	v_mfma_f32_16x16x32_bf16 v[124:127], v[106:109], v[204:207], v[124:127]
	v_mfma_f32_16x16x32_bf16 v[120:123], v[168:171], v[204:207], v[120:123]
	v_mfma_f32_16x16x32_bf16 v[92:95], v[106:109], v[212:215], v[92:95]
	v_mfma_f32_16x16x32_bf16 v[88:91], v[168:171], v[212:215], v[88:91]
	v_mfma_f32_16x16x32_bf16 v[76:79], v[106:109], v[220:223], v[76:79]
	v_mfma_f32_16x16x32_bf16 v[72:75], v[168:171], v[220:223], v[72:75]
	v_mfma_f32_16x16x32_bf16 v[140:143], v[154:157], v[200:203], v[140:143]
	v_mfma_f32_16x16x32_bf16 v[136:139], v[172:175], v[200:203], v[136:139]
	v_mfma_f32_16x16x32_bf16 v[124:127], v[154:157], v[208:211], v[124:127]
	v_mfma_f32_16x16x32_bf16 v[120:123], v[172:175], v[208:211], v[120:123]
	v_mfma_f32_16x16x32_bf16 v[92:95], v[154:157], v[216:219], v[92:95]
	v_mfma_f32_16x16x32_bf16 v[88:91], v[172:175], v[216:219], v[88:91]
	v_mfma_f32_16x16x32_bf16 v[76:79], v[154:157], v[224:227], v[76:79]
	v_mfma_f32_16x16x32_bf16 v[72:75], v[172:175], v[224:227], v[72:75]
	s_setprio 0
	s_setprio 1
	v_mfma_f32_16x16x32_bf16 v[132:135], v[176:179], v[196:199], v[132:135]
	v_mfma_f32_16x16x32_bf16 v[128:131], v[184:187], v[196:199], v[128:131]
	v_mfma_f32_16x16x32_bf16 v[114:117], v[176:179], v[204:207], v[116:119]
	v_mfma_f32_16x16x32_bf16 v[110:113], v[184:187], v[204:207], v[110:113]
	v_mfma_f32_16x16x32_bf16 v[84:87], v[176:179], v[212:215], v[84:87]
	v_mfma_f32_16x16x32_bf16 v[80:83], v[184:187], v[212:215], v[80:83]
	v_mfma_f32_16x16x32_bf16 v[68:71], v[176:179], v[220:223], v[68:71]
	v_mfma_f32_16x16x32_bf16 v[64:67], v[184:187], v[220:223], v[64:67]
	v_mfma_f32_16x16x32_bf16 v[132:135], v[180:183], v[200:203], v[132:135]
	v_mfma_f32_16x16x32_bf16 v[128:131], v[188:191], v[200:203], v[128:131]
	v_mfma_f32_16x16x32_bf16 v[116:119], v[180:183], v[208:211], v[114:117]
	v_mfma_f32_16x16x32_bf16 v[112:115], v[188:191], v[208:211], v[110:113]
	v_mfma_f32_16x16x32_bf16 v[84:87], v[180:183], v[216:219], v[84:87]
	v_mfma_f32_16x16x32_bf16 v[80:83], v[188:191], v[216:219], v[80:83]
	v_mfma_f32_16x16x32_bf16 v[68:71], v[180:183], v[224:227], v[68:71]
	v_mfma_f32_16x16x32_bf16 v[64:67], v[188:191], v[224:227], v[64:67]
	s_setprio 0
	s_barrier
; #define PG8_STAGE(bufoff, gbase, voff) do { _Pragma("unroll") for (int _i = 0; _i < 2; ++_i) \
;         __builtin_amdgcn_global_load_lds((const unsigned*)((const char*)(gbase) + (voff)[_i]), (PG8_LAS unsigned*)(lds + (bufoff) + ldsw + _i * 8192), 16, 0, 0); } while (0)
; #define PG8_LDA(dst, b, h) do { _Pragma("unroll") for (int m = 0; m < 4; ++m) _Pragma("unroll") for (int k = 0; k < 2; ++k) dst[m][k] = *(const PG8_LAS bf16x8*)(lds + PG8_SA(b, h) + aoff + m * 2048 + k * 1024); } while (0)
; #define PG8_MMA(ai, bj, At, Bt) do { __builtin_amdgcn_s_setprio(1); _Pragma("unroll") for (int m = 0; m < 4; ++m) _Pragma("unroll") for (int n = 0; n < 2; ++n) _Pragma("unroll") for (int k = 0; k < 2; ++k) \
;         acc[ai][bj][m][n] = __builtin_amdgcn_mfma_f32_16x16x32_bf16(Bt[n][k], At[m][k], acc[ai][bj][m][n], 0, 0, 0); __builtin_amdgcn_s_setprio(0); } while (0)
; #define PG8_WAIT_V(n) asm volatile("s_waitcnt vmcnt(" #n ")" ::: "memory")
; #define PG8_WAIT_L(n) asm volatile("s_waitcnt lgkmcnt(" #n ")" ::: "memory")
; #define PG8_BAR __builtin_amdgcn_s_barrier()
; #define PG8_SCHED __builtin_amdgcn_sched_barrier(0)
; template <class Epi, class Sched, bool ALIGN_EPI = false, bool SP2 = false>
; __device__ __forceinline__ void gemm_phase(PG8_LAS unsigned char* lds, const Gemm g, const Sched& S, const Epi& E) {
;     ...
;             PG8_LDA(At, 1, 1); PG8_STAGE(PG8_SB(1, 0), b3, voffB); PG8_STAGE(PG8_SB(1, 1), b3 + hstepB, voffB); PG8_STAGE(PG8_SA(1, 0), a3, voffA);
;             PG8_WAIT_V(8); PG8_WAIT_L(0); PG8_BAR; PG8_MMA(1, 0, At, B0); PG8_MMA(1, 1, At, B1); PG8_BAR; PG8_SCHED;
;     ...
;     PG8_WAIT_V(0);
;     if constexpr (!ALIGN_EPI) { if (wr == 0) PG8_BAR; }
;     PG8_BAR;
	s_mov_b32 m0, s56
	v_lshl_add_u64 v[110:111], v[158:159], 0, s[6:7]
	s_add_u32 s22, s22, 0x40080
	ds_read_b128 v[196:199], v102 offset:49152
	ds_read_b128 v[200:203], v102 offset:50176
	ds_read_b128 v[204:207], v102 offset:51200
	ds_read_b128 v[208:211], v102 offset:52224
	ds_read_b128 v[212:215], v102 offset:53248
	ds_read_b128 v[216:219], v102 offset:54272
	ds_read_b128 v[220:223], v102 offset:55296
	ds_read_b128 v[224:227], v102 offset:56320
	global_load_lds_dwordx4 v[110:111], off
	v_lshl_add_u64 v[110:111], v[228:229], 0, s[6:7]
	s_mov_b32 m0, s57
	s_addc_u32 s23, s23, 0
	global_load_lds_dwordx4 v[110:111], off
	s_mov_b32 m0, s58
	s_nop 0
	global_load_lds_dwordx4 v146, s[22:23]
	s_mov_b32 m0, s59
	s_nop 0
	global_load_lds_dwordx4 v150, s[22:23]
	v_lshl_add_u64 v[110:111], v[230:231], 0, s[6:7]
	s_mov_b32 m0, s45
	s_nop 0
	global_load_lds_dwordx4 v[110:111], off
	v_lshl_add_u64 v[110:111], v[232:233], 0, s[6:7]
	s_mov_b32 m0, s46
	s_nop 0
	global_load_lds_dwordx4 v[110:111], off
	s_waitcnt vmcnt(8)
	s_waitcnt lgkmcnt(0)
	s_barrier
	s_setprio 1
	s_waitcnt lgkmcnt(0)
	v_mfma_f32_16x16x32_bf16 v[60:63], v[106:109], v[196:199], v[60:63]
	v_mfma_f32_16x16x32_bf16 v[56:59], v[168:171], v[196:199], v[56:59]
	v_mfma_f32_16x16x32_bf16 v[44:47], v[106:109], v[204:207], v[44:47]
	v_mfma_f32_16x16x32_bf16 v[40:43], v[168:171], v[204:207], v[40:43]
	v_mfma_f32_16x16x32_bf16 v[28:31], v[106:109], v[212:215], v[28:31]
	v_mfma_f32_16x16x32_bf16 v[24:27], v[168:171], v[212:215], v[24:27]
	v_mfma_f32_16x16x32_bf16 v[12:15], v[106:109], v[220:223], v[12:15]
	v_mfma_f32_16x16x32_bf16 v[8:11], v[168:171], v[220:223], v[8:11]
	v_mfma_f32_16x16x32_bf16 v[60:63], v[154:157], v[200:203], v[60:63]
	v_mfma_f32_16x16x32_bf16 v[56:59], v[172:175], v[200:203], v[56:59]
	v_mfma_f32_16x16x32_bf16 v[44:47], v[154:157], v[208:211], v[44:47]
	v_mfma_f32_16x16x32_bf16 v[40:43], v[172:175], v[208:211], v[40:43]
	v_mfma_f32_16x16x32_bf16 v[28:31], v[154:157], v[216:219], v[28:31]
	v_mfma_f32_16x16x32_bf16 v[24:27], v[172:175], v[216:219], v[24:27]
	v_mfma_f32_16x16x32_bf16 v[12:15], v[154:157], v[224:227], v[12:15]
	v_mfma_f32_16x16x32_bf16 v[8:11], v[172:175], v[224:227], v[8:11]
	s_setprio 0
	s_setprio 1
	v_mfma_f32_16x16x32_bf16 v[52:55], v[176:179], v[196:199], v[52:55]
	v_mfma_f32_16x16x32_bf16 v[48:51], v[184:187], v[196:199], v[48:51]
	v_mfma_f32_16x16x32_bf16 v[36:39], v[176:179], v[204:207], v[36:39]
	v_mfma_f32_16x16x32_bf16 v[32:35], v[184:187], v[204:207], v[32:35]
	v_mfma_f32_16x16x32_bf16 v[20:23], v[176:179], v[212:215], v[20:23]
	v_mfma_f32_16x16x32_bf16 v[16:19], v[184:187], v[212:215], v[16:19]
	v_mfma_f32_16x16x32_bf16 v[4:7], v[176:179], v[220:223], v[4:7]
	v_mfma_f32_16x16x32_bf16 v[0:3], v[184:187], v[220:223], v[0:3]
	v_mfma_f32_16x16x32_bf16 v[52:55], v[180:183], v[200:203], v[52:55]
	v_mfma_f32_16x16x32_bf16 v[48:51], v[188:191], v[200:203], v[48:51]
	v_mfma_f32_16x16x32_bf16 v[36:39], v[180:183], v[208:211], v[36:39]
	v_mfma_f32_16x16x32_bf16 v[32:35], v[188:191], v[208:211], v[32:35]
	v_mfma_f32_16x16x32_bf16 v[20:23], v[180:183], v[216:219], v[20:23]
	v_mfma_f32_16x16x32_bf16 v[16:19], v[188:191], v[216:219], v[16:19]
	v_mfma_f32_16x16x32_bf16 v[4:7], v[180:183], v[224:227], v[4:7]
	v_mfma_f32_16x16x32_bf16 v[0:3], v[188:191], v[224:227], v[0:3]
	s_setprio 0
	s_barrier
	s_add_i32 s49, s49, 2
	s_add_u32 s20, s20, 0x100
	s_addc_u32 s21, s21, 0
	s_cmp_lt_u32 s49, 14
	s_cbranch_scc1 .LBB0_885
	s_waitcnt vmcnt(0)
	s_cmpk_gt_u32 s40, 0xff
	s_cbranch_scc1 .LBB0_888
	s_barrier

; #define PG8_STAGE(bufoff, gbase, voff) do { _Pragma("unroll") for (int _i = 0; _i < 2; ++_i) \
;         __builtin_amdgcn_global_load_lds((const unsigned*)((const char*)(gbase) + (voff)[_i]), (PG8_LAS unsigned*)(lds + (bufoff) + ldsw + _i * 8192), 16, 0, 0); } while (0)
; #define PG8_WAIT_V(n) asm volatile("s_waitcnt vmcnt(" #n ")" ::: "memory")
; #define PG8_BAR __builtin_amdgcn_s_barrier()
; template <class Epi, class Sched, bool ALIGN_EPI = false, bool SP2 = false>
; __device__ __forceinline__ void gemm_phase(PG8_LAS unsigned char* lds, const Gemm g, const Sched& S, const Epi& E) {
;     ...
; #pragma unroll
;     for (int a = 0; a < 2; ++a)
; #pragma unroll
;         for (int b = 0; b < 2; ++b)
; #pragma unroll
;             for (int m = 0; m < 4; ++m)
; #pragma unroll
;                 for (int n = 0; n < 2; ++n) acc[a][b][m][n] = (f32x4){0.f, 0.f, 0.f, 0.f};
;     bf16x8 At[4][2], B0[2][2], B1[2][2];
;     const char* cA = PG8_UA(cur); const char* cB = PG8_UB(cur);
;     S.a_ready(cur);
;     if constexpr (SP2) {
;         PG8_STAGE(PG8_SB(0, 0), cB, voffB); PG8_STAGE(PG8_SB(0, 1), cB + hstepB, voffB); PG8_STAGE(PG8_SA(0, 0), cA, voffA); PG8_STAGE(PG8_SA(0, 1), cA + hstepA, voffA);
;         if (wr == 1) PG8_BAR;
;         PG8_WAIT_V(2); PG8_BAR;
;         PG8_STAGE(PG8_SB(1, 0), cB + kstep, voffB); PG8_STAGE(PG8_SA(1, 0), cA + kstep, voffA); PG8_STAGE(PG8_SB(1, 1), cB + hstepB + kstep, voffB);
;         PG8_WAIT_V(6); PG8_BAR;
.LBB0_939:
	v_lshlrev_b32_e32 v9, 2, v161
	s_and_b32 s30, s6, 3
	v_lshl_or_b32 v8, v161, 6, v166
	s_lshl_b32 s6, s3, 13
	v_and_b32_e32 v9, 32, v9
	v_bitop3_b32 v8, v8, s6, v9 bitop3:0xde
	s_mov_b64 s[6:7], 0x80
	s_add_i32 m0, s31, 0x18000
	v_lshl_add_u64 v[6:7], v[6:7], 0, s[6:7]
	s_waitcnt vmcnt(2)
	s_barrier
	global_load_lds_dwordx4 v[6:7], off
	v_lshl_add_u64 v[4:5], v[4:5], 0, s[6:7]
	s_add_i32 m0, s31, 0x1a000
	s_add_i32 s43, s31, 0x8000
	s_add_i32 s44, s31, 0xa000
	global_load_lds_dwordx4 v[4:5], off
	v_lshl_add_u64 v[2:3], v[2:3], 0, s[6:7]
	s_mov_b32 m0, s43
	s_add_u32 s24, s0, 0x40080
	global_load_lds_dwordx4 v[2:3], off
	v_lshl_add_u64 v[0:1], v[0:1], 0, s[6:7]
	s_mov_b32 m0, s44
	s_addc_u32 s25, s1, 0
	global_load_lds_dwordx4 v[0:1], off
	s_add_i32 m0, s31, 0x1c000
	global_load_lds_dwordx4 v146, s[24:25]
	v_lshl_add_u64 v[0:1], s[24:25], 0, v[150:151]
	s_add_i32 m0, s31, 0x1e000
	v_lshlrev_b32_e32 v2, 11, v164
	global_load_lds_dwordx4 v[0:1], off
	v_lshlrev_b32_e32 v0, 8, v194
	v_and_b32_e32 v0, 0x38000, v0
	s_add_u32 s18, s34, s18
	v_or3_b32 v0, v162, v0, v2
	s_addc_u32 s19, s35, s19
	v_add_u32_e32 v0, v0, v163
	v_mov_b32_e32 v1, v147
	v_lshl_add_u64 v[0:1], s[18:19], 0, v[0:1]
	s_mov_b64 s[24:25], 0x3840080
	v_lshl_add_u64 v[96:97], v[0:1], 0, s[24:25]
	v_lshlrev_b32_e32 v0, 4, v165
	s_add_u32 s20, s34, s20
	v_and_b32_e32 v0, 0x78000, v0
	s_addc_u32 s21, s35, s21
	v_or3_b32 v0, v162, v0, v2
	s_add_u32 s45, s20, 0x700100
	v_lshl_or_b32 v9, s30, 12, v167
	s_waitcnt vmcnt(6)
	v_add_u32_e32 v0, v0, v163
	v_mov_b32_e32 v1, v147
	s_addc_u32 s46, s21, 0
	s_add_i32 s50, 0, 0x10000
	s_add_i32 s52, 0, 0x14000
	s_add_i32 s54, 0, 0x18000
	s_add_i32 s56, 0, 0x1c000
	v_lshl_add_u64 v[0:1], s[18:19], 0, v[0:1]
	v_add_u32_e32 v100, s50, v9
	v_add_u32_e32 v101, s52, v9
	s_add_i32 s50, s50, s22
	s_add_i32 s52, s52, s22
	v_add_u32_e32 v103, s54, v9
	v_add_u32_e32 v104, s56, v9
	s_add_i32 s54, s54, s22
	s_add_i32 s56, s56, s22
	v_lshl_or_b32 v152, s3, 6, v161
	v_lshl_add_u64 v[98:99], v[0:1], 0, s[24:25]
	s_mov_b32 s47, -2
	s_mov_b64 s[20:21], 0
	v_add_u32_e32 v102, 0, v8
	s_add_i32 s48, s31, 0xc000
	s_add_i32 s49, s31, 0xe000
	s_add_i32 s51, s50, 0x2000
	s_add_i32 s53, s52, 0x2000
	s_add_i32 s55, s54, 0x2000
	s_add_i32 s57, s56, 0x2000
	v_mov_b32_e32 v0, v147
	v_mov_b32_e32 v1, v147
	v_mov_b32_e32 v2, v147
	v_mov_b32_e32 v3, v147
	v_mov_b32_e32 v4, v147
	v_mov_b32_e32 v5, v147
	v_mov_b32_e32 v6, v147
	v_mov_b32_e32 v7, v147
	v_mov_b32_e32 v16, v147
	v_mov_b32_e32 v17, v147
	v_mov_b32_e32 v18, v147
	v_mov_b32_e32 v19, v147
	v_mov_b32_e32 v20, v147
	v_mov_b32_e32 v21, v147
	v_mov_b32_e32 v22, v147
	v_mov_b32_e32 v23, v147
	v_mov_b32_e32 v32, v147
	v_mov_b32_e32 v33, v147
	v_mov_b32_e32 v34, v147
	v_mov_b32_e32 v35, v147
	v_mov_b32_e32 v36, v147
	v_mov_b32_e32 v37, v147
	v_mov_b32_e32 v38, v147
	v_mov_b32_e32 v39, v147
	v_mov_b32_e32 v48, v147
	v_mov_b32_e32 v49, v147
	v_mov_b32_e32 v50, v147
	v_mov_b32_e32 v51, v147
	v_mov_b32_e32 v52, v147
	v_mov_b32_e32 v53, v147
	v_mov_b32_e32 v54, v147
	v_mov_b32_e32 v55, v147
	v_mov_b32_e32 v8, v147
	v_mov_b32_e32 v9, v147
	v_mov_b32_e32 v10, v147
	v_mov_b32_e32 v11, v147
	v_mov_b32_e32 v12, v147
	v_mov_b32_e32 v13, v147
	v_mov_b32_e32 v14, v147
	v_mov_b32_e32 v15, v147
	v_mov_b32_e32 v24, v147
	v_mov_b32_e32 v25, v147
	v_mov_b32_e32 v26, v147
	v_mov_b32_e32 v27, v147
	v_mov_b32_e32 v28, v147
	v_mov_b32_e32 v29, v147
	v_mov_b32_e32 v30, v147
	v_mov_b32_e32 v31, v147
	v_mov_b32_e32 v40, v147
	v_mov_b32_e32 v41, v147
	v_mov_b32_e32 v42, v147
	v_mov_b32_e32 v43, v147
	v_mov_b32_e32 v44, v147
	v_mov_b32_e32 v45, v147
	v_mov_b32_e32 v46, v147
	v_mov_b32_e32 v47, v147
	v_mov_b32_e32 v56, v147
	v_mov_b32_e32 v57, v147
	v_mov_b32_e32 v58, v147
	v_mov_b32_e32 v59, v147
	v_mov_b32_e32 v60, v147
	v_mov_b32_e32 v61, v147
	v_mov_b32_e32 v62, v147
	v_mov_b32_e32 v63, v147
	v_mov_b32_e32 v64, v147
	v_mov_b32_e32 v65, v147
	v_mov_b32_e32 v66, v147
	v_mov_b32_e32 v67, v147
	v_mov_b32_e32 v68, v147
	v_mov_b32_e32 v69, v147
	v_mov_b32_e32 v70, v147
	v_mov_b32_e32 v71, v147
	v_mov_b32_e32 v80, v147
	v_mov_b32_e32 v81, v147
	v_mov_b32_e32 v82, v147
	v_mov_b32_e32 v83, v147
	v_mov_b32_e32 v84, v147
	v_mov_b32_e32 v85, v147
	v_mov_b32_e32 v86, v147
	v_mov_b32_e32 v87, v147
	v_mov_b32_e32 v112, v147
	v_mov_b32_e32 v113, v147
	v_mov_b32_e32 v114, v147
	v_mov_b32_e32 v115, v147
	v_mov_b32_e32 v116, v147
	v_mov_b32_e32 v117, v147
	v_mov_b32_e32 v118, v147
	v_mov_b32_e32 v119, v147
	v_mov_b32_e32 v128, v147
	v_mov_b32_e32 v129, v147
	v_mov_b32_e32 v130, v147
	v_mov_b32_e32 v131, v147
	v_mov_b32_e32 v132, v147
	v_mov_b32_e32 v133, v147
	v_mov_b32_e32 v134, v147
	v_mov_b32_e32 v135, v147
	v_mov_b32_e32 v72, v147
	v_mov_b32_e32 v73, v147
	v_mov_b32_e32 v74, v147
	v_mov_b32_e32 v75, v147
	v_mov_b32_e32 v76, v147
	v_mov_b32_e32 v77, v147
	v_mov_b32_e32 v78, v147
	v_mov_b32_e32 v79, v147
	v_mov_b32_e32 v88, v147
	v_mov_b32_e32 v89, v147
	v_mov_b32_e32 v90, v147
	v_mov_b32_e32 v91, v147
	v_mov_b32_e32 v92, v147
	v_mov_b32_e32 v93, v147
	v_mov_b32_e32 v94, v147
	v_mov_b32_e32 v95, v147
	v_mov_b32_e32 v120, v147
	v_mov_b32_e32 v121, v147
	v_mov_b32_e32 v122, v147
	v_mov_b32_e32 v123, v147
	v_mov_b32_e32 v124, v147
	v_mov_b32_e32 v125, v147
	v_mov_b32_e32 v126, v147
	v_mov_b32_e32 v127, v147
	v_mov_b32_e32 v136, v147
	v_mov_b32_e32 v137, v147
	v_mov_b32_e32 v138, v147
	v_mov_b32_e32 v139, v147
	v_mov_b32_e32 v140, v147
	v_mov_b32_e32 v141, v147
	v_mov_b32_e32 v142, v147
	v_mov_b32_e32 v143, v147
	s_barrier
; #define PG8_STAGE(bufoff, gbase, voff) do { _Pragma("unroll") for (int _i = 0; _i < 2; ++_i) \
;         __builtin_amdgcn_global_load_lds((const unsigned*)((const char*)(gbase) + (voff)[_i]), (PG8_LAS unsigned*)(lds + (bufoff) + ldsw + _i * 8192), 16, 0, 0); } while (0)
; #define PG8_LDA(dst, b, h) do { _Pragma("unroll") for (int m = 0; m < 4; ++m) _Pragma("unroll") for (int k = 0; k < 2; ++k) dst[m][k] = *(const PG8_LAS bf16x8*)(lds + PG8_SA(b, h) + aoff + m * 2048 + k * 1024); } while (0)
; #define PG8_LDB(dst, b, h) do { _Pragma("unroll") for (int n = 0; n < 2; ++n) _Pragma("unroll") for (int k = 0; k < 2; ++k) dst[n][k] = *(const PG8_LAS bf16x8*)(lds + PG8_SB(b, h) + boff + n * 2048 + k * 1024); } while (0)
; #define PG8_MMA(ai, bj, At, Bt) do { __builtin_amdgcn_s_setprio(1); _Pragma("unroll") for (int m = 0; m < 4; ++m) _Pragma("unroll") for (int n = 0; n < 2; ++n) _Pragma("unroll") for (int k = 0; k < 2; ++k) \
;         acc[ai][bj][m][n] = __builtin_amdgcn_mfma_f32_16x16x32_bf16(Bt[n][k], At[m][k], acc[ai][bj][m][n], 0, 0, 0); __builtin_amdgcn_s_setprio(0); } while (0)
; #define PG8_WAIT_V(n) asm volatile("s_waitcnt vmcnt(" #n ")" ::: "memory")
; #define PG8_WAIT_L(n) asm volatile("s_waitcnt lgkmcnt(" #n ")" ::: "memory")
; template <class Epi, class Sched, bool ALIGN_EPI = false, bool SP2 = false>
; __device__ __forceinline__ void gemm_phase(PG8_LAS unsigned char* lds, const Gemm g, const Sched& S, const Epi& E) {
;     ...
;         const char* nA = has_next ? PG8_UA(nxt) : cA; const char* nB = has_next ? PG8_UB(nxt) : cB;
;         for (int t = 0; t < nt; t += 2) {
;             const bool last = (t == nt - 2);
;             const char* a1 = cA + (size_t)(t + 1) * kstep;
;             const char* a2 = last ? nA : cA + (size_t)(t + 2) * kstep; const char* b2 = last ? nB : cB + (size_t)(t + 2) * kstep;
;             const char* a3 = a2 + kstep; const char* b3 = b2 + kstep;
;             if (last && has_next) S.a_ready(nxt);
;             if constexpr (SP2) {
;             PG8_LDB(B0, 0, 0); PG8_LDB(B1, 0, 1); PG8_SCHED; PG8_LDA(At, 0, 0); PG8_STAGE(PG8_SA(1, 1), a1 + hstepA, voffA);
;             PG8_WAIT_V(8); PG8_WAIT_L(0); PG8_BAR; PG8_MMA(0, 0, At, B0); PG8_MMA(0, 1, At, B1); PG8_BAR; PG8_SCHED;
;             PG8_LDA(At, 0, 1); PG8_STAGE(PG8_SB(0, 0), b2, voffB); PG8_STAGE(PG8_SB(0, 1), b2 + hstepB, voffB); PG8_STAGE(PG8_SA(0, 0), a2, voffA);
.LBB0_940:
	ds_read_b128 v[106:109], v100
	ds_read_b128 v[154:157], v100 offset:1024
	ds_read_b128 v[162:165], v100 offset:2048
	ds_read_b128 v[166:169], v100 offset:3072
	ds_read_b128 v[170:173], v101
	ds_read_b128 v[174:177], v101 offset:1024
	ds_read_b128 v[178:181], v101 offset:2048
	ds_read_b128 v[182:185], v101 offset:3072
	s_add_u32 s22, s18, s20
	s_addc_u32 s23, s19, s21
	s_add_u32 s22, s22, 0x3800100
	s_addc_u32 s23, s23, 0
	s_add_u32 s58, s45, s20
	s_addc_u32 s59, s46, s21
	s_cmpk_eq_i32 s20, 0x700
	s_cselect_b32 s25, s5, s23
	s_cselect_b32 s24, s4, s22
	s_cselect_b32 s23, s1, s59
	s_cselect_b32 s22, s0, s58
	s_mov_b32 m0, s48
	v_lshl_add_u64 v[110:111], v[96:97], 0, s[20:21]
	ds_read_b128 v[186:189], v102
	ds_read_b128 v[196:199], v102 offset:1024
	ds_read_b128 v[200:203], v102 offset:2048
	ds_read_b128 v[204:207], v102 offset:3072
	ds_read_b128 v[208:211], v102 offset:4096
	ds_read_b128 v[212:215], v102 offset:5120
	ds_read_b128 v[216:219], v102 offset:6144
	ds_read_b128 v[220:223], v102 offset:7168
	global_load_lds_dwordx4 v[110:111], off
	v_lshl_add_u64 v[110:111], v[98:99], 0, s[20:21]
	s_mov_b32 m0, s49
	s_nop 0
	global_load_lds_dwordx4 v[110:111], off
	s_waitcnt vmcnt(8)
	s_waitcnt lgkmcnt(0)
	s_barrier
	s_setprio 1
	s_waitcnt lgkmcnt(0)
	v_mfma_f32_16x16x32_bf16 v[140:143], v[106:109], v[186:189], v[140:143]
	v_mfma_f32_16x16x32_bf16 v[136:139], v[162:165], v[186:189], v[136:139]
	v_mfma_f32_16x16x32_bf16 v[124:127], v[106:109], v[200:203], v[124:127]
	v_mfma_f32_16x16x32_bf16 v[120:123], v[162:165], v[200:203], v[120:123]
	v_mfma_f32_16x16x32_bf16 v[92:95], v[106:109], v[208:211], v[92:95]
	v_mfma_f32_16x16x32_bf16 v[88:91], v[162:165], v[208:211], v[88:91]
	v_mfma_f32_16x16x32_bf16 v[76:79], v[106:109], v[216:219], v[76:79]
	v_mfma_f32_16x16x32_bf16 v[72:75], v[162:165], v[216:219], v[72:75]
	v_mfma_f32_16x16x32_bf16 v[140:143], v[154:157], v[196:199], v[140:143]
	v_mfma_f32_16x16x32_bf16 v[136:139], v[166:169], v[196:199], v[136:139]
	v_mfma_f32_16x16x32_bf16 v[124:127], v[154:157], v[204:207], v[124:127]
	v_mfma_f32_16x16x32_bf16 v[120:123], v[166:169], v[204:207], v[120:123]
	v_mfma_f32_16x16x32_bf16 v[92:95], v[154:157], v[212:215], v[92:95]
	v_mfma_f32_16x16x32_bf16 v[88:91], v[166:169], v[212:215], v[88:91]
	v_mfma_f32_16x16x32_bf16 v[76:79], v[154:157], v[220:223], v[76:79]
	v_mfma_f32_16x16x32_bf16 v[72:75], v[166:169], v[220:223], v[72:75]
	s_setprio 0
	s_setprio 1
	v_mfma_f32_16x16x32_bf16 v[132:135], v[170:173], v[186:189], v[132:135]
	v_mfma_f32_16x16x32_bf16 v[128:131], v[178:181], v[186:189], v[128:131]
	v_mfma_f32_16x16x32_bf16 v[116:119], v[170:173], v[200:203], v[116:119]
	v_mfma_f32_16x16x32_bf16 v[110:113], v[178:181], v[200:203], v[112:115]
	v_mfma_f32_16x16x32_bf16 v[84:87], v[170:173], v[208:211], v[84:87]
	v_mfma_f32_16x16x32_bf16 v[80:83], v[178:181], v[208:211], v[80:83]
	v_mfma_f32_16x16x32_bf16 v[68:71], v[170:173], v[216:219], v[68:71]
	v_mfma_f32_16x16x32_bf16 v[64:67], v[178:181], v[216:219], v[64:67]
	v_mfma_f32_16x16x32_bf16 v[132:135], v[174:177], v[196:199], v[132:135]
	v_mfma_f32_16x16x32_bf16 v[128:131], v[182:185], v[196:199], v[128:131]
	v_mfma_f32_16x16x32_bf16 v[116:119], v[174:177], v[204:207], v[116:119]
	v_mfma_f32_16x16x32_bf16 v[110:113], v[182:185], v[204:207], v[110:113]
	v_mfma_f32_16x16x32_bf16 v[84:87], v[174:177], v[212:215], v[84:87]
	v_mfma_f32_16x16x32_bf16 v[80:83], v[182:185], v[212:215], v[80:83]
	v_mfma_f32_16x16x32_bf16 v[68:71], v[174:177], v[220:223], v[68:71]
	v_mfma_f32_16x16x32_bf16 v[64:67], v[182:185], v[220:223], v[64:67]
	s_setprio 0
	s_barrier
	s_mov_b32 m0, s50
	v_lshl_add_u64 v[158:159], s[22:23], 0, v[146:147]
	s_add_u32 s58, s22, 0x40000
	ds_read_b128 v[186:189], v102 offset:16384
	ds_read_b128 v[196:199], v102 offset:17408
	ds_read_b128 v[200:203], v102 offset:18432
	ds_read_b128 v[204:207], v102 offset:19456
	ds_read_b128 v[208:211], v102 offset:20480
	ds_read_b128 v[212:215], v102 offset:21504
	ds_read_b128 v[216:219], v102 offset:22528
	ds_read_b128 v[220:223], v102 offset:23552
	global_load_lds_dwordx4 v[158:159], off
	v_lshl_add_u64 v[190:191], s[22:23], 0, v[150:151]
	s_mov_b32 m0, s51
	s_addc_u32 s59, s23, 0
	global_load_lds_dwordx4 v[190:191], off
	s_mov_b32 m0, s52
	v_lshl_add_u64 v[224:225], s[24:25], 0, v[144:145]
	global_load_lds_dwordx4 v146, s[58:59]
	s_mov_b32 m0, s53
	v_lshl_add_u64 v[226:227], s[24:25], 0, v[148:149]
	global_load_lds_dwordx4 v150, s[58:59]
	s_mov_b32 m0, s31
	s_nop 0
	global_load_lds_dwordx4 v[224:225], off
	s_mov_b32 m0, s40
	s_nop 0
	global_load_lds_dwordx4 v[226:227], off
	s_waitcnt vmcnt(8)
	s_waitcnt lgkmcnt(0)
	s_barrier
; #define PG8_STAGE(bufoff, gbase, voff) do { _Pragma("unroll") for (int _i = 0; _i < 2; ++_i) \
;         __builtin_amdgcn_global_load_lds((const unsigned*)((const char*)(gbase) + (voff)[_i]), (PG8_LAS unsigned*)(lds + (bufoff) + ldsw + _i * 8192), 16, 0, 0); } while (0)
; #define PG8_LDA(dst, b, h) do { _Pragma("unroll") for (int m = 0; m < 4; ++m) _Pragma("unroll") for (int k = 0; k < 2; ++k) dst[m][k] = *(const PG8_LAS bf16x8*)(lds + PG8_SA(b, h) + aoff + m * 2048 + k * 1024); } while (0)
; #define PG8_LDB(dst, b, h) do { _Pragma("unroll") for (int n = 0; n < 2; ++n) _Pragma("unroll") for (int k = 0; k < 2; ++k) dst[n][k] = *(const PG8_LAS bf16x8*)(lds + PG8_SB(b, h) + boff + n * 2048 + k * 1024); } while (0)
; #define PG8_MMA(ai, bj, At, Bt) do { __builtin_amdgcn_s_setprio(1); _Pragma("unroll") for (int m = 0; m < 4; ++m) _Pragma("unroll") for (int n = 0; n < 2; ++n) _Pragma("unroll") for (int k = 0; k < 2; ++k) \
;         acc[ai][bj][m][n] = __builtin_amdgcn_mfma_f32_16x16x32_bf16(Bt[n][k], At[m][k], acc[ai][bj][m][n], 0, 0, 0); __builtin_amdgcn_s_setprio(0); } while (0)
; #define PG8_WAIT_V(n) asm volatile("s_waitcnt vmcnt(" #n ")" ::: "memory")
; #define PG8_WAIT_L(n) asm volatile("s_waitcnt lgkmcnt(" #n ")" ::: "memory")
; #define PG8_BAR __builtin_amdgcn_s_barrier()
; #define PG8_SCHED __builtin_amdgcn_sched_barrier(0)
; template <class Epi, class Sched, bool ALIGN_EPI = false, bool SP2 = false>
; __device__ __forceinline__ void gemm_phase(PG8_LAS unsigned char* lds, const Gemm g, const Sched& S, const Epi& E) {
;     ...
;             PG8_WAIT_V(8); PG8_WAIT_L(0); PG8_BAR; PG8_MMA(1, 0, At, B0); PG8_MMA(1, 1, At, B1); PG8_BAR; PG8_SCHED;
;             PG8_LDB(B0, 1, 0); PG8_LDB(B1, 1, 1); PG8_SCHED; PG8_LDA(At, 1, 0); PG8_STAGE(PG8_SA(0, 1), a2 + hstepA, voffA);
;             PG8_WAIT_V(8); PG8_WAIT_L(0); PG8_BAR; PG8_MMA(0, 0, At, B0); PG8_MMA(0, 1, At, B1); PG8_BAR; PG8_SCHED;
	s_setprio 1
	s_waitcnt lgkmcnt(0)
	v_mfma_f32_16x16x32_bf16 v[60:63], v[106:109], v[186:189], v[60:63]
	v_mfma_f32_16x16x32_bf16 v[56:59], v[162:165], v[186:189], v[56:59]
	v_mfma_f32_16x16x32_bf16 v[44:47], v[106:109], v[200:203], v[44:47]
	v_mfma_f32_16x16x32_bf16 v[40:43], v[162:165], v[200:203], v[40:43]
	v_mfma_f32_16x16x32_bf16 v[28:31], v[106:109], v[208:211], v[28:31]
	v_mfma_f32_16x16x32_bf16 v[24:27], v[162:165], v[208:211], v[24:27]
	v_mfma_f32_16x16x32_bf16 v[12:15], v[106:109], v[216:219], v[12:15]
	v_mfma_f32_16x16x32_bf16 v[8:11], v[162:165], v[216:219], v[8:11]
	v_mfma_f32_16x16x32_bf16 v[60:63], v[154:157], v[196:199], v[60:63]
	v_mfma_f32_16x16x32_bf16 v[56:59], v[166:169], v[196:199], v[56:59]
	v_mfma_f32_16x16x32_bf16 v[44:47], v[154:157], v[204:207], v[44:47]
	v_mfma_f32_16x16x32_bf16 v[40:43], v[166:169], v[204:207], v[40:43]
	v_mfma_f32_16x16x32_bf16 v[28:31], v[154:157], v[212:215], v[28:31]
	v_mfma_f32_16x16x32_bf16 v[24:27], v[166:169], v[212:215], v[24:27]
	v_mfma_f32_16x16x32_bf16 v[12:15], v[154:157], v[220:223], v[12:15]
	v_mfma_f32_16x16x32_bf16 v[8:11], v[166:169], v[220:223], v[8:11]
	s_setprio 0
	s_setprio 1
	v_mfma_f32_16x16x32_bf16 v[52:55], v[170:173], v[186:189], v[52:55]
	v_mfma_f32_16x16x32_bf16 v[48:51], v[178:181], v[186:189], v[48:51]
	v_mfma_f32_16x16x32_bf16 v[36:39], v[170:173], v[200:203], v[36:39]
	v_mfma_f32_16x16x32_bf16 v[32:35], v[178:181], v[200:203], v[32:35]
	v_mfma_f32_16x16x32_bf16 v[20:23], v[170:173], v[208:211], v[20:23]
	v_mfma_f32_16x16x32_bf16 v[16:19], v[178:181], v[208:211], v[16:19]
	v_mfma_f32_16x16x32_bf16 v[4:7], v[170:173], v[216:219], v[4:7]
	v_mfma_f32_16x16x32_bf16 v[0:3], v[178:181], v[216:219], v[0:3]
	v_mfma_f32_16x16x32_bf16 v[52:55], v[174:177], v[196:199], v[52:55]
	v_mfma_f32_16x16x32_bf16 v[48:51], v[182:185], v[196:199], v[48:51]
	v_mfma_f32_16x16x32_bf16 v[36:39], v[174:177], v[204:207], v[36:39]
	v_mfma_f32_16x16x32_bf16 v[32:35], v[182:185], v[204:207], v[32:35]
	v_mfma_f32_16x16x32_bf16 v[20:23], v[174:177], v[212:215], v[20:23]
	v_mfma_f32_16x16x32_bf16 v[16:19], v[182:185], v[212:215], v[16:19]
	v_mfma_f32_16x16x32_bf16 v[4:7], v[174:177], v[220:223], v[4:7]
	v_mfma_f32_16x16x32_bf16 v[0:3], v[182:185], v[220:223], v[0:3]
	s_setprio 0
	s_barrier
	ds_read_b128 v[106:109], v103
	ds_read_b128 v[154:157], v103 offset:1024
	ds_read_b128 v[162:165], v103 offset:2048
	ds_read_b128 v[166:169], v103 offset:3072
	ds_read_b128 v[170:173], v104
	ds_read_b128 v[174:177], v104 offset:1024
	ds_read_b128 v[178:181], v104 offset:2048
	ds_read_b128 v[182:185], v104 offset:3072
	s_add_u32 s24, s24, 0x40000
	s_addc_u32 s25, s25, 0
	s_mov_b32 m0, s41
	v_lshl_add_u64 v[114:115], s[24:25], 0, v[144:145]
	ds_read_b128 v[186:189], v102 offset:32768
	ds_read_b128 v[196:199], v102 offset:33792
	ds_read_b128 v[200:203], v102 offset:34816
	ds_read_b128 v[204:207], v102 offset:35840
	ds_read_b128 v[208:211], v102 offset:36864
	ds_read_b128 v[212:215], v102 offset:37888
	ds_read_b128 v[216:219], v102 offset:38912
	ds_read_b128 v[220:223], v102 offset:39936
	global_load_lds_dwordx4 v[114:115], off
	v_lshl_add_u64 v[114:115], s[24:25], 0, v[148:149]
	s_mov_b32 m0, s42
	s_nop 0
	global_load_lds_dwordx4 v[114:115], off
	s_waitcnt vmcnt(8)
	s_waitcnt lgkmcnt(0)
	s_barrier
	s_setprio 1
	s_waitcnt lgkmcnt(0)
	v_mfma_f32_16x16x32_bf16 v[140:143], v[106:109], v[186:189], v[140:143]
	v_mfma_f32_16x16x32_bf16 v[136:139], v[162:165], v[186:189], v[136:139]
	v_mfma_f32_16x16x32_bf16 v[124:127], v[106:109], v[200:203], v[124:127]
	v_mfma_f32_16x16x32_bf16 v[120:123], v[162:165], v[200:203], v[120:123]
	v_mfma_f32_16x16x32_bf16 v[92:95], v[106:109], v[208:211], v[92:95]
	v_mfma_f32_16x16x32_bf16 v[88:91], v[162:165], v[208:211], v[88:91]
	v_mfma_f32_16x16x32_bf16 v[76:79], v[106:109], v[216:219], v[76:79]
	v_mfma_f32_16x16x32_bf16 v[72:75], v[162:165], v[216:219], v[72:75]
	v_mfma_f32_16x16x32_bf16 v[140:143], v[154:157], v[196:199], v[140:143]
	v_mfma_f32_16x16x32_bf16 v[136:139], v[166:169], v[196:199], v[136:139]
	v_mfma_f32_16x16x32_bf16 v[124:127], v[154:157], v[204:207], v[124:127]
	v_mfma_f32_16x16x32_bf16 v[120:123], v[166:169], v[204:207], v[120:123]
	v_mfma_f32_16x16x32_bf16 v[92:95], v[154:157], v[212:215], v[92:95]
	v_mfma_f32_16x16x32_bf16 v[88:91], v[166:169], v[212:215], v[88:91]
	v_mfma_f32_16x16x32_bf16 v[76:79], v[154:157], v[220:223], v[76:79]
	v_mfma_f32_16x16x32_bf16 v[72:75], v[166:169], v[220:223], v[72:75]
	s_setprio 0
	s_setprio 1
	v_mfma_f32_16x16x32_bf16 v[132:135], v[170:173], v[186:189], v[132:135]
	v_mfma_f32_16x16x32_bf16 v[128:131], v[178:181], v[186:189], v[128:131]
	v_mfma_f32_16x16x32_bf16 v[114:117], v[170:173], v[200:203], v[116:119]
	v_mfma_f32_16x16x32_bf16 v[110:113], v[178:181], v[200:203], v[110:113]
	v_mfma_f32_16x16x32_bf16 v[84:87], v[170:173], v[208:211], v[84:87]
	v_mfma_f32_16x16x32_bf16 v[80:83], v[178:181], v[208:211], v[80:83]
	v_mfma_f32_16x16x32_bf16 v[68:71], v[170:173], v[216:219], v[68:71]
	v_mfma_f32_16x16x32_bf16 v[64:67], v[178:181], v[216:219], v[64:67]
	v_mfma_f32_16x16x32_bf16 v[132:135], v[174:177], v[196:199], v[132:135]
	v_mfma_f32_16x16x32_bf16 v[128:131], v[182:185], v[196:199], v[128:131]
	v_mfma_f32_16x16x32_bf16 v[116:119], v[174:177], v[204:207], v[114:117]
	v_mfma_f32_16x16x32_bf16 v[112:115], v[182:185], v[204:207], v[110:113]
	v_mfma_f32_16x16x32_bf16 v[84:87], v[174:177], v[212:215], v[84:87]
	v_mfma_f32_16x16x32_bf16 v[80:83], v[182:185], v[212:215], v[80:83]
	v_mfma_f32_16x16x32_bf16 v[68:71], v[174:177], v[220:223], v[68:71]
	v_mfma_f32_16x16x32_bf16 v[64:67], v[182:185], v[220:223], v[64:67]
	s_setprio 0
	s_barrier
; #define PG8_STAGE(bufoff, gbase, voff) do { _Pragma("unroll") for (int _i = 0; _i < 2; ++_i) \
;         __builtin_amdgcn_global_load_lds((const unsigned*)((const char*)(gbase) + (voff)[_i]), (PG8_LAS unsigned*)(lds + (bufoff) + ldsw + _i * 8192), 16, 0, 0); } while (0)
; #define PG8_LDA(dst, b, h) do { _Pragma("unroll") for (int m = 0; m < 4; ++m) _Pragma("unroll") for (int k = 0; k < 2; ++k) dst[m][k] = *(const PG8_LAS bf16x8*)(lds + PG8_SA(b, h) + aoff + m * 2048 + k * 1024); } while (0)
; #define PG8_MMA(ai, bj, At, Bt) do { __builtin_amdgcn_s_setprio(1); _Pragma("unroll") for (int m = 0; m < 4; ++m) _Pragma("unroll") for (int n = 0; n < 2; ++n) _Pragma("unroll") for (int k = 0; k < 2; ++k) \
;         acc[ai][bj][m][n] = __builtin_amdgcn_mfma_f32_16x16x32_bf16(Bt[n][k], At[m][k], acc[ai][bj][m][n], 0, 0, 0); __builtin_amdgcn_s_setprio(0); } while (0)
; #define PG8_WAIT_V(n) asm volatile("s_waitcnt vmcnt(" #n ")" ::: "memory")
; #define PG8_WAIT_L(n) asm volatile("s_waitcnt lgkmcnt(" #n ")" ::: "memory")
; #define PG8_BAR __builtin_amdgcn_s_barrier()
; #define PG8_SCHED __builtin_amdgcn_sched_barrier(0)
; template <class Epi, class Sched, bool ALIGN_EPI = false, bool SP2 = false>
; __device__ __forceinline__ void gemm_phase(PG8_LAS unsigned char* lds, const Gemm g, const Sched& S, const Epi& E) {
;     ...
;             PG8_LDA(At, 1, 1); PG8_STAGE(PG8_SB(1, 0), b3, voffB); PG8_STAGE(PG8_SB(1, 1), b3 + hstepB, voffB); PG8_STAGE(PG8_SA(1, 0), a3, voffA);
;             PG8_WAIT_V(8); PG8_WAIT_L(0); PG8_BAR; PG8_MMA(1, 0, At, B0); PG8_MMA(1, 1, At, B1); PG8_BAR; PG8_SCHED;
;     ...
;     PG8_WAIT_V(0);
;     if constexpr (!ALIGN_EPI) { if (wr == 0) PG8_BAR; }
;     PG8_BAR;
	s_mov_b32 m0, s54
	v_lshl_add_u64 v[110:111], v[158:159], 0, s[6:7]
	s_add_u32 s22, s22, 0x40080
	ds_read_b128 v[186:189], v102 offset:49152
	ds_read_b128 v[196:199], v102 offset:50176
	ds_read_b128 v[200:203], v102 offset:51200
	ds_read_b128 v[204:207], v102 offset:52224
	ds_read_b128 v[208:211], v102 offset:53248
	ds_read_b128 v[212:215], v102 offset:54272
	ds_read_b128 v[216:219], v102 offset:55296
	ds_read_b128 v[220:223], v102 offset:56320
	global_load_lds_dwordx4 v[110:111], off
	v_lshl_add_u64 v[110:111], v[190:191], 0, s[6:7]
	s_mov_b32 m0, s55
	s_addc_u32 s23, s23, 0
	global_load_lds_dwordx4 v[110:111], off
	s_mov_b32 m0, s56
	s_nop 0
	global_load_lds_dwordx4 v146, s[22:23]
	s_mov_b32 m0, s57
	s_nop 0
	global_load_lds_dwordx4 v150, s[22:23]
	v_lshl_add_u64 v[110:111], v[224:225], 0, s[6:7]
	s_mov_b32 m0, s43
	s_nop 0
	global_load_lds_dwordx4 v[110:111], off
	v_lshl_add_u64 v[110:111], v[226:227], 0, s[6:7]
	s_mov_b32 m0, s44
	s_nop 0
	global_load_lds_dwordx4 v[110:111], off
	s_waitcnt vmcnt(8)
	s_waitcnt lgkmcnt(0)
	s_barrier
	s_setprio 1
	s_waitcnt lgkmcnt(0)
	v_mfma_f32_16x16x32_bf16 v[60:63], v[106:109], v[186:189], v[60:63]
	v_mfma_f32_16x16x32_bf16 v[56:59], v[162:165], v[186:189], v[56:59]
	v_mfma_f32_16x16x32_bf16 v[44:47], v[106:109], v[200:203], v[44:47]
	v_mfma_f32_16x16x32_bf16 v[40:43], v[162:165], v[200:203], v[40:43]
	v_mfma_f32_16x16x32_bf16 v[28:31], v[106:109], v[208:211], v[28:31]
	v_mfma_f32_16x16x32_bf16 v[24:27], v[162:165], v[208:211], v[24:27]
	v_mfma_f32_16x16x32_bf16 v[12:15], v[106:109], v[216:219], v[12:15]
	v_mfma_f32_16x16x32_bf16 v[8:11], v[162:165], v[216:219], v[8:11]
	v_mfma_f32_16x16x32_bf16 v[60:63], v[154:157], v[196:199], v[60:63]
	v_mfma_f32_16x16x32_bf16 v[56:59], v[166:169], v[196:199], v[56:59]
	v_mfma_f32_16x16x32_bf16 v[44:47], v[154:157], v[204:207], v[44:47]
	v_mfma_f32_16x16x32_bf16 v[40:43], v[166:169], v[204:207], v[40:43]
	v_mfma_f32_16x16x32_bf16 v[28:31], v[154:157], v[212:215], v[28:31]
	v_mfma_f32_16x16x32_bf16 v[24:27], v[166:169], v[212:215], v[24:27]
	v_mfma_f32_16x16x32_bf16 v[12:15], v[154:157], v[220:223], v[12:15]
	v_mfma_f32_16x16x32_bf16 v[8:11], v[166:169], v[220:223], v[8:11]
	s_setprio 0
	s_setprio 1
	v_mfma_f32_16x16x32_bf16 v[52:55], v[170:173], v[186:189], v[52:55]
	v_mfma_f32_16x16x32_bf16 v[48:51], v[178:181], v[186:189], v[48:51]
	v_mfma_f32_16x16x32_bf16 v[36:39], v[170:173], v[200:203], v[36:39]
	v_mfma_f32_16x16x32_bf16 v[32:35], v[178:181], v[200:203], v[32:35]
	v_mfma_f32_16x16x32_bf16 v[20:23], v[170:173], v[208:211], v[20:23]
	v_mfma_f32_16x16x32_bf16 v[16:19], v[178:181], v[208:211], v[16:19]
	v_mfma_f32_16x16x32_bf16 v[4:7], v[170:173], v[216:219], v[4:7]
	v_mfma_f32_16x16x32_bf16 v[0:3], v[178:181], v[216:219], v[0:3]
	v_mfma_f32_16x16x32_bf16 v[52:55], v[174:177], v[196:199], v[52:55]
	v_mfma_f32_16x16x32_bf16 v[48:51], v[182:185], v[196:199], v[48:51]
	v_mfma_f32_16x16x32_bf16 v[36:39], v[174:177], v[204:207], v[36:39]
	v_mfma_f32_16x16x32_bf16 v[32:35], v[182:185], v[204:207], v[32:35]
	v_mfma_f32_16x16x32_bf16 v[20:23], v[174:177], v[212:215], v[20:23]
	v_mfma_f32_16x16x32_bf16 v[16:19], v[182:185], v[212:215], v[16:19]
	v_mfma_f32_16x16x32_bf16 v[4:7], v[174:177], v[220:223], v[4:7]
	v_mfma_f32_16x16x32_bf16 v[0:3], v[182:185], v[220:223], v[0:3]
	s_setprio 0
	s_barrier
	s_add_i32 s47, s47, 2
	s_add_u32 s20, s20, 0x100
	s_addc_u32 s21, s21, 0
	s_cmp_lt_u32 s47, 14
	s_cbranch_scc1 .LBB0_940
	s_waitcnt vmcnt(0)
	s_cmpk_gt_u32 s2, 0xff
	s_cbranch_scc1 .LBB0_943
	s_barrier

; #define PG8_STAGE(bufoff, gbase, voff) do { _Pragma("unroll") for (int _i = 0; _i < 2; ++_i) \
;         __builtin_amdgcn_global_load_lds((const unsigned*)((const char*)(gbase) + (voff)[_i]), (PG8_LAS unsigned*)(lds + (bufoff) + ldsw + _i * 8192), 16, 0, 0); } while (0)
; #define PG8_WAIT_V(n) asm volatile("s_waitcnt vmcnt(" #n ")" ::: "memory")
; #define PG8_BAR __builtin_amdgcn_s_barrier()
; template <class Epi, class Sched, bool ALIGN_EPI = false, bool SP2 = false>
; __device__ __forceinline__ void gemm_phase(PG8_LAS unsigned char* lds, const Gemm g, const Sched& S, const Epi& E) {
;     ...
;         PG8_STAGE(PG8_SB(1, 0), cB + kstep, voffB); PG8_STAGE(PG8_SA(1, 0), cA + kstep, voffA); PG8_STAGE(PG8_SB(1, 1), cB + hstepB + kstep, voffB);
;         PG8_WAIT_V(6); PG8_BAR;
;     __device__ __forceinline__ void operator()(const f32x4 (&acc)[2][2][4][2], const Unit& u, int wr, int wc, int fr, int fq) const {
;     ...
;             const int hc = (u.pn * BM + colt) >> 1; const float r = 1.f / sqrtf(rstd[row] * (1.f / DM) + RMS_EPS);
.LBB0_1043:
	s_add_u32 s10, s34, 0x7800000
	s_addc_u32 s11, s35, 0
	s_add_u32 s12, s34, 0x3420000
	s_addc_u32 s13, s35, 0
	s_lshl_b32 s4, s4, 5
	s_mov_b64 s[14:15], 0x80
	s_and_b32 s18, s4, 0x60
	s_add_i32 m0, s42, 0x18000
	v_lshl_add_u64 v[6:7], v[6:7], 0, s[14:15]
	s_lshl_b32 s1, s3, 13
	s_lshl_b32 s16, s18, 7
	s_waitcnt vmcnt(2)
	s_barrier
	global_load_lds_dwordx4 v[6:7], off
	v_lshl_add_u64 v[4:5], v[4:5], 0, s[14:15]
	s_add_i32 m0, s42, 0x1a000
	s_add_i32 s47, s42, 0x8000
	s_add_i32 s48, s42, 0xa000
	global_load_lds_dwordx4 v[4:5], off
	v_lshl_add_u64 v[0:1], v[0:1], 0, s[14:15]
	s_mov_b32 m0, s47
	s_add_u32 s4, s26, 0x40080
	global_load_lds_dwordx4 v[0:1], off
	v_lshl_add_u64 v[0:1], v[2:3], 0, s[14:15]
	s_mov_b32 m0, s48
	s_addc_u32 s5, s27, 0
	global_load_lds_dwordx4 v[0:1], off
	s_add_i32 m0, s42, 0x1c000
	global_load_lds_dwordx4 v132, s[4:5]
	v_lshl_add_u64 v[0:1], s[4:5], 0, v[128:129]
	s_add_i32 m0, s42, 0x1e000
	v_lshlrev_b32_e32 v2, 2, v194
	global_load_lds_dwordx4 v[0:1], off
	v_and_b32_e32 v0, 15, v194
	v_lshlrev_b32_e32 v1, 1, v11
	v_lshl_or_b32 v146, s3, 6, v0
	v_lshl_or_b32 v0, v0, 6, v1
	v_and_b32_e32 v2, 32, v2
	v_bitop3_b32 v0, v0, s1, v2 bitop3:0xde
	v_lshlrev_b32_e32 v3, 6, v194
	s_movk_i32 s1, 0x3c0
	v_and_or_b32 v1, v3, s1, v1
	v_bitop3_b32 v147, s16, v1, v2 bitop3:0xf6
	v_lshlrev_b32_e32 v1, 8, v194
	v_and_b32_e32 v1, 0x38000, v1
	v_lshlrev_b32_e32 v2, 11, v12
	v_or3_b32 v1, v9, v1, v2
	v_add_u32_e32 v136, v1, v10
	v_lshlrev_b32_e32 v1, 4, v8
	s_waitcnt vmcnt(6)
	s_cmpk_lt_u32 s2, 0x100
	v_and_b32_e32 v1, 0x78000, v1
	s_cselect_b64 s[16:17], -1, 0
	v_readlane_b32 s2, v251, 13
	v_or3_b32 v1, v9, v1, v2
	s_add_i32 s51, 0, 0x10000
	s_add_i32 s52, 0, 0x14000
	s_ashr_i32 s49, s2, 31
	s_mov_b32 s50, s2
	v_or_b32_e32 v148, s18, v11
	v_mov_b32_e32 v137, v133
	v_add_u32_e32 v138, v1, v10
	v_mov_b32_e32 v139, v133
	v_mov_b64_e32 v[140:141], 0xb00
	v_mov_b64_e32 v[142:143], 0xaff
	s_waitcnt vmcnt(0)
	v_add_u32_e32 v149, s51, v147
	v_add_u32_e32 v150, s52, v147
	v_add_u32_e32 v151, 0, v0
	v_mov_b32_e32 v152, 0x358637bd
	s_mov_b32 s53, 0xf800000
	v_mov_b32_e32 v153, 0x260
	s_movk_i32 s54, 0x1680
	v_lshl_add_u32 v246, s0, 8, v146
	v_mov_b32_e32 v247, 0
	v_lshl_add_u64 v[246:247], v[246:247], 2, s[12:13]
	global_load_dword v238, v[246:247], off
	global_load_dword v239, v[246:247], off offset:64
	global_load_dword v240, v[246:247], off offset:128
	global_load_dword v241, v[246:247], off offset:192
	global_load_dword v242, v[246:247], off offset:512
	global_load_dword v243, v[246:247], off offset:576
	global_load_dword v244, v[246:247], off offset:640
	global_load_dword v245, v[246:247], off offset:704
	s_barrier
	v_readlane_b32 s3, v251, 14
	s_branch .LBB0_1046

; #define PG8_STAGE(bufoff, gbase, voff) do { _Pragma("unroll") for (int _i = 0; _i < 2; ++_i) \
;         __builtin_amdgcn_global_load_lds((const unsigned*)((const char*)(gbase) + (voff)[_i]), (PG8_LAS unsigned*)(lds + (bufoff) + ldsw + _i * 8192), 16, 0, 0); } while (0)
; #define PG8_LDA(dst, b, h) do { _Pragma("unroll") for (int m = 0; m < 4; ++m) _Pragma("unroll") for (int k = 0; k < 2; ++k) dst[m][k] = *(const PG8_LAS bf16x8*)(lds + PG8_SA(b, h) + aoff + m * 2048 + k * 1024); } while (0)
; #define PG8_LDB(dst, b, h) do { _Pragma("unroll") for (int n = 0; n < 2; ++n) _Pragma("unroll") for (int k = 0; k < 2; ++k) dst[n][k] = *(const PG8_LAS bf16x8*)(lds + PG8_SB(b, h) + boff + n * 2048 + k * 1024); } while (0)
; #define PG8_MMA(ai, bj, At, Bt) do { __builtin_amdgcn_s_setprio(1); _Pragma("unroll") for (int m = 0; m < 4; ++m) _Pragma("unroll") for (int n = 0; n < 2; ++n) _Pragma("unroll") for (int k = 0; k < 2; ++k) \
;         acc[ai][bj][m][n] = __builtin_amdgcn_mfma_f32_16x16x32_bf16(Bt[n][k], At[m][k], acc[ai][bj][m][n], 0, 0, 0); __builtin_amdgcn_s_setprio(0); } while (0)
; #define PG8_WAIT_V(n) asm volatile("s_waitcnt vmcnt(" #n ")" ::: "memory")
; #define PG8_WAIT_L(n) asm volatile("s_waitcnt lgkmcnt(" #n ")" ::: "memory")
; template <class Epi, class Sched, bool ALIGN_EPI = false, bool SP2 = false>
; __device__ __forceinline__ void gemm_phase(PG8_LAS unsigned char* lds, const Gemm g, const Sched& S, const Epi& E) {
;     ...
;         const char* nA = has_next ? PG8_UA(nxt) : cA; const char* nB = has_next ? PG8_UB(nxt) : cB;
;         for (int t = 0; t < nt; t += 2) {
;             const bool last = (t == nt - 2);
;             const char* a1 = cA + (size_t)(t + 1) * kstep;
;             const char* a2 = last ? nA : cA + (size_t)(t + 2) * kstep; const char* b2 = last ? nB : cB + (size_t)(t + 2) * kstep;
;             const char* a3 = a2 + kstep; const char* b3 = b2 + kstep;
;             if (last && has_next) S.a_ready(nxt);
;             if constexpr (SP2) {
;             PG8_LDB(B0, 0, 0); PG8_LDB(B1, 0, 1); PG8_SCHED; PG8_LDA(At, 0, 0); PG8_STAGE(PG8_SA(1, 1), a1 + hstepA, voffA);
;             PG8_WAIT_V(8); PG8_WAIT_L(0); PG8_BAR; PG8_MMA(0, 0, At, B0); PG8_MMA(0, 1, At, B1); PG8_BAR; PG8_SCHED;
;             PG8_LDA(At, 0, 1); PG8_STAGE(PG8_SB(0, 0), b2, voffB); PG8_STAGE(PG8_SB(0, 1), b2 + hstepB, voffB); PG8_STAGE(PG8_SA(0, 0), a2, voffA);
.LBB0_1049:
	ds_read_b128 v[154:157], v149
	ds_read_b128 v[158:161], v149 offset:1024
	ds_read_b128 v[162:165], v149 offset:2048
	ds_read_b128 v[166:169], v149 offset:3072
	ds_read_b128 v[170:173], v150
	ds_read_b128 v[174:177], v150 offset:1024
	ds_read_b128 v[178:181], v150 offset:2048
	ds_read_b128 v[182:185], v150 offset:3072
	s_add_u32 s26, s24, 0xfffc0080
	s_addc_u32 s27, s25, -1
	s_cmp_eq_u32 s59, 12
	s_cselect_b32 s29, s1, s27
	s_cselect_b32 s28, s2, s26
	s_cselect_b32 s27, s3, s58
	s_cselect_b32 s26, s19, s57
	v_lshl_add_u64 v[144:145], s[24:25], 0, v[136:137]
	s_add_i32 m0, s42, 0xc000
	ds_read_b128 v[186:189], v151
	ds_read_b128 v[196:199], v151 offset:1024
	ds_read_b128 v[200:203], v151 offset:2048
	ds_read_b128 v[204:207], v151 offset:3072
	ds_read_b128 v[208:211], v151 offset:4096
	ds_read_b128 v[212:215], v151 offset:5120
	ds_read_b128 v[216:219], v151 offset:6144
	ds_read_b128 v[220:223], v151 offset:7168
	global_load_lds_dwordx4 v[144:145], off
	s_add_i32 m0, s42, 0xe000
	s_nop 0
	global_load_lds_dwordx4 v138, s[24:25]
	s_waitcnt vmcnt(8)
	s_waitcnt lgkmcnt(0)
	s_barrier
	s_setprio 1
	s_waitcnt lgkmcnt(0)
	v_mfma_f32_16x16x32_bf16 v[124:127], v[154:157], v[186:189], v[124:127]
	v_mfma_f32_16x16x32_bf16 v[120:123], v[162:165], v[186:189], v[120:123]
	v_mfma_f32_16x16x32_bf16 v[108:111], v[154:157], v[200:203], v[108:111]
	v_mfma_f32_16x16x32_bf16 v[104:107], v[162:165], v[200:203], v[104:107]
	v_mfma_f32_16x16x32_bf16 v[92:95], v[154:157], v[208:211], v[92:95]
	v_mfma_f32_16x16x32_bf16 v[88:91], v[162:165], v[208:211], v[88:91]
	v_mfma_f32_16x16x32_bf16 v[76:79], v[154:157], v[216:219], v[76:79]
	v_mfma_f32_16x16x32_bf16 v[72:75], v[162:165], v[216:219], v[72:75]
	v_mfma_f32_16x16x32_bf16 v[124:127], v[158:161], v[196:199], v[124:127]
	v_mfma_f32_16x16x32_bf16 v[120:123], v[166:169], v[196:199], v[120:123]
	v_mfma_f32_16x16x32_bf16 v[108:111], v[158:161], v[204:207], v[108:111]
	v_mfma_f32_16x16x32_bf16 v[104:107], v[166:169], v[204:207], v[104:107]
	v_mfma_f32_16x16x32_bf16 v[92:95], v[158:161], v[212:215], v[92:95]
	v_mfma_f32_16x16x32_bf16 v[88:91], v[166:169], v[212:215], v[88:91]
	v_mfma_f32_16x16x32_bf16 v[76:79], v[158:161], v[220:223], v[76:79]
	v_mfma_f32_16x16x32_bf16 v[72:75], v[166:169], v[220:223], v[72:75]
	s_setprio 0
	s_setprio 1
	v_mfma_f32_16x16x32_bf16 v[116:119], v[170:173], v[186:189], v[116:119]
	v_mfma_f32_16x16x32_bf16 v[112:115], v[178:181], v[186:189], v[112:115]
	v_mfma_f32_16x16x32_bf16 v[100:103], v[170:173], v[200:203], v[100:103]
	v_mfma_f32_16x16x32_bf16 v[96:99], v[178:181], v[200:203], v[96:99]
	v_mfma_f32_16x16x32_bf16 v[84:87], v[170:173], v[208:211], v[84:87]
	v_mfma_f32_16x16x32_bf16 v[80:83], v[178:181], v[208:211], v[80:83]
	v_mfma_f32_16x16x32_bf16 v[68:71], v[170:173], v[216:219], v[68:71]
	v_mfma_f32_16x16x32_bf16 v[64:67], v[178:181], v[216:219], v[64:67]
	v_mfma_f32_16x16x32_bf16 v[116:119], v[174:177], v[196:199], v[116:119]
	v_mfma_f32_16x16x32_bf16 v[112:115], v[182:185], v[196:199], v[112:115]
	v_mfma_f32_16x16x32_bf16 v[100:103], v[174:177], v[204:207], v[100:103]
	v_mfma_f32_16x16x32_bf16 v[96:99], v[182:185], v[204:207], v[96:99]
	v_mfma_f32_16x16x32_bf16 v[84:87], v[174:177], v[212:215], v[84:87]
	v_mfma_f32_16x16x32_bf16 v[80:83], v[182:185], v[212:215], v[80:83]
	v_mfma_f32_16x16x32_bf16 v[68:71], v[174:177], v[220:223], v[68:71]
	v_mfma_f32_16x16x32_bf16 v[64:67], v[182:185], v[220:223], v[64:67]
	s_setprio 0
	s_barrier
	s_add_i32 s60, s51, s37
	v_lshl_add_u64 v[144:145], s[26:27], 0, v[132:133]
	s_mov_b32 m0, s60
	ds_read_b128 v[186:189], v151 offset:16384
	ds_read_b128 v[196:199], v151 offset:17408
	ds_read_b128 v[200:203], v151 offset:18432
	ds_read_b128 v[204:207], v151 offset:19456
	ds_read_b128 v[208:211], v151 offset:20480
	ds_read_b128 v[212:215], v151 offset:21504
	ds_read_b128 v[216:219], v151 offset:22528
	ds_read_b128 v[220:223], v151 offset:23552
	global_load_lds_dwordx4 v[144:145], off
	s_add_i32 m0, s60, 0x2000
	s_add_u32 s60, s26, 0x40000
	v_lshl_add_u64 v[190:191], s[26:27], 0, v[128:129]
	s_addc_u32 s61, s27, 0
	s_add_i32 s62, s52, s37
	global_load_lds_dwordx4 v[190:191], off
	s_mov_b32 m0, s62
	v_lshl_add_u64 v[226:227], s[28:29], 0, v[130:131]
	global_load_lds_dwordx4 v132, s[60:61]
	s_add_i32 m0, s62, 0x2000
	s_nop 0
	global_load_lds_dwordx4 v128, s[60:61]
	v_lshl_add_u64 v[224:225], s[28:29], 0, v[134:135]
	s_mov_b32 m0, s42
	s_nop 0
	global_load_lds_dwordx4 v[224:225], off
	s_mov_b32 m0, s43
	s_nop 0
	global_load_lds_dwordx4 v[226:227], off
	s_waitcnt vmcnt(8)
	s_waitcnt lgkmcnt(0)
	s_barrier
; #define PG8_STAGE(bufoff, gbase, voff) do { _Pragma("unroll") for (int _i = 0; _i < 2; ++_i) \
;         __builtin_amdgcn_global_load_lds((const unsigned*)((const char*)(gbase) + (voff)[_i]), (PG8_LAS unsigned*)(lds + (bufoff) + ldsw + _i * 8192), 16, 0, 0); } while (0)
; #define PG8_LDA(dst, b, h) do { _Pragma("unroll") for (int m = 0; m < 4; ++m) _Pragma("unroll") for (int k = 0; k < 2; ++k) dst[m][k] = *(const PG8_LAS bf16x8*)(lds + PG8_SA(b, h) + aoff + m * 2048 + k * 1024); } while (0)
; #define PG8_LDB(dst, b, h) do { _Pragma("unroll") for (int n = 0; n < 2; ++n) _Pragma("unroll") for (int k = 0; k < 2; ++k) dst[n][k] = *(const PG8_LAS bf16x8*)(lds + PG8_SB(b, h) + boff + n * 2048 + k * 1024); } while (0)
; #define PG8_MMA(ai, bj, At, Bt) do { __builtin_amdgcn_s_setprio(1); _Pragma("unroll") for (int m = 0; m < 4; ++m) _Pragma("unroll") for (int n = 0; n < 2; ++n) _Pragma("unroll") for (int k = 0; k < 2; ++k) \
;         acc[ai][bj][m][n] = __builtin_amdgcn_mfma_f32_16x16x32_bf16(Bt[n][k], At[m][k], acc[ai][bj][m][n], 0, 0, 0); __builtin_amdgcn_s_setprio(0); } while (0)
; #define PG8_WAIT_V(n) asm volatile("s_waitcnt vmcnt(" #n ")" ::: "memory")
; #define PG8_WAIT_L(n) asm volatile("s_waitcnt lgkmcnt(" #n ")" ::: "memory")
; #define PG8_BAR __builtin_amdgcn_s_barrier()
; #define PG8_SCHED __builtin_amdgcn_sched_barrier(0)
; template <class Epi, class Sched, bool ALIGN_EPI = false, bool SP2 = false>
; __device__ __forceinline__ void gemm_phase(PG8_LAS unsigned char* lds, const Gemm g, const Sched& S, const Epi& E) {
;     ...
;             PG8_WAIT_V(8); PG8_WAIT_L(0); PG8_BAR; PG8_MMA(1, 0, At, B0); PG8_MMA(1, 1, At, B1); PG8_BAR; PG8_SCHED;
;             PG8_LDB(B0, 1, 0); PG8_LDB(B1, 1, 1); PG8_SCHED; PG8_LDA(At, 1, 0); PG8_STAGE(PG8_SA(0, 1), a2 + hstepA, voffA);
;             PG8_WAIT_V(8); PG8_WAIT_L(0); PG8_BAR; PG8_MMA(0, 0, At, B0); PG8_MMA(0, 1, At, B1); PG8_BAR; PG8_SCHED;
	s_setprio 1
	s_waitcnt lgkmcnt(0)
	v_mfma_f32_16x16x32_bf16 v[60:63], v[154:157], v[186:189], v[60:63]
	v_mfma_f32_16x16x32_bf16 v[56:59], v[162:165], v[186:189], v[56:59]
	v_mfma_f32_16x16x32_bf16 v[44:47], v[154:157], v[200:203], v[44:47]
	v_mfma_f32_16x16x32_bf16 v[40:43], v[162:165], v[200:203], v[40:43]
	v_mfma_f32_16x16x32_bf16 v[28:31], v[154:157], v[208:211], v[28:31]
	v_mfma_f32_16x16x32_bf16 v[24:27], v[162:165], v[208:211], v[24:27]
	v_mfma_f32_16x16x32_bf16 v[12:15], v[154:157], v[216:219], v[12:15]
	v_mfma_f32_16x16x32_bf16 v[8:11], v[162:165], v[216:219], v[8:11]
	v_mfma_f32_16x16x32_bf16 v[60:63], v[158:161], v[196:199], v[60:63]
	v_mfma_f32_16x16x32_bf16 v[56:59], v[166:169], v[196:199], v[56:59]
	v_mfma_f32_16x16x32_bf16 v[44:47], v[158:161], v[204:207], v[44:47]
	v_mfma_f32_16x16x32_bf16 v[40:43], v[166:169], v[204:207], v[40:43]
	v_mfma_f32_16x16x32_bf16 v[28:31], v[158:161], v[212:215], v[28:31]
	v_mfma_f32_16x16x32_bf16 v[24:27], v[166:169], v[212:215], v[24:27]
	v_mfma_f32_16x16x32_bf16 v[12:15], v[158:161], v[220:223], v[12:15]
	v_mfma_f32_16x16x32_bf16 v[8:11], v[166:169], v[220:223], v[8:11]
	s_setprio 0
	s_setprio 1
	v_mfma_f32_16x16x32_bf16 v[52:55], v[170:173], v[186:189], v[52:55]
	v_mfma_f32_16x16x32_bf16 v[48:51], v[178:181], v[186:189], v[48:51]
	v_mfma_f32_16x16x32_bf16 v[36:39], v[170:173], v[200:203], v[36:39]
	v_mfma_f32_16x16x32_bf16 v[32:35], v[178:181], v[200:203], v[32:35]
	v_mfma_f32_16x16x32_bf16 v[20:23], v[170:173], v[208:211], v[20:23]
	v_mfma_f32_16x16x32_bf16 v[16:19], v[178:181], v[208:211], v[16:19]
	v_mfma_f32_16x16x32_bf16 v[4:7], v[170:173], v[216:219], v[4:7]
	v_mfma_f32_16x16x32_bf16 v[0:3], v[178:181], v[216:219], v[0:3]
	v_mfma_f32_16x16x32_bf16 v[52:55], v[174:177], v[196:199], v[52:55]
	v_mfma_f32_16x16x32_bf16 v[48:51], v[182:185], v[196:199], v[48:51]
	v_mfma_f32_16x16x32_bf16 v[36:39], v[174:177], v[204:207], v[36:39]
	v_mfma_f32_16x16x32_bf16 v[32:35], v[182:185], v[204:207], v[32:35]
	v_mfma_f32_16x16x32_bf16 v[20:23], v[174:177], v[212:215], v[20:23]
	v_mfma_f32_16x16x32_bf16 v[16:19], v[182:185], v[212:215], v[16:19]
	v_mfma_f32_16x16x32_bf16 v[4:7], v[174:177], v[220:223], v[4:7]
	v_mfma_f32_16x16x32_bf16 v[0:3], v[182:185], v[220:223], v[0:3]
	s_setprio 0
	s_barrier
	s_add_i32 s60, 0, 0x18000
	s_add_i32 s61, 0, 0x1c000
	v_add_u32_e32 v166, s60, v147
	v_add_u32_e32 v182, s61, v147
	ds_read_b128 v[154:157], v166
	ds_read_b128 v[158:161], v166 offset:1024
	ds_read_b128 v[162:165], v166 offset:2048
	ds_read_b128 v[166:169], v166 offset:3072
	ds_read_b128 v[170:173], v182
	ds_read_b128 v[174:177], v182 offset:1024
	ds_read_b128 v[178:181], v182 offset:2048
	ds_read_b128 v[182:185], v182 offset:3072
	s_add_u32 s28, s28, 0x40000
	s_addc_u32 s29, s29, 0
	s_mov_b32 m0, s44
	v_lshl_add_u64 v[228:229], s[28:29], 0, v[134:135]
	ds_read_b128 v[186:189], v151 offset:32768
	ds_read_b128 v[196:199], v151 offset:33792
	ds_read_b128 v[200:203], v151 offset:34816
	ds_read_b128 v[204:207], v151 offset:35840
	ds_read_b128 v[208:211], v151 offset:36864
	ds_read_b128 v[212:215], v151 offset:37888
	ds_read_b128 v[216:219], v151 offset:38912
	ds_read_b128 v[220:223], v151 offset:39936
	global_load_lds_dwordx4 v[228:229], off
	v_lshl_add_u64 v[228:229], s[28:29], 0, v[130:131]
	s_mov_b32 m0, s45
	s_nop 0
	global_load_lds_dwordx4 v[228:229], off
	s_waitcnt vmcnt(8)
	s_waitcnt lgkmcnt(0)
	s_barrier
	s_setprio 1
	s_waitcnt lgkmcnt(0)
	v_mfma_f32_16x16x32_bf16 v[124:127], v[154:157], v[186:189], v[124:127]
	v_mfma_f32_16x16x32_bf16 v[120:123], v[162:165], v[186:189], v[120:123]
	v_mfma_f32_16x16x32_bf16 v[108:111], v[154:157], v[200:203], v[108:111]
	v_mfma_f32_16x16x32_bf16 v[104:107], v[162:165], v[200:203], v[104:107]
	v_mfma_f32_16x16x32_bf16 v[92:95], v[154:157], v[208:211], v[92:95]
	v_mfma_f32_16x16x32_bf16 v[88:91], v[162:165], v[208:211], v[88:91]
	v_mfma_f32_16x16x32_bf16 v[76:79], v[154:157], v[216:219], v[76:79]
	v_mfma_f32_16x16x32_bf16 v[72:75], v[162:165], v[216:219], v[72:75]
	v_mfma_f32_16x16x32_bf16 v[124:127], v[158:161], v[196:199], v[124:127]
	v_mfma_f32_16x16x32_bf16 v[120:123], v[166:169], v[196:199], v[120:123]
	v_mfma_f32_16x16x32_bf16 v[108:111], v[158:161], v[204:207], v[108:111]
	v_mfma_f32_16x16x32_bf16 v[104:107], v[166:169], v[204:207], v[104:107]
	v_mfma_f32_16x16x32_bf16 v[92:95], v[158:161], v[212:215], v[92:95]
	v_mfma_f32_16x16x32_bf16 v[88:91], v[166:169], v[212:215], v[88:91]
	v_mfma_f32_16x16x32_bf16 v[76:79], v[158:161], v[220:223], v[76:79]
	v_mfma_f32_16x16x32_bf16 v[72:75], v[166:169], v[220:223], v[72:75]
	s_setprio 0
	s_setprio 1
	v_mfma_f32_16x16x32_bf16 v[116:119], v[170:173], v[186:189], v[116:119]
	v_mfma_f32_16x16x32_bf16 v[112:115], v[178:181], v[186:189], v[112:115]
	v_mfma_f32_16x16x32_bf16 v[100:103], v[170:173], v[200:203], v[100:103]
	v_mfma_f32_16x16x32_bf16 v[96:99], v[178:181], v[200:203], v[96:99]
	v_mfma_f32_16x16x32_bf16 v[84:87], v[170:173], v[208:211], v[84:87]
	v_mfma_f32_16x16x32_bf16 v[80:83], v[178:181], v[208:211], v[80:83]
	v_mfma_f32_16x16x32_bf16 v[68:71], v[170:173], v[216:219], v[68:71]
	v_mfma_f32_16x16x32_bf16 v[64:67], v[178:181], v[216:219], v[64:67]
	v_mfma_f32_16x16x32_bf16 v[116:119], v[174:177], v[196:199], v[116:119]
	v_mfma_f32_16x16x32_bf16 v[112:115], v[182:185], v[196:199], v[112:115]
	v_mfma_f32_16x16x32_bf16 v[100:103], v[174:177], v[204:207], v[100:103]
	v_mfma_f32_16x16x32_bf16 v[96:99], v[182:185], v[204:207], v[96:99]
	v_mfma_f32_16x16x32_bf16 v[84:87], v[174:177], v[212:215], v[84:87]
	v_mfma_f32_16x16x32_bf16 v[80:83], v[182:185], v[212:215], v[80:83]
	v_mfma_f32_16x16x32_bf16 v[68:71], v[174:177], v[220:223], v[68:71]
	v_mfma_f32_16x16x32_bf16 v[64:67], v[182:185], v[220:223], v[64:67]
	s_setprio 0
	s_barrier
; #define PG8_STAGE(bufoff, gbase, voff) do { _Pragma("unroll") for (int _i = 0; _i < 2; ++_i) \
;         __builtin_amdgcn_global_load_lds((const unsigned*)((const char*)(gbase) + (voff)[_i]), (PG8_LAS unsigned*)(lds + (bufoff) + ldsw + _i * 8192), 16, 0, 0); } while (0)
; #define PG8_LDA(dst, b, h) do { _Pragma("unroll") for (int m = 0; m < 4; ++m) _Pragma("unroll") for (int k = 0; k < 2; ++k) dst[m][k] = *(const PG8_LAS bf16x8*)(lds + PG8_SA(b, h) + aoff + m * 2048 + k * 1024); } while (0)
; #define PG8_MMA(ai, bj, At, Bt) do { __builtin_amdgcn_s_setprio(1); _Pragma("unroll") for (int m = 0; m < 4; ++m) _Pragma("unroll") for (int n = 0; n < 2; ++n) _Pragma("unroll") for (int k = 0; k < 2; ++k) \
;         acc[ai][bj][m][n] = __builtin_amdgcn_mfma_f32_16x16x32_bf16(Bt[n][k], At[m][k], acc[ai][bj][m][n], 0, 0, 0); __builtin_amdgcn_s_setprio(0); } while (0)
; #define PG8_WAIT_V(n) asm volatile("s_waitcnt vmcnt(" #n ")" ::: "memory")
; #define PG8_WAIT_L(n) asm volatile("s_waitcnt lgkmcnt(" #n ")" ::: "memory")
; #define PG8_BAR __builtin_amdgcn_s_barrier()
; #define PG8_SCHED __builtin_amdgcn_sched_barrier(0)
; template <class Epi, class Sched, bool ALIGN_EPI = false, bool SP2 = false>
; __device__ __forceinline__ void gemm_phase(PG8_LAS unsigned char* lds, const Gemm g, const Sched& S, const Epi& E) {
;     ...
;             PG8_LDA(At, 1, 1); PG8_STAGE(PG8_SB(1, 0), b3, voffB); PG8_STAGE(PG8_SB(1, 1), b3 + hstepB, voffB); PG8_STAGE(PG8_SA(1, 0), a3, voffA);
;             PG8_WAIT_V(8); PG8_WAIT_L(0); PG8_BAR; PG8_MMA(1, 0, At, B0); PG8_MMA(1, 1, At, B1); PG8_BAR; PG8_SCHED;
;     ...
;         if constexpr (ALIGN_EPI) { if (wr == 0) PG8_BAR; }
	s_add_i32 s28, s60, s37
	v_lshl_add_u64 v[144:145], v[144:145], 0, s[14:15]
	s_mov_b32 m0, s28
	ds_read_b128 v[186:189], v151 offset:49152
	ds_read_b128 v[196:199], v151 offset:50176
	ds_read_b128 v[200:203], v151 offset:51200
	ds_read_b128 v[204:207], v151 offset:52224
	ds_read_b128 v[208:211], v151 offset:53248
	ds_read_b128 v[212:215], v151 offset:54272
	ds_read_b128 v[216:219], v151 offset:55296
	ds_read_b128 v[220:223], v151 offset:56320
	global_load_lds_dwordx4 v[144:145], off
	s_add_i32 m0, s28, 0x2000
	s_add_u32 s26, s26, 0x40080
	v_lshl_add_u64 v[144:145], v[190:191], 0, s[14:15]
	s_addc_u32 s27, s27, 0
	s_add_i32 s28, s61, s37
	global_load_lds_dwordx4 v[144:145], off
	s_mov_b32 m0, s28
	s_nop 0
	global_load_lds_dwordx4 v132, s[26:27]
	s_add_i32 m0, s28, 0x2000
	s_nop 0
	global_load_lds_dwordx4 v128, s[26:27]
	v_lshl_add_u64 v[144:145], v[224:225], 0, s[14:15]
	s_mov_b32 m0, s47
	s_nop 0
	global_load_lds_dwordx4 v[144:145], off
	v_lshl_add_u64 v[144:145], v[226:227], 0, s[14:15]
	s_mov_b32 m0, s48
	s_nop 0
	global_load_lds_dwordx4 v[144:145], off
	s_waitcnt vmcnt(8)
	s_waitcnt lgkmcnt(0)
	s_barrier
	s_setprio 1
	s_waitcnt lgkmcnt(0)
	v_mfma_f32_16x16x32_bf16 v[60:63], v[154:157], v[186:189], v[60:63]
	v_mfma_f32_16x16x32_bf16 v[56:59], v[162:165], v[186:189], v[56:59]
	v_mfma_f32_16x16x32_bf16 v[44:47], v[154:157], v[200:203], v[44:47]
	v_mfma_f32_16x16x32_bf16 v[40:43], v[162:165], v[200:203], v[40:43]
	v_mfma_f32_16x16x32_bf16 v[28:31], v[154:157], v[208:211], v[28:31]
	v_mfma_f32_16x16x32_bf16 v[24:27], v[162:165], v[208:211], v[24:27]
	v_mfma_f32_16x16x32_bf16 v[12:15], v[154:157], v[216:219], v[12:15]
	v_mfma_f32_16x16x32_bf16 v[8:11], v[162:165], v[216:219], v[8:11]
	v_mfma_f32_16x16x32_bf16 v[60:63], v[158:161], v[196:199], v[60:63]
	v_mfma_f32_16x16x32_bf16 v[56:59], v[166:169], v[196:199], v[56:59]
	v_mfma_f32_16x16x32_bf16 v[44:47], v[158:161], v[204:207], v[44:47]
	v_mfma_f32_16x16x32_bf16 v[40:43], v[166:169], v[204:207], v[40:43]
	v_mfma_f32_16x16x32_bf16 v[28:31], v[158:161], v[212:215], v[28:31]
	v_mfma_f32_16x16x32_bf16 v[24:27], v[166:169], v[212:215], v[24:27]
	v_mfma_f32_16x16x32_bf16 v[12:15], v[158:161], v[220:223], v[12:15]
	v_mfma_f32_16x16x32_bf16 v[8:11], v[166:169], v[220:223], v[8:11]
	s_setprio 0
	s_setprio 1
	v_mfma_f32_16x16x32_bf16 v[52:55], v[170:173], v[186:189], v[52:55]
	v_mfma_f32_16x16x32_bf16 v[48:51], v[178:181], v[186:189], v[48:51]
	v_mfma_f32_16x16x32_bf16 v[36:39], v[170:173], v[200:203], v[36:39]
	v_mfma_f32_16x16x32_bf16 v[32:35], v[178:181], v[200:203], v[32:35]
	v_mfma_f32_16x16x32_bf16 v[20:23], v[170:173], v[208:211], v[20:23]
	v_mfma_f32_16x16x32_bf16 v[16:19], v[178:181], v[208:211], v[16:19]
	v_mfma_f32_16x16x32_bf16 v[4:7], v[170:173], v[216:219], v[4:7]
	v_mfma_f32_16x16x32_bf16 v[0:3], v[178:181], v[216:219], v[0:3]
	v_mfma_f32_16x16x32_bf16 v[52:55], v[174:177], v[196:199], v[52:55]
	v_mfma_f32_16x16x32_bf16 v[48:51], v[182:185], v[196:199], v[48:51]
	v_mfma_f32_16x16x32_bf16 v[36:39], v[174:177], v[204:207], v[36:39]
	v_mfma_f32_16x16x32_bf16 v[32:35], v[182:185], v[204:207], v[32:35]
	v_mfma_f32_16x16x32_bf16 v[20:23], v[174:177], v[212:215], v[20:23]
	v_mfma_f32_16x16x32_bf16 v[16:19], v[182:185], v[212:215], v[16:19]
	v_mfma_f32_16x16x32_bf16 v[4:7], v[174:177], v[220:223], v[4:7]
	v_mfma_f32_16x16x32_bf16 v[0:3], v[182:185], v[220:223], v[0:3]
	s_setprio 0
	s_barrier
	s_add_i32 s59, s59, 2
	s_add_u32 s24, s24, 0x100
	s_addc_u32 s25, s25, 0
	s_add_u32 s57, s57, 0x100
	s_addc_u32 s58, s58, 0
	s_cmp_gt_u32 s59, 13
	s_cbranch_scc0 .LBB0_1049
	s_and_b64 vcc, exec, s[16:17]
	s_cbranch_vccz .LBB0_1052
	s_barrier

; #define PG8_STAGE(bufoff, gbase, voff) do { _Pragma("unroll") for (int _i = 0; _i < 2; ++_i) \
;         __builtin_amdgcn_global_load_lds((const unsigned*)((const char*)(gbase) + (voff)[_i]), (PG8_LAS unsigned*)(lds + (bufoff) + ldsw + _i * 8192), 16, 0, 0); } while (0)
; #define PG8_WAIT_V(n) asm volatile("s_waitcnt vmcnt(" #n ")" ::: "memory")
; #define PG8_BAR __builtin_amdgcn_s_barrier()
; template <class Epi, class Sched, bool ALIGN_EPI = false, bool SP2 = false>
; __device__ __forceinline__ void gemm_phase(PG8_LAS unsigned char* lds, const Gemm g, const Sched& S, const Epi& E) {
;     ...
; #pragma unroll
;     for (int a = 0; a < 2; ++a)
; #pragma unroll
;         for (int b = 0; b < 2; ++b)
; #pragma unroll
;             for (int m = 0; m < 4; ++m)
; #pragma unroll
;                 for (int n = 0; n < 2; ++n) acc[a][b][m][n] = (f32x4){0.f, 0.f, 0.f, 0.f};
;     bf16x8 At[4][2], B0[2][2], B1[2][2];
;     const char* cA = PG8_UA(cur); const char* cB = PG8_UB(cur);
;     S.a_ready(cur);
;     if constexpr (SP2) {
;         PG8_STAGE(PG8_SB(0, 0), cB, voffB); PG8_STAGE(PG8_SB(0, 1), cB + hstepB, voffB); PG8_STAGE(PG8_SA(0, 0), cA, voffA); PG8_STAGE(PG8_SA(0, 1), cA + hstepA, voffA);
;         if (wr == 1) PG8_BAR;
;         PG8_WAIT_V(2); PG8_BAR;
;         PG8_STAGE(PG8_SB(1, 0), cB + kstep, voffB); PG8_STAGE(PG8_SA(1, 0), cA + kstep, voffA); PG8_STAGE(PG8_SB(1, 1), cB + hstepB + kstep, voffB);
;         PG8_WAIT_V(6); PG8_BAR;
.LBB0_1120:
	v_lshlrev_b32_e32 v9, 2, v161
	s_and_b32 s37, s6, 3
	v_lshl_or_b32 v8, v161, 6, v166
	s_lshl_b32 s6, s2, 13
	v_and_b32_e32 v9, 32, v9
	v_bitop3_b32 v8, v8, s6, v9 bitop3:0xde
	s_mov_b64 s[6:7], 0x80
	s_add_i32 m0, s3, 0x18000
	v_lshl_add_u64 v[6:7], v[6:7], 0, s[6:7]
	s_waitcnt vmcnt(2)
	s_barrier
	global_load_lds_dwordx4 v[6:7], off
	v_lshl_add_u64 v[4:5], v[4:5], 0, s[6:7]
	s_add_i32 m0, s3, 0x1a000
	s_add_i32 s43, s3, 0x8000
	s_add_i32 s44, s3, 0xa000
	global_load_lds_dwordx4 v[4:5], off
	v_lshl_add_u64 v[2:3], v[2:3], 0, s[6:7]
	s_mov_b32 m0, s43
	s_add_u32 s22, s0, 0xb0080
	global_load_lds_dwordx4 v[2:3], off
	v_lshl_add_u64 v[0:1], v[0:1], 0, s[6:7]
	s_mov_b32 m0, s44
	s_addc_u32 s23, s1, 0
	global_load_lds_dwordx4 v[0:1], off
	s_add_i32 m0, s3, 0x1c000
	global_load_lds_dwordx4 v146, s[22:23]
	v_lshl_add_u64 v[0:1], s[22:23], 0, v[150:151]
	s_add_i32 m0, s3, 0x1e000
	s_add_u32 s22, s34, s19
	global_load_lds_dwordx4 v[0:1], off
	v_add_u16_e32 v0, v162, v163
	v_lshrrev_b16_e32 v2, 1, v0
	v_lshl_or_b32 v9, s37, 12, v167
	s_waitcnt vmcnt(6)
	v_add_lshl_u32 v0, v164, v2, 1
	v_mov_b32_e32 v1, v147
	s_addc_u32 s23, s35, s18
	s_add_i32 s48, 0, 0x10000
	s_add_i32 s50, 0, 0x14000
	s_add_i32 s52, 0, 0x18000
	s_add_i32 s54, 0, 0x1c000
	v_lshl_add_u64 v[96:97], s[22:23], 0, v[0:1]
	v_add_lshl_u32 v0, v165, v2, 1
	v_add_u32_e32 v100, s48, v9
	v_add_u32_e32 v101, s50, v9
	s_add_i32 s48, s48, s20
	s_add_i32 s50, s50, s20
	v_add_u32_e32 v103, s52, v9
	v_add_u32_e32 v104, s54, v9
	s_add_i32 s52, s52, s20
	s_add_i32 s54, s54, s20
	v_lshl_or_b32 v152, s2, 6, v161
	v_lshl_add_u64 v[98:99], s[22:23], 0, v[0:1]
	s_mov_b32 s45, -2
	s_mov_b64 s[18:19], 0x78b4080
	v_add_u32_e32 v102, 0, v8
	s_add_i32 s46, s3, 0xc000
	s_add_i32 s47, s3, 0xe000
	s_add_i32 s49, s48, 0x2000
	s_add_i32 s51, s50, 0x2000
	s_add_i32 s53, s52, 0x2000
	s_add_i32 s55, s54, 0x2000
	v_mov_b32_e32 v0, v147
	v_mov_b32_e32 v2, v147
	v_mov_b32_e32 v3, v147
	v_mov_b32_e32 v4, v147
	v_mov_b32_e32 v5, v147
	v_mov_b32_e32 v6, v147
	v_mov_b32_e32 v7, v147
	v_mov_b32_e32 v16, v147
	v_mov_b32_e32 v17, v147
	v_mov_b32_e32 v18, v147
	v_mov_b32_e32 v19, v147
	v_mov_b32_e32 v20, v147
	v_mov_b32_e32 v21, v147
	v_mov_b32_e32 v22, v147
	v_mov_b32_e32 v23, v147
	v_mov_b32_e32 v32, v147
	v_mov_b32_e32 v33, v147
	v_mov_b32_e32 v34, v147
	v_mov_b32_e32 v35, v147
	v_mov_b32_e32 v36, v147
	v_mov_b32_e32 v37, v147
	v_mov_b32_e32 v38, v147
	v_mov_b32_e32 v39, v147
	v_mov_b32_e32 v48, v147
	v_mov_b32_e32 v49, v147
	v_mov_b32_e32 v50, v147
	v_mov_b32_e32 v51, v147
	v_mov_b32_e32 v52, v147
	v_mov_b32_e32 v53, v147
	v_mov_b32_e32 v54, v147
	v_mov_b32_e32 v55, v147
	v_mov_b32_e32 v8, v147
	v_mov_b32_e32 v9, v147
	v_mov_b32_e32 v10, v147
	v_mov_b32_e32 v11, v147
	v_mov_b32_e32 v12, v147
	v_mov_b32_e32 v13, v147
	v_mov_b32_e32 v14, v147
	v_mov_b32_e32 v15, v147
	v_mov_b32_e32 v24, v147
	v_mov_b32_e32 v25, v147
	v_mov_b32_e32 v26, v147
	v_mov_b32_e32 v27, v147
	v_mov_b32_e32 v28, v147
	v_mov_b32_e32 v29, v147
	v_mov_b32_e32 v30, v147
	v_mov_b32_e32 v31, v147
	v_mov_b32_e32 v40, v147
	v_mov_b32_e32 v41, v147
	v_mov_b32_e32 v42, v147
	v_mov_b32_e32 v43, v147
	v_mov_b32_e32 v44, v147
	v_mov_b32_e32 v45, v147
	v_mov_b32_e32 v46, v147
	v_mov_b32_e32 v47, v147
	v_mov_b32_e32 v56, v147
	v_mov_b32_e32 v57, v147
	v_mov_b32_e32 v58, v147
	v_mov_b32_e32 v59, v147
	v_mov_b32_e32 v60, v147
	v_mov_b32_e32 v61, v147
	v_mov_b32_e32 v62, v147
	v_mov_b32_e32 v63, v147
	v_mov_b32_e32 v64, v147
	v_mov_b32_e32 v65, v147
	v_mov_b32_e32 v66, v147
	v_mov_b32_e32 v67, v147
	v_mov_b32_e32 v68, v147
	v_mov_b32_e32 v69, v147
	v_mov_b32_e32 v70, v147
	v_mov_b32_e32 v71, v147
	v_mov_b32_e32 v80, v147
	v_mov_b32_e32 v81, v147
	v_mov_b32_e32 v82, v147
	v_mov_b32_e32 v83, v147
	v_mov_b32_e32 v84, v147
	v_mov_b32_e32 v85, v147
	v_mov_b32_e32 v86, v147
	v_mov_b32_e32 v87, v147
	v_mov_b32_e32 v112, v147
	v_mov_b32_e32 v113, v147
	v_mov_b32_e32 v114, v147
	v_mov_b32_e32 v115, v147
	v_mov_b32_e32 v116, v147
	v_mov_b32_e32 v117, v147
	v_mov_b32_e32 v118, v147
	v_mov_b32_e32 v119, v147
	v_mov_b32_e32 v128, v147
	v_mov_b32_e32 v129, v147
	v_mov_b32_e32 v130, v147
	v_mov_b32_e32 v131, v147
	v_mov_b32_e32 v132, v147
	v_mov_b32_e32 v133, v147
	v_mov_b32_e32 v134, v147
	v_mov_b32_e32 v135, v147
	v_mov_b32_e32 v72, v147
	v_mov_b32_e32 v73, v147
	v_mov_b32_e32 v74, v147
	v_mov_b32_e32 v75, v147
	v_mov_b32_e32 v76, v147
	v_mov_b32_e32 v77, v147
	v_mov_b32_e32 v78, v147
	v_mov_b32_e32 v79, v147
	v_mov_b32_e32 v88, v147
	v_mov_b32_e32 v89, v147
	v_mov_b32_e32 v90, v147
	v_mov_b32_e32 v91, v147
	v_mov_b32_e32 v92, v147
	v_mov_b32_e32 v93, v147
	v_mov_b32_e32 v94, v147
	v_mov_b32_e32 v95, v147
	v_mov_b32_e32 v120, v147
	v_mov_b32_e32 v121, v147
	v_mov_b32_e32 v122, v147
	v_mov_b32_e32 v123, v147
	v_mov_b32_e32 v124, v147
	v_mov_b32_e32 v125, v147
	v_mov_b32_e32 v126, v147
	v_mov_b32_e32 v127, v147
	v_mov_b32_e32 v136, v147
	v_mov_b32_e32 v137, v147
	v_mov_b32_e32 v138, v147
	v_mov_b32_e32 v139, v147
	v_mov_b32_e32 v140, v147
	v_mov_b32_e32 v141, v147
	v_mov_b32_e32 v142, v147
	v_mov_b32_e32 v143, v147
	s_barrier
; #define PG8_STAGE(bufoff, gbase, voff) do { _Pragma("unroll") for (int _i = 0; _i < 2; ++_i) \
;         __builtin_amdgcn_global_load_lds((const unsigned*)((const char*)(gbase) + (voff)[_i]), (PG8_LAS unsigned*)(lds + (bufoff) + ldsw + _i * 8192), 16, 0, 0); } while (0)
; #define PG8_LDA(dst, b, h) do { _Pragma("unroll") for (int m = 0; m < 4; ++m) _Pragma("unroll") for (int k = 0; k < 2; ++k) dst[m][k] = *(const PG8_LAS bf16x8*)(lds + PG8_SA(b, h) + aoff + m * 2048 + k * 1024); } while (0)
; #define PG8_LDB(dst, b, h) do { _Pragma("unroll") for (int n = 0; n < 2; ++n) _Pragma("unroll") for (int k = 0; k < 2; ++k) dst[n][k] = *(const PG8_LAS bf16x8*)(lds + PG8_SB(b, h) + boff + n * 2048 + k * 1024); } while (0)
; #define PG8_MMA(ai, bj, At, Bt) do { __builtin_amdgcn_s_setprio(1); _Pragma("unroll") for (int m = 0; m < 4; ++m) _Pragma("unroll") for (int n = 0; n < 2; ++n) _Pragma("unroll") for (int k = 0; k < 2; ++k) \
;         acc[ai][bj][m][n] = __builtin_amdgcn_mfma_f32_16x16x32_bf16(Bt[n][k], At[m][k], acc[ai][bj][m][n], 0, 0, 0); __builtin_amdgcn_s_setprio(0); } while (0)
; #define PG8_WAIT_V(n) asm volatile("s_waitcnt vmcnt(" #n ")" ::: "memory")
; #define PG8_WAIT_L(n) asm volatile("s_waitcnt lgkmcnt(" #n ")" ::: "memory")
; template <class Epi, class Sched, bool ALIGN_EPI = false, bool SP2 = false>
; __device__ __forceinline__ void gemm_phase(PG8_LAS unsigned char* lds, const Gemm g, const Sched& S, const Epi& E) {
;     ...
;         const char* nA = has_next ? PG8_UA(nxt) : cA; const char* nB = has_next ? PG8_UB(nxt) : cB;
;         for (int t = 0; t < nt; t += 2) {
;             const bool last = (t == nt - 2);
;             const char* a1 = cA + (size_t)(t + 1) * kstep;
;             const char* a2 = last ? nA : cA + (size_t)(t + 2) * kstep; const char* b2 = last ? nB : cB + (size_t)(t + 2) * kstep;
;             const char* a3 = a2 + kstep; const char* b3 = b2 + kstep;
;             if (last && has_next) S.a_ready(nxt);
;             if constexpr (SP2) {
;             PG8_LDB(B0, 0, 0); PG8_LDB(B1, 0, 1); PG8_SCHED; PG8_LDA(At, 0, 0); PG8_STAGE(PG8_SA(1, 1), a1 + hstepA, voffA);
;             PG8_WAIT_V(8); PG8_WAIT_L(0); PG8_BAR; PG8_MMA(0, 0, At, B0); PG8_MMA(0, 1, At, B1); PG8_BAR; PG8_SCHED;
;             PG8_LDA(At, 0, 1); PG8_STAGE(PG8_SB(0, 0), b2, voffB); PG8_STAGE(PG8_SB(0, 1), b2 + hstepB, voffB); PG8_STAGE(PG8_SA(0, 0), a2, voffA);
.LBB0_1121:
	ds_read_b128 v[106:109], v100
	ds_read_b128 v[154:157], v100 offset:1024
	ds_read_b128 v[168:171], v100 offset:2048
	ds_read_b128 v[172:175], v100 offset:3072
	ds_read_b128 v[176:179], v101
	ds_read_b128 v[180:183], v101 offset:1024
	ds_read_b128 v[184:187], v101 offset:2048
	ds_read_b128 v[188:191], v101 offset:3072
	s_add_u32 s20, s18, 0xf874c080
	s_addc_u32 s21, s19, -1
	s_cmp_lg_u32 s45, 40
	s_cselect_b32 s20, s20, 0
	s_cselect_b32 s21, s21, 0
	s_add_u32 s22, s4, s20
	s_addc_u32 s23, s5, s21
	s_add_u32 s20, s0, s20
	s_addc_u32 s21, s1, s21
	s_mov_b32 m0, s46
	v_lshl_add_u64 v[110:111], v[96:97], 0, s[18:19]
	ds_read_b128 v[196:199], v102
	ds_read_b128 v[200:203], v102 offset:1024
	ds_read_b128 v[204:207], v102 offset:2048
	ds_read_b128 v[208:211], v102 offset:3072
	ds_read_b128 v[212:215], v102 offset:4096
	ds_read_b128 v[216:219], v102 offset:5120
	ds_read_b128 v[220:223], v102 offset:6144
	ds_read_b128 v[224:227], v102 offset:7168
	global_load_lds_dwordx4 v[110:111], off
	v_lshl_add_u64 v[110:111], v[98:99], 0, s[18:19]
	s_mov_b32 m0, s47
	s_nop 0
	global_load_lds_dwordx4 v[110:111], off
	s_waitcnt vmcnt(8)
	s_waitcnt lgkmcnt(0)
	s_barrier
	s_setprio 1
	s_waitcnt lgkmcnt(0)
	v_mfma_f32_16x16x32_bf16 v[140:143], v[106:109], v[196:199], v[140:143]
	v_mfma_f32_16x16x32_bf16 v[136:139], v[168:171], v[196:199], v[136:139]
	v_mfma_f32_16x16x32_bf16 v[124:127], v[106:109], v[204:207], v[124:127]
	v_mfma_f32_16x16x32_bf16 v[120:123], v[168:171], v[204:207], v[120:123]
	v_mfma_f32_16x16x32_bf16 v[92:95], v[106:109], v[212:215], v[92:95]
	v_mfma_f32_16x16x32_bf16 v[88:91], v[168:171], v[212:215], v[88:91]
	v_mfma_f32_16x16x32_bf16 v[76:79], v[106:109], v[220:223], v[76:79]
	v_mfma_f32_16x16x32_bf16 v[72:75], v[168:171], v[220:223], v[72:75]
	v_mfma_f32_16x16x32_bf16 v[140:143], v[154:157], v[200:203], v[140:143]
	v_mfma_f32_16x16x32_bf16 v[136:139], v[172:175], v[200:203], v[136:139]
	v_mfma_f32_16x16x32_bf16 v[124:127], v[154:157], v[208:211], v[124:127]
	v_mfma_f32_16x16x32_bf16 v[120:123], v[172:175], v[208:211], v[120:123]
	v_mfma_f32_16x16x32_bf16 v[92:95], v[154:157], v[216:219], v[92:95]
	v_mfma_f32_16x16x32_bf16 v[88:91], v[172:175], v[216:219], v[88:91]
	v_mfma_f32_16x16x32_bf16 v[76:79], v[154:157], v[224:227], v[76:79]
	v_mfma_f32_16x16x32_bf16 v[72:75], v[172:175], v[224:227], v[72:75]
	s_setprio 0
	s_setprio 1
	v_mfma_f32_16x16x32_bf16 v[132:135], v[176:179], v[196:199], v[132:135]
	v_mfma_f32_16x16x32_bf16 v[128:131], v[184:187], v[196:199], v[128:131]
	v_mfma_f32_16x16x32_bf16 v[116:119], v[176:179], v[204:207], v[116:119]
	v_mfma_f32_16x16x32_bf16 v[110:113], v[184:187], v[204:207], v[112:115]
	v_mfma_f32_16x16x32_bf16 v[84:87], v[176:179], v[212:215], v[84:87]
	v_mfma_f32_16x16x32_bf16 v[80:83], v[184:187], v[212:215], v[80:83]
	v_mfma_f32_16x16x32_bf16 v[68:71], v[176:179], v[220:223], v[68:71]
	v_mfma_f32_16x16x32_bf16 v[64:67], v[184:187], v[220:223], v[64:67]
	v_mfma_f32_16x16x32_bf16 v[132:135], v[180:183], v[200:203], v[132:135]
	v_mfma_f32_16x16x32_bf16 v[128:131], v[188:191], v[200:203], v[128:131]
	v_mfma_f32_16x16x32_bf16 v[116:119], v[180:183], v[208:211], v[116:119]
	v_mfma_f32_16x16x32_bf16 v[110:113], v[188:191], v[208:211], v[110:113]
	v_mfma_f32_16x16x32_bf16 v[84:87], v[180:183], v[216:219], v[84:87]
	v_mfma_f32_16x16x32_bf16 v[80:83], v[188:191], v[216:219], v[80:83]
	v_mfma_f32_16x16x32_bf16 v[68:71], v[180:183], v[224:227], v[68:71]
	v_mfma_f32_16x16x32_bf16 v[64:67], v[188:191], v[224:227], v[64:67]
	s_setprio 0
	s_barrier
	s_mov_b32 m0, s48
	v_lshl_add_u64 v[158:159], s[20:21], 0, v[146:147]
	s_add_u32 s56, s20, 0xb0000
	ds_read_b128 v[196:199], v102 offset:16384
	ds_read_b128 v[200:203], v102 offset:17408
	ds_read_b128 v[204:207], v102 offset:18432
	ds_read_b128 v[208:211], v102 offset:19456
	ds_read_b128 v[212:215], v102 offset:20480
	ds_read_b128 v[216:219], v102 offset:21504
	ds_read_b128 v[220:223], v102 offset:22528
	ds_read_b128 v[224:227], v102 offset:23552
	global_load_lds_dwordx4 v[158:159], off
	v_lshl_add_u64 v[228:229], s[20:21], 0, v[150:151]
	s_mov_b32 m0, s49
	s_addc_u32 s57, s21, 0
	global_load_lds_dwordx4 v[228:229], off
	s_mov_b32 m0, s50
	v_lshl_add_u64 v[230:231], s[22:23], 0, v[144:145]
	global_load_lds_dwordx4 v146, s[56:57]
	s_mov_b32 m0, s51
	v_lshl_add_u64 v[232:233], s[22:23], 0, v[148:149]
	global_load_lds_dwordx4 v150, s[56:57]
	s_mov_b32 m0, s3
	s_nop 0
	global_load_lds_dwordx4 v[230:231], off
	s_mov_b32 m0, s40
	s_nop 0
	global_load_lds_dwordx4 v[232:233], off
	s_waitcnt vmcnt(8)
	s_waitcnt lgkmcnt(0)
	s_barrier
; #define PG8_STAGE(bufoff, gbase, voff) do { _Pragma("unroll") for (int _i = 0; _i < 2; ++_i) \
;         __builtin_amdgcn_global_load_lds((const unsigned*)((const char*)(gbase) + (voff)[_i]), (PG8_LAS unsigned*)(lds + (bufoff) + ldsw + _i * 8192), 16, 0, 0); } while (0)
; #define PG8_LDA(dst, b, h) do { _Pragma("unroll") for (int m = 0; m < 4; ++m) _Pragma("unroll") for (int k = 0; k < 2; ++k) dst[m][k] = *(const PG8_LAS bf16x8*)(lds + PG8_SA(b, h) + aoff + m * 2048 + k * 1024); } while (0)
; #define PG8_LDB(dst, b, h) do { _Pragma("unroll") for (int n = 0; n < 2; ++n) _Pragma("unroll") for (int k = 0; k < 2; ++k) dst[n][k] = *(const PG8_LAS bf16x8*)(lds + PG8_SB(b, h) + boff + n * 2048 + k * 1024); } while (0)
; #define PG8_MMA(ai, bj, At, Bt) do { __builtin_amdgcn_s_setprio(1); _Pragma("unroll") for (int m = 0; m < 4; ++m) _Pragma("unroll") for (int n = 0; n < 2; ++n) _Pragma("unroll") for (int k = 0; k < 2; ++k) \
;         acc[ai][bj][m][n] = __builtin_amdgcn_mfma_f32_16x16x32_bf16(Bt[n][k], At[m][k], acc[ai][bj][m][n], 0, 0, 0); __builtin_amdgcn_s_setprio(0); } while (0)
; #define PG8_WAIT_V(n) asm volatile("s_waitcnt vmcnt(" #n ")" ::: "memory")
; #define PG8_WAIT_L(n) asm volatile("s_waitcnt lgkmcnt(" #n ")" ::: "memory")
; #define PG8_BAR __builtin_amdgcn_s_barrier()
; #define PG8_SCHED __builtin_amdgcn_sched_barrier(0)
; template <class Epi, class Sched, bool ALIGN_EPI = false, bool SP2 = false>
; __device__ __forceinline__ void gemm_phase(PG8_LAS unsigned char* lds, const Gemm g, const Sched& S, const Epi& E) {
;     ...
;             PG8_WAIT_V(8); PG8_WAIT_L(0); PG8_BAR; PG8_MMA(1, 0, At, B0); PG8_MMA(1, 1, At, B1); PG8_BAR; PG8_SCHED;
;             PG8_LDB(B0, 1, 0); PG8_LDB(B1, 1, 1); PG8_SCHED; PG8_LDA(At, 1, 0); PG8_STAGE(PG8_SA(0, 1), a2 + hstepA, voffA);
;             PG8_WAIT_V(8); PG8_WAIT_L(0); PG8_BAR; PG8_MMA(0, 0, At, B0); PG8_MMA(0, 1, At, B1); PG8_BAR; PG8_SCHED;
	s_setprio 1
	s_waitcnt lgkmcnt(0)
	v_mfma_f32_16x16x32_bf16 v[60:63], v[106:109], v[196:199], v[60:63]
	v_mfma_f32_16x16x32_bf16 v[56:59], v[168:171], v[196:199], v[56:59]
	v_mfma_f32_16x16x32_bf16 v[44:47], v[106:109], v[204:207], v[44:47]
	v_mfma_f32_16x16x32_bf16 v[40:43], v[168:171], v[204:207], v[40:43]
	v_mfma_f32_16x16x32_bf16 v[28:31], v[106:109], v[212:215], v[28:31]
	v_mfma_f32_16x16x32_bf16 v[24:27], v[168:171], v[212:215], v[24:27]
	v_mfma_f32_16x16x32_bf16 v[12:15], v[106:109], v[220:223], v[12:15]
	v_mfma_f32_16x16x32_bf16 v[8:11], v[168:171], v[220:223], v[8:11]
	v_mfma_f32_16x16x32_bf16 v[60:63], v[154:157], v[200:203], v[60:63]
	v_mfma_f32_16x16x32_bf16 v[56:59], v[172:175], v[200:203], v[56:59]
	v_mfma_f32_16x16x32_bf16 v[44:47], v[154:157], v[208:211], v[44:47]
	v_mfma_f32_16x16x32_bf16 v[40:43], v[172:175], v[208:211], v[40:43]
	v_mfma_f32_16x16x32_bf16 v[28:31], v[154:157], v[216:219], v[28:31]
	v_mfma_f32_16x16x32_bf16 v[24:27], v[172:175], v[216:219], v[24:27]
	v_mfma_f32_16x16x32_bf16 v[12:15], v[154:157], v[224:227], v[12:15]
	v_mfma_f32_16x16x32_bf16 v[8:11], v[172:175], v[224:227], v[8:11]
	s_setprio 0
	s_setprio 1
	v_mfma_f32_16x16x32_bf16 v[52:55], v[176:179], v[196:199], v[52:55]
	v_mfma_f32_16x16x32_bf16 v[48:51], v[184:187], v[196:199], v[48:51]
	v_mfma_f32_16x16x32_bf16 v[36:39], v[176:179], v[204:207], v[36:39]
	v_mfma_f32_16x16x32_bf16 v[32:35], v[184:187], v[204:207], v[32:35]
	v_mfma_f32_16x16x32_bf16 v[20:23], v[176:179], v[212:215], v[20:23]
	v_mfma_f32_16x16x32_bf16 v[16:19], v[184:187], v[212:215], v[16:19]
	v_mfma_f32_16x16x32_bf16 v[4:7], v[176:179], v[220:223], v[4:7]
	v_mfma_f32_16x16x32_bf16 v[0:3], v[184:187], v[220:223], v[0:3]
	v_mfma_f32_16x16x32_bf16 v[52:55], v[180:183], v[200:203], v[52:55]
	v_mfma_f32_16x16x32_bf16 v[48:51], v[188:191], v[200:203], v[48:51]
	v_mfma_f32_16x16x32_bf16 v[36:39], v[180:183], v[208:211], v[36:39]
	v_mfma_f32_16x16x32_bf16 v[32:35], v[188:191], v[208:211], v[32:35]
	v_mfma_f32_16x16x32_bf16 v[20:23], v[180:183], v[216:219], v[20:23]
	v_mfma_f32_16x16x32_bf16 v[16:19], v[188:191], v[216:219], v[16:19]
	v_mfma_f32_16x16x32_bf16 v[4:7], v[180:183], v[224:227], v[4:7]
	v_mfma_f32_16x16x32_bf16 v[0:3], v[188:191], v[224:227], v[0:3]
	s_setprio 0
	s_barrier
	ds_read_b128 v[106:109], v103
	ds_read_b128 v[154:157], v103 offset:1024
	ds_read_b128 v[168:171], v103 offset:2048
	ds_read_b128 v[172:175], v103 offset:3072
	ds_read_b128 v[176:179], v104
	ds_read_b128 v[180:183], v104 offset:1024
	ds_read_b128 v[184:187], v104 offset:2048
	ds_read_b128 v[188:191], v104 offset:3072
	s_add_u32 s22, s22, 0xb4000
	s_addc_u32 s23, s23, 0
	s_mov_b32 m0, s41
	v_lshl_add_u64 v[114:115], s[22:23], 0, v[144:145]
	ds_read_b128 v[196:199], v102 offset:32768
	ds_read_b128 v[200:203], v102 offset:33792
	ds_read_b128 v[204:207], v102 offset:34816
	ds_read_b128 v[208:211], v102 offset:35840
	ds_read_b128 v[212:215], v102 offset:36864
	ds_read_b128 v[216:219], v102 offset:37888
	ds_read_b128 v[220:223], v102 offset:38912
	ds_read_b128 v[224:227], v102 offset:39936
	global_load_lds_dwordx4 v[114:115], off
	v_lshl_add_u64 v[114:115], s[22:23], 0, v[148:149]
	s_mov_b32 m0, s42
	s_nop 0
	global_load_lds_dwordx4 v[114:115], off
	s_waitcnt vmcnt(8)
	s_waitcnt lgkmcnt(0)
	s_barrier
	s_setprio 1
	s_waitcnt lgkmcnt(0)
	v_mfma_f32_16x16x32_bf16 v[140:143], v[106:109], v[196:199], v[140:143]
	v_mfma_f32_16x16x32_bf16 v[136:139], v[168:171], v[196:199], v[136:139]
	v_mfma_f32_16x16x32_bf16 v[124:127], v[106:109], v[204:207], v[124:127]
	v_mfma_f32_16x16x32_bf16 v[120:123], v[168:171], v[204:207], v[120:123]
	v_mfma_f32_16x16x32_bf16 v[92:95], v[106:109], v[212:215], v[92:95]
	v_mfma_f32_16x16x32_bf16 v[88:91], v[168:171], v[212:215], v[88:91]
	v_mfma_f32_16x16x32_bf16 v[76:79], v[106:109], v[220:223], v[76:79]
	v_mfma_f32_16x16x32_bf16 v[72:75], v[168:171], v[220:223], v[72:75]
	v_mfma_f32_16x16x32_bf16 v[140:143], v[154:157], v[200:203], v[140:143]
	v_mfma_f32_16x16x32_bf16 v[136:139], v[172:175], v[200:203], v[136:139]
	v_mfma_f32_16x16x32_bf16 v[124:127], v[154:157], v[208:211], v[124:127]
	v_mfma_f32_16x16x32_bf16 v[120:123], v[172:175], v[208:211], v[120:123]
	v_mfma_f32_16x16x32_bf16 v[92:95], v[154:157], v[216:219], v[92:95]
	v_mfma_f32_16x16x32_bf16 v[88:91], v[172:175], v[216:219], v[88:91]
	v_mfma_f32_16x16x32_bf16 v[76:79], v[154:157], v[224:227], v[76:79]
	v_mfma_f32_16x16x32_bf16 v[72:75], v[172:175], v[224:227], v[72:75]
	s_setprio 0
	s_setprio 1
	v_mfma_f32_16x16x32_bf16 v[132:135], v[176:179], v[196:199], v[132:135]
	v_mfma_f32_16x16x32_bf16 v[128:131], v[184:187], v[196:199], v[128:131]
	v_mfma_f32_16x16x32_bf16 v[114:117], v[176:179], v[204:207], v[116:119]
	v_mfma_f32_16x16x32_bf16 v[110:113], v[184:187], v[204:207], v[110:113]
	v_mfma_f32_16x16x32_bf16 v[84:87], v[176:179], v[212:215], v[84:87]
	v_mfma_f32_16x16x32_bf16 v[80:83], v[184:187], v[212:215], v[80:83]
	v_mfma_f32_16x16x32_bf16 v[68:71], v[176:179], v[220:223], v[68:71]
	v_mfma_f32_16x16x32_bf16 v[64:67], v[184:187], v[220:223], v[64:67]
	v_mfma_f32_16x16x32_bf16 v[132:135], v[180:183], v[200:203], v[132:135]
	v_mfma_f32_16x16x32_bf16 v[128:131], v[188:191], v[200:203], v[128:131]
	v_mfma_f32_16x16x32_bf16 v[116:119], v[180:183], v[208:211], v[114:117]
	v_mfma_f32_16x16x32_bf16 v[112:115], v[188:191], v[208:211], v[110:113]
	v_mfma_f32_16x16x32_bf16 v[84:87], v[180:183], v[216:219], v[84:87]
	v_mfma_f32_16x16x32_bf16 v[80:83], v[188:191], v[216:219], v[80:83]
	v_mfma_f32_16x16x32_bf16 v[68:71], v[180:183], v[224:227], v[68:71]
	v_mfma_f32_16x16x32_bf16 v[64:67], v[188:191], v[224:227], v[64:67]
	s_setprio 0
	s_barrier
; #define PG8_STAGE(bufoff, gbase, voff) do { _Pragma("unroll") for (int _i = 0; _i < 2; ++_i) \
;         __builtin_amdgcn_global_load_lds((const unsigned*)((const char*)(gbase) + (voff)[_i]), (PG8_LAS unsigned*)(lds + (bufoff) + ldsw + _i * 8192), 16, 0, 0); } while (0)
; #define PG8_LDA(dst, b, h) do { _Pragma("unroll") for (int m = 0; m < 4; ++m) _Pragma("unroll") for (int k = 0; k < 2; ++k) dst[m][k] = *(const PG8_LAS bf16x8*)(lds + PG8_SA(b, h) + aoff + m * 2048 + k * 1024); } while (0)
; #define PG8_MMA(ai, bj, At, Bt) do { __builtin_amdgcn_s_setprio(1); _Pragma("unroll") for (int m = 0; m < 4; ++m) _Pragma("unroll") for (int n = 0; n < 2; ++n) _Pragma("unroll") for (int k = 0; k < 2; ++k) \
;         acc[ai][bj][m][n] = __builtin_amdgcn_mfma_f32_16x16x32_bf16(Bt[n][k], At[m][k], acc[ai][bj][m][n], 0, 0, 0); __builtin_amdgcn_s_setprio(0); } while (0)
; #define PG8_WAIT_V(n) asm volatile("s_waitcnt vmcnt(" #n ")" ::: "memory")
; #define PG8_WAIT_L(n) asm volatile("s_waitcnt lgkmcnt(" #n ")" ::: "memory")
; #define PG8_BAR __builtin_amdgcn_s_barrier()
; #define PG8_SCHED __builtin_amdgcn_sched_barrier(0)
; template <class Epi, class Sched, bool ALIGN_EPI = false, bool SP2 = false>
; __device__ __forceinline__ void gemm_phase(PG8_LAS unsigned char* lds, const Gemm g, const Sched& S, const Epi& E) {
;     ...
;             PG8_LDA(At, 1, 1); PG8_STAGE(PG8_SB(1, 0), b3, voffB); PG8_STAGE(PG8_SB(1, 1), b3 + hstepB, voffB); PG8_STAGE(PG8_SA(1, 0), a3, voffA);
;             PG8_WAIT_V(8); PG8_WAIT_L(0); PG8_BAR; PG8_MMA(1, 0, At, B0); PG8_MMA(1, 1, At, B1); PG8_BAR; PG8_SCHED;
;     ...
;     PG8_WAIT_V(0);
;     if constexpr (!ALIGN_EPI) { if (wr == 0) PG8_BAR; }
;     PG8_BAR;
	s_mov_b32 m0, s52
	v_lshl_add_u64 v[110:111], v[158:159], 0, s[6:7]
	s_add_u32 s20, s20, 0xb0080
	ds_read_b128 v[196:199], v102 offset:49152
	ds_read_b128 v[200:203], v102 offset:50176
	ds_read_b128 v[204:207], v102 offset:51200
	ds_read_b128 v[208:211], v102 offset:52224
	ds_read_b128 v[212:215], v102 offset:53248
	ds_read_b128 v[216:219], v102 offset:54272
	ds_read_b128 v[220:223], v102 offset:55296
	ds_read_b128 v[224:227], v102 offset:56320
	global_load_lds_dwordx4 v[110:111], off
	v_lshl_add_u64 v[110:111], v[228:229], 0, s[6:7]
	s_mov_b32 m0, s53
	s_addc_u32 s21, s21, 0
	global_load_lds_dwordx4 v[110:111], off
	s_mov_b32 m0, s54
	s_nop 0
	global_load_lds_dwordx4 v146, s[20:21]
	s_mov_b32 m0, s55
	s_nop 0
	global_load_lds_dwordx4 v150, s[20:21]
	v_lshl_add_u64 v[110:111], v[230:231], 0, s[6:7]
	s_mov_b32 m0, s43
	s_nop 0
	global_load_lds_dwordx4 v[110:111], off
	v_lshl_add_u64 v[110:111], v[232:233], 0, s[6:7]
	s_mov_b32 m0, s44
	s_nop 0
	global_load_lds_dwordx4 v[110:111], off
	s_waitcnt vmcnt(8)
	s_waitcnt lgkmcnt(0)
	s_barrier
	s_setprio 1
	s_waitcnt lgkmcnt(0)
	v_mfma_f32_16x16x32_bf16 v[60:63], v[106:109], v[196:199], v[60:63]
	v_mfma_f32_16x16x32_bf16 v[56:59], v[168:171], v[196:199], v[56:59]
	v_mfma_f32_16x16x32_bf16 v[44:47], v[106:109], v[204:207], v[44:47]
	v_mfma_f32_16x16x32_bf16 v[40:43], v[168:171], v[204:207], v[40:43]
	v_mfma_f32_16x16x32_bf16 v[28:31], v[106:109], v[212:215], v[28:31]
	v_mfma_f32_16x16x32_bf16 v[24:27], v[168:171], v[212:215], v[24:27]
	v_mfma_f32_16x16x32_bf16 v[12:15], v[106:109], v[220:223], v[12:15]
	v_mfma_f32_16x16x32_bf16 v[8:11], v[168:171], v[220:223], v[8:11]
	v_mfma_f32_16x16x32_bf16 v[60:63], v[154:157], v[200:203], v[60:63]
	v_mfma_f32_16x16x32_bf16 v[56:59], v[172:175], v[200:203], v[56:59]
	v_mfma_f32_16x16x32_bf16 v[44:47], v[154:157], v[208:211], v[44:47]
	v_mfma_f32_16x16x32_bf16 v[40:43], v[172:175], v[208:211], v[40:43]
	v_mfma_f32_16x16x32_bf16 v[28:31], v[154:157], v[216:219], v[28:31]
	v_mfma_f32_16x16x32_bf16 v[24:27], v[172:175], v[216:219], v[24:27]
	v_mfma_f32_16x16x32_bf16 v[12:15], v[154:157], v[224:227], v[12:15]
	v_mfma_f32_16x16x32_bf16 v[8:11], v[172:175], v[224:227], v[8:11]
	s_setprio 0
	s_setprio 1
	v_mfma_f32_16x16x32_bf16 v[52:55], v[176:179], v[196:199], v[52:55]
	v_mfma_f32_16x16x32_bf16 v[48:51], v[184:187], v[196:199], v[48:51]
	v_mfma_f32_16x16x32_bf16 v[36:39], v[176:179], v[204:207], v[36:39]
	v_mfma_f32_16x16x32_bf16 v[32:35], v[184:187], v[204:207], v[32:35]
	v_mfma_f32_16x16x32_bf16 v[20:23], v[176:179], v[212:215], v[20:23]
	v_mfma_f32_16x16x32_bf16 v[16:19], v[184:187], v[212:215], v[16:19]
	v_mfma_f32_16x16x32_bf16 v[4:7], v[176:179], v[220:223], v[4:7]
	v_mfma_f32_16x16x32_bf16 v[0:3], v[184:187], v[220:223], v[0:3]
	v_mfma_f32_16x16x32_bf16 v[52:55], v[180:183], v[200:203], v[52:55]
	v_mfma_f32_16x16x32_bf16 v[48:51], v[188:191], v[200:203], v[48:51]
	v_mfma_f32_16x16x32_bf16 v[36:39], v[180:183], v[208:211], v[36:39]
	v_mfma_f32_16x16x32_bf16 v[32:35], v[188:191], v[208:211], v[32:35]
	v_mfma_f32_16x16x32_bf16 v[20:23], v[180:183], v[216:219], v[20:23]
	v_mfma_f32_16x16x32_bf16 v[16:19], v[188:191], v[216:219], v[16:19]
	v_mfma_f32_16x16x32_bf16 v[4:7], v[180:183], v[224:227], v[4:7]
	v_mfma_f32_16x16x32_bf16 v[0:3], v[188:191], v[224:227], v[0:3]
	s_setprio 0
	s_barrier
	s_add_i32 s45, s45, 2
	s_add_u32 s18, s18, 0x100
	s_addc_u32 s19, s19, 0
	s_cmp_lt_u32 s45, 42
	s_cbranch_scc1 .LBB0_1121
	s_waitcnt vmcnt(0)
	s_cmpk_gt_u32 s36, 0xff
	s_cbranch_scc1 .LBB0_1124
	s_barrier

; #define PG8_STAGE(bufoff, gbase, voff) do { _Pragma("unroll") for (int _i = 0; _i < 2; ++_i) \
;         __builtin_amdgcn_global_load_lds((const unsigned*)((const char*)(gbase) + (voff)[_i]), (PG8_LAS unsigned*)(lds + (bufoff) + ldsw + _i * 8192), 16, 0, 0); } while (0)
; #define PG8_WAIT_V(n) asm volatile("s_waitcnt vmcnt(" #n ")" ::: "memory")
; #define PG8_BAR __builtin_amdgcn_s_barrier()
; template <class Epi, class Sched, bool ALIGN_EPI = false, bool SP2 = false>
; __device__ __forceinline__ void gemm_phase(PG8_LAS unsigned char* lds, const Gemm g, const Sched& S, const Epi& E) {
;     ...
; #pragma unroll
;     for (int a = 0; a < 2; ++a)
; #pragma unroll
;         for (int b = 0; b < 2; ++b)
; #pragma unroll
;             for (int m = 0; m < 4; ++m)
; #pragma unroll
;                 for (int n = 0; n < 2; ++n) acc[a][b][m][n] = (f32x4){0.f, 0.f, 0.f, 0.f};
;     bf16x8 At[4][2], B0[2][2], B1[2][2];
;     const char* cA = PG8_UA(cur); const char* cB = PG8_UB(cur);
;     S.a_ready(cur);
;     if constexpr (SP2) {
;         PG8_STAGE(PG8_SB(0, 0), cB, voffB); PG8_STAGE(PG8_SB(0, 1), cB + hstepB, voffB); PG8_STAGE(PG8_SA(0, 0), cA, voffA); PG8_STAGE(PG8_SA(0, 1), cA + hstepA, voffA);
;         if (wr == 1) PG8_BAR;
;         PG8_WAIT_V(2); PG8_BAR;
;         PG8_STAGE(PG8_SB(1, 0), cB + kstep, voffB); PG8_STAGE(PG8_SA(1, 0), cA + kstep, voffA); PG8_STAGE(PG8_SB(1, 1), cB + hstepB + kstep, voffB);
;         PG8_WAIT_V(6); PG8_BAR;
.LBB0_1175:
	v_lshlrev_b32_e32 v9, 2, v161
	s_and_b32 s28, s6, 3
	v_lshl_or_b32 v8, v161, 6, v166
	s_lshl_b32 s6, s3, 13
	v_and_b32_e32 v9, 32, v9
	v_bitop3_b32 v8, v8, s6, v9 bitop3:0xde
	s_mov_b64 s[6:7], 0x80
	s_add_i32 m0, s30, 0x18000
	v_lshl_add_u64 v[6:7], v[6:7], 0, s[6:7]
	s_waitcnt vmcnt(2)
	s_barrier
	global_load_lds_dwordx4 v[6:7], off
	v_lshl_add_u64 v[4:5], v[4:5], 0, s[6:7]
	s_add_i32 m0, s30, 0x1a000
	s_add_i32 s37, s30, 0x8000
	s_add_i32 s40, s30, 0xa000
	global_load_lds_dwordx4 v[4:5], off
	v_lshl_add_u64 v[2:3], v[2:3], 0, s[6:7]
	s_mov_b32 m0, s37
	s_add_u32 s22, s0, 0xb0080
	global_load_lds_dwordx4 v[2:3], off
	v_lshl_add_u64 v[0:1], v[0:1], 0, s[6:7]
	s_mov_b32 m0, s40
	s_addc_u32 s23, s1, 0
	global_load_lds_dwordx4 v[0:1], off
	s_add_i32 m0, s30, 0x1c000
	global_load_lds_dwordx4 v146, s[22:23]
	v_lshl_add_u64 v[0:1], s[22:23], 0, v[150:151]
	s_add_i32 m0, s30, 0x1e000
	s_add_u32 s22, s34, s19
	global_load_lds_dwordx4 v[0:1], off
	v_add_u16_e32 v0, v162, v163
	v_lshrrev_b16_e32 v2, 1, v0
	v_lshl_or_b32 v9, s28, 12, v167
	s_waitcnt vmcnt(6)
	v_add_lshl_u32 v0, v164, v2, 1
	v_mov_b32_e32 v1, v147
	s_addc_u32 s23, s35, s18
	s_add_i32 s44, 0, 0x10000
	s_add_i32 s46, 0, 0x14000
	s_add_i32 s48, 0, 0x18000
	s_add_i32 s50, 0, 0x1c000
	v_lshl_add_u64 v[96:97], s[22:23], 0, v[0:1]
	v_add_lshl_u32 v0, v165, v2, 1
	v_add_u32_e32 v100, s44, v9
	v_add_u32_e32 v101, s46, v9
	s_add_i32 s44, s44, s20
	s_add_i32 s46, s46, s20
	v_add_u32_e32 v103, s48, v9
	v_add_u32_e32 v104, s50, v9
	s_add_i32 s48, s48, s20
	s_add_i32 s50, s50, s20
	v_lshl_or_b32 v152, s3, 6, v161
	v_lshl_add_u64 v[98:99], s[22:23], 0, v[0:1]
	s_mov_b32 s41, -2
	s_mov_b64 s[18:19], 0x78b4080
	v_add_u32_e32 v102, 0, v8
	s_add_i32 s42, s30, 0xc000
	s_add_i32 s43, s30, 0xe000
	s_add_i32 s45, s44, 0x2000
	s_add_i32 s47, s46, 0x2000
	s_add_i32 s49, s48, 0x2000
	s_add_i32 s51, s50, 0x2000
	v_mov_b32_e32 v0, v147
	v_mov_b32_e32 v2, v147
	v_mov_b32_e32 v3, v147
	v_mov_b32_e32 v4, v147
	v_mov_b32_e32 v5, v147
	v_mov_b32_e32 v6, v147
	v_mov_b32_e32 v7, v147
	v_mov_b32_e32 v16, v147
	v_mov_b32_e32 v17, v147
	v_mov_b32_e32 v18, v147
	v_mov_b32_e32 v19, v147
	v_mov_b32_e32 v20, v147
	v_mov_b32_e32 v21, v147
	v_mov_b32_e32 v22, v147
	v_mov_b32_e32 v23, v147
	v_mov_b32_e32 v32, v147
	v_mov_b32_e32 v33, v147
	v_mov_b32_e32 v34, v147
	v_mov_b32_e32 v35, v147
	v_mov_b32_e32 v36, v147
	v_mov_b32_e32 v37, v147
	v_mov_b32_e32 v38, v147
	v_mov_b32_e32 v39, v147
	v_mov_b32_e32 v48, v147
	v_mov_b32_e32 v49, v147
	v_mov_b32_e32 v50, v147
	v_mov_b32_e32 v51, v147
	v_mov_b32_e32 v52, v147
	v_mov_b32_e32 v53, v147
	v_mov_b32_e32 v54, v147
	v_mov_b32_e32 v55, v147
	v_mov_b32_e32 v8, v147
	v_mov_b32_e32 v9, v147
	v_mov_b32_e32 v10, v147
	v_mov_b32_e32 v11, v147
	v_mov_b32_e32 v12, v147
	v_mov_b32_e32 v13, v147
	v_mov_b32_e32 v14, v147
	v_mov_b32_e32 v15, v147
	v_mov_b32_e32 v24, v147
	v_mov_b32_e32 v25, v147
	v_mov_b32_e32 v26, v147
	v_mov_b32_e32 v27, v147
	v_mov_b32_e32 v28, v147
	v_mov_b32_e32 v29, v147
	v_mov_b32_e32 v30, v147
	v_mov_b32_e32 v31, v147
	v_mov_b32_e32 v40, v147
	v_mov_b32_e32 v41, v147
	v_mov_b32_e32 v42, v147
	v_mov_b32_e32 v43, v147
	v_mov_b32_e32 v44, v147
	v_mov_b32_e32 v45, v147
	v_mov_b32_e32 v46, v147
	v_mov_b32_e32 v47, v147
	v_mov_b32_e32 v56, v147
	v_mov_b32_e32 v57, v147
	v_mov_b32_e32 v58, v147
	v_mov_b32_e32 v59, v147
	v_mov_b32_e32 v60, v147
	v_mov_b32_e32 v61, v147
	v_mov_b32_e32 v62, v147
	v_mov_b32_e32 v63, v147
	v_mov_b32_e32 v64, v147
	v_mov_b32_e32 v65, v147
	v_mov_b32_e32 v66, v147
	v_mov_b32_e32 v67, v147
	v_mov_b32_e32 v68, v147
	v_mov_b32_e32 v69, v147
	v_mov_b32_e32 v70, v147
	v_mov_b32_e32 v71, v147
	v_mov_b32_e32 v80, v147
	v_mov_b32_e32 v81, v147
	v_mov_b32_e32 v82, v147
	v_mov_b32_e32 v83, v147
	v_mov_b32_e32 v84, v147
	v_mov_b32_e32 v85, v147
	v_mov_b32_e32 v86, v147
	v_mov_b32_e32 v87, v147
	v_mov_b32_e32 v112, v147
	v_mov_b32_e32 v113, v147
	v_mov_b32_e32 v114, v147
	v_mov_b32_e32 v115, v147
	v_mov_b32_e32 v116, v147
	v_mov_b32_e32 v117, v147
	v_mov_b32_e32 v118, v147
	v_mov_b32_e32 v119, v147
	v_mov_b32_e32 v128, v147
	v_mov_b32_e32 v129, v147
	v_mov_b32_e32 v130, v147
	v_mov_b32_e32 v131, v147
	v_mov_b32_e32 v132, v147
	v_mov_b32_e32 v133, v147
	v_mov_b32_e32 v134, v147
	v_mov_b32_e32 v135, v147
	v_mov_b32_e32 v72, v147
	v_mov_b32_e32 v73, v147
	v_mov_b32_e32 v74, v147
	v_mov_b32_e32 v75, v147
	v_mov_b32_e32 v76, v147
	v_mov_b32_e32 v77, v147
	v_mov_b32_e32 v78, v147
	v_mov_b32_e32 v79, v147
	v_mov_b32_e32 v88, v147
	v_mov_b32_e32 v89, v147
	v_mov_b32_e32 v90, v147
	v_mov_b32_e32 v91, v147
	v_mov_b32_e32 v92, v147
	v_mov_b32_e32 v93, v147
	v_mov_b32_e32 v94, v147
	v_mov_b32_e32 v95, v147
	v_mov_b32_e32 v120, v147
	v_mov_b32_e32 v121, v147
	v_mov_b32_e32 v122, v147
	v_mov_b32_e32 v123, v147
	v_mov_b32_e32 v124, v147
	v_mov_b32_e32 v125, v147
	v_mov_b32_e32 v126, v147
	v_mov_b32_e32 v127, v147
	v_mov_b32_e32 v136, v147
	v_mov_b32_e32 v137, v147
	v_mov_b32_e32 v138, v147
	v_mov_b32_e32 v139, v147
	v_mov_b32_e32 v140, v147
	v_mov_b32_e32 v141, v147
	v_mov_b32_e32 v142, v147
	v_mov_b32_e32 v143, v147
	s_barrier
; #define PG8_STAGE(bufoff, gbase, voff) do { _Pragma("unroll") for (int _i = 0; _i < 2; ++_i) \
;         __builtin_amdgcn_global_load_lds((const unsigned*)((const char*)(gbase) + (voff)[_i]), (PG8_LAS unsigned*)(lds + (bufoff) + ldsw + _i * 8192), 16, 0, 0); } while (0)
; #define PG8_LDA(dst, b, h) do { _Pragma("unroll") for (int m = 0; m < 4; ++m) _Pragma("unroll") for (int k = 0; k < 2; ++k) dst[m][k] = *(const PG8_LAS bf16x8*)(lds + PG8_SA(b, h) + aoff + m * 2048 + k * 1024); } while (0)
; #define PG8_LDB(dst, b, h) do { _Pragma("unroll") for (int n = 0; n < 2; ++n) _Pragma("unroll") for (int k = 0; k < 2; ++k) dst[n][k] = *(const PG8_LAS bf16x8*)(lds + PG8_SB(b, h) + boff + n * 2048 + k * 1024); } while (0)
; #define PG8_MMA(ai, bj, At, Bt) do { __builtin_amdgcn_s_setprio(1); _Pragma("unroll") for (int m = 0; m < 4; ++m) _Pragma("unroll") for (int n = 0; n < 2; ++n) _Pragma("unroll") for (int k = 0; k < 2; ++k) \
;         acc[ai][bj][m][n] = __builtin_amdgcn_mfma_f32_16x16x32_bf16(Bt[n][k], At[m][k], acc[ai][bj][m][n], 0, 0, 0); __builtin_amdgcn_s_setprio(0); } while (0)
; #define PG8_WAIT_V(n) asm volatile("s_waitcnt vmcnt(" #n ")" ::: "memory")
; #define PG8_WAIT_L(n) asm volatile("s_waitcnt lgkmcnt(" #n ")" ::: "memory")
; template <class Epi, class Sched, bool ALIGN_EPI = false, bool SP2 = false>
; __device__ __forceinline__ void gemm_phase(PG8_LAS unsigned char* lds, const Gemm g, const Sched& S, const Epi& E) {
;     ...
;         const char* nA = has_next ? PG8_UA(nxt) : cA; const char* nB = has_next ? PG8_UB(nxt) : cB;
;         for (int t = 0; t < nt; t += 2) {
;             const bool last = (t == nt - 2);
;             const char* a1 = cA + (size_t)(t + 1) * kstep;
;             const char* a2 = last ? nA : cA + (size_t)(t + 2) * kstep; const char* b2 = last ? nB : cB + (size_t)(t + 2) * kstep;
;             const char* a3 = a2 + kstep; const char* b3 = b2 + kstep;
;             if (last && has_next) S.a_ready(nxt);
;             if constexpr (SP2) {
;             PG8_LDB(B0, 0, 0); PG8_LDB(B1, 0, 1); PG8_SCHED; PG8_LDA(At, 0, 0); PG8_STAGE(PG8_SA(1, 1), a1 + hstepA, voffA);
;             PG8_WAIT_V(8); PG8_WAIT_L(0); PG8_BAR; PG8_MMA(0, 0, At, B0); PG8_MMA(0, 1, At, B1); PG8_BAR; PG8_SCHED;
;             PG8_LDA(At, 0, 1); PG8_STAGE(PG8_SB(0, 0), b2, voffB); PG8_STAGE(PG8_SB(0, 1), b2 + hstepB, voffB); PG8_STAGE(PG8_SA(0, 0), a2, voffA);
.LBB0_1176:
	ds_read_b128 v[106:109], v100
	ds_read_b128 v[154:157], v100 offset:1024
	ds_read_b128 v[162:165], v100 offset:2048
	ds_read_b128 v[166:169], v100 offset:3072
	ds_read_b128 v[170:173], v101
	ds_read_b128 v[174:177], v101 offset:1024
	ds_read_b128 v[178:181], v101 offset:2048
	ds_read_b128 v[182:185], v101 offset:3072
	s_add_u32 s20, s18, 0xf874c080
	s_addc_u32 s21, s19, -1
	s_cmp_lg_u32 s41, 40
	s_cselect_b32 s20, s20, 0
	s_cselect_b32 s21, s21, 0
	s_add_u32 s22, s4, s20
	s_addc_u32 s23, s5, s21
	s_add_u32 s20, s0, s20
	s_addc_u32 s21, s1, s21
	s_mov_b32 m0, s42
	v_lshl_add_u64 v[110:111], v[96:97], 0, s[18:19]
	ds_read_b128 v[186:189], v102
	ds_read_b128 v[196:199], v102 offset:1024
	ds_read_b128 v[200:203], v102 offset:2048
	ds_read_b128 v[204:207], v102 offset:3072
	ds_read_b128 v[208:211], v102 offset:4096
	ds_read_b128 v[212:215], v102 offset:5120
	ds_read_b128 v[216:219], v102 offset:6144
	ds_read_b128 v[220:223], v102 offset:7168
	global_load_lds_dwordx4 v[110:111], off
	v_lshl_add_u64 v[110:111], v[98:99], 0, s[18:19]
	s_mov_b32 m0, s43
	s_nop 0
	global_load_lds_dwordx4 v[110:111], off
	s_waitcnt vmcnt(8)
	s_waitcnt lgkmcnt(0)
	s_barrier
	s_setprio 1
	s_waitcnt lgkmcnt(0)
	v_mfma_f32_16x16x32_bf16 v[140:143], v[106:109], v[186:189], v[140:143]
	v_mfma_f32_16x16x32_bf16 v[136:139], v[162:165], v[186:189], v[136:139]
	v_mfma_f32_16x16x32_bf16 v[124:127], v[106:109], v[200:203], v[124:127]
	v_mfma_f32_16x16x32_bf16 v[120:123], v[162:165], v[200:203], v[120:123]
	v_mfma_f32_16x16x32_bf16 v[92:95], v[106:109], v[208:211], v[92:95]
	v_mfma_f32_16x16x32_bf16 v[88:91], v[162:165], v[208:211], v[88:91]
	v_mfma_f32_16x16x32_bf16 v[76:79], v[106:109], v[216:219], v[76:79]
	v_mfma_f32_16x16x32_bf16 v[72:75], v[162:165], v[216:219], v[72:75]
	v_mfma_f32_16x16x32_bf16 v[140:143], v[154:157], v[196:199], v[140:143]
	v_mfma_f32_16x16x32_bf16 v[136:139], v[166:169], v[196:199], v[136:139]
	v_mfma_f32_16x16x32_bf16 v[124:127], v[154:157], v[204:207], v[124:127]
	v_mfma_f32_16x16x32_bf16 v[120:123], v[166:169], v[204:207], v[120:123]
	v_mfma_f32_16x16x32_bf16 v[92:95], v[154:157], v[212:215], v[92:95]
	v_mfma_f32_16x16x32_bf16 v[88:91], v[166:169], v[212:215], v[88:91]
	v_mfma_f32_16x16x32_bf16 v[76:79], v[154:157], v[220:223], v[76:79]
	v_mfma_f32_16x16x32_bf16 v[72:75], v[166:169], v[220:223], v[72:75]
	s_setprio 0
	s_setprio 1
	v_mfma_f32_16x16x32_bf16 v[132:135], v[170:173], v[186:189], v[132:135]
	v_mfma_f32_16x16x32_bf16 v[128:131], v[178:181], v[186:189], v[128:131]
	v_mfma_f32_16x16x32_bf16 v[116:119], v[170:173], v[200:203], v[116:119]
	v_mfma_f32_16x16x32_bf16 v[110:113], v[178:181], v[200:203], v[112:115]
	v_mfma_f32_16x16x32_bf16 v[84:87], v[170:173], v[208:211], v[84:87]
	v_mfma_f32_16x16x32_bf16 v[80:83], v[178:181], v[208:211], v[80:83]
	v_mfma_f32_16x16x32_bf16 v[68:71], v[170:173], v[216:219], v[68:71]
	v_mfma_f32_16x16x32_bf16 v[64:67], v[178:181], v[216:219], v[64:67]
	v_mfma_f32_16x16x32_bf16 v[132:135], v[174:177], v[196:199], v[132:135]
	v_mfma_f32_16x16x32_bf16 v[128:131], v[182:185], v[196:199], v[128:131]
	v_mfma_f32_16x16x32_bf16 v[116:119], v[174:177], v[204:207], v[116:119]
	v_mfma_f32_16x16x32_bf16 v[110:113], v[182:185], v[204:207], v[110:113]
	v_mfma_f32_16x16x32_bf16 v[84:87], v[174:177], v[212:215], v[84:87]
	v_mfma_f32_16x16x32_bf16 v[80:83], v[182:185], v[212:215], v[80:83]
	v_mfma_f32_16x16x32_bf16 v[68:71], v[174:177], v[220:223], v[68:71]
	v_mfma_f32_16x16x32_bf16 v[64:67], v[182:185], v[220:223], v[64:67]
	s_setprio 0
	s_barrier
	s_mov_b32 m0, s44
	v_lshl_add_u64 v[158:159], s[20:21], 0, v[146:147]
	s_add_u32 s52, s20, 0xb0000
	ds_read_b128 v[186:189], v102 offset:16384
	ds_read_b128 v[196:199], v102 offset:17408
	ds_read_b128 v[200:203], v102 offset:18432
	ds_read_b128 v[204:207], v102 offset:19456
	ds_read_b128 v[208:211], v102 offset:20480
	ds_read_b128 v[212:215], v102 offset:21504
	ds_read_b128 v[216:219], v102 offset:22528
	ds_read_b128 v[220:223], v102 offset:23552
	global_load_lds_dwordx4 v[158:159], off
	v_lshl_add_u64 v[190:191], s[20:21], 0, v[150:151]
	s_mov_b32 m0, s45
	s_addc_u32 s53, s21, 0
	global_load_lds_dwordx4 v[190:191], off
	s_mov_b32 m0, s46
	v_lshl_add_u64 v[224:225], s[22:23], 0, v[144:145]
	global_load_lds_dwordx4 v146, s[52:53]
	s_mov_b32 m0, s47
	v_lshl_add_u64 v[226:227], s[22:23], 0, v[148:149]
	global_load_lds_dwordx4 v150, s[52:53]
	s_mov_b32 m0, s30
	s_nop 0
	global_load_lds_dwordx4 v[224:225], off
	s_mov_b32 m0, s29
	s_nop 0
	global_load_lds_dwordx4 v[226:227], off
	s_waitcnt vmcnt(8)
	s_waitcnt lgkmcnt(0)
	s_barrier
; #define PG8_STAGE(bufoff, gbase, voff) do { _Pragma("unroll") for (int _i = 0; _i < 2; ++_i) \
;         __builtin_amdgcn_global_load_lds((const unsigned*)((const char*)(gbase) + (voff)[_i]), (PG8_LAS unsigned*)(lds + (bufoff) + ldsw + _i * 8192), 16, 0, 0); } while (0)
; #define PG8_LDA(dst, b, h) do { _Pragma("unroll") for (int m = 0; m < 4; ++m) _Pragma("unroll") for (int k = 0; k < 2; ++k) dst[m][k] = *(const PG8_LAS bf16x8*)(lds + PG8_SA(b, h) + aoff + m * 2048 + k * 1024); } while (0)
; #define PG8_LDB(dst, b, h) do { _Pragma("unroll") for (int n = 0; n < 2; ++n) _Pragma("unroll") for (int k = 0; k < 2; ++k) dst[n][k] = *(const PG8_LAS bf16x8*)(lds + PG8_SB(b, h) + boff + n * 2048 + k * 1024); } while (0)
; #define PG8_MMA(ai, bj, At, Bt) do { __builtin_amdgcn_s_setprio(1); _Pragma("unroll") for (int m = 0; m < 4; ++m) _Pragma("unroll") for (int n = 0; n < 2; ++n) _Pragma("unroll") for (int k = 0; k < 2; ++k) \
;         acc[ai][bj][m][n] = __builtin_amdgcn_mfma_f32_16x16x32_bf16(Bt[n][k], At[m][k], acc[ai][bj][m][n], 0, 0, 0); __builtin_amdgcn_s_setprio(0); } while (0)
; #define PG8_WAIT_V(n) asm volatile("s_waitcnt vmcnt(" #n ")" ::: "memory")
; #define PG8_WAIT_L(n) asm volatile("s_waitcnt lgkmcnt(" #n ")" ::: "memory")
; #define PG8_BAR __builtin_amdgcn_s_barrier()
; #define PG8_SCHED __builtin_amdgcn_sched_barrier(0)
; template <class Epi, class Sched, bool ALIGN_EPI = false, bool SP2 = false>
; __device__ __forceinline__ void gemm_phase(PG8_LAS unsigned char* lds, const Gemm g, const Sched& S, const Epi& E) {
;     ...
;             PG8_WAIT_V(8); PG8_WAIT_L(0); PG8_BAR; PG8_MMA(1, 0, At, B0); PG8_MMA(1, 1, At, B1); PG8_BAR; PG8_SCHED;
;             PG8_LDB(B0, 1, 0); PG8_LDB(B1, 1, 1); PG8_SCHED; PG8_LDA(At, 1, 0); PG8_STAGE(PG8_SA(0, 1), a2 + hstepA, voffA);
;             PG8_WAIT_V(8); PG8_WAIT_L(0); PG8_BAR; PG8_MMA(0, 0, At, B0); PG8_MMA(0, 1, At, B1); PG8_BAR; PG8_SCHED;
	s_setprio 1
	s_waitcnt lgkmcnt(0)
	v_mfma_f32_16x16x32_bf16 v[60:63], v[106:109], v[186:189], v[60:63]
	v_mfma_f32_16x16x32_bf16 v[56:59], v[162:165], v[186:189], v[56:59]
	v_mfma_f32_16x16x32_bf16 v[44:47], v[106:109], v[200:203], v[44:47]
	v_mfma_f32_16x16x32_bf16 v[40:43], v[162:165], v[200:203], v[40:43]
	v_mfma_f32_16x16x32_bf16 v[28:31], v[106:109], v[208:211], v[28:31]
	v_mfma_f32_16x16x32_bf16 v[24:27], v[162:165], v[208:211], v[24:27]
	v_mfma_f32_16x16x32_bf16 v[12:15], v[106:109], v[216:219], v[12:15]
	v_mfma_f32_16x16x32_bf16 v[8:11], v[162:165], v[216:219], v[8:11]
	v_mfma_f32_16x16x32_bf16 v[60:63], v[154:157], v[196:199], v[60:63]
	v_mfma_f32_16x16x32_bf16 v[56:59], v[166:169], v[196:199], v[56:59]
	v_mfma_f32_16x16x32_bf16 v[44:47], v[154:157], v[204:207], v[44:47]
	v_mfma_f32_16x16x32_bf16 v[40:43], v[166:169], v[204:207], v[40:43]
	v_mfma_f32_16x16x32_bf16 v[28:31], v[154:157], v[212:215], v[28:31]
	v_mfma_f32_16x16x32_bf16 v[24:27], v[166:169], v[212:215], v[24:27]
	v_mfma_f32_16x16x32_bf16 v[12:15], v[154:157], v[220:223], v[12:15]
	v_mfma_f32_16x16x32_bf16 v[8:11], v[166:169], v[220:223], v[8:11]
	s_setprio 0
	s_setprio 1
	v_mfma_f32_16x16x32_bf16 v[52:55], v[170:173], v[186:189], v[52:55]
	v_mfma_f32_16x16x32_bf16 v[48:51], v[178:181], v[186:189], v[48:51]
	v_mfma_f32_16x16x32_bf16 v[36:39], v[170:173], v[200:203], v[36:39]
	v_mfma_f32_16x16x32_bf16 v[32:35], v[178:181], v[200:203], v[32:35]
	v_mfma_f32_16x16x32_bf16 v[20:23], v[170:173], v[208:211], v[20:23]
	v_mfma_f32_16x16x32_bf16 v[16:19], v[178:181], v[208:211], v[16:19]
	v_mfma_f32_16x16x32_bf16 v[4:7], v[170:173], v[216:219], v[4:7]
	v_mfma_f32_16x16x32_bf16 v[0:3], v[178:181], v[216:219], v[0:3]
	v_mfma_f32_16x16x32_bf16 v[52:55], v[174:177], v[196:199], v[52:55]
	v_mfma_f32_16x16x32_bf16 v[48:51], v[182:185], v[196:199], v[48:51]
	v_mfma_f32_16x16x32_bf16 v[36:39], v[174:177], v[204:207], v[36:39]
	v_mfma_f32_16x16x32_bf16 v[32:35], v[182:185], v[204:207], v[32:35]
	v_mfma_f32_16x16x32_bf16 v[20:23], v[174:177], v[212:215], v[20:23]
	v_mfma_f32_16x16x32_bf16 v[16:19], v[182:185], v[212:215], v[16:19]
	v_mfma_f32_16x16x32_bf16 v[4:7], v[174:177], v[220:223], v[4:7]
	v_mfma_f32_16x16x32_bf16 v[0:3], v[182:185], v[220:223], v[0:3]
	s_setprio 0
	s_barrier
	ds_read_b128 v[106:109], v103
	ds_read_b128 v[154:157], v103 offset:1024
	ds_read_b128 v[162:165], v103 offset:2048
	ds_read_b128 v[166:169], v103 offset:3072
	ds_read_b128 v[170:173], v104
	ds_read_b128 v[174:177], v104 offset:1024
	ds_read_b128 v[178:181], v104 offset:2048
	ds_read_b128 v[182:185], v104 offset:3072
	s_add_u32 s22, s22, 0xb4000
	s_addc_u32 s23, s23, 0
	s_mov_b32 m0, s31
	v_lshl_add_u64 v[114:115], s[22:23], 0, v[144:145]
	ds_read_b128 v[186:189], v102 offset:32768
	ds_read_b128 v[196:199], v102 offset:33792
	ds_read_b128 v[200:203], v102 offset:34816
	ds_read_b128 v[204:207], v102 offset:35840
	ds_read_b128 v[208:211], v102 offset:36864
	ds_read_b128 v[212:215], v102 offset:37888
	ds_read_b128 v[216:219], v102 offset:38912
	ds_read_b128 v[220:223], v102 offset:39936
	global_load_lds_dwordx4 v[114:115], off
	v_lshl_add_u64 v[114:115], s[22:23], 0, v[148:149]
	s_mov_b32 m0, s36
	s_nop 0
	global_load_lds_dwordx4 v[114:115], off
	s_waitcnt vmcnt(8)
	s_waitcnt lgkmcnt(0)
	s_barrier
	s_setprio 1
	s_waitcnt lgkmcnt(0)
	v_mfma_f32_16x16x32_bf16 v[140:143], v[106:109], v[186:189], v[140:143]
	v_mfma_f32_16x16x32_bf16 v[136:139], v[162:165], v[186:189], v[136:139]
	v_mfma_f32_16x16x32_bf16 v[124:127], v[106:109], v[200:203], v[124:127]
	v_mfma_f32_16x16x32_bf16 v[120:123], v[162:165], v[200:203], v[120:123]
	v_mfma_f32_16x16x32_bf16 v[92:95], v[106:109], v[208:211], v[92:95]
	v_mfma_f32_16x16x32_bf16 v[88:91], v[162:165], v[208:211], v[88:91]
	v_mfma_f32_16x16x32_bf16 v[76:79], v[106:109], v[216:219], v[76:79]
	v_mfma_f32_16x16x32_bf16 v[72:75], v[162:165], v[216:219], v[72:75]
	v_mfma_f32_16x16x32_bf16 v[140:143], v[154:157], v[196:199], v[140:143]
	v_mfma_f32_16x16x32_bf16 v[136:139], v[166:169], v[196:199], v[136:139]
	v_mfma_f32_16x16x32_bf16 v[124:127], v[154:157], v[204:207], v[124:127]
	v_mfma_f32_16x16x32_bf16 v[120:123], v[166:169], v[204:207], v[120:123]
	v_mfma_f32_16x16x32_bf16 v[92:95], v[154:157], v[212:215], v[92:95]
	v_mfma_f32_16x16x32_bf16 v[88:91], v[166:169], v[212:215], v[88:91]
	v_mfma_f32_16x16x32_bf16 v[76:79], v[154:157], v[220:223], v[76:79]
	v_mfma_f32_16x16x32_bf16 v[72:75], v[166:169], v[220:223], v[72:75]
	s_setprio 0
	s_setprio 1
	v_mfma_f32_16x16x32_bf16 v[132:135], v[170:173], v[186:189], v[132:135]
	v_mfma_f32_16x16x32_bf16 v[128:131], v[178:181], v[186:189], v[128:131]
	v_mfma_f32_16x16x32_bf16 v[114:117], v[170:173], v[200:203], v[116:119]
	v_mfma_f32_16x16x32_bf16 v[110:113], v[178:181], v[200:203], v[110:113]
	v_mfma_f32_16x16x32_bf16 v[84:87], v[170:173], v[208:211], v[84:87]
	v_mfma_f32_16x16x32_bf16 v[80:83], v[178:181], v[208:211], v[80:83]
	v_mfma_f32_16x16x32_bf16 v[68:71], v[170:173], v[216:219], v[68:71]
	v_mfma_f32_16x16x32_bf16 v[64:67], v[178:181], v[216:219], v[64:67]
	v_mfma_f32_16x16x32_bf16 v[132:135], v[174:177], v[196:199], v[132:135]
	v_mfma_f32_16x16x32_bf16 v[128:131], v[182:185], v[196:199], v[128:131]
	v_mfma_f32_16x16x32_bf16 v[116:119], v[174:177], v[204:207], v[114:117]
	v_mfma_f32_16x16x32_bf16 v[112:115], v[182:185], v[204:207], v[110:113]
	v_mfma_f32_16x16x32_bf16 v[84:87], v[174:177], v[212:215], v[84:87]
	v_mfma_f32_16x16x32_bf16 v[80:83], v[182:185], v[212:215], v[80:83]
	v_mfma_f32_16x16x32_bf16 v[68:71], v[174:177], v[220:223], v[68:71]
	v_mfma_f32_16x16x32_bf16 v[64:67], v[182:185], v[220:223], v[64:67]
	s_setprio 0
	s_barrier
; #define PG8_STAGE(bufoff, gbase, voff) do { _Pragma("unroll") for (int _i = 0; _i < 2; ++_i) \
;         __builtin_amdgcn_global_load_lds((const unsigned*)((const char*)(gbase) + (voff)[_i]), (PG8_LAS unsigned*)(lds + (bufoff) + ldsw + _i * 8192), 16, 0, 0); } while (0)
; #define PG8_LDA(dst, b, h) do { _Pragma("unroll") for (int m = 0; m < 4; ++m) _Pragma("unroll") for (int k = 0; k < 2; ++k) dst[m][k] = *(const PG8_LAS bf16x8*)(lds + PG8_SA(b, h) + aoff + m * 2048 + k * 1024); } while (0)
; #define PG8_MMA(ai, bj, At, Bt) do { __builtin_amdgcn_s_setprio(1); _Pragma("unroll") for (int m = 0; m < 4; ++m) _Pragma("unroll") for (int n = 0; n < 2; ++n) _Pragma("unroll") for (int k = 0; k < 2; ++k) \
;         acc[ai][bj][m][n] = __builtin_amdgcn_mfma_f32_16x16x32_bf16(Bt[n][k], At[m][k], acc[ai][bj][m][n], 0, 0, 0); __builtin_amdgcn_s_setprio(0); } while (0)
; #define PG8_WAIT_V(n) asm volatile("s_waitcnt vmcnt(" #n ")" ::: "memory")
; #define PG8_WAIT_L(n) asm volatile("s_waitcnt lgkmcnt(" #n ")" ::: "memory")
; #define PG8_BAR __builtin_amdgcn_s_barrier()
; #define PG8_SCHED __builtin_amdgcn_sched_barrier(0)
; template <class Epi, class Sched, bool ALIGN_EPI = false, bool SP2 = false>
; __device__ __forceinline__ void gemm_phase(PG8_LAS unsigned char* lds, const Gemm g, const Sched& S, const Epi& E) {
;     ...
;             PG8_LDA(At, 1, 1); PG8_STAGE(PG8_SB(1, 0), b3, voffB); PG8_STAGE(PG8_SB(1, 1), b3 + hstepB, voffB); PG8_STAGE(PG8_SA(1, 0), a3, voffA);
;             PG8_WAIT_V(8); PG8_WAIT_L(0); PG8_BAR; PG8_MMA(1, 0, At, B0); PG8_MMA(1, 1, At, B1); PG8_BAR; PG8_SCHED;
;     ...
;     PG8_WAIT_V(0);
;     if constexpr (!ALIGN_EPI) { if (wr == 0) PG8_BAR; }
;     PG8_BAR;
	s_mov_b32 m0, s48
	v_lshl_add_u64 v[110:111], v[158:159], 0, s[6:7]
	s_add_u32 s20, s20, 0xb0080
	ds_read_b128 v[186:189], v102 offset:49152
	ds_read_b128 v[196:199], v102 offset:50176
	ds_read_b128 v[200:203], v102 offset:51200
	ds_read_b128 v[204:207], v102 offset:52224
	ds_read_b128 v[208:211], v102 offset:53248
	ds_read_b128 v[212:215], v102 offset:54272
	ds_read_b128 v[216:219], v102 offset:55296
	ds_read_b128 v[220:223], v102 offset:56320
	global_load_lds_dwordx4 v[110:111], off
	v_lshl_add_u64 v[110:111], v[190:191], 0, s[6:7]
	s_mov_b32 m0, s49
	s_addc_u32 s21, s21, 0
	global_load_lds_dwordx4 v[110:111], off
	s_mov_b32 m0, s50
	s_nop 0
	global_load_lds_dwordx4 v146, s[20:21]
	s_mov_b32 m0, s51
	s_nop 0
	global_load_lds_dwordx4 v150, s[20:21]
	v_lshl_add_u64 v[110:111], v[224:225], 0, s[6:7]
	s_mov_b32 m0, s37
	s_nop 0
	global_load_lds_dwordx4 v[110:111], off
	v_lshl_add_u64 v[110:111], v[226:227], 0, s[6:7]
	s_mov_b32 m0, s40
	s_nop 0
	global_load_lds_dwordx4 v[110:111], off
	s_waitcnt vmcnt(8)
	s_waitcnt lgkmcnt(0)
	s_barrier
	s_setprio 1
	s_waitcnt lgkmcnt(0)
	v_mfma_f32_16x16x32_bf16 v[60:63], v[106:109], v[186:189], v[60:63]
	v_mfma_f32_16x16x32_bf16 v[56:59], v[162:165], v[186:189], v[56:59]
	v_mfma_f32_16x16x32_bf16 v[44:47], v[106:109], v[200:203], v[44:47]
	v_mfma_f32_16x16x32_bf16 v[40:43], v[162:165], v[200:203], v[40:43]
	v_mfma_f32_16x16x32_bf16 v[28:31], v[106:109], v[208:211], v[28:31]
	v_mfma_f32_16x16x32_bf16 v[24:27], v[162:165], v[208:211], v[24:27]
	v_mfma_f32_16x16x32_bf16 v[12:15], v[106:109], v[216:219], v[12:15]
	v_mfma_f32_16x16x32_bf16 v[8:11], v[162:165], v[216:219], v[8:11]
	v_mfma_f32_16x16x32_bf16 v[60:63], v[154:157], v[196:199], v[60:63]
	v_mfma_f32_16x16x32_bf16 v[56:59], v[166:169], v[196:199], v[56:59]
	v_mfma_f32_16x16x32_bf16 v[44:47], v[154:157], v[204:207], v[44:47]
	v_mfma_f32_16x16x32_bf16 v[40:43], v[166:169], v[204:207], v[40:43]
	v_mfma_f32_16x16x32_bf16 v[28:31], v[154:157], v[212:215], v[28:31]
	v_mfma_f32_16x16x32_bf16 v[24:27], v[166:169], v[212:215], v[24:27]
	v_mfma_f32_16x16x32_bf16 v[12:15], v[154:157], v[220:223], v[12:15]
	v_mfma_f32_16x16x32_bf16 v[8:11], v[166:169], v[220:223], v[8:11]
	s_setprio 0
	s_setprio 1
	v_mfma_f32_16x16x32_bf16 v[52:55], v[170:173], v[186:189], v[52:55]
	v_mfma_f32_16x16x32_bf16 v[48:51], v[178:181], v[186:189], v[48:51]
	v_mfma_f32_16x16x32_bf16 v[36:39], v[170:173], v[200:203], v[36:39]
	v_mfma_f32_16x16x32_bf16 v[32:35], v[178:181], v[200:203], v[32:35]
	v_mfma_f32_16x16x32_bf16 v[20:23], v[170:173], v[208:211], v[20:23]
	v_mfma_f32_16x16x32_bf16 v[16:19], v[178:181], v[208:211], v[16:19]
	v_mfma_f32_16x16x32_bf16 v[4:7], v[170:173], v[216:219], v[4:7]
	v_mfma_f32_16x16x32_bf16 v[0:3], v[178:181], v[216:219], v[0:3]
	v_mfma_f32_16x16x32_bf16 v[52:55], v[174:177], v[196:199], v[52:55]
	v_mfma_f32_16x16x32_bf16 v[48:51], v[182:185], v[196:199], v[48:51]
	v_mfma_f32_16x16x32_bf16 v[36:39], v[174:177], v[204:207], v[36:39]
	v_mfma_f32_16x16x32_bf16 v[32:35], v[182:185], v[204:207], v[32:35]
	v_mfma_f32_16x16x32_bf16 v[20:23], v[174:177], v[212:215], v[20:23]
	v_mfma_f32_16x16x32_bf16 v[16:19], v[182:185], v[212:215], v[16:19]
	v_mfma_f32_16x16x32_bf16 v[4:7], v[174:177], v[220:223], v[4:7]
	v_mfma_f32_16x16x32_bf16 v[0:3], v[182:185], v[220:223], v[0:3]
	s_setprio 0
	s_barrier
	s_add_i32 s41, s41, 2
	s_add_u32 s18, s18, 0x100
	s_addc_u32 s19, s19, 0
	s_cmp_lt_u32 s41, 42
	s_cbranch_scc1 .LBB0_1176
	s_waitcnt vmcnt(0)
	s_cmpk_gt_u32 s2, 0xff
	s_cbranch_scc1 .LBB0_1179
	s_barrier

; #define PG8_STAGE(bufoff, gbase, voff) do { _Pragma("unroll") for (int _i = 0; _i < 2; ++_i) \
;         __builtin_amdgcn_global_load_lds((const unsigned*)((const char*)(gbase) + (voff)[_i]), (PG8_LAS unsigned*)(lds + (bufoff) + ldsw + _i * 8192), 16, 0, 0); } while (0)
; #define PG8_WAIT_V(n) asm volatile("s_waitcnt vmcnt(" #n ")" ::: "memory")
; #define PG8_BAR __builtin_amdgcn_s_barrier()
; template <class Epi, class Sched, bool ALIGN_EPI = false, bool SP2 = false>
; __device__ __forceinline__ void gemm_phase(PG8_LAS unsigned char* lds, const Gemm g, const Sched& S, const Epi& E) {
;     ...
; #pragma unroll
;     for (int a = 0; a < 2; ++a)
; #pragma unroll
;         for (int b = 0; b < 2; ++b)
; #pragma unroll
;             for (int m = 0; m < 4; ++m)
; #pragma unroll
;                 for (int n = 0; n < 2; ++n) acc[a][b][m][n] = (f32x4){0.f, 0.f, 0.f, 0.f};
;     bf16x8 At[4][2], B0[2][2], B1[2][2];
;     const char* cA = PG8_UA(cur); const char* cB = PG8_UB(cur);
;     S.a_ready(cur);
;     if constexpr (SP2) {
;         PG8_STAGE(PG8_SB(0, 0), cB, voffB); PG8_STAGE(PG8_SB(0, 1), cB + hstepB, voffB); PG8_STAGE(PG8_SA(0, 0), cA, voffA); PG8_STAGE(PG8_SA(0, 1), cA + hstepA, voffA);
;         if (wr == 1) PG8_BAR;
;         PG8_WAIT_V(2); PG8_BAR;
;         PG8_STAGE(PG8_SB(1, 0), cB + kstep, voffB); PG8_STAGE(PG8_SA(1, 0), cA + kstep, voffA); PG8_STAGE(PG8_SB(1, 1), cB + hstepB + kstep, voffB);
;         PG8_WAIT_V(6); PG8_BAR;
.LBB0_1366:
	v_lshlrev_b32_e32 v9, 2, v161
	s_and_b32 s1, s20, 3
	v_lshl_or_b32 v8, v161, 6, v162
	s_lshl_b32 s20, s42, 13
	v_and_b32_e32 v9, 32, v9
	v_bitop3_b32 v8, v8, s20, v9 bitop3:0xde
	s_mov_b64 s[20:21], 0x80
	s_add_i32 m0, s2, 0x18000
	v_lshl_add_u64 v[6:7], v[6:7], 0, s[20:21]
	s_waitcnt vmcnt(2)
	s_barrier
	global_load_lds_dwordx4 v[6:7], off
	v_lshl_add_u64 v[4:5], v[4:5], 0, s[20:21]
	s_add_i32 m0, s2, 0x1a000
	s_add_i32 s45, s2, 0x8000
	s_add_i32 s46, s2, 0xa000
	global_load_lds_dwordx4 v[4:5], off
	v_lshl_add_u64 v[2:3], v[2:3], 0, s[20:21]
	s_mov_b32 m0, s45
	s_add_u32 s22, s4, 0x10080
	global_load_lds_dwordx4 v[2:3], off
	v_lshl_add_u64 v[0:1], v[0:1], 0, s[20:21]
	s_mov_b32 m0, s46
	s_addc_u32 s23, s5, 0
	global_load_lds_dwordx4 v[0:1], off
	s_add_i32 m0, s2, 0x1c000
	global_load_lds_dwordx4 v146, s[22:23]
	v_lshl_add_u64 v[0:1], s[22:23], 0, v[150:151]
	s_add_i32 m0, s2, 0x1e000
	v_lshl_or_b32 v9, s1, 12, v163
	global_load_lds_dwordx4 v[0:1], off
	s_waitcnt vmcnt(6)
	s_add_i32 s49, 0, 0x10000
	s_add_i32 s51, 0, 0x14000
	s_add_i32 s53, 0, 0x18000
	s_add_i32 s55, 0, 0x1c000
	v_add_u32_e32 v96, s49, v9
	v_add_u32_e32 v97, s51, v9
	s_add_i32 s49, s49, s26
	s_add_i32 s51, s51, s26
	v_add_u32_e32 v99, s53, v9
	v_add_u32_e32 v100, s55, v9
	s_add_i32 s53, s53, s26
	s_add_i32 s55, s55, s26
	v_lshl_or_b32 v152, s42, 6, v161
	s_mov_b64 s[22:23], -1
	s_mov_b64 s[24:25], 0
	v_add_u32_e32 v98, 0, v8
	s_add_i32 s47, s2, 0xc000
	s_add_i32 s48, s2, 0xe000
	s_add_i32 s50, s49, 0x2000
	s_add_i32 s52, s51, 0x2000
	s_add_i32 s54, s53, 0x2000
	s_add_i32 s56, s55, 0x2000
	v_mov_b32_e32 v0, v147
	v_mov_b32_e32 v1, v147
	v_mov_b32_e32 v2, v147
	v_mov_b32_e32 v3, v147
	v_mov_b32_e32 v4, v147
	v_mov_b32_e32 v5, v147
	v_mov_b32_e32 v6, v147
	v_mov_b32_e32 v7, v147
	v_mov_b32_e32 v16, v147
	v_mov_b32_e32 v17, v147
	v_mov_b32_e32 v18, v147
	v_mov_b32_e32 v19, v147
	v_mov_b32_e32 v20, v147
	v_mov_b32_e32 v21, v147
	v_mov_b32_e32 v22, v147
	v_mov_b32_e32 v23, v147
	v_mov_b32_e32 v32, v147
	v_mov_b32_e32 v33, v147
	v_mov_b32_e32 v34, v147
	v_mov_b32_e32 v35, v147
	v_mov_b32_e32 v36, v147
	v_mov_b32_e32 v37, v147
	v_mov_b32_e32 v38, v147
	v_mov_b32_e32 v39, v147
	v_mov_b32_e32 v48, v147
	v_mov_b32_e32 v49, v147
	v_mov_b32_e32 v50, v147
	v_mov_b32_e32 v51, v147
	v_mov_b32_e32 v52, v147
	v_mov_b32_e32 v53, v147
	v_mov_b32_e32 v54, v147
	v_mov_b32_e32 v55, v147
	v_mov_b32_e32 v8, v147
	v_mov_b32_e32 v9, v147
	v_mov_b32_e32 v10, v147
	v_mov_b32_e32 v11, v147
	v_mov_b32_e32 v12, v147
	v_mov_b32_e32 v13, v147
	v_mov_b32_e32 v14, v147
	v_mov_b32_e32 v15, v147
	v_mov_b32_e32 v24, v147
	v_mov_b32_e32 v25, v147
	v_mov_b32_e32 v26, v147
	v_mov_b32_e32 v27, v147
	v_mov_b32_e32 v28, v147
	v_mov_b32_e32 v29, v147
	v_mov_b32_e32 v30, v147
	v_mov_b32_e32 v31, v147
	v_mov_b32_e32 v40, v147
	v_mov_b32_e32 v41, v147
	v_mov_b32_e32 v42, v147
	v_mov_b32_e32 v43, v147
	v_mov_b32_e32 v44, v147
	v_mov_b32_e32 v45, v147
	v_mov_b32_e32 v46, v147
	v_mov_b32_e32 v47, v147
	v_mov_b32_e32 v56, v147
	v_mov_b32_e32 v57, v147
	v_mov_b32_e32 v58, v147
	v_mov_b32_e32 v59, v147
	v_mov_b32_e32 v60, v147
	v_mov_b32_e32 v61, v147
	v_mov_b32_e32 v62, v147
	v_mov_b32_e32 v63, v147
	v_mov_b32_e32 v64, v147
	v_mov_b32_e32 v65, v147
	v_mov_b32_e32 v66, v147
	v_mov_b32_e32 v67, v147
	v_mov_b32_e32 v68, v147
	v_mov_b32_e32 v69, v147
	v_mov_b32_e32 v70, v147
	v_mov_b32_e32 v71, v147
	v_mov_b32_e32 v80, v147
	v_mov_b32_e32 v81, v147
	v_mov_b32_e32 v82, v147
	v_mov_b32_e32 v83, v147
	v_mov_b32_e32 v84, v147
	v_mov_b32_e32 v85, v147
	v_mov_b32_e32 v86, v147
	v_mov_b32_e32 v87, v147
	v_mov_b32_e32 v112, v147
	v_mov_b32_e32 v113, v147
	v_mov_b32_e32 v114, v147
	v_mov_b32_e32 v115, v147
	v_mov_b32_e32 v116, v147
	v_mov_b32_e32 v117, v147
	v_mov_b32_e32 v118, v147
	v_mov_b32_e32 v119, v147
	v_mov_b32_e32 v128, v147
	v_mov_b32_e32 v129, v147
	v_mov_b32_e32 v130, v147
	v_mov_b32_e32 v131, v147
	v_mov_b32_e32 v132, v147
	v_mov_b32_e32 v133, v147
	v_mov_b32_e32 v134, v147
	v_mov_b32_e32 v135, v147
	v_mov_b32_e32 v72, v147
	v_mov_b32_e32 v73, v147
	v_mov_b32_e32 v74, v147
	v_mov_b32_e32 v75, v147
	v_mov_b32_e32 v76, v147
	v_mov_b32_e32 v77, v147
	v_mov_b32_e32 v78, v147
	v_mov_b32_e32 v79, v147
	v_mov_b32_e32 v88, v147
	v_mov_b32_e32 v89, v147
	v_mov_b32_e32 v90, v147
	v_mov_b32_e32 v91, v147
	v_mov_b32_e32 v92, v147
	v_mov_b32_e32 v93, v147
	v_mov_b32_e32 v94, v147
	v_mov_b32_e32 v95, v147
	v_mov_b32_e32 v120, v147
	v_mov_b32_e32 v121, v147
	v_mov_b32_e32 v122, v147
	v_mov_b32_e32 v123, v147
	v_mov_b32_e32 v124, v147
	v_mov_b32_e32 v125, v147
	v_mov_b32_e32 v126, v147
	v_mov_b32_e32 v127, v147
	v_mov_b32_e32 v136, v147
	v_mov_b32_e32 v137, v147
	v_mov_b32_e32 v138, v147
	v_mov_b32_e32 v139, v147
	v_mov_b32_e32 v140, v147
	v_mov_b32_e32 v141, v147
	v_mov_b32_e32 v142, v147
	v_mov_b32_e32 v143, v147
	s_barrier
; #define PG8_STAGE(bufoff, gbase, voff) do { _Pragma("unroll") for (int _i = 0; _i < 2; ++_i) \
;         __builtin_amdgcn_global_load_lds((const unsigned*)((const char*)(gbase) + (voff)[_i]), (PG8_LAS unsigned*)(lds + (bufoff) + ldsw + _i * 8192), 16, 0, 0); } while (0)
; #define PG8_LDA(dst, b, h) do { _Pragma("unroll") for (int m = 0; m < 4; ++m) _Pragma("unroll") for (int k = 0; k < 2; ++k) dst[m][k] = *(const PG8_LAS bf16x8*)(lds + PG8_SA(b, h) + aoff + m * 2048 + k * 1024); } while (0)
; #define PG8_LDB(dst, b, h) do { _Pragma("unroll") for (int n = 0; n < 2; ++n) _Pragma("unroll") for (int k = 0; k < 2; ++k) dst[n][k] = *(const PG8_LAS bf16x8*)(lds + PG8_SB(b, h) + boff + n * 2048 + k * 1024); } while (0)
; #define PG8_MMA(ai, bj, At, Bt) do { __builtin_amdgcn_s_setprio(1); _Pragma("unroll") for (int m = 0; m < 4; ++m) _Pragma("unroll") for (int n = 0; n < 2; ++n) _Pragma("unroll") for (int k = 0; k < 2; ++k) \
;         acc[ai][bj][m][n] = __builtin_amdgcn_mfma_f32_16x16x32_bf16(Bt[n][k], At[m][k], acc[ai][bj][m][n], 0, 0, 0); __builtin_amdgcn_s_setprio(0); } while (0)
; #define PG8_WAIT_V(n) asm volatile("s_waitcnt vmcnt(" #n ")" ::: "memory")
; #define PG8_WAIT_L(n) asm volatile("s_waitcnt lgkmcnt(" #n ")" ::: "memory")
; template <class Epi, class Sched, bool ALIGN_EPI = false, bool SP2 = false>
; __device__ __forceinline__ void gemm_phase(PG8_LAS unsigned char* lds, const Gemm g, const Sched& S, const Epi& E) {
;     ...
;         const char* nA = has_next ? PG8_UA(nxt) : cA; const char* nB = has_next ? PG8_UB(nxt) : cB;
;         for (int t = 0; t < nt; t += 2) {
;             const bool last = (t == nt - 2);
;             const char* a1 = cA + (size_t)(t + 1) * kstep;
;             const char* a2 = last ? nA : cA + (size_t)(t + 2) * kstep; const char* b2 = last ? nB : cB + (size_t)(t + 2) * kstep;
;             const char* a3 = a2 + kstep; const char* b3 = b2 + kstep;
;             if (last && has_next) S.a_ready(nxt);
;             if constexpr (SP2) {
;             PG8_LDB(B0, 0, 0); PG8_LDB(B1, 0, 1); PG8_SCHED; PG8_LDA(At, 0, 0); PG8_STAGE(PG8_SA(1, 1), a1 + hstepA, voffA);
;             PG8_WAIT_V(8); PG8_WAIT_L(0); PG8_BAR; PG8_MMA(0, 0, At, B0); PG8_MMA(0, 1, At, B1); PG8_BAR; PG8_SCHED;
;             PG8_LDA(At, 0, 1); PG8_STAGE(PG8_SB(0, 0), b2, voffB); PG8_STAGE(PG8_SB(0, 1), b2 + hstepB, voffB); PG8_STAGE(PG8_SA(0, 0), a2, voffA);
.LBB0_1367:
	ds_read_b128 v[102:105], v96
	ds_read_b128 v[106:109], v96 offset:1024
	ds_read_b128 v[154:157], v96 offset:2048
	ds_read_b128 v[164:167], v96 offset:3072
	ds_read_b128 v[168:171], v97
	ds_read_b128 v[172:175], v97 offset:1024
	ds_read_b128 v[176:179], v97 offset:2048
	ds_read_b128 v[180:183], v97 offset:3072
	s_add_i32 s26, s57, 0x100
	s_and_b64 s[24:25], s[24:25], exec
	s_cselect_b32 s24, 0, s26
	s_cselect_b32 s25, 0, 0
	s_add_u32 s26, s6, s24
	s_addc_u32 s27, s7, s25
	s_add_u32 s24, s4, s24
	s_addc_u32 s25, s5, s25
	s_add_u32 s58, s18, s57
	s_addc_u32 s59, s19, 0
	v_lshl_add_u64 v[110:111], s[58:59], 0, v[144:145]
	s_mov_b32 m0, s47
	v_lshl_add_u64 v[110:111], v[110:111], 0, s[20:21]
	ds_read_b128 v[184:187], v98
	ds_read_b128 v[188:191], v98 offset:1024
	ds_read_b128 v[196:199], v98 offset:2048
	ds_read_b128 v[200:203], v98 offset:3072
	ds_read_b128 v[204:207], v98 offset:4096
	ds_read_b128 v[208:211], v98 offset:5120
	ds_read_b128 v[212:215], v98 offset:6144
	ds_read_b128 v[216:219], v98 offset:7168
	global_load_lds_dwordx4 v[110:111], off
	v_lshl_add_u64 v[110:111], s[58:59], 0, v[148:149]
	v_lshl_add_u64 v[110:111], v[110:111], 0, s[20:21]
	s_mov_b32 m0, s48
	s_nop 0
	global_load_lds_dwordx4 v[110:111], off
	s_waitcnt vmcnt(8)
	s_waitcnt lgkmcnt(0)
	s_barrier
	s_setprio 1
	s_waitcnt lgkmcnt(0)
	v_mfma_f32_16x16x32_bf16 v[140:143], v[102:105], v[184:187], v[140:143]
	v_mfma_f32_16x16x32_bf16 v[136:139], v[154:157], v[184:187], v[136:139]
	v_mfma_f32_16x16x32_bf16 v[124:127], v[102:105], v[196:199], v[124:127]
	v_mfma_f32_16x16x32_bf16 v[120:123], v[154:157], v[196:199], v[120:123]
	v_mfma_f32_16x16x32_bf16 v[92:95], v[102:105], v[204:207], v[92:95]
	v_mfma_f32_16x16x32_bf16 v[88:91], v[154:157], v[204:207], v[88:91]
	v_mfma_f32_16x16x32_bf16 v[76:79], v[102:105], v[212:215], v[76:79]
	v_mfma_f32_16x16x32_bf16 v[72:75], v[154:157], v[212:215], v[72:75]
	v_mfma_f32_16x16x32_bf16 v[140:143], v[106:109], v[188:191], v[140:143]
	v_mfma_f32_16x16x32_bf16 v[136:139], v[164:167], v[188:191], v[136:139]
	v_mfma_f32_16x16x32_bf16 v[124:127], v[106:109], v[200:203], v[124:127]
	v_mfma_f32_16x16x32_bf16 v[120:123], v[164:167], v[200:203], v[120:123]
	v_mfma_f32_16x16x32_bf16 v[92:95], v[106:109], v[208:211], v[92:95]
	v_mfma_f32_16x16x32_bf16 v[88:91], v[164:167], v[208:211], v[88:91]
	v_mfma_f32_16x16x32_bf16 v[76:79], v[106:109], v[216:219], v[76:79]
	v_mfma_f32_16x16x32_bf16 v[72:75], v[164:167], v[216:219], v[72:75]
	s_setprio 0
	s_setprio 1
	v_mfma_f32_16x16x32_bf16 v[132:135], v[168:171], v[184:187], v[132:135]
	v_mfma_f32_16x16x32_bf16 v[128:131], v[176:179], v[184:187], v[128:131]
	v_mfma_f32_16x16x32_bf16 v[116:119], v[168:171], v[196:199], v[116:119]
	v_mfma_f32_16x16x32_bf16 v[110:113], v[176:179], v[196:199], v[112:115]
	v_mfma_f32_16x16x32_bf16 v[84:87], v[168:171], v[204:207], v[84:87]
	v_mfma_f32_16x16x32_bf16 v[80:83], v[176:179], v[204:207], v[80:83]
	v_mfma_f32_16x16x32_bf16 v[68:71], v[168:171], v[212:215], v[68:71]
	v_mfma_f32_16x16x32_bf16 v[64:67], v[176:179], v[212:215], v[64:67]
	v_mfma_f32_16x16x32_bf16 v[132:135], v[172:175], v[188:191], v[132:135]
	v_mfma_f32_16x16x32_bf16 v[128:131], v[180:183], v[188:191], v[128:131]
	v_mfma_f32_16x16x32_bf16 v[116:119], v[172:175], v[200:203], v[116:119]
	v_mfma_f32_16x16x32_bf16 v[110:113], v[180:183], v[200:203], v[110:113]
	v_mfma_f32_16x16x32_bf16 v[84:87], v[172:175], v[208:211], v[84:87]
	v_mfma_f32_16x16x32_bf16 v[80:83], v[180:183], v[208:211], v[80:83]
	v_mfma_f32_16x16x32_bf16 v[68:71], v[172:175], v[216:219], v[68:71]
	v_mfma_f32_16x16x32_bf16 v[64:67], v[180:183], v[216:219], v[64:67]
	s_setprio 0
	s_barrier
	s_mov_b32 m0, s49
	v_lshl_add_u64 v[158:159], s[24:25], 0, v[146:147]
	s_add_u32 s58, s24, 0x10000
	ds_read_b128 v[184:187], v98 offset:16384
	ds_read_b128 v[188:191], v98 offset:17408
	ds_read_b128 v[196:199], v98 offset:18432
	ds_read_b128 v[200:203], v98 offset:19456
	ds_read_b128 v[204:207], v98 offset:20480
	ds_read_b128 v[208:211], v98 offset:21504
	ds_read_b128 v[212:215], v98 offset:22528
	ds_read_b128 v[216:219], v98 offset:23552
	global_load_lds_dwordx4 v[158:159], off
	v_lshl_add_u64 v[220:221], s[24:25], 0, v[150:151]
	s_mov_b32 m0, s50
	s_addc_u32 s59, s25, 0
	global_load_lds_dwordx4 v[220:221], off
	s_mov_b32 m0, s51
	v_lshl_add_u64 v[222:223], s[26:27], 0, v[144:145]
	global_load_lds_dwordx4 v146, s[58:59]
	s_mov_b32 m0, s52
	v_lshl_add_u64 v[224:225], s[26:27], 0, v[148:149]
	global_load_lds_dwordx4 v150, s[58:59]
	s_mov_b32 m0, s2
	s_nop 0
	global_load_lds_dwordx4 v[222:223], off
	s_mov_b32 m0, s3
	s_nop 0
	global_load_lds_dwordx4 v[224:225], off
	s_waitcnt vmcnt(8)
	s_waitcnt lgkmcnt(0)
	s_barrier
; #define PG8_STAGE(bufoff, gbase, voff) do { _Pragma("unroll") for (int _i = 0; _i < 2; ++_i) \
;         __builtin_amdgcn_global_load_lds((const unsigned*)((const char*)(gbase) + (voff)[_i]), (PG8_LAS unsigned*)(lds + (bufoff) + ldsw + _i * 8192), 16, 0, 0); } while (0)
; #define PG8_LDA(dst, b, h) do { _Pragma("unroll") for (int m = 0; m < 4; ++m) _Pragma("unroll") for (int k = 0; k < 2; ++k) dst[m][k] = *(const PG8_LAS bf16x8*)(lds + PG8_SA(b, h) + aoff + m * 2048 + k * 1024); } while (0)
; #define PG8_LDB(dst, b, h) do { _Pragma("unroll") for (int n = 0; n < 2; ++n) _Pragma("unroll") for (int k = 0; k < 2; ++k) dst[n][k] = *(const PG8_LAS bf16x8*)(lds + PG8_SB(b, h) + boff + n * 2048 + k * 1024); } while (0)
; #define PG8_MMA(ai, bj, At, Bt) do { __builtin_amdgcn_s_setprio(1); _Pragma("unroll") for (int m = 0; m < 4; ++m) _Pragma("unroll") for (int n = 0; n < 2; ++n) _Pragma("unroll") for (int k = 0; k < 2; ++k) \
;         acc[ai][bj][m][n] = __builtin_amdgcn_mfma_f32_16x16x32_bf16(Bt[n][k], At[m][k], acc[ai][bj][m][n], 0, 0, 0); __builtin_amdgcn_s_setprio(0); } while (0)
; #define PG8_WAIT_V(n) asm volatile("s_waitcnt vmcnt(" #n ")" ::: "memory")
; #define PG8_WAIT_L(n) asm volatile("s_waitcnt lgkmcnt(" #n ")" ::: "memory")
; #define PG8_BAR __builtin_amdgcn_s_barrier()
; #define PG8_SCHED __builtin_amdgcn_sched_barrier(0)
; template <class Epi, class Sched, bool ALIGN_EPI = false, bool SP2 = false>
; __device__ __forceinline__ void gemm_phase(PG8_LAS unsigned char* lds, const Gemm g, const Sched& S, const Epi& E) {
;     ...
;             PG8_WAIT_V(8); PG8_WAIT_L(0); PG8_BAR; PG8_MMA(1, 0, At, B0); PG8_MMA(1, 1, At, B1); PG8_BAR; PG8_SCHED;
;             PG8_LDB(B0, 1, 0); PG8_LDB(B1, 1, 1); PG8_SCHED; PG8_LDA(At, 1, 0); PG8_STAGE(PG8_SA(0, 1), a2 + hstepA, voffA);
;             PG8_WAIT_V(8); PG8_WAIT_L(0); PG8_BAR; PG8_MMA(0, 0, At, B0); PG8_MMA(0, 1, At, B1); PG8_BAR; PG8_SCHED;
	s_setprio 1
	s_waitcnt lgkmcnt(0)
	v_mfma_f32_16x16x32_bf16 v[60:63], v[102:105], v[184:187], v[60:63]
	v_mfma_f32_16x16x32_bf16 v[56:59], v[154:157], v[184:187], v[56:59]
	v_mfma_f32_16x16x32_bf16 v[44:47], v[102:105], v[196:199], v[44:47]
	v_mfma_f32_16x16x32_bf16 v[40:43], v[154:157], v[196:199], v[40:43]
	v_mfma_f32_16x16x32_bf16 v[28:31], v[102:105], v[204:207], v[28:31]
	v_mfma_f32_16x16x32_bf16 v[24:27], v[154:157], v[204:207], v[24:27]
	v_mfma_f32_16x16x32_bf16 v[12:15], v[102:105], v[212:215], v[12:15]
	v_mfma_f32_16x16x32_bf16 v[8:11], v[154:157], v[212:215], v[8:11]
	v_mfma_f32_16x16x32_bf16 v[60:63], v[106:109], v[188:191], v[60:63]
	v_mfma_f32_16x16x32_bf16 v[56:59], v[164:167], v[188:191], v[56:59]
	v_mfma_f32_16x16x32_bf16 v[44:47], v[106:109], v[200:203], v[44:47]
	v_mfma_f32_16x16x32_bf16 v[40:43], v[164:167], v[200:203], v[40:43]
	v_mfma_f32_16x16x32_bf16 v[28:31], v[106:109], v[208:211], v[28:31]
	v_mfma_f32_16x16x32_bf16 v[24:27], v[164:167], v[208:211], v[24:27]
	v_mfma_f32_16x16x32_bf16 v[12:15], v[106:109], v[216:219], v[12:15]
	v_mfma_f32_16x16x32_bf16 v[8:11], v[164:167], v[216:219], v[8:11]
	s_setprio 0
	s_setprio 1
	v_mfma_f32_16x16x32_bf16 v[52:55], v[168:171], v[184:187], v[52:55]
	v_mfma_f32_16x16x32_bf16 v[48:51], v[176:179], v[184:187], v[48:51]
	v_mfma_f32_16x16x32_bf16 v[36:39], v[168:171], v[196:199], v[36:39]
	v_mfma_f32_16x16x32_bf16 v[32:35], v[176:179], v[196:199], v[32:35]
	v_mfma_f32_16x16x32_bf16 v[20:23], v[168:171], v[204:207], v[20:23]
	v_mfma_f32_16x16x32_bf16 v[16:19], v[176:179], v[204:207], v[16:19]
	v_mfma_f32_16x16x32_bf16 v[4:7], v[168:171], v[212:215], v[4:7]
	v_mfma_f32_16x16x32_bf16 v[0:3], v[176:179], v[212:215], v[0:3]
	v_mfma_f32_16x16x32_bf16 v[52:55], v[172:175], v[188:191], v[52:55]
	v_mfma_f32_16x16x32_bf16 v[48:51], v[180:183], v[188:191], v[48:51]
	v_mfma_f32_16x16x32_bf16 v[36:39], v[172:175], v[200:203], v[36:39]
	v_mfma_f32_16x16x32_bf16 v[32:35], v[180:183], v[200:203], v[32:35]
	v_mfma_f32_16x16x32_bf16 v[20:23], v[172:175], v[208:211], v[20:23]
	v_mfma_f32_16x16x32_bf16 v[16:19], v[180:183], v[208:211], v[16:19]
	v_mfma_f32_16x16x32_bf16 v[4:7], v[172:175], v[216:219], v[4:7]
	v_mfma_f32_16x16x32_bf16 v[0:3], v[180:183], v[216:219], v[0:3]
	s_setprio 0
	s_barrier
	ds_read_b128 v[102:105], v99
	ds_read_b128 v[106:109], v99 offset:1024
	ds_read_b128 v[154:157], v99 offset:2048
	ds_read_b128 v[164:167], v99 offset:3072
	ds_read_b128 v[168:171], v100
	ds_read_b128 v[172:175], v100 offset:1024
	ds_read_b128 v[176:179], v100 offset:2048
	ds_read_b128 v[180:183], v100 offset:3072
	s_add_u32 s26, s26, 0x40000
	s_addc_u32 s27, s27, 0
	s_mov_b32 m0, s43
	v_lshl_add_u64 v[114:115], s[26:27], 0, v[144:145]
	ds_read_b128 v[184:187], v98 offset:32768
	ds_read_b128 v[188:191], v98 offset:33792
	ds_read_b128 v[196:199], v98 offset:34816
	ds_read_b128 v[200:203], v98 offset:35840
	ds_read_b128 v[204:207], v98 offset:36864
	ds_read_b128 v[208:211], v98 offset:37888
	ds_read_b128 v[212:215], v98 offset:38912
	ds_read_b128 v[216:219], v98 offset:39936
	global_load_lds_dwordx4 v[114:115], off
	v_lshl_add_u64 v[114:115], s[26:27], 0, v[148:149]
	s_mov_b32 m0, s44
	s_nop 0
	global_load_lds_dwordx4 v[114:115], off
	s_waitcnt vmcnt(8)
	s_waitcnt lgkmcnt(0)
	s_barrier
	s_setprio 1
	s_waitcnt lgkmcnt(0)
	v_mfma_f32_16x16x32_bf16 v[140:143], v[102:105], v[184:187], v[140:143]
	v_mfma_f32_16x16x32_bf16 v[136:139], v[154:157], v[184:187], v[136:139]
	v_mfma_f32_16x16x32_bf16 v[124:127], v[102:105], v[196:199], v[124:127]
	v_mfma_f32_16x16x32_bf16 v[120:123], v[154:157], v[196:199], v[120:123]
	v_mfma_f32_16x16x32_bf16 v[92:95], v[102:105], v[204:207], v[92:95]
	v_mfma_f32_16x16x32_bf16 v[88:91], v[154:157], v[204:207], v[88:91]
	v_mfma_f32_16x16x32_bf16 v[76:79], v[102:105], v[212:215], v[76:79]
	v_mfma_f32_16x16x32_bf16 v[72:75], v[154:157], v[212:215], v[72:75]
	v_mfma_f32_16x16x32_bf16 v[140:143], v[106:109], v[188:191], v[140:143]
	v_mfma_f32_16x16x32_bf16 v[136:139], v[164:167], v[188:191], v[136:139]
	v_mfma_f32_16x16x32_bf16 v[124:127], v[106:109], v[200:203], v[124:127]
	v_mfma_f32_16x16x32_bf16 v[120:123], v[164:167], v[200:203], v[120:123]
	v_mfma_f32_16x16x32_bf16 v[92:95], v[106:109], v[208:211], v[92:95]
	v_mfma_f32_16x16x32_bf16 v[88:91], v[164:167], v[208:211], v[88:91]
	v_mfma_f32_16x16x32_bf16 v[76:79], v[106:109], v[216:219], v[76:79]
	v_mfma_f32_16x16x32_bf16 v[72:75], v[164:167], v[216:219], v[72:75]
	s_setprio 0
	s_setprio 1
	v_mfma_f32_16x16x32_bf16 v[132:135], v[168:171], v[184:187], v[132:135]
	v_mfma_f32_16x16x32_bf16 v[128:131], v[176:179], v[184:187], v[128:131]
	v_mfma_f32_16x16x32_bf16 v[114:117], v[168:171], v[196:199], v[116:119]
	v_mfma_f32_16x16x32_bf16 v[110:113], v[176:179], v[196:199], v[110:113]
	v_mfma_f32_16x16x32_bf16 v[84:87], v[168:171], v[204:207], v[84:87]
	v_mfma_f32_16x16x32_bf16 v[80:83], v[176:179], v[204:207], v[80:83]
	v_mfma_f32_16x16x32_bf16 v[68:71], v[168:171], v[212:215], v[68:71]
	v_mfma_f32_16x16x32_bf16 v[64:67], v[176:179], v[212:215], v[64:67]
	v_mfma_f32_16x16x32_bf16 v[132:135], v[172:175], v[188:191], v[132:135]
	v_mfma_f32_16x16x32_bf16 v[128:131], v[180:183], v[188:191], v[128:131]
	v_mfma_f32_16x16x32_bf16 v[116:119], v[172:175], v[200:203], v[114:117]
	v_mfma_f32_16x16x32_bf16 v[112:115], v[180:183], v[200:203], v[110:113]
	v_mfma_f32_16x16x32_bf16 v[84:87], v[172:175], v[208:211], v[84:87]
	v_mfma_f32_16x16x32_bf16 v[80:83], v[180:183], v[208:211], v[80:83]
	v_mfma_f32_16x16x32_bf16 v[68:71], v[172:175], v[216:219], v[68:71]
	v_mfma_f32_16x16x32_bf16 v[64:67], v[180:183], v[216:219], v[64:67]
	s_setprio 0
	s_barrier
; #define PG8_STAGE(bufoff, gbase, voff) do { _Pragma("unroll") for (int _i = 0; _i < 2; ++_i) \
;         __builtin_amdgcn_global_load_lds((const unsigned*)((const char*)(gbase) + (voff)[_i]), (PG8_LAS unsigned*)(lds + (bufoff) + ldsw + _i * 8192), 16, 0, 0); } while (0)
; #define PG8_LDA(dst, b, h) do { _Pragma("unroll") for (int m = 0; m < 4; ++m) _Pragma("unroll") for (int k = 0; k < 2; ++k) dst[m][k] = *(const PG8_LAS bf16x8*)(lds + PG8_SA(b, h) + aoff + m * 2048 + k * 1024); } while (0)
; #define PG8_MMA(ai, bj, At, Bt) do { __builtin_amdgcn_s_setprio(1); _Pragma("unroll") for (int m = 0; m < 4; ++m) _Pragma("unroll") for (int n = 0; n < 2; ++n) _Pragma("unroll") for (int k = 0; k < 2; ++k) \
;         acc[ai][bj][m][n] = __builtin_amdgcn_mfma_f32_16x16x32_bf16(Bt[n][k], At[m][k], acc[ai][bj][m][n], 0, 0, 0); __builtin_amdgcn_s_setprio(0); } while (0)
; #define PG8_WAIT_V(n) asm volatile("s_waitcnt vmcnt(" #n ")" ::: "memory")
; #define PG8_WAIT_L(n) asm volatile("s_waitcnt lgkmcnt(" #n ")" ::: "memory")
; #define PG8_BAR __builtin_amdgcn_s_barrier()
; #define PG8_SCHED __builtin_amdgcn_sched_barrier(0)
; template <class Epi, class Sched, bool ALIGN_EPI = false, bool SP2 = false>
; __device__ __forceinline__ void gemm_phase(PG8_LAS unsigned char* lds, const Gemm g, const Sched& S, const Epi& E) {
;     ...
;             PG8_LDA(At, 1, 1); PG8_STAGE(PG8_SB(1, 0), b3, voffB); PG8_STAGE(PG8_SB(1, 1), b3 + hstepB, voffB); PG8_STAGE(PG8_SA(1, 0), a3, voffA);
;             PG8_WAIT_V(8); PG8_WAIT_L(0); PG8_BAR; PG8_MMA(1, 0, At, B0); PG8_MMA(1, 1, At, B1); PG8_BAR; PG8_SCHED;
;     ...
;     PG8_WAIT_V(0);
;     if constexpr (!ALIGN_EPI) { if (wr == 0) PG8_BAR; }
;     PG8_BAR;
	s_mov_b32 m0, s53
	v_lshl_add_u64 v[110:111], v[158:159], 0, s[20:21]
	s_add_u32 s24, s24, 0x10080
	ds_read_b128 v[184:187], v98 offset:49152
	ds_read_b128 v[188:191], v98 offset:50176
	ds_read_b128 v[196:199], v98 offset:51200
	ds_read_b128 v[200:203], v98 offset:52224
	ds_read_b128 v[204:207], v98 offset:53248
	ds_read_b128 v[208:211], v98 offset:54272
	ds_read_b128 v[212:215], v98 offset:55296
	ds_read_b128 v[216:219], v98 offset:56320
	global_load_lds_dwordx4 v[110:111], off
	v_lshl_add_u64 v[110:111], v[220:221], 0, s[20:21]
	s_mov_b32 m0, s54
	s_addc_u32 s25, s25, 0
	global_load_lds_dwordx4 v[110:111], off
	s_mov_b32 m0, s55
	s_nop 0
	global_load_lds_dwordx4 v146, s[24:25]
	s_mov_b32 m0, s56
	s_nop 0
	global_load_lds_dwordx4 v150, s[24:25]
	v_lshl_add_u64 v[110:111], v[222:223], 0, s[20:21]
	s_mov_b32 m0, s45
	s_nop 0
	global_load_lds_dwordx4 v[110:111], off
	v_lshl_add_u64 v[110:111], v[224:225], 0, s[20:21]
	s_mov_b32 m0, s46
	s_nop 0
	global_load_lds_dwordx4 v[110:111], off
	s_waitcnt vmcnt(8)
	s_waitcnt lgkmcnt(0)
	s_barrier
	s_setprio 1
	s_waitcnt lgkmcnt(0)
	v_mfma_f32_16x16x32_bf16 v[60:63], v[102:105], v[184:187], v[60:63]
	v_mfma_f32_16x16x32_bf16 v[56:59], v[154:157], v[184:187], v[56:59]
	v_mfma_f32_16x16x32_bf16 v[44:47], v[102:105], v[196:199], v[44:47]
	v_mfma_f32_16x16x32_bf16 v[40:43], v[154:157], v[196:199], v[40:43]
	v_mfma_f32_16x16x32_bf16 v[28:31], v[102:105], v[204:207], v[28:31]
	v_mfma_f32_16x16x32_bf16 v[24:27], v[154:157], v[204:207], v[24:27]
	v_mfma_f32_16x16x32_bf16 v[12:15], v[102:105], v[212:215], v[12:15]
	v_mfma_f32_16x16x32_bf16 v[8:11], v[154:157], v[212:215], v[8:11]
	v_mfma_f32_16x16x32_bf16 v[60:63], v[106:109], v[188:191], v[60:63]
	v_mfma_f32_16x16x32_bf16 v[56:59], v[164:167], v[188:191], v[56:59]
	v_mfma_f32_16x16x32_bf16 v[44:47], v[106:109], v[200:203], v[44:47]
	v_mfma_f32_16x16x32_bf16 v[40:43], v[164:167], v[200:203], v[40:43]
	v_mfma_f32_16x16x32_bf16 v[28:31], v[106:109], v[208:211], v[28:31]
	v_mfma_f32_16x16x32_bf16 v[24:27], v[164:167], v[208:211], v[24:27]
	v_mfma_f32_16x16x32_bf16 v[12:15], v[106:109], v[216:219], v[12:15]
	v_mfma_f32_16x16x32_bf16 v[8:11], v[164:167], v[216:219], v[8:11]
	s_setprio 0
	s_setprio 1
	v_mfma_f32_16x16x32_bf16 v[52:55], v[168:171], v[184:187], v[52:55]
	v_mfma_f32_16x16x32_bf16 v[48:51], v[176:179], v[184:187], v[48:51]
	v_mfma_f32_16x16x32_bf16 v[36:39], v[168:171], v[196:199], v[36:39]
	v_mfma_f32_16x16x32_bf16 v[32:35], v[176:179], v[196:199], v[32:35]
	v_mfma_f32_16x16x32_bf16 v[20:23], v[168:171], v[204:207], v[20:23]
	v_mfma_f32_16x16x32_bf16 v[16:19], v[176:179], v[204:207], v[16:19]
	v_mfma_f32_16x16x32_bf16 v[4:7], v[168:171], v[212:215], v[4:7]
	v_mfma_f32_16x16x32_bf16 v[0:3], v[176:179], v[212:215], v[0:3]
	v_mfma_f32_16x16x32_bf16 v[52:55], v[172:175], v[188:191], v[52:55]
	v_mfma_f32_16x16x32_bf16 v[48:51], v[180:183], v[188:191], v[48:51]
	v_mfma_f32_16x16x32_bf16 v[36:39], v[172:175], v[200:203], v[36:39]
	v_mfma_f32_16x16x32_bf16 v[32:35], v[180:183], v[200:203], v[32:35]
	v_mfma_f32_16x16x32_bf16 v[20:23], v[172:175], v[208:211], v[20:23]
	v_mfma_f32_16x16x32_bf16 v[16:19], v[180:183], v[208:211], v[16:19]
	v_mfma_f32_16x16x32_bf16 v[4:7], v[172:175], v[216:219], v[4:7]
	v_mfma_f32_16x16x32_bf16 v[0:3], v[180:183], v[216:219], v[0:3]
	s_setprio 0
	s_barrier
	s_and_b64 vcc, exec, s[22:23]
	s_mov_b64 s[24:25], -1
	s_mov_b64 s[22:23], 0
	s_movk_i32 s57, 0x100
	s_cbranch_vccnz .LBB0_1367
	s_waitcnt vmcnt(0)
	s_cmpk_gt_u32 s41, 0xff
	s_cbranch_scc1 .LBB0_1370
	s_barrier

; #define PG8_STAGE(bufoff, gbase, voff) do { _Pragma("unroll") for (int _i = 0; _i < 2; ++_i) \
;         __builtin_amdgcn_global_load_lds((const unsigned*)((const char*)(gbase) + (voff)[_i]), (PG8_LAS unsigned*)(lds + (bufoff) + ldsw + _i * 8192), 16, 0, 0); } while (0)
; #define PG8_WAIT_V(n) asm volatile("s_waitcnt vmcnt(" #n ")" ::: "memory")
; #define PG8_BAR __builtin_amdgcn_s_barrier()
; template <class Epi, class Sched, bool ALIGN_EPI = false, bool SP2 = false>
; __device__ __forceinline__ void gemm_phase(PG8_LAS unsigned char* lds, const Gemm g, const Sched& S, const Epi& E) {
;     ...
; #pragma unroll
;     for (int a = 0; a < 2; ++a)
; #pragma unroll
;         for (int b = 0; b < 2; ++b)
; #pragma unroll
;             for (int m = 0; m < 4; ++m)
; #pragma unroll
;                 for (int n = 0; n < 2; ++n) acc[a][b][m][n] = (f32x4){0.f, 0.f, 0.f, 0.f};
;     bf16x8 At[4][2], B0[2][2], B1[2][2];
;     const char* cA = PG8_UA(cur); const char* cB = PG8_UB(cur);
;     S.a_ready(cur);
;     if constexpr (SP2) {
;         PG8_STAGE(PG8_SB(0, 0), cB, voffB); PG8_STAGE(PG8_SB(0, 1), cB + hstepB, voffB); PG8_STAGE(PG8_SA(0, 0), cA, voffA); PG8_STAGE(PG8_SA(0, 1), cA + hstepA, voffA);
;         if (wr == 1) PG8_BAR;
;         PG8_WAIT_V(2); PG8_BAR;
;         PG8_STAGE(PG8_SB(1, 0), cB + kstep, voffB); PG8_STAGE(PG8_SA(1, 0), cA + kstep, voffA); PG8_STAGE(PG8_SB(1, 1), cB + hstepB + kstep, voffB);
;         PG8_WAIT_V(6); PG8_BAR;
.LBB0_1421:
	v_lshlrev_b32_e32 v9, 2, v161
	s_and_b32 s1, s20, 3
	v_lshl_or_b32 v8, v161, 6, v162
	s_lshl_b32 s20, s42, 13
	v_and_b32_e32 v9, 32, v9
	v_bitop3_b32 v8, v8, s20, v9 bitop3:0xde
	s_mov_b64 s[20:21], 0x80
	s_add_i32 m0, s2, 0x18000
	v_lshl_add_u64 v[6:7], v[6:7], 0, s[20:21]
	s_waitcnt vmcnt(2)
	s_barrier
	global_load_lds_dwordx4 v[6:7], off
	v_lshl_add_u64 v[4:5], v[4:5], 0, s[20:21]
	s_add_i32 m0, s2, 0x1a000
	s_add_i32 s37, s2, 0x8000
	s_add_i32 s40, s2, 0xa000
	global_load_lds_dwordx4 v[4:5], off
	v_lshl_add_u64 v[2:3], v[2:3], 0, s[20:21]
	s_mov_b32 m0, s37
	s_add_u32 s22, s4, 0x10080
	global_load_lds_dwordx4 v[2:3], off
	v_lshl_add_u64 v[0:1], v[0:1], 0, s[20:21]
	s_mov_b32 m0, s40
	s_addc_u32 s23, s5, 0
	global_load_lds_dwordx4 v[0:1], off
	s_add_i32 m0, s2, 0x1c000
	global_load_lds_dwordx4 v146, s[22:23]
	v_lshl_add_u64 v[0:1], s[22:23], 0, v[150:151]
	s_add_i32 m0, s2, 0x1e000
	v_lshl_or_b32 v9, s1, 12, v163
	global_load_lds_dwordx4 v[0:1], off
	s_waitcnt vmcnt(6)
	s_add_i32 s45, 0, 0x10000
	s_add_i32 s47, 0, 0x14000
	s_add_i32 s49, 0, 0x18000
	s_add_i32 s51, 0, 0x1c000
	v_add_u32_e32 v96, s45, v9
	v_add_u32_e32 v97, s47, v9
	s_add_i32 s45, s45, s26
	s_add_i32 s47, s47, s26
	v_add_u32_e32 v99, s49, v9
	v_add_u32_e32 v100, s51, v9
	s_add_i32 s49, s49, s26
	s_add_i32 s51, s51, s26
	v_lshl_or_b32 v152, s42, 6, v161
	s_mov_b64 s[22:23], -1
	s_mov_b64 s[24:25], 0
	v_add_u32_e32 v98, 0, v8
	s_add_i32 s43, s2, 0xc000
	s_add_i32 s44, s2, 0xe000
	s_add_i32 s46, s45, 0x2000
	s_add_i32 s48, s47, 0x2000
	s_add_i32 s50, s49, 0x2000
	s_add_i32 s52, s51, 0x2000
	v_mov_b32_e32 v0, v147
	v_mov_b32_e32 v1, v147
	v_mov_b32_e32 v2, v147
	v_mov_b32_e32 v3, v147
	v_mov_b32_e32 v4, v147
	v_mov_b32_e32 v5, v147
	v_mov_b32_e32 v6, v147
	v_mov_b32_e32 v7, v147
	v_mov_b32_e32 v16, v147
	v_mov_b32_e32 v17, v147
	v_mov_b32_e32 v18, v147
	v_mov_b32_e32 v19, v147
	v_mov_b32_e32 v20, v147
	v_mov_b32_e32 v21, v147
	v_mov_b32_e32 v22, v147
	v_mov_b32_e32 v23, v147
	v_mov_b32_e32 v32, v147
	v_mov_b32_e32 v33, v147
	v_mov_b32_e32 v34, v147
	v_mov_b32_e32 v35, v147
	v_mov_b32_e32 v36, v147
	v_mov_b32_e32 v37, v147
	v_mov_b32_e32 v38, v147
	v_mov_b32_e32 v39, v147
	v_mov_b32_e32 v48, v147
	v_mov_b32_e32 v49, v147
	v_mov_b32_e32 v50, v147
	v_mov_b32_e32 v51, v147
	v_mov_b32_e32 v52, v147
	v_mov_b32_e32 v53, v147
	v_mov_b32_e32 v54, v147
	v_mov_b32_e32 v55, v147
	v_mov_b32_e32 v8, v147
	v_mov_b32_e32 v9, v147
	v_mov_b32_e32 v10, v147
	v_mov_b32_e32 v11, v147
	v_mov_b32_e32 v12, v147
	v_mov_b32_e32 v13, v147
	v_mov_b32_e32 v14, v147
	v_mov_b32_e32 v15, v147
	v_mov_b32_e32 v24, v147
	v_mov_b32_e32 v25, v147
	v_mov_b32_e32 v26, v147
	v_mov_b32_e32 v27, v147
	v_mov_b32_e32 v28, v147
	v_mov_b32_e32 v29, v147
	v_mov_b32_e32 v30, v147
	v_mov_b32_e32 v31, v147
	v_mov_b32_e32 v40, v147
	v_mov_b32_e32 v41, v147
	v_mov_b32_e32 v42, v147
	v_mov_b32_e32 v43, v147
	v_mov_b32_e32 v44, v147
	v_mov_b32_e32 v45, v147
	v_mov_b32_e32 v46, v147
	v_mov_b32_e32 v47, v147
	v_mov_b32_e32 v56, v147
	v_mov_b32_e32 v57, v147
	v_mov_b32_e32 v58, v147
	v_mov_b32_e32 v59, v147
	v_mov_b32_e32 v60, v147
	v_mov_b32_e32 v61, v147
	v_mov_b32_e32 v62, v147
	v_mov_b32_e32 v63, v147
	v_mov_b32_e32 v64, v147
	v_mov_b32_e32 v65, v147
	v_mov_b32_e32 v66, v147
	v_mov_b32_e32 v67, v147
	v_mov_b32_e32 v68, v147
	v_mov_b32_e32 v69, v147
	v_mov_b32_e32 v70, v147
	v_mov_b32_e32 v71, v147
	v_mov_b32_e32 v80, v147
	v_mov_b32_e32 v81, v147
	v_mov_b32_e32 v82, v147
	v_mov_b32_e32 v83, v147
	v_mov_b32_e32 v84, v147
	v_mov_b32_e32 v85, v147
	v_mov_b32_e32 v86, v147
	v_mov_b32_e32 v87, v147
	v_mov_b32_e32 v112, v147
	v_mov_b32_e32 v113, v147
	v_mov_b32_e32 v114, v147
	v_mov_b32_e32 v115, v147
	v_mov_b32_e32 v116, v147
	v_mov_b32_e32 v117, v147
	v_mov_b32_e32 v118, v147
	v_mov_b32_e32 v119, v147
	v_mov_b32_e32 v128, v147
	v_mov_b32_e32 v129, v147
	v_mov_b32_e32 v130, v147
	v_mov_b32_e32 v131, v147
	v_mov_b32_e32 v132, v147
	v_mov_b32_e32 v133, v147
	v_mov_b32_e32 v134, v147
	v_mov_b32_e32 v135, v147
	v_mov_b32_e32 v72, v147
	v_mov_b32_e32 v73, v147
	v_mov_b32_e32 v74, v147
	v_mov_b32_e32 v75, v147
	v_mov_b32_e32 v76, v147
	v_mov_b32_e32 v77, v147
	v_mov_b32_e32 v78, v147
	v_mov_b32_e32 v79, v147
	v_mov_b32_e32 v88, v147
	v_mov_b32_e32 v89, v147
	v_mov_b32_e32 v90, v147
	v_mov_b32_e32 v91, v147
	v_mov_b32_e32 v92, v147
	v_mov_b32_e32 v93, v147
	v_mov_b32_e32 v94, v147
	v_mov_b32_e32 v95, v147
	v_mov_b32_e32 v120, v147
	v_mov_b32_e32 v121, v147
	v_mov_b32_e32 v122, v147
	v_mov_b32_e32 v123, v147
	v_mov_b32_e32 v124, v147
	v_mov_b32_e32 v125, v147
	v_mov_b32_e32 v126, v147
	v_mov_b32_e32 v127, v147
	v_mov_b32_e32 v136, v147
	v_mov_b32_e32 v137, v147
	v_mov_b32_e32 v138, v147
	v_mov_b32_e32 v139, v147
	v_mov_b32_e32 v140, v147
	v_mov_b32_e32 v141, v147
	v_mov_b32_e32 v142, v147
	v_mov_b32_e32 v143, v147
	s_barrier
; #define PG8_STAGE(bufoff, gbase, voff) do { _Pragma("unroll") for (int _i = 0; _i < 2; ++_i) \
;         __builtin_amdgcn_global_load_lds((const unsigned*)((const char*)(gbase) + (voff)[_i]), (PG8_LAS unsigned*)(lds + (bufoff) + ldsw + _i * 8192), 16, 0, 0); } while (0)
; #define PG8_LDA(dst, b, h) do { _Pragma("unroll") for (int m = 0; m < 4; ++m) _Pragma("unroll") for (int k = 0; k < 2; ++k) dst[m][k] = *(const PG8_LAS bf16x8*)(lds + PG8_SA(b, h) + aoff + m * 2048 + k * 1024); } while (0)
; #define PG8_LDB(dst, b, h) do { _Pragma("unroll") for (int n = 0; n < 2; ++n) _Pragma("unroll") for (int k = 0; k < 2; ++k) dst[n][k] = *(const PG8_LAS bf16x8*)(lds + PG8_SB(b, h) + boff + n * 2048 + k * 1024); } while (0)
; #define PG8_MMA(ai, bj, At, Bt) do { __builtin_amdgcn_s_setprio(1); _Pragma("unroll") for (int m = 0; m < 4; ++m) _Pragma("unroll") for (int n = 0; n < 2; ++n) _Pragma("unroll") for (int k = 0; k < 2; ++k) \
;         acc[ai][bj][m][n] = __builtin_amdgcn_mfma_f32_16x16x32_bf16(Bt[n][k], At[m][k], acc[ai][bj][m][n], 0, 0, 0); __builtin_amdgcn_s_setprio(0); } while (0)
; #define PG8_WAIT_V(n) asm volatile("s_waitcnt vmcnt(" #n ")" ::: "memory")
; #define PG8_WAIT_L(n) asm volatile("s_waitcnt lgkmcnt(" #n ")" ::: "memory")
; template <class Epi, class Sched, bool ALIGN_EPI = false, bool SP2 = false>
; __device__ __forceinline__ void gemm_phase(PG8_LAS unsigned char* lds, const Gemm g, const Sched& S, const Epi& E) {
;     ...
;         const char* nA = has_next ? PG8_UA(nxt) : cA; const char* nB = has_next ? PG8_UB(nxt) : cB;
;         for (int t = 0; t < nt; t += 2) {
;             const bool last = (t == nt - 2);
;             const char* a1 = cA + (size_t)(t + 1) * kstep;
;             const char* a2 = last ? nA : cA + (size_t)(t + 2) * kstep; const char* b2 = last ? nB : cB + (size_t)(t + 2) * kstep;
;             const char* a3 = a2 + kstep; const char* b3 = b2 + kstep;
;             if (last && has_next) S.a_ready(nxt);
;             if constexpr (SP2) {
;             PG8_LDB(B0, 0, 0); PG8_LDB(B1, 0, 1); PG8_SCHED; PG8_LDA(At, 0, 0); PG8_STAGE(PG8_SA(1, 1), a1 + hstepA, voffA);
;             PG8_WAIT_V(8); PG8_WAIT_L(0); PG8_BAR; PG8_MMA(0, 0, At, B0); PG8_MMA(0, 1, At, B1); PG8_BAR; PG8_SCHED;
;             PG8_LDA(At, 0, 1); PG8_STAGE(PG8_SB(0, 0), b2, voffB); PG8_STAGE(PG8_SB(0, 1), b2 + hstepB, voffB); PG8_STAGE(PG8_SA(0, 0), a2, voffA);
.LBB0_1422:
	ds_read_b128 v[102:105], v96
	ds_read_b128 v[106:109], v96 offset:1024
	ds_read_b128 v[154:157], v96 offset:2048
	ds_read_b128 v[162:165], v96 offset:3072
	ds_read_b128 v[166:169], v97
	ds_read_b128 v[170:173], v97 offset:1024
	ds_read_b128 v[174:177], v97 offset:2048
	ds_read_b128 v[178:181], v97 offset:3072
	s_add_i32 s26, s53, 0x100
	s_and_b64 s[24:25], s[24:25], exec
	s_cselect_b32 s24, 0, s26
	s_cselect_b32 s25, 0, 0
	s_add_u32 s26, s6, s24
	s_addc_u32 s27, s7, s25
	s_add_u32 s24, s4, s24
	s_addc_u32 s25, s5, s25
	s_add_u32 s54, s18, s53
	s_addc_u32 s55, s19, 0
	v_lshl_add_u64 v[110:111], s[54:55], 0, v[144:145]
	s_mov_b32 m0, s43
	v_lshl_add_u64 v[110:111], v[110:111], 0, s[20:21]
	ds_read_b128 v[182:185], v98
	ds_read_b128 v[186:189], v98 offset:1024
	ds_read_b128 v[196:199], v98 offset:2048
	ds_read_b128 v[200:203], v98 offset:3072
	ds_read_b128 v[204:207], v98 offset:4096
	ds_read_b128 v[208:211], v98 offset:5120
	ds_read_b128 v[212:215], v98 offset:6144
	ds_read_b128 v[216:219], v98 offset:7168
	global_load_lds_dwordx4 v[110:111], off
	v_lshl_add_u64 v[110:111], s[54:55], 0, v[148:149]
	v_lshl_add_u64 v[110:111], v[110:111], 0, s[20:21]
	s_mov_b32 m0, s44
	s_nop 0
	global_load_lds_dwordx4 v[110:111], off
	s_waitcnt vmcnt(8)
	s_waitcnt lgkmcnt(0)
	s_barrier
	s_setprio 1
	s_waitcnt lgkmcnt(0)
	v_mfma_f32_16x16x32_bf16 v[140:143], v[102:105], v[182:185], v[140:143]
	v_mfma_f32_16x16x32_bf16 v[136:139], v[154:157], v[182:185], v[136:139]
	v_mfma_f32_16x16x32_bf16 v[124:127], v[102:105], v[196:199], v[124:127]
	v_mfma_f32_16x16x32_bf16 v[120:123], v[154:157], v[196:199], v[120:123]
	v_mfma_f32_16x16x32_bf16 v[92:95], v[102:105], v[204:207], v[92:95]
	v_mfma_f32_16x16x32_bf16 v[88:91], v[154:157], v[204:207], v[88:91]
	v_mfma_f32_16x16x32_bf16 v[76:79], v[102:105], v[212:215], v[76:79]
	v_mfma_f32_16x16x32_bf16 v[72:75], v[154:157], v[212:215], v[72:75]
	v_mfma_f32_16x16x32_bf16 v[140:143], v[106:109], v[186:189], v[140:143]
	v_mfma_f32_16x16x32_bf16 v[136:139], v[162:165], v[186:189], v[136:139]
	v_mfma_f32_16x16x32_bf16 v[124:127], v[106:109], v[200:203], v[124:127]
	v_mfma_f32_16x16x32_bf16 v[120:123], v[162:165], v[200:203], v[120:123]
	v_mfma_f32_16x16x32_bf16 v[92:95], v[106:109], v[208:211], v[92:95]
	v_mfma_f32_16x16x32_bf16 v[88:91], v[162:165], v[208:211], v[88:91]
	v_mfma_f32_16x16x32_bf16 v[76:79], v[106:109], v[216:219], v[76:79]
	v_mfma_f32_16x16x32_bf16 v[72:75], v[162:165], v[216:219], v[72:75]
	s_setprio 0
	s_setprio 1
	v_mfma_f32_16x16x32_bf16 v[132:135], v[166:169], v[182:185], v[132:135]
	v_mfma_f32_16x16x32_bf16 v[128:131], v[174:177], v[182:185], v[128:131]
	v_mfma_f32_16x16x32_bf16 v[116:119], v[166:169], v[196:199], v[116:119]
	v_mfma_f32_16x16x32_bf16 v[110:113], v[174:177], v[196:199], v[112:115]
	v_mfma_f32_16x16x32_bf16 v[84:87], v[166:169], v[204:207], v[84:87]
	v_mfma_f32_16x16x32_bf16 v[80:83], v[174:177], v[204:207], v[80:83]
	v_mfma_f32_16x16x32_bf16 v[68:71], v[166:169], v[212:215], v[68:71]
	v_mfma_f32_16x16x32_bf16 v[64:67], v[174:177], v[212:215], v[64:67]
	v_mfma_f32_16x16x32_bf16 v[132:135], v[170:173], v[186:189], v[132:135]
	v_mfma_f32_16x16x32_bf16 v[128:131], v[178:181], v[186:189], v[128:131]
	v_mfma_f32_16x16x32_bf16 v[116:119], v[170:173], v[200:203], v[116:119]
	v_mfma_f32_16x16x32_bf16 v[110:113], v[178:181], v[200:203], v[110:113]
	v_mfma_f32_16x16x32_bf16 v[84:87], v[170:173], v[208:211], v[84:87]
	v_mfma_f32_16x16x32_bf16 v[80:83], v[178:181], v[208:211], v[80:83]
	v_mfma_f32_16x16x32_bf16 v[68:71], v[170:173], v[216:219], v[68:71]
	v_mfma_f32_16x16x32_bf16 v[64:67], v[178:181], v[216:219], v[64:67]
	s_setprio 0
	s_barrier
	s_mov_b32 m0, s45
	v_lshl_add_u64 v[158:159], s[24:25], 0, v[146:147]
	s_add_u32 s54, s24, 0x10000
	ds_read_b128 v[182:185], v98 offset:16384
	ds_read_b128 v[186:189], v98 offset:17408
	ds_read_b128 v[196:199], v98 offset:18432
	ds_read_b128 v[200:203], v98 offset:19456
	ds_read_b128 v[204:207], v98 offset:20480
	ds_read_b128 v[208:211], v98 offset:21504
	ds_read_b128 v[212:215], v98 offset:22528
	ds_read_b128 v[216:219], v98 offset:23552
	global_load_lds_dwordx4 v[158:159], off
	v_lshl_add_u64 v[190:191], s[24:25], 0, v[150:151]
	s_mov_b32 m0, s46
	s_addc_u32 s55, s25, 0
	global_load_lds_dwordx4 v[190:191], off
	s_mov_b32 m0, s47
	v_lshl_add_u64 v[220:221], s[26:27], 0, v[144:145]
	global_load_lds_dwordx4 v146, s[54:55]
	s_mov_b32 m0, s48
	v_lshl_add_u64 v[222:223], s[26:27], 0, v[148:149]
	global_load_lds_dwordx4 v150, s[54:55]
	s_mov_b32 m0, s2
	s_nop 0
	global_load_lds_dwordx4 v[220:221], off
	s_mov_b32 m0, s3
	s_nop 0
	global_load_lds_dwordx4 v[222:223], off
	s_waitcnt vmcnt(8)
	s_waitcnt lgkmcnt(0)
	s_barrier
; #define PG8_STAGE(bufoff, gbase, voff) do { _Pragma("unroll") for (int _i = 0; _i < 2; ++_i) \
;         __builtin_amdgcn_global_load_lds((const unsigned*)((const char*)(gbase) + (voff)[_i]), (PG8_LAS unsigned*)(lds + (bufoff) + ldsw + _i * 8192), 16, 0, 0); } while (0)
; #define PG8_LDA(dst, b, h) do { _Pragma("unroll") for (int m = 0; m < 4; ++m) _Pragma("unroll") for (int k = 0; k < 2; ++k) dst[m][k] = *(const PG8_LAS bf16x8*)(lds + PG8_SA(b, h) + aoff + m * 2048 + k * 1024); } while (0)
; #define PG8_LDB(dst, b, h) do { _Pragma("unroll") for (int n = 0; n < 2; ++n) _Pragma("unroll") for (int k = 0; k < 2; ++k) dst[n][k] = *(const PG8_LAS bf16x8*)(lds + PG8_SB(b, h) + boff + n * 2048 + k * 1024); } while (0)
; #define PG8_MMA(ai, bj, At, Bt) do { __builtin_amdgcn_s_setprio(1); _Pragma("unroll") for (int m = 0; m < 4; ++m) _Pragma("unroll") for (int n = 0; n < 2; ++n) _Pragma("unroll") for (int k = 0; k < 2; ++k) \
;         acc[ai][bj][m][n] = __builtin_amdgcn_mfma_f32_16x16x32_bf16(Bt[n][k], At[m][k], acc[ai][bj][m][n], 0, 0, 0); __builtin_amdgcn_s_setprio(0); } while (0)
; #define PG8_WAIT_V(n) asm volatile("s_waitcnt vmcnt(" #n ")" ::: "memory")
; #define PG8_WAIT_L(n) asm volatile("s_waitcnt lgkmcnt(" #n ")" ::: "memory")
; #define PG8_BAR __builtin_amdgcn_s_barrier()
; #define PG8_SCHED __builtin_amdgcn_sched_barrier(0)
; template <class Epi, class Sched, bool ALIGN_EPI = false, bool SP2 = false>
; __device__ __forceinline__ void gemm_phase(PG8_LAS unsigned char* lds, const Gemm g, const Sched& S, const Epi& E) {
;     ...
;             PG8_WAIT_V(8); PG8_WAIT_L(0); PG8_BAR; PG8_MMA(1, 0, At, B0); PG8_MMA(1, 1, At, B1); PG8_BAR; PG8_SCHED;
;             PG8_LDB(B0, 1, 0); PG8_LDB(B1, 1, 1); PG8_SCHED; PG8_LDA(At, 1, 0); PG8_STAGE(PG8_SA(0, 1), a2 + hstepA, voffA);
;             PG8_WAIT_V(8); PG8_WAIT_L(0); PG8_BAR; PG8_MMA(0, 0, At, B0); PG8_MMA(0, 1, At, B1); PG8_BAR; PG8_SCHED;
	s_setprio 1
	s_waitcnt lgkmcnt(0)
	v_mfma_f32_16x16x32_bf16 v[60:63], v[102:105], v[182:185], v[60:63]
	v_mfma_f32_16x16x32_bf16 v[56:59], v[154:157], v[182:185], v[56:59]
	v_mfma_f32_16x16x32_bf16 v[44:47], v[102:105], v[196:199], v[44:47]
	v_mfma_f32_16x16x32_bf16 v[40:43], v[154:157], v[196:199], v[40:43]
	v_mfma_f32_16x16x32_bf16 v[28:31], v[102:105], v[204:207], v[28:31]
	v_mfma_f32_16x16x32_bf16 v[24:27], v[154:157], v[204:207], v[24:27]
	v_mfma_f32_16x16x32_bf16 v[12:15], v[102:105], v[212:215], v[12:15]
	v_mfma_f32_16x16x32_bf16 v[8:11], v[154:157], v[212:215], v[8:11]
	v_mfma_f32_16x16x32_bf16 v[60:63], v[106:109], v[186:189], v[60:63]
	v_mfma_f32_16x16x32_bf16 v[56:59], v[162:165], v[186:189], v[56:59]
	v_mfma_f32_16x16x32_bf16 v[44:47], v[106:109], v[200:203], v[44:47]
	v_mfma_f32_16x16x32_bf16 v[40:43], v[162:165], v[200:203], v[40:43]
	v_mfma_f32_16x16x32_bf16 v[28:31], v[106:109], v[208:211], v[28:31]
	v_mfma_f32_16x16x32_bf16 v[24:27], v[162:165], v[208:211], v[24:27]
	v_mfma_f32_16x16x32_bf16 v[12:15], v[106:109], v[216:219], v[12:15]
	v_mfma_f32_16x16x32_bf16 v[8:11], v[162:165], v[216:219], v[8:11]
	s_setprio 0
	s_setprio 1
	v_mfma_f32_16x16x32_bf16 v[52:55], v[166:169], v[182:185], v[52:55]
	v_mfma_f32_16x16x32_bf16 v[48:51], v[174:177], v[182:185], v[48:51]
	v_mfma_f32_16x16x32_bf16 v[36:39], v[166:169], v[196:199], v[36:39]
	v_mfma_f32_16x16x32_bf16 v[32:35], v[174:177], v[196:199], v[32:35]
	v_mfma_f32_16x16x32_bf16 v[20:23], v[166:169], v[204:207], v[20:23]
	v_mfma_f32_16x16x32_bf16 v[16:19], v[174:177], v[204:207], v[16:19]
	v_mfma_f32_16x16x32_bf16 v[4:7], v[166:169], v[212:215], v[4:7]
	v_mfma_f32_16x16x32_bf16 v[0:3], v[174:177], v[212:215], v[0:3]
	v_mfma_f32_16x16x32_bf16 v[52:55], v[170:173], v[186:189], v[52:55]
	v_mfma_f32_16x16x32_bf16 v[48:51], v[178:181], v[186:189], v[48:51]
	v_mfma_f32_16x16x32_bf16 v[36:39], v[170:173], v[200:203], v[36:39]
	v_mfma_f32_16x16x32_bf16 v[32:35], v[178:181], v[200:203], v[32:35]
	v_mfma_f32_16x16x32_bf16 v[20:23], v[170:173], v[208:211], v[20:23]
	v_mfma_f32_16x16x32_bf16 v[16:19], v[178:181], v[208:211], v[16:19]
	v_mfma_f32_16x16x32_bf16 v[4:7], v[170:173], v[216:219], v[4:7]
	v_mfma_f32_16x16x32_bf16 v[0:3], v[178:181], v[216:219], v[0:3]
	s_setprio 0
	s_barrier
	ds_read_b128 v[102:105], v99
	ds_read_b128 v[106:109], v99 offset:1024
	ds_read_b128 v[154:157], v99 offset:2048
	ds_read_b128 v[162:165], v99 offset:3072
	ds_read_b128 v[166:169], v100
	ds_read_b128 v[170:173], v100 offset:1024
	ds_read_b128 v[174:177], v100 offset:2048
	ds_read_b128 v[178:181], v100 offset:3072
	s_add_u32 s26, s26, 0x40000
	s_addc_u32 s27, s27, 0
	s_mov_b32 m0, s33
	v_lshl_add_u64 v[114:115], s[26:27], 0, v[144:145]
	ds_read_b128 v[182:185], v98 offset:32768
	ds_read_b128 v[186:189], v98 offset:33792
	ds_read_b128 v[196:199], v98 offset:34816
	ds_read_b128 v[200:203], v98 offset:35840
	ds_read_b128 v[204:207], v98 offset:36864
	ds_read_b128 v[208:211], v98 offset:37888
	ds_read_b128 v[212:215], v98 offset:38912
	ds_read_b128 v[216:219], v98 offset:39936
	global_load_lds_dwordx4 v[114:115], off
	v_lshl_add_u64 v[114:115], s[26:27], 0, v[148:149]
	s_mov_b32 m0, s36
	s_nop 0
	global_load_lds_dwordx4 v[114:115], off
	s_waitcnt vmcnt(8)
	s_waitcnt lgkmcnt(0)
	s_barrier
	s_setprio 1
	s_waitcnt lgkmcnt(0)
	v_mfma_f32_16x16x32_bf16 v[140:143], v[102:105], v[182:185], v[140:143]
	v_mfma_f32_16x16x32_bf16 v[136:139], v[154:157], v[182:185], v[136:139]
	v_mfma_f32_16x16x32_bf16 v[124:127], v[102:105], v[196:199], v[124:127]
	v_mfma_f32_16x16x32_bf16 v[120:123], v[154:157], v[196:199], v[120:123]
	v_mfma_f32_16x16x32_bf16 v[92:95], v[102:105], v[204:207], v[92:95]
	v_mfma_f32_16x16x32_bf16 v[88:91], v[154:157], v[204:207], v[88:91]
	v_mfma_f32_16x16x32_bf16 v[76:79], v[102:105], v[212:215], v[76:79]
	v_mfma_f32_16x16x32_bf16 v[72:75], v[154:157], v[212:215], v[72:75]
	v_mfma_f32_16x16x32_bf16 v[140:143], v[106:109], v[186:189], v[140:143]
	v_mfma_f32_16x16x32_bf16 v[136:139], v[162:165], v[186:189], v[136:139]
	v_mfma_f32_16x16x32_bf16 v[124:127], v[106:109], v[200:203], v[124:127]
	v_mfma_f32_16x16x32_bf16 v[120:123], v[162:165], v[200:203], v[120:123]
	v_mfma_f32_16x16x32_bf16 v[92:95], v[106:109], v[208:211], v[92:95]
	v_mfma_f32_16x16x32_bf16 v[88:91], v[162:165], v[208:211], v[88:91]
	v_mfma_f32_16x16x32_bf16 v[76:79], v[106:109], v[216:219], v[76:79]
	v_mfma_f32_16x16x32_bf16 v[72:75], v[162:165], v[216:219], v[72:75]
	s_setprio 0
	s_setprio 1
	v_mfma_f32_16x16x32_bf16 v[132:135], v[166:169], v[182:185], v[132:135]
	v_mfma_f32_16x16x32_bf16 v[128:131], v[174:177], v[182:185], v[128:131]
	v_mfma_f32_16x16x32_bf16 v[114:117], v[166:169], v[196:199], v[116:119]
	v_mfma_f32_16x16x32_bf16 v[110:113], v[174:177], v[196:199], v[110:113]
	v_mfma_f32_16x16x32_bf16 v[84:87], v[166:169], v[204:207], v[84:87]
	v_mfma_f32_16x16x32_bf16 v[80:83], v[174:177], v[204:207], v[80:83]
	v_mfma_f32_16x16x32_bf16 v[68:71], v[166:169], v[212:215], v[68:71]
	v_mfma_f32_16x16x32_bf16 v[64:67], v[174:177], v[212:215], v[64:67]
	v_mfma_f32_16x16x32_bf16 v[132:135], v[170:173], v[186:189], v[132:135]
	v_mfma_f32_16x16x32_bf16 v[128:131], v[178:181], v[186:189], v[128:131]
	v_mfma_f32_16x16x32_bf16 v[116:119], v[170:173], v[200:203], v[114:117]
	v_mfma_f32_16x16x32_bf16 v[112:115], v[178:181], v[200:203], v[110:113]
	v_mfma_f32_16x16x32_bf16 v[84:87], v[170:173], v[208:211], v[84:87]
	v_mfma_f32_16x16x32_bf16 v[80:83], v[178:181], v[208:211], v[80:83]
	v_mfma_f32_16x16x32_bf16 v[68:71], v[170:173], v[216:219], v[68:71]
	v_mfma_f32_16x16x32_bf16 v[64:67], v[178:181], v[216:219], v[64:67]
	s_setprio 0
	s_barrier
; #define PG8_STAGE(bufoff, gbase, voff) do { _Pragma("unroll") for (int _i = 0; _i < 2; ++_i) \
;         __builtin_amdgcn_global_load_lds((const unsigned*)((const char*)(gbase) + (voff)[_i]), (PG8_LAS unsigned*)(lds + (bufoff) + ldsw + _i * 8192), 16, 0, 0); } while (0)
; #define PG8_LDA(dst, b, h) do { _Pragma("unroll") for (int m = 0; m < 4; ++m) _Pragma("unroll") for (int k = 0; k < 2; ++k) dst[m][k] = *(const PG8_LAS bf16x8*)(lds + PG8_SA(b, h) + aoff + m * 2048 + k * 1024); } while (0)
; #define PG8_MMA(ai, bj, At, Bt) do { __builtin_amdgcn_s_setprio(1); _Pragma("unroll") for (int m = 0; m < 4; ++m) _Pragma("unroll") for (int n = 0; n < 2; ++n) _Pragma("unroll") for (int k = 0; k < 2; ++k) \
;         acc[ai][bj][m][n] = __builtin_amdgcn_mfma_f32_16x16x32_bf16(Bt[n][k], At[m][k], acc[ai][bj][m][n], 0, 0, 0); __builtin_amdgcn_s_setprio(0); } while (0)
; #define PG8_WAIT_V(n) asm volatile("s_waitcnt vmcnt(" #n ")" ::: "memory")
; #define PG8_WAIT_L(n) asm volatile("s_waitcnt lgkmcnt(" #n ")" ::: "memory")
; #define PG8_BAR __builtin_amdgcn_s_barrier()
; #define PG8_SCHED __builtin_amdgcn_sched_barrier(0)
; template <class Epi, class Sched, bool ALIGN_EPI = false, bool SP2 = false>
; __device__ __forceinline__ void gemm_phase(PG8_LAS unsigned char* lds, const Gemm g, const Sched& S, const Epi& E) {
;     ...
;             PG8_LDA(At, 1, 1); PG8_STAGE(PG8_SB(1, 0), b3, voffB); PG8_STAGE(PG8_SB(1, 1), b3 + hstepB, voffB); PG8_STAGE(PG8_SA(1, 0), a3, voffA);
;             PG8_WAIT_V(8); PG8_WAIT_L(0); PG8_BAR; PG8_MMA(1, 0, At, B0); PG8_MMA(1, 1, At, B1); PG8_BAR; PG8_SCHED;
;     ...
;     PG8_WAIT_V(0);
;     if constexpr (!ALIGN_EPI) { if (wr == 0) PG8_BAR; }
;     PG8_BAR;
	s_mov_b32 m0, s49
	v_lshl_add_u64 v[110:111], v[158:159], 0, s[20:21]
	s_add_u32 s24, s24, 0x10080
	ds_read_b128 v[182:185], v98 offset:49152
	ds_read_b128 v[186:189], v98 offset:50176
	ds_read_b128 v[196:199], v98 offset:51200
	ds_read_b128 v[200:203], v98 offset:52224
	ds_read_b128 v[204:207], v98 offset:53248
	ds_read_b128 v[208:211], v98 offset:54272
	ds_read_b128 v[212:215], v98 offset:55296
	ds_read_b128 v[216:219], v98 offset:56320
	global_load_lds_dwordx4 v[110:111], off
	v_lshl_add_u64 v[110:111], v[190:191], 0, s[20:21]
	s_mov_b32 m0, s50
	s_addc_u32 s25, s25, 0
	global_load_lds_dwordx4 v[110:111], off
	s_mov_b32 m0, s51
	s_nop 0
	global_load_lds_dwordx4 v146, s[24:25]
	s_mov_b32 m0, s52
	s_nop 0
	global_load_lds_dwordx4 v150, s[24:25]
	v_lshl_add_u64 v[110:111], v[220:221], 0, s[20:21]
	s_mov_b32 m0, s37
	s_nop 0
	global_load_lds_dwordx4 v[110:111], off
	v_lshl_add_u64 v[110:111], v[222:223], 0, s[20:21]
	s_mov_b32 m0, s40
	s_nop 0
	global_load_lds_dwordx4 v[110:111], off
	s_waitcnt vmcnt(8)
	s_waitcnt lgkmcnt(0)
	s_barrier
	s_setprio 1
	s_waitcnt lgkmcnt(0)
	v_mfma_f32_16x16x32_bf16 v[60:63], v[102:105], v[182:185], v[60:63]
	v_mfma_f32_16x16x32_bf16 v[56:59], v[154:157], v[182:185], v[56:59]
	v_mfma_f32_16x16x32_bf16 v[44:47], v[102:105], v[196:199], v[44:47]
	v_mfma_f32_16x16x32_bf16 v[40:43], v[154:157], v[196:199], v[40:43]
	v_mfma_f32_16x16x32_bf16 v[28:31], v[102:105], v[204:207], v[28:31]
	v_mfma_f32_16x16x32_bf16 v[24:27], v[154:157], v[204:207], v[24:27]
	v_mfma_f32_16x16x32_bf16 v[12:15], v[102:105], v[212:215], v[12:15]
	v_mfma_f32_16x16x32_bf16 v[8:11], v[154:157], v[212:215], v[8:11]
	v_mfma_f32_16x16x32_bf16 v[60:63], v[106:109], v[186:189], v[60:63]
	v_mfma_f32_16x16x32_bf16 v[56:59], v[162:165], v[186:189], v[56:59]
	v_mfma_f32_16x16x32_bf16 v[44:47], v[106:109], v[200:203], v[44:47]
	v_mfma_f32_16x16x32_bf16 v[40:43], v[162:165], v[200:203], v[40:43]
	v_mfma_f32_16x16x32_bf16 v[28:31], v[106:109], v[208:211], v[28:31]
	v_mfma_f32_16x16x32_bf16 v[24:27], v[162:165], v[208:211], v[24:27]
	v_mfma_f32_16x16x32_bf16 v[12:15], v[106:109], v[216:219], v[12:15]
	v_mfma_f32_16x16x32_bf16 v[8:11], v[162:165], v[216:219], v[8:11]
	s_setprio 0
	s_setprio 1
	v_mfma_f32_16x16x32_bf16 v[52:55], v[166:169], v[182:185], v[52:55]
	v_mfma_f32_16x16x32_bf16 v[48:51], v[174:177], v[182:185], v[48:51]
	v_mfma_f32_16x16x32_bf16 v[36:39], v[166:169], v[196:199], v[36:39]
	v_mfma_f32_16x16x32_bf16 v[32:35], v[174:177], v[196:199], v[32:35]
	v_mfma_f32_16x16x32_bf16 v[20:23], v[166:169], v[204:207], v[20:23]
	v_mfma_f32_16x16x32_bf16 v[16:19], v[174:177], v[204:207], v[16:19]
	v_mfma_f32_16x16x32_bf16 v[4:7], v[166:169], v[212:215], v[4:7]
	v_mfma_f32_16x16x32_bf16 v[0:3], v[174:177], v[212:215], v[0:3]
	v_mfma_f32_16x16x32_bf16 v[52:55], v[170:173], v[186:189], v[52:55]
	v_mfma_f32_16x16x32_bf16 v[48:51], v[178:181], v[186:189], v[48:51]
	v_mfma_f32_16x16x32_bf16 v[36:39], v[170:173], v[200:203], v[36:39]
	v_mfma_f32_16x16x32_bf16 v[32:35], v[178:181], v[200:203], v[32:35]
	v_mfma_f32_16x16x32_bf16 v[20:23], v[170:173], v[208:211], v[20:23]
	v_mfma_f32_16x16x32_bf16 v[16:19], v[178:181], v[208:211], v[16:19]
	v_mfma_f32_16x16x32_bf16 v[4:7], v[170:173], v[216:219], v[4:7]
	v_mfma_f32_16x16x32_bf16 v[0:3], v[178:181], v[216:219], v[0:3]
	s_setprio 0
	s_barrier
	s_and_b64 vcc, exec, s[22:23]
	s_mov_b64 s[24:25], -1
	s_mov_b64 s[22:23], 0
	s_movk_i32 s53, 0x100
	s_cbranch_vccnz .LBB0_1422
	s_waitcnt vmcnt(0)
	s_cmpk_gt_u32 s41, 0xff
	s_cbranch_scc1 .LBB0_1425
	s_barrier

; #define PG8_STAGE(bufoff, gbase, voff) do { _Pragma("unroll") for (int _i = 0; _i < 2; ++_i) \
;         __builtin_amdgcn_global_load_lds((const unsigned*)((const char*)(gbase) + (voff)[_i]), (PG8_LAS unsigned*)(lds + (bufoff) + ldsw + _i * 8192), 16, 0, 0); } while (0)
; #define PG8_WAIT_V(n) asm volatile("s_waitcnt vmcnt(" #n ")" ::: "memory")
; #define PG8_BAR __builtin_amdgcn_s_barrier()
; template <class Epi, class Sched, bool ALIGN_EPI = false, bool SP2 = false>
; __device__ __forceinline__ void gemm_phase(PG8_LAS unsigned char* lds, const Gemm g, const Sched& S, const Epi& E) {
;     ...
;         PG8_STAGE(PG8_SB(1, 0), cB + kstep, voffB); PG8_STAGE(PG8_SA(1, 0), cA + kstep, voffA); PG8_STAGE(PG8_SB(1, 1), cB + hstepB + kstep, voffB);
;         PG8_WAIT_V(6); PG8_BAR;
;     __device__ __forceinline__ void operator()(const f32x4 (&acc)[2][2][4][2], const Unit& u, int wr, int wc, int fr, int fq) const {
;     ...
;             const int hc = (u.pn * BM + colt) >> 1; const float r = 1.f / sqrtf(rstd[row] * (1.f / DM) + RMS_EPS);
.LBB0_1525:
	s_add_u32 s10, s34, 0x7800000
	s_addc_u32 s11, s35, 0
	s_add_u32 s12, s34, 0x34a0000
	s_addc_u32 s13, s35, 0
	s_lshl_b32 s4, s4, 5
	s_mov_b64 s[14:15], 0x80
	s_and_b32 s18, s4, 0x60
	s_add_i32 m0, s42, 0x18000
	v_lshl_add_u64 v[6:7], v[6:7], 0, s[14:15]
	s_lshl_b32 s1, s3, 13
	s_lshl_b32 s16, s18, 7
	s_waitcnt vmcnt(2)
	s_barrier
	global_load_lds_dwordx4 v[6:7], off
	v_lshl_add_u64 v[4:5], v[4:5], 0, s[14:15]
	s_add_i32 m0, s42, 0x1a000
	s_add_i32 s47, s42, 0x8000
	s_add_i32 s48, s42, 0xa000
	global_load_lds_dwordx4 v[4:5], off
	v_lshl_add_u64 v[0:1], v[0:1], 0, s[14:15]
	s_mov_b32 m0, s47
	s_add_u32 s4, s26, 0x40080
	global_load_lds_dwordx4 v[0:1], off
	v_lshl_add_u64 v[0:1], v[2:3], 0, s[14:15]
	s_mov_b32 m0, s48
	s_addc_u32 s5, s27, 0
	global_load_lds_dwordx4 v[0:1], off
	s_add_i32 m0, s42, 0x1c000
	global_load_lds_dwordx4 v132, s[4:5]
	v_lshl_add_u64 v[0:1], s[4:5], 0, v[128:129]
	s_add_i32 m0, s42, 0x1e000
	v_lshlrev_b32_e32 v2, 2, v194
	global_load_lds_dwordx4 v[0:1], off
	v_and_b32_e32 v0, 15, v194
	v_lshlrev_b32_e32 v1, 1, v11
	v_lshl_or_b32 v146, s3, 6, v0
	v_lshl_or_b32 v0, v0, 6, v1
	v_and_b32_e32 v2, 32, v2
	v_bitop3_b32 v0, v0, s1, v2 bitop3:0xde
	v_lshlrev_b32_e32 v3, 6, v194
	s_movk_i32 s1, 0x3c0
	v_and_or_b32 v1, v3, s1, v1
	v_bitop3_b32 v147, s16, v1, v2 bitop3:0xf6
	v_lshlrev_b32_e32 v1, 8, v194
	v_and_b32_e32 v1, 0x38000, v1
	v_lshlrev_b32_e32 v2, 11, v12
	v_or3_b32 v1, v9, v1, v2
	v_add_u32_e32 v136, v1, v10
	v_lshlrev_b32_e32 v1, 4, v8
	s_waitcnt vmcnt(6)
	s_cmpk_lt_u32 s2, 0x100
	v_and_b32_e32 v1, 0x78000, v1
	s_cselect_b64 s[16:17], -1, 0
	v_readlane_b32 s2, v251, 13
	v_or3_b32 v1, v9, v1, v2
	s_add_i32 s51, 0, 0x10000
	s_add_i32 s52, 0, 0x14000
	s_ashr_i32 s49, s2, 31
	s_mov_b32 s50, s2
	v_or_b32_e32 v148, s18, v11
	v_mov_b32_e32 v137, v133
	v_add_u32_e32 v138, v1, v10
	v_mov_b32_e32 v139, v133
	v_mov_b64_e32 v[140:141], 0xb00
	v_mov_b64_e32 v[142:143], 0xaff
	s_waitcnt vmcnt(0)
	v_add_u32_e32 v149, s51, v147
	v_add_u32_e32 v150, s52, v147
	v_add_u32_e32 v151, 0, v0
	v_mov_b32_e32 v152, 0x358637bd
	s_mov_b32 s53, 0xf800000
	v_mov_b32_e32 v153, 0x260
	s_movk_i32 s54, 0x1680
	v_lshl_add_u32 v246, s0, 8, v146
	v_mov_b32_e32 v247, 0
	v_lshl_add_u64 v[246:247], v[246:247], 2, s[12:13]
	global_load_dword v238, v[246:247], off
	global_load_dword v239, v[246:247], off offset:64
	global_load_dword v240, v[246:247], off offset:128
	global_load_dword v241, v[246:247], off offset:192
	global_load_dword v242, v[246:247], off offset:512
	global_load_dword v243, v[246:247], off offset:576
	global_load_dword v244, v[246:247], off offset:640
	global_load_dword v245, v[246:247], off offset:704
	s_barrier
	v_readlane_b32 s3, v251, 14
	s_branch .LBB0_1528

; #define PG8_STAGE(bufoff, gbase, voff) do { _Pragma("unroll") for (int _i = 0; _i < 2; ++_i) \
;         __builtin_amdgcn_global_load_lds((const unsigned*)((const char*)(gbase) + (voff)[_i]), (PG8_LAS unsigned*)(lds + (bufoff) + ldsw + _i * 8192), 16, 0, 0); } while (0)
; #define PG8_WAIT_V(n) asm volatile("s_waitcnt vmcnt(" #n ")" ::: "memory")
; #define PG8_BAR __builtin_amdgcn_s_barrier()
; template <class Epi, class Sched, bool ALIGN_EPI = false, bool SP2 = false>
; __device__ __forceinline__ void gemm_phase(PG8_LAS unsigned char* lds, const Gemm g, const Sched& S, const Epi& E) {
;     ...
;     f32x4 acc[2][2][4][2];
; #pragma unroll
;     for (int a = 0; a < 2; ++a)
; #pragma unroll
;         for (int b = 0; b < 2; ++b)
; #pragma unroll
;             for (int m = 0; m < 4; ++m)
; #pragma unroll
;                 for (int n = 0; n < 2; ++n) acc[a][b][m][n] = (f32x4){0.f, 0.f, 0.f, 0.f};
;     ...
;         PG8_STAGE(PG8_SB(0, 0), cB, voffB); PG8_STAGE(PG8_SB(0, 1), cB + hstepB, voffB); PG8_STAGE(PG8_SA(0, 0), cA, voffA); PG8_STAGE(PG8_SA(0, 1), cA + hstepA, voffA);
;         if (wr == 1) PG8_BAR;
;         PG8_WAIT_V(2); PG8_BAR;
;         PG8_STAGE(PG8_SB(1, 0), cB + kstep, voffB); PG8_STAGE(PG8_SA(1, 0), cA + kstep, voffA); PG8_STAGE(PG8_SB(1, 1), cB + hstepB + kstep, voffB);
;         PG8_WAIT_V(6); PG8_BAR;
.LBB0_1602:
	v_lshlrev_b32_e32 v9, 2, v157
	s_and_b32 s33, s14, 3
	v_lshl_or_b32 v8, v157, 6, v162
	s_lshl_b32 s14, s36, 13
	v_and_b32_e32 v9, 32, v9
	v_bitop3_b32 v8, v8, s14, v9 bitop3:0xde
	s_mov_b64 s[14:15], 0x80
	s_add_i32 m0, s2, 0x18000
	v_lshl_add_u64 v[6:7], v[6:7], 0, s[14:15]
	s_waitcnt vmcnt(2)
	s_barrier
	global_load_lds_dwordx4 v[6:7], off
	v_lshl_add_u64 v[4:5], v[4:5], 0, s[14:15]
	s_add_i32 m0, s2, 0x1a000
	s_add_i32 s39, s2, 0x8000
	s_add_i32 s40, s2, 0xa000
	global_load_lds_dwordx4 v[4:5], off
	v_lshl_add_u64 v[2:3], v[2:3], 0, s[14:15]
	s_mov_b32 m0, s39
	s_add_u32 s22, s10, 0xb0080
	global_load_lds_dwordx4 v[2:3], off
	v_lshl_add_u64 v[0:1], v[0:1], 0, s[14:15]
	s_mov_b32 m0, s40
	s_addc_u32 s23, s11, 0
	global_load_lds_dwordx4 v[0:1], off
	s_add_i32 m0, s2, 0x1c000
	global_load_lds_dwordx4 v146, s[22:23]
	v_lshl_add_u64 v[0:1], s[22:23], 0, v[150:151]
	s_add_i32 m0, s2, 0x1e000
	s_add_u32 s16, s34, s16
	global_load_lds_dwordx4 v[0:1], off
	s_addc_u32 s17, s35, s17
	v_add_u16_e32 v0, v158, v159
	v_lshrrev_b16_e32 v2, 1, v0
	s_add_u32 s19, s34, s19
	v_add_lshl_u32 v0, v160, v2, 1
	v_mov_b32_e32 v1, v147
	s_addc_u32 s18, s35, s18
	v_lshl_add_u64 v[0:1], s[16:17], 0, v[0:1]
	s_mov_b64 s[22:23], 0x78b4080
	s_add_u32 s41, s19, 0x2a00100
	v_lshl_or_b32 v9, s33, 12, v163
	s_waitcnt vmcnt(6)
	v_lshl_add_u64 v[108:109], v[0:1], 0, s[22:23]
	v_add_lshl_u32 v0, v161, v2, 1
	v_mov_b32_e32 v1, v147
	s_addc_u32 s42, s18, 0
	s_add_i32 s46, 0, 0x10000
	s_add_i32 s48, 0, 0x14000
	s_add_i32 s50, 0, 0x18000
	s_add_i32 s52, 0, 0x1c000
	v_lshl_add_u64 v[0:1], s[16:17], 0, v[0:1]
	v_add_u32_e32 v116, s46, v9
	v_add_u32_e32 v117, s48, v9
	s_add_i32 s46, s46, s20
	s_add_i32 s48, s48, s20
	v_add_u32_e32 v119, s50, v9
	v_add_u32_e32 v120, s52, v9
	s_add_i32 s50, s50, s20
	s_add_i32 s52, s52, s20
	v_lshl_or_b32 v152, s36, 6, v157
	v_lshl_add_u64 v[110:111], v[0:1], 0, s[22:23]
	s_mov_b32 s43, -2
	s_mov_b64 s[18:19], 0
	v_add_u32_e32 v118, 0, v8
	s_add_i32 s44, s2, 0xc000
	s_add_i32 s45, s2, 0xe000
	s_add_i32 s47, s46, 0x2000
	s_add_i32 s49, s48, 0x2000
	s_add_i32 s51, s50, 0x2000
	s_add_i32 s53, s52, 0x2000
	v_mov_b32_e32 v0, v147
	v_mov_b32_e32 v1, v147
	v_mov_b32_e32 v2, v147
	v_mov_b32_e32 v3, v147
	v_mov_b32_e32 v4, v147
	v_mov_b32_e32 v5, v147
	v_mov_b32_e32 v6, v147
	v_mov_b32_e32 v7, v147
	v_mov_b32_e32 v16, v147
	v_mov_b32_e32 v17, v147
	v_mov_b32_e32 v18, v147
	v_mov_b32_e32 v19, v147
	v_mov_b32_e32 v20, v147
	v_mov_b32_e32 v21, v147
	v_mov_b32_e32 v22, v147
	v_mov_b32_e32 v23, v147
	v_mov_b32_e32 v32, v147
	v_mov_b32_e32 v33, v147
	v_mov_b32_e32 v34, v147
	v_mov_b32_e32 v35, v147
	v_mov_b32_e32 v36, v147
	v_mov_b32_e32 v37, v147
	v_mov_b32_e32 v38, v147
	v_mov_b32_e32 v39, v147
	v_mov_b32_e32 v48, v147
	v_mov_b32_e32 v49, v147
	v_mov_b32_e32 v50, v147
	v_mov_b32_e32 v51, v147
	v_mov_b32_e32 v52, v147
	v_mov_b32_e32 v53, v147
	v_mov_b32_e32 v54, v147
	v_mov_b32_e32 v55, v147
	v_mov_b32_e32 v8, v147
	v_mov_b32_e32 v9, v147
	v_mov_b32_e32 v10, v147
	v_mov_b32_e32 v11, v147
	v_mov_b32_e32 v12, v147
	v_mov_b32_e32 v13, v147
	v_mov_b32_e32 v14, v147
	v_mov_b32_e32 v15, v147
	v_mov_b32_e32 v24, v147
	v_mov_b32_e32 v25, v147
	v_mov_b32_e32 v26, v147
	v_mov_b32_e32 v27, v147
	v_mov_b32_e32 v28, v147
	v_mov_b32_e32 v29, v147
	v_mov_b32_e32 v30, v147
	v_mov_b32_e32 v31, v147
	v_mov_b32_e32 v40, v147
	v_mov_b32_e32 v41, v147
	v_mov_b32_e32 v42, v147
	v_mov_b32_e32 v43, v147
	v_mov_b32_e32 v44, v147
	v_mov_b32_e32 v45, v147
	v_mov_b32_e32 v46, v147
	v_mov_b32_e32 v47, v147
	v_mov_b32_e32 v56, v147
	v_mov_b32_e32 v57, v147
	v_mov_b32_e32 v58, v147
	v_mov_b32_e32 v59, v147
	v_mov_b32_e32 v60, v147
	v_mov_b32_e32 v61, v147
	v_mov_b32_e32 v62, v147
	v_mov_b32_e32 v63, v147
	v_mov_b32_e32 v64, v147
	v_mov_b32_e32 v65, v147
	v_mov_b32_e32 v66, v147
	v_mov_b32_e32 v67, v147
	v_mov_b32_e32 v68, v147
	v_mov_b32_e32 v69, v147
	v_mov_b32_e32 v70, v147
	v_mov_b32_e32 v71, v147
	v_mov_b32_e32 v80, v147
	v_mov_b32_e32 v81, v147
	v_mov_b32_e32 v82, v147
	v_mov_b32_e32 v83, v147
	v_mov_b32_e32 v84, v147
	v_mov_b32_e32 v85, v147
	v_mov_b32_e32 v86, v147
	v_mov_b32_e32 v87, v147
	v_mov_b32_e32 v96, v147
	v_mov_b32_e32 v97, v147
	v_mov_b32_e32 v98, v147
	v_mov_b32_e32 v99, v147
	v_mov_b32_e32 v100, v147
	v_mov_b32_e32 v101, v147
	v_mov_b32_e32 v102, v147
	v_mov_b32_e32 v103, v147
	v_mov_b32_e32 v128, v147
	v_mov_b32_e32 v129, v147
	v_mov_b32_e32 v130, v147
	v_mov_b32_e32 v131, v147
	v_mov_b32_e32 v132, v147
	v_mov_b32_e32 v133, v147
	v_mov_b32_e32 v134, v147
	v_mov_b32_e32 v135, v147
	v_mov_b32_e32 v72, v147
	v_mov_b32_e32 v73, v147
	v_mov_b32_e32 v74, v147
	v_mov_b32_e32 v75, v147
	v_mov_b32_e32 v76, v147
	v_mov_b32_e32 v77, v147
	v_mov_b32_e32 v78, v147
	v_mov_b32_e32 v79, v147
	v_mov_b32_e32 v88, v147
	v_mov_b32_e32 v89, v147
	v_mov_b32_e32 v90, v147
	v_mov_b32_e32 v91, v147
	v_mov_b32_e32 v92, v147
	v_mov_b32_e32 v93, v147
	v_mov_b32_e32 v94, v147
	v_mov_b32_e32 v95, v147
	v_mov_b32_e32 v104, v147
	v_mov_b32_e32 v105, v147
	v_mov_b32_e32 v106, v147
	v_mov_b32_e32 v107, v147
	v_mov_b32_e32 v112, v147
	v_mov_b32_e32 v113, v147
	v_mov_b32_e32 v114, v147
	v_mov_b32_e32 v115, v147
	v_mov_b32_e32 v136, v147
	v_mov_b32_e32 v137, v147
	v_mov_b32_e32 v138, v147
	v_mov_b32_e32 v139, v147
	v_mov_b32_e32 v140, v147
	v_mov_b32_e32 v141, v147
	v_mov_b32_e32 v142, v147
	v_mov_b32_e32 v143, v147
	s_barrier
; #define PG8_STAGE(bufoff, gbase, voff) do { _Pragma("unroll") for (int _i = 0; _i < 2; ++_i) \
;         __builtin_amdgcn_global_load_lds((const unsigned*)((const char*)(gbase) + (voff)[_i]), (PG8_LAS unsigned*)(lds + (bufoff) + ldsw + _i * 8192), 16, 0, 0); } while (0)
; #define PG8_LDA(dst, b, h) do { _Pragma("unroll") for (int m = 0; m < 4; ++m) _Pragma("unroll") for (int k = 0; k < 2; ++k) dst[m][k] = *(const PG8_LAS bf16x8*)(lds + PG8_SA(b, h) + aoff + m * 2048 + k * 1024); } while (0)
; #define PG8_LDB(dst, b, h) do { _Pragma("unroll") for (int n = 0; n < 2; ++n) _Pragma("unroll") for (int k = 0; k < 2; ++k) dst[n][k] = *(const PG8_LAS bf16x8*)(lds + PG8_SB(b, h) + boff + n * 2048 + k * 1024); } while (0)
; #define PG8_MMA(ai, bj, At, Bt) do { __builtin_amdgcn_s_setprio(1); _Pragma("unroll") for (int m = 0; m < 4; ++m) _Pragma("unroll") for (int n = 0; n < 2; ++n) _Pragma("unroll") for (int k = 0; k < 2; ++k) \
;         acc[ai][bj][m][n] = __builtin_amdgcn_mfma_f32_16x16x32_bf16(Bt[n][k], At[m][k], acc[ai][bj][m][n], 0, 0, 0); __builtin_amdgcn_s_setprio(0); } while (0)
; #define PG8_WAIT_V(n) asm volatile("s_waitcnt vmcnt(" #n ")" ::: "memory")
; #define PG8_WAIT_L(n) asm volatile("s_waitcnt lgkmcnt(" #n ")" ::: "memory")
; #define PG8_BAR __builtin_amdgcn_s_barrier()
; #define PG8_SCHED __builtin_amdgcn_sched_barrier(0)
; template <class Epi, class Sched, bool ALIGN_EPI = false, bool SP2 = false>
; __device__ __forceinline__ void gemm_phase(PG8_LAS unsigned char* lds, const Gemm g, const Sched& S, const Epi& E) {
;     ...
;             PG8_LDB(B0, 0, 0); PG8_LDB(B1, 0, 1); PG8_SCHED; PG8_LDA(At, 0, 0); PG8_STAGE(PG8_SA(1, 1), a1 + hstepA, voffA);
;             PG8_WAIT_V(8); PG8_WAIT_L(0); PG8_BAR; PG8_MMA(0, 0, At, B0); PG8_MMA(0, 1, At, B1); PG8_BAR; PG8_SCHED;
;             PG8_LDA(At, 0, 1); PG8_STAGE(PG8_SB(0, 0), b2, voffB); PG8_STAGE(PG8_SB(0, 1), b2 + hstepB, voffB); PG8_STAGE(PG8_SA(0, 0), a2, voffA);
;             PG8_WAIT_V(8); PG8_WAIT_L(0); PG8_BAR; PG8_MMA(1, 0, At, B0); PG8_MMA(1, 1, At, B1); PG8_BAR; PG8_SCHED;
.LBB0_1603:
	ds_read_b128 v[122:125], v116
	ds_read_b128 v[164:167], v116 offset:1024
	ds_read_b128 v[168:171], v116 offset:2048
	ds_read_b128 v[172:175], v116 offset:3072
	ds_read_b128 v[176:179], v117
	ds_read_b128 v[180:183], v117 offset:1024
	ds_read_b128 v[184:187], v117 offset:2048
	ds_read_b128 v[188:191], v117 offset:3072
	s_add_u32 s20, s16, s18
	s_addc_u32 s21, s17, s19
	s_add_u32 s20, s20, 0x7800100
	s_addc_u32 s21, s21, 0
	s_add_u32 s54, s41, s18
	s_addc_u32 s55, s42, s19
	s_cmpk_eq_i32 s18, 0x1500
	s_cselect_b32 s23, s13, s21
	s_cselect_b32 s22, s12, s20
	s_cselect_b32 s21, s11, s55
	s_cselect_b32 s20, s10, s54
	s_mov_b32 m0, s44
	v_lshl_add_u64 v[126:127], v[108:109], 0, s[18:19]
	ds_read_b128 v[196:199], v118
	ds_read_b128 v[200:203], v118 offset:1024
	ds_read_b128 v[204:207], v118 offset:2048
	ds_read_b128 v[208:211], v118 offset:3072
	ds_read_b128 v[212:215], v118 offset:4096
	ds_read_b128 v[216:219], v118 offset:5120
	ds_read_b128 v[220:223], v118 offset:6144
	ds_read_b128 v[224:227], v118 offset:7168
	global_load_lds_dwordx4 v[126:127], off
	v_lshl_add_u64 v[126:127], v[110:111], 0, s[18:19]
	s_mov_b32 m0, s45
	s_nop 0
	global_load_lds_dwordx4 v[126:127], off
	s_waitcnt vmcnt(8)
	s_waitcnt lgkmcnt(0)
	s_barrier
	s_setprio 1
	s_waitcnt lgkmcnt(0)
	v_mfma_f32_16x16x32_bf16 v[140:143], v[122:125], v[196:199], v[140:143]
	v_mfma_f32_16x16x32_bf16 v[136:139], v[168:171], v[196:199], v[136:139]
	v_mfma_f32_16x16x32_bf16 v[112:115], v[122:125], v[204:207], v[112:115]
	v_mfma_f32_16x16x32_bf16 v[104:107], v[168:171], v[204:207], v[104:107]
	v_mfma_f32_16x16x32_bf16 v[92:95], v[122:125], v[212:215], v[92:95]
	v_mfma_f32_16x16x32_bf16 v[88:91], v[168:171], v[212:215], v[88:91]
	v_mfma_f32_16x16x32_bf16 v[76:79], v[122:125], v[220:223], v[76:79]
	v_mfma_f32_16x16x32_bf16 v[72:75], v[168:171], v[220:223], v[72:75]
	v_mfma_f32_16x16x32_bf16 v[140:143], v[164:167], v[200:203], v[140:143]
	v_mfma_f32_16x16x32_bf16 v[136:139], v[172:175], v[200:203], v[136:139]
	v_mfma_f32_16x16x32_bf16 v[112:115], v[164:167], v[208:211], v[112:115]
	v_mfma_f32_16x16x32_bf16 v[104:107], v[172:175], v[208:211], v[104:107]
	v_mfma_f32_16x16x32_bf16 v[92:95], v[164:167], v[216:219], v[92:95]
	v_mfma_f32_16x16x32_bf16 v[88:91], v[172:175], v[216:219], v[88:91]
	v_mfma_f32_16x16x32_bf16 v[76:79], v[164:167], v[224:227], v[76:79]
	v_mfma_f32_16x16x32_bf16 v[72:75], v[172:175], v[224:227], v[72:75]
	s_setprio 0
	s_setprio 1
	v_mfma_f32_16x16x32_bf16 v[132:135], v[176:179], v[196:199], v[132:135]
	v_mfma_f32_16x16x32_bf16 v[126:129], v[184:187], v[196:199], v[128:131]
	v_mfma_f32_16x16x32_bf16 v[100:103], v[176:179], v[204:207], v[100:103]
	v_mfma_f32_16x16x32_bf16 v[96:99], v[184:187], v[204:207], v[96:99]
	v_mfma_f32_16x16x32_bf16 v[84:87], v[176:179], v[212:215], v[84:87]
	v_mfma_f32_16x16x32_bf16 v[80:83], v[184:187], v[212:215], v[80:83]
	v_mfma_f32_16x16x32_bf16 v[68:71], v[176:179], v[220:223], v[68:71]
	v_mfma_f32_16x16x32_bf16 v[64:67], v[184:187], v[220:223], v[64:67]
	v_mfma_f32_16x16x32_bf16 v[132:135], v[180:183], v[200:203], v[132:135]
	v_mfma_f32_16x16x32_bf16 v[126:129], v[188:191], v[200:203], v[126:129]
	v_mfma_f32_16x16x32_bf16 v[100:103], v[180:183], v[208:211], v[100:103]
	v_mfma_f32_16x16x32_bf16 v[96:99], v[188:191], v[208:211], v[96:99]
	v_mfma_f32_16x16x32_bf16 v[84:87], v[180:183], v[216:219], v[84:87]
	v_mfma_f32_16x16x32_bf16 v[80:83], v[188:191], v[216:219], v[80:83]
	v_mfma_f32_16x16x32_bf16 v[68:71], v[180:183], v[224:227], v[68:71]
	v_mfma_f32_16x16x32_bf16 v[64:67], v[188:191], v[224:227], v[64:67]
	s_setprio 0
	s_barrier
	s_mov_b32 m0, s46
	v_lshl_add_u64 v[154:155], s[20:21], 0, v[146:147]
	s_add_u32 s54, s20, 0xb0000
	ds_read_b128 v[196:199], v118 offset:16384
	ds_read_b128 v[200:203], v118 offset:17408
	ds_read_b128 v[204:207], v118 offset:18432
	ds_read_b128 v[208:211], v118 offset:19456
	ds_read_b128 v[212:215], v118 offset:20480
	ds_read_b128 v[216:219], v118 offset:21504
	ds_read_b128 v[220:223], v118 offset:22528
	ds_read_b128 v[224:227], v118 offset:23552
	global_load_lds_dwordx4 v[154:155], off
	v_lshl_add_u64 v[228:229], s[20:21], 0, v[150:151]
	s_mov_b32 m0, s47
	s_addc_u32 s55, s21, 0
	global_load_lds_dwordx4 v[228:229], off
	s_mov_b32 m0, s48
	v_lshl_add_u64 v[230:231], s[22:23], 0, v[144:145]
	global_load_lds_dwordx4 v146, s[54:55]
	s_mov_b32 m0, s49
	v_lshl_add_u64 v[232:233], s[22:23], 0, v[148:149]
	global_load_lds_dwordx4 v150, s[54:55]
	s_mov_b32 m0, s2
	s_nop 0
	global_load_lds_dwordx4 v[230:231], off
	s_mov_b32 m0, s3
	s_nop 0
	global_load_lds_dwordx4 v[232:233], off
	s_waitcnt vmcnt(8)
	s_waitcnt lgkmcnt(0)
	s_barrier
; #define PG8_STAGE(bufoff, gbase, voff) do { _Pragma("unroll") for (int _i = 0; _i < 2; ++_i) \
;         __builtin_amdgcn_global_load_lds((const unsigned*)((const char*)(gbase) + (voff)[_i]), (PG8_LAS unsigned*)(lds + (bufoff) + ldsw + _i * 8192), 16, 0, 0); } while (0)
; #define PG8_LDA(dst, b, h) do { _Pragma("unroll") for (int m = 0; m < 4; ++m) _Pragma("unroll") for (int k = 0; k < 2; ++k) dst[m][k] = *(const PG8_LAS bf16x8*)(lds + PG8_SA(b, h) + aoff + m * 2048 + k * 1024); } while (0)
; #define PG8_LDB(dst, b, h) do { _Pragma("unroll") for (int n = 0; n < 2; ++n) _Pragma("unroll") for (int k = 0; k < 2; ++k) dst[n][k] = *(const PG8_LAS bf16x8*)(lds + PG8_SB(b, h) + boff + n * 2048 + k * 1024); } while (0)
; #define PG8_MMA(ai, bj, At, Bt) do { __builtin_amdgcn_s_setprio(1); _Pragma("unroll") for (int m = 0; m < 4; ++m) _Pragma("unroll") for (int n = 0; n < 2; ++n) _Pragma("unroll") for (int k = 0; k < 2; ++k) \
;         acc[ai][bj][m][n] = __builtin_amdgcn_mfma_f32_16x16x32_bf16(Bt[n][k], At[m][k], acc[ai][bj][m][n], 0, 0, 0); __builtin_amdgcn_s_setprio(0); } while (0)
; #define PG8_WAIT_V(n) asm volatile("s_waitcnt vmcnt(" #n ")" ::: "memory")
; #define PG8_WAIT_L(n) asm volatile("s_waitcnt lgkmcnt(" #n ")" ::: "memory")
; #define PG8_BAR __builtin_amdgcn_s_barrier()
; #define PG8_SCHED __builtin_amdgcn_sched_barrier(0)
; template <class Epi, class Sched, bool ALIGN_EPI = false, bool SP2 = false>
; __device__ __forceinline__ void gemm_phase(PG8_LAS unsigned char* lds, const Gemm g, const Sched& S, const Epi& E) {
;     ...
;             PG8_WAIT_V(8); PG8_WAIT_L(0); PG8_BAR; PG8_MMA(1, 0, At, B0); PG8_MMA(1, 1, At, B1); PG8_BAR; PG8_SCHED;
;             PG8_LDB(B0, 1, 0); PG8_LDB(B1, 1, 1); PG8_SCHED; PG8_LDA(At, 1, 0); PG8_STAGE(PG8_SA(0, 1), a2 + hstepA, voffA);
;             PG8_WAIT_V(8); PG8_WAIT_L(0); PG8_BAR; PG8_MMA(0, 0, At, B0); PG8_MMA(0, 1, At, B1); PG8_BAR; PG8_SCHED;
	s_setprio 1
	s_waitcnt lgkmcnt(0)
	v_mfma_f32_16x16x32_bf16 v[60:63], v[122:125], v[196:199], v[60:63]
	v_mfma_f32_16x16x32_bf16 v[56:59], v[168:171], v[196:199], v[56:59]
	v_mfma_f32_16x16x32_bf16 v[44:47], v[122:125], v[204:207], v[44:47]
	v_mfma_f32_16x16x32_bf16 v[40:43], v[168:171], v[204:207], v[40:43]
	v_mfma_f32_16x16x32_bf16 v[28:31], v[122:125], v[212:215], v[28:31]
	v_mfma_f32_16x16x32_bf16 v[24:27], v[168:171], v[212:215], v[24:27]
	v_mfma_f32_16x16x32_bf16 v[12:15], v[122:125], v[220:223], v[12:15]
	v_mfma_f32_16x16x32_bf16 v[8:11], v[168:171], v[220:223], v[8:11]
	v_mfma_f32_16x16x32_bf16 v[60:63], v[164:167], v[200:203], v[60:63]
	v_mfma_f32_16x16x32_bf16 v[56:59], v[172:175], v[200:203], v[56:59]
	v_mfma_f32_16x16x32_bf16 v[44:47], v[164:167], v[208:211], v[44:47]
	v_mfma_f32_16x16x32_bf16 v[40:43], v[172:175], v[208:211], v[40:43]
	v_mfma_f32_16x16x32_bf16 v[28:31], v[164:167], v[216:219], v[28:31]
	v_mfma_f32_16x16x32_bf16 v[24:27], v[172:175], v[216:219], v[24:27]
	v_mfma_f32_16x16x32_bf16 v[12:15], v[164:167], v[224:227], v[12:15]
	v_mfma_f32_16x16x32_bf16 v[8:11], v[172:175], v[224:227], v[8:11]
	s_setprio 0
	s_setprio 1
	v_mfma_f32_16x16x32_bf16 v[52:55], v[176:179], v[196:199], v[52:55]
	v_mfma_f32_16x16x32_bf16 v[48:51], v[184:187], v[196:199], v[48:51]
	v_mfma_f32_16x16x32_bf16 v[36:39], v[176:179], v[204:207], v[36:39]
	v_mfma_f32_16x16x32_bf16 v[32:35], v[184:187], v[204:207], v[32:35]
	v_mfma_f32_16x16x32_bf16 v[20:23], v[176:179], v[212:215], v[20:23]
	v_mfma_f32_16x16x32_bf16 v[16:19], v[184:187], v[212:215], v[16:19]
	v_mfma_f32_16x16x32_bf16 v[4:7], v[176:179], v[220:223], v[4:7]
	v_mfma_f32_16x16x32_bf16 v[0:3], v[184:187], v[220:223], v[0:3]
	v_mfma_f32_16x16x32_bf16 v[52:55], v[180:183], v[200:203], v[52:55]
	v_mfma_f32_16x16x32_bf16 v[48:51], v[188:191], v[200:203], v[48:51]
	v_mfma_f32_16x16x32_bf16 v[36:39], v[180:183], v[208:211], v[36:39]
	v_mfma_f32_16x16x32_bf16 v[32:35], v[188:191], v[208:211], v[32:35]
	v_mfma_f32_16x16x32_bf16 v[20:23], v[180:183], v[216:219], v[20:23]
	v_mfma_f32_16x16x32_bf16 v[16:19], v[188:191], v[216:219], v[16:19]
	v_mfma_f32_16x16x32_bf16 v[4:7], v[180:183], v[224:227], v[4:7]
	v_mfma_f32_16x16x32_bf16 v[0:3], v[188:191], v[224:227], v[0:3]
	s_setprio 0
	s_barrier
	ds_read_b128 v[122:125], v119
	ds_read_b128 v[164:167], v119 offset:1024
	ds_read_b128 v[168:171], v119 offset:2048
	ds_read_b128 v[172:175], v119 offset:3072
	ds_read_b128 v[176:179], v120
	ds_read_b128 v[180:183], v120 offset:1024
	ds_read_b128 v[184:187], v120 offset:2048
	ds_read_b128 v[188:191], v120 offset:3072
	s_add_u32 s22, s22, 0xb4000
	s_addc_u32 s23, s23, 0
	s_mov_b32 m0, s37
	v_lshl_add_u64 v[130:131], s[22:23], 0, v[144:145]
	ds_read_b128 v[196:199], v118 offset:32768
	ds_read_b128 v[200:203], v118 offset:33792
	ds_read_b128 v[204:207], v118 offset:34816
	ds_read_b128 v[208:211], v118 offset:35840
	ds_read_b128 v[212:215], v118 offset:36864
	ds_read_b128 v[216:219], v118 offset:37888
	ds_read_b128 v[220:223], v118 offset:38912
	ds_read_b128 v[224:227], v118 offset:39936
	global_load_lds_dwordx4 v[130:131], off
	v_lshl_add_u64 v[130:131], s[22:23], 0, v[148:149]
	s_mov_b32 m0, s38
	s_nop 0
	global_load_lds_dwordx4 v[130:131], off
	s_waitcnt vmcnt(8)
	s_waitcnt lgkmcnt(0)
	s_barrier
	s_setprio 1
	s_waitcnt lgkmcnt(0)
	v_mfma_f32_16x16x32_bf16 v[140:143], v[122:125], v[196:199], v[140:143]
	v_mfma_f32_16x16x32_bf16 v[136:139], v[168:171], v[196:199], v[136:139]
	v_mfma_f32_16x16x32_bf16 v[112:115], v[122:125], v[204:207], v[112:115]
	v_mfma_f32_16x16x32_bf16 v[104:107], v[168:171], v[204:207], v[104:107]
	v_mfma_f32_16x16x32_bf16 v[92:95], v[122:125], v[212:215], v[92:95]
	v_mfma_f32_16x16x32_bf16 v[88:91], v[168:171], v[212:215], v[88:91]
	v_mfma_f32_16x16x32_bf16 v[76:79], v[122:125], v[220:223], v[76:79]
	v_mfma_f32_16x16x32_bf16 v[72:75], v[168:171], v[220:223], v[72:75]
	v_mfma_f32_16x16x32_bf16 v[140:143], v[164:167], v[200:203], v[140:143]
	v_mfma_f32_16x16x32_bf16 v[136:139], v[172:175], v[200:203], v[136:139]
	v_mfma_f32_16x16x32_bf16 v[112:115], v[164:167], v[208:211], v[112:115]
	v_mfma_f32_16x16x32_bf16 v[104:107], v[172:175], v[208:211], v[104:107]
	v_mfma_f32_16x16x32_bf16 v[92:95], v[164:167], v[216:219], v[92:95]
	v_mfma_f32_16x16x32_bf16 v[88:91], v[172:175], v[216:219], v[88:91]
	v_mfma_f32_16x16x32_bf16 v[76:79], v[164:167], v[224:227], v[76:79]
	v_mfma_f32_16x16x32_bf16 v[72:75], v[172:175], v[224:227], v[72:75]
	s_setprio 0
	s_setprio 1
	v_mfma_f32_16x16x32_bf16 v[130:133], v[176:179], v[196:199], v[132:135]
	v_mfma_f32_16x16x32_bf16 v[126:129], v[184:187], v[196:199], v[126:129]
	v_mfma_f32_16x16x32_bf16 v[100:103], v[176:179], v[204:207], v[100:103]
	v_mfma_f32_16x16x32_bf16 v[96:99], v[184:187], v[204:207], v[96:99]
	v_mfma_f32_16x16x32_bf16 v[84:87], v[176:179], v[212:215], v[84:87]
	v_mfma_f32_16x16x32_bf16 v[80:83], v[184:187], v[212:215], v[80:83]
	v_mfma_f32_16x16x32_bf16 v[68:71], v[176:179], v[220:223], v[68:71]
	v_mfma_f32_16x16x32_bf16 v[64:67], v[184:187], v[220:223], v[64:67]
	v_mfma_f32_16x16x32_bf16 v[132:135], v[180:183], v[200:203], v[130:133]
	v_mfma_f32_16x16x32_bf16 v[128:131], v[188:191], v[200:203], v[126:129]
	v_mfma_f32_16x16x32_bf16 v[100:103], v[180:183], v[208:211], v[100:103]
	v_mfma_f32_16x16x32_bf16 v[96:99], v[188:191], v[208:211], v[96:99]
	v_mfma_f32_16x16x32_bf16 v[84:87], v[180:183], v[216:219], v[84:87]
	v_mfma_f32_16x16x32_bf16 v[80:83], v[188:191], v[216:219], v[80:83]
	v_mfma_f32_16x16x32_bf16 v[68:71], v[180:183], v[224:227], v[68:71]
	v_mfma_f32_16x16x32_bf16 v[64:67], v[188:191], v[224:227], v[64:67]
	s_setprio 0
	s_barrier
; #define PG8_STAGE(bufoff, gbase, voff) do { _Pragma("unroll") for (int _i = 0; _i < 2; ++_i) \
;         __builtin_amdgcn_global_load_lds((const unsigned*)((const char*)(gbase) + (voff)[_i]), (PG8_LAS unsigned*)(lds + (bufoff) + ldsw + _i * 8192), 16, 0, 0); } while (0)
; #define PG8_LDA(dst, b, h) do { _Pragma("unroll") for (int m = 0; m < 4; ++m) _Pragma("unroll") for (int k = 0; k < 2; ++k) dst[m][k] = *(const PG8_LAS bf16x8*)(lds + PG8_SA(b, h) + aoff + m * 2048 + k * 1024); } while (0)
; #define PG8_MMA(ai, bj, At, Bt) do { __builtin_amdgcn_s_setprio(1); _Pragma("unroll") for (int m = 0; m < 4; ++m) _Pragma("unroll") for (int n = 0; n < 2; ++n) _Pragma("unroll") for (int k = 0; k < 2; ++k) \
;         acc[ai][bj][m][n] = __builtin_amdgcn_mfma_f32_16x16x32_bf16(Bt[n][k], At[m][k], acc[ai][bj][m][n], 0, 0, 0); __builtin_amdgcn_s_setprio(0); } while (0)
; #define PG8_WAIT_V(n) asm volatile("s_waitcnt vmcnt(" #n ")" ::: "memory")
; #define PG8_WAIT_L(n) asm volatile("s_waitcnt lgkmcnt(" #n ")" ::: "memory")
; #define PG8_BAR __builtin_amdgcn_s_barrier()
; #define PG8_SCHED __builtin_amdgcn_sched_barrier(0)
; template <class Epi, class Sched, bool ALIGN_EPI = false, bool SP2 = false>
; __device__ __forceinline__ void gemm_phase(PG8_LAS unsigned char* lds, const Gemm g, const Sched& S, const Epi& E) {
;     ...
;             PG8_LDA(At, 1, 1); PG8_STAGE(PG8_SB(1, 0), b3, voffB); PG8_STAGE(PG8_SB(1, 1), b3 + hstepB, voffB); PG8_STAGE(PG8_SA(1, 0), a3, voffA);
;             PG8_WAIT_V(8); PG8_WAIT_L(0); PG8_BAR; PG8_MMA(1, 0, At, B0); PG8_MMA(1, 1, At, B1); PG8_BAR; PG8_SCHED;
;     ...
;     PG8_WAIT_V(0);
;     if constexpr (!ALIGN_EPI) { if (wr == 0) PG8_BAR; }
;     PG8_BAR;
	s_mov_b32 m0, s50
	v_lshl_add_u64 v[126:127], v[154:155], 0, s[14:15]
	s_add_u32 s20, s20, 0xb0080
	ds_read_b128 v[196:199], v118 offset:49152
	ds_read_b128 v[200:203], v118 offset:50176
	ds_read_b128 v[204:207], v118 offset:51200
	ds_read_b128 v[208:211], v118 offset:52224
	ds_read_b128 v[212:215], v118 offset:53248
	ds_read_b128 v[216:219], v118 offset:54272
	ds_read_b128 v[220:223], v118 offset:55296
	ds_read_b128 v[224:227], v118 offset:56320
	global_load_lds_dwordx4 v[126:127], off
	v_lshl_add_u64 v[126:127], v[228:229], 0, s[14:15]
	s_mov_b32 m0, s51
	s_addc_u32 s21, s21, 0
	global_load_lds_dwordx4 v[126:127], off
	s_mov_b32 m0, s52
	s_nop 0
	global_load_lds_dwordx4 v146, s[20:21]
	s_mov_b32 m0, s53
	s_nop 0
	global_load_lds_dwordx4 v150, s[20:21]
	v_lshl_add_u64 v[126:127], v[230:231], 0, s[14:15]
	s_mov_b32 m0, s39
	s_nop 0
	global_load_lds_dwordx4 v[126:127], off
	v_lshl_add_u64 v[126:127], v[232:233], 0, s[14:15]
	s_mov_b32 m0, s40
	s_nop 0
	global_load_lds_dwordx4 v[126:127], off
	s_waitcnt vmcnt(8)
	s_waitcnt lgkmcnt(0)
	s_barrier
	s_setprio 1
	s_waitcnt lgkmcnt(0)
	v_mfma_f32_16x16x32_bf16 v[60:63], v[122:125], v[196:199], v[60:63]
	v_mfma_f32_16x16x32_bf16 v[56:59], v[168:171], v[196:199], v[56:59]
	v_mfma_f32_16x16x32_bf16 v[44:47], v[122:125], v[204:207], v[44:47]
	v_mfma_f32_16x16x32_bf16 v[40:43], v[168:171], v[204:207], v[40:43]
	v_mfma_f32_16x16x32_bf16 v[28:31], v[122:125], v[212:215], v[28:31]
	v_mfma_f32_16x16x32_bf16 v[24:27], v[168:171], v[212:215], v[24:27]
	v_mfma_f32_16x16x32_bf16 v[12:15], v[122:125], v[220:223], v[12:15]
	v_mfma_f32_16x16x32_bf16 v[8:11], v[168:171], v[220:223], v[8:11]
	v_mfma_f32_16x16x32_bf16 v[60:63], v[164:167], v[200:203], v[60:63]
	v_mfma_f32_16x16x32_bf16 v[56:59], v[172:175], v[200:203], v[56:59]
	v_mfma_f32_16x16x32_bf16 v[44:47], v[164:167], v[208:211], v[44:47]
	v_mfma_f32_16x16x32_bf16 v[40:43], v[172:175], v[208:211], v[40:43]
	v_mfma_f32_16x16x32_bf16 v[28:31], v[164:167], v[216:219], v[28:31]
	v_mfma_f32_16x16x32_bf16 v[24:27], v[172:175], v[216:219], v[24:27]
	v_mfma_f32_16x16x32_bf16 v[12:15], v[164:167], v[224:227], v[12:15]
	v_mfma_f32_16x16x32_bf16 v[8:11], v[172:175], v[224:227], v[8:11]
	s_setprio 0
	s_setprio 1
	v_mfma_f32_16x16x32_bf16 v[52:55], v[176:179], v[196:199], v[52:55]
	v_mfma_f32_16x16x32_bf16 v[48:51], v[184:187], v[196:199], v[48:51]
	v_mfma_f32_16x16x32_bf16 v[36:39], v[176:179], v[204:207], v[36:39]
	v_mfma_f32_16x16x32_bf16 v[32:35], v[184:187], v[204:207], v[32:35]
	v_mfma_f32_16x16x32_bf16 v[20:23], v[176:179], v[212:215], v[20:23]
	v_mfma_f32_16x16x32_bf16 v[16:19], v[184:187], v[212:215], v[16:19]
	v_mfma_f32_16x16x32_bf16 v[4:7], v[176:179], v[220:223], v[4:7]
	v_mfma_f32_16x16x32_bf16 v[0:3], v[184:187], v[220:223], v[0:3]
	v_mfma_f32_16x16x32_bf16 v[52:55], v[180:183], v[200:203], v[52:55]
	v_mfma_f32_16x16x32_bf16 v[48:51], v[188:191], v[200:203], v[48:51]
	v_mfma_f32_16x16x32_bf16 v[36:39], v[180:183], v[208:211], v[36:39]
	v_mfma_f32_16x16x32_bf16 v[32:35], v[188:191], v[208:211], v[32:35]
	v_mfma_f32_16x16x32_bf16 v[20:23], v[180:183], v[216:219], v[20:23]
	v_mfma_f32_16x16x32_bf16 v[16:19], v[188:191], v[216:219], v[16:19]
	v_mfma_f32_16x16x32_bf16 v[4:7], v[180:183], v[224:227], v[4:7]
	v_mfma_f32_16x16x32_bf16 v[0:3], v[188:191], v[224:227], v[0:3]
	s_setprio 0
	s_barrier
	s_add_i32 s43, s43, 2
	s_add_u32 s18, s18, 0x100
	s_addc_u32 s19, s19, 0
	s_cmp_lt_u32 s43, 42
	s_cbranch_scc1 .LBB0_1603
	s_waitcnt vmcnt(0)
	s_cmpk_gt_u32 s31, 0xff
	s_cbranch_scc1 .LBB0_1606
	s_barrier

; #define PG8_STAGE(bufoff, gbase, voff) do { _Pragma("unroll") for (int _i = 0; _i < 2; ++_i) \
;         __builtin_amdgcn_global_load_lds((const unsigned*)((const char*)(gbase) + (voff)[_i]), (PG8_LAS unsigned*)(lds + (bufoff) + ldsw + _i * 8192), 16, 0, 0); } while (0)
; #define PG8_WAIT_V(n) asm volatile("s_waitcnt vmcnt(" #n ")" ::: "memory")
; #define PG8_BAR __builtin_amdgcn_s_barrier()
; template <class Epi, class Sched, bool ALIGN_EPI = false, bool SP2 = false>
; __device__ __forceinline__ void gemm_phase(PG8_LAS unsigned char* lds, const Gemm g, const Sched& S, const Epi& E) {
;     ...
;     f32x4 acc[2][2][4][2];
; #pragma unroll
;     for (int a = 0; a < 2; ++a)
; #pragma unroll
;         for (int b = 0; b < 2; ++b)
; #pragma unroll
;             for (int m = 0; m < 4; ++m)
; #pragma unroll
;                 for (int n = 0; n < 2; ++n) acc[a][b][m][n] = (f32x4){0.f, 0.f, 0.f, 0.f};
;     ...
;         PG8_STAGE(PG8_SB(0, 0), cB, voffB); PG8_STAGE(PG8_SB(0, 1), cB + hstepB, voffB); PG8_STAGE(PG8_SA(0, 0), cA, voffA); PG8_STAGE(PG8_SA(0, 1), cA + hstepA, voffA);
;         if (wr == 1) PG8_BAR;
;         PG8_WAIT_V(2); PG8_BAR;
;         PG8_STAGE(PG8_SB(1, 0), cB + kstep, voffB); PG8_STAGE(PG8_SA(1, 0), cA + kstep, voffA); PG8_STAGE(PG8_SB(1, 1), cB + hstepB + kstep, voffB);
;         PG8_WAIT_V(6); PG8_BAR;
.LBB0_1639:
	v_lshlrev_b32_e32 v9, 2, v157
	s_and_b32 s26, s12, 3
	v_lshl_or_b32 v8, v157, 6, v162
	s_lshl_b32 s12, s30, 13
	v_and_b32_e32 v9, 32, v9
	v_bitop3_b32 v8, v8, s12, v9 bitop3:0xde
	s_mov_b64 s[12:13], 0x80
	s_add_i32 m0, s28, 0x18000
	v_lshl_add_u64 v[6:7], v[6:7], 0, s[12:13]
	s_waitcnt vmcnt(2)
	s_barrier
	global_load_lds_dwordx4 v[6:7], off
	v_lshl_add_u64 v[4:5], v[4:5], 0, s[12:13]
	s_add_i32 m0, s28, 0x1a000
	s_add_i32 s33, s28, 0x8000
	s_add_i32 s36, s28, 0xa000
	global_load_lds_dwordx4 v[4:5], off
	v_lshl_add_u64 v[2:3], v[2:3], 0, s[12:13]
	s_mov_b32 m0, s33
	s_add_u32 s20, s0, 0xb0080
	global_load_lds_dwordx4 v[2:3], off
	v_lshl_add_u64 v[0:1], v[0:1], 0, s[12:13]
	s_mov_b32 m0, s36
	s_addc_u32 s21, s1, 0
	global_load_lds_dwordx4 v[0:1], off
	s_add_i32 m0, s28, 0x1c000
	global_load_lds_dwordx4 v146, s[20:21]
	v_lshl_add_u64 v[0:1], s[20:21], 0, v[150:151]
	s_add_i32 m0, s28, 0x1e000
	s_add_u32 s14, s34, s14
	global_load_lds_dwordx4 v[0:1], off
	s_addc_u32 s15, s35, s15
	v_add_u16_e32 v0, v158, v159
	v_lshrrev_b16_e32 v2, 1, v0
	s_add_u32 s17, s34, s17
	v_add_lshl_u32 v0, v160, v2, 1
	v_mov_b32_e32 v1, v147
	s_addc_u32 s16, s35, s16
	v_lshl_add_u64 v[0:1], s[14:15], 0, v[0:1]
	s_mov_b64 s[20:21], 0x78b4080
	s_add_u32 s34, s17, 0x2a00100
	v_lshl_or_b32 v9, s26, 12, v163
	s_waitcnt vmcnt(6)
	v_lshl_add_u64 v[112:113], v[0:1], 0, s[20:21]
	v_add_lshl_u32 v0, v161, v2, 1
	v_mov_b32_e32 v1, v147
	s_addc_u32 s35, s16, 0
	s_add_i32 s40, 0, 0x10000
	s_add_i32 s42, 0, 0x14000
	s_add_i32 s44, 0, 0x18000
	s_add_i32 s46, 0, 0x1c000
	v_lshl_add_u64 v[0:1], s[14:15], 0, v[0:1]
	v_add_u32_e32 v116, s40, v9
	v_add_u32_e32 v117, s42, v9
	s_add_i32 s40, s40, s18
	s_add_i32 s42, s42, s18
	v_add_u32_e32 v119, s44, v9
	v_add_u32_e32 v120, s46, v9
	s_add_i32 s44, s44, s18
	s_add_i32 s46, s46, s18
	v_lshl_or_b32 v152, s30, 6, v157
	v_lshl_add_u64 v[114:115], v[0:1], 0, s[20:21]
	s_mov_b32 s37, -2
	s_mov_b64 s[16:17], 0
	v_add_u32_e32 v118, 0, v8
	s_add_i32 s38, s28, 0xc000
	s_add_i32 s39, s28, 0xe000
	s_add_i32 s41, s40, 0x2000
	s_add_i32 s43, s42, 0x2000
	s_add_i32 s45, s44, 0x2000
	s_add_i32 s47, s46, 0x2000
	v_mov_b32_e32 v0, v147
	v_mov_b32_e32 v1, v147
	v_mov_b32_e32 v2, v147
	v_mov_b32_e32 v3, v147
	v_mov_b32_e32 v4, v147
	v_mov_b32_e32 v5, v147
	v_mov_b32_e32 v6, v147
	v_mov_b32_e32 v7, v147
	v_mov_b32_e32 v16, v147
	v_mov_b32_e32 v17, v147
	v_mov_b32_e32 v18, v147
	v_mov_b32_e32 v19, v147
	v_mov_b32_e32 v20, v147
	v_mov_b32_e32 v21, v147
	v_mov_b32_e32 v22, v147
	v_mov_b32_e32 v23, v147
	v_mov_b32_e32 v32, v147
	v_mov_b32_e32 v33, v147
	v_mov_b32_e32 v34, v147
	v_mov_b32_e32 v35, v147
	v_mov_b32_e32 v36, v147
	v_mov_b32_e32 v37, v147
	v_mov_b32_e32 v38, v147
	v_mov_b32_e32 v39, v147
	v_mov_b32_e32 v48, v147
	v_mov_b32_e32 v49, v147
	v_mov_b32_e32 v50, v147
	v_mov_b32_e32 v51, v147
	v_mov_b32_e32 v52, v147
	v_mov_b32_e32 v53, v147
	v_mov_b32_e32 v54, v147
	v_mov_b32_e32 v55, v147
	v_mov_b32_e32 v8, v147
	v_mov_b32_e32 v9, v147
	v_mov_b32_e32 v10, v147
	v_mov_b32_e32 v11, v147
	v_mov_b32_e32 v12, v147
	v_mov_b32_e32 v13, v147
	v_mov_b32_e32 v14, v147
	v_mov_b32_e32 v15, v147
	v_mov_b32_e32 v24, v147
	v_mov_b32_e32 v25, v147
	v_mov_b32_e32 v26, v147
	v_mov_b32_e32 v27, v147
	v_mov_b32_e32 v28, v147
	v_mov_b32_e32 v29, v147
	v_mov_b32_e32 v30, v147
	v_mov_b32_e32 v31, v147
	v_mov_b32_e32 v40, v147
	v_mov_b32_e32 v41, v147
	v_mov_b32_e32 v42, v147
	v_mov_b32_e32 v43, v147
	v_mov_b32_e32 v44, v147
	v_mov_b32_e32 v45, v147
	v_mov_b32_e32 v46, v147
	v_mov_b32_e32 v47, v147
	v_mov_b32_e32 v56, v147
	v_mov_b32_e32 v57, v147
	v_mov_b32_e32 v58, v147
	v_mov_b32_e32 v59, v147
	v_mov_b32_e32 v60, v147
	v_mov_b32_e32 v61, v147
	v_mov_b32_e32 v62, v147
	v_mov_b32_e32 v63, v147
	v_mov_b32_e32 v64, v147
	v_mov_b32_e32 v65, v147
	v_mov_b32_e32 v66, v147
	v_mov_b32_e32 v67, v147
	v_mov_b32_e32 v68, v147
	v_mov_b32_e32 v69, v147
	v_mov_b32_e32 v70, v147
	v_mov_b32_e32 v71, v147
	v_mov_b32_e32 v80, v147
	v_mov_b32_e32 v81, v147
	v_mov_b32_e32 v82, v147
	v_mov_b32_e32 v83, v147
	v_mov_b32_e32 v84, v147
	v_mov_b32_e32 v85, v147
	v_mov_b32_e32 v86, v147
	v_mov_b32_e32 v87, v147
	v_mov_b32_e32 v96, v147
	v_mov_b32_e32 v97, v147
	v_mov_b32_e32 v98, v147
	v_mov_b32_e32 v99, v147
	v_mov_b32_e32 v100, v147
	v_mov_b32_e32 v101, v147
	v_mov_b32_e32 v102, v147
	v_mov_b32_e32 v103, v147
	v_mov_b32_e32 v128, v147
	v_mov_b32_e32 v129, v147
	v_mov_b32_e32 v130, v147
	v_mov_b32_e32 v131, v147
	v_mov_b32_e32 v132, v147
	v_mov_b32_e32 v133, v147
	v_mov_b32_e32 v134, v147
	v_mov_b32_e32 v135, v147
	v_mov_b32_e32 v72, v147
	v_mov_b32_e32 v73, v147
	v_mov_b32_e32 v74, v147
	v_mov_b32_e32 v75, v147
	v_mov_b32_e32 v76, v147
	v_mov_b32_e32 v77, v147
	v_mov_b32_e32 v78, v147
	v_mov_b32_e32 v79, v147
	v_mov_b32_e32 v88, v147
	v_mov_b32_e32 v89, v147
	v_mov_b32_e32 v90, v147
	v_mov_b32_e32 v91, v147
	v_mov_b32_e32 v92, v147
	v_mov_b32_e32 v93, v147
	v_mov_b32_e32 v94, v147
	v_mov_b32_e32 v95, v147
	v_mov_b32_e32 v104, v147
	v_mov_b32_e32 v105, v147
	v_mov_b32_e32 v106, v147
	v_mov_b32_e32 v107, v147
	v_mov_b32_e32 v108, v147
	v_mov_b32_e32 v109, v147
	v_mov_b32_e32 v110, v147
	v_mov_b32_e32 v111, v147
	v_mov_b32_e32 v136, v147
	v_mov_b32_e32 v137, v147
	v_mov_b32_e32 v138, v147
	v_mov_b32_e32 v139, v147
	v_mov_b32_e32 v140, v147
	v_mov_b32_e32 v141, v147
	v_mov_b32_e32 v142, v147
	v_mov_b32_e32 v143, v147
	s_barrier
; #define PG8_STAGE(bufoff, gbase, voff) do { _Pragma("unroll") for (int _i = 0; _i < 2; ++_i) \
;         __builtin_amdgcn_global_load_lds((const unsigned*)((const char*)(gbase) + (voff)[_i]), (PG8_LAS unsigned*)(lds + (bufoff) + ldsw + _i * 8192), 16, 0, 0); } while (0)
; #define PG8_LDA(dst, b, h) do { _Pragma("unroll") for (int m = 0; m < 4; ++m) _Pragma("unroll") for (int k = 0; k < 2; ++k) dst[m][k] = *(const PG8_LAS bf16x8*)(lds + PG8_SA(b, h) + aoff + m * 2048 + k * 1024); } while (0)
; #define PG8_LDB(dst, b, h) do { _Pragma("unroll") for (int n = 0; n < 2; ++n) _Pragma("unroll") for (int k = 0; k < 2; ++k) dst[n][k] = *(const PG8_LAS bf16x8*)(lds + PG8_SB(b, h) + boff + n * 2048 + k * 1024); } while (0)
; #define PG8_MMA(ai, bj, At, Bt) do { __builtin_amdgcn_s_setprio(1); _Pragma("unroll") for (int m = 0; m < 4; ++m) _Pragma("unroll") for (int n = 0; n < 2; ++n) _Pragma("unroll") for (int k = 0; k < 2; ++k) \
;         acc[ai][bj][m][n] = __builtin_amdgcn_mfma_f32_16x16x32_bf16(Bt[n][k], At[m][k], acc[ai][bj][m][n], 0, 0, 0); __builtin_amdgcn_s_setprio(0); } while (0)
; #define PG8_WAIT_V(n) asm volatile("s_waitcnt vmcnt(" #n ")" ::: "memory")
; #define PG8_WAIT_L(n) asm volatile("s_waitcnt lgkmcnt(" #n ")" ::: "memory")
; #define PG8_BAR __builtin_amdgcn_s_barrier()
; #define PG8_SCHED __builtin_amdgcn_sched_barrier(0)
; template <class Epi, class Sched, bool ALIGN_EPI = false, bool SP2 = false>
; __device__ __forceinline__ void gemm_phase(PG8_LAS unsigned char* lds, const Gemm g, const Sched& S, const Epi& E) {
;     ...
;             PG8_LDB(B0, 0, 0); PG8_LDB(B1, 0, 1); PG8_SCHED; PG8_LDA(At, 0, 0); PG8_STAGE(PG8_SA(1, 1), a1 + hstepA, voffA);
;             PG8_WAIT_V(8); PG8_WAIT_L(0); PG8_BAR; PG8_MMA(0, 0, At, B0); PG8_MMA(0, 1, At, B1); PG8_BAR; PG8_SCHED;
;             PG8_LDA(At, 0, 1); PG8_STAGE(PG8_SB(0, 0), b2, voffB); PG8_STAGE(PG8_SB(0, 1), b2 + hstepB, voffB); PG8_STAGE(PG8_SA(0, 0), a2, voffA);
;             PG8_WAIT_V(8); PG8_WAIT_L(0); PG8_BAR; PG8_MMA(1, 0, At, B0); PG8_MMA(1, 1, At, B1); PG8_BAR; PG8_SCHED;
.LBB0_1640:
	ds_read_b128 v[122:125], v116
	ds_read_b128 v[158:161], v116 offset:1024
	ds_read_b128 v[162:165], v116 offset:2048
	ds_read_b128 v[166:169], v116 offset:3072
	ds_read_b128 v[170:173], v117
	ds_read_b128 v[174:177], v117 offset:1024
	ds_read_b128 v[178:181], v117 offset:2048
	ds_read_b128 v[182:185], v117 offset:3072
	s_add_u32 s18, s14, s16
	s_addc_u32 s19, s15, s17
	s_add_u32 s18, s18, 0x7800100
	s_addc_u32 s19, s19, 0
	s_add_u32 s48, s34, s16
	s_addc_u32 s49, s35, s17
	s_cmpk_eq_i32 s16, 0x1500
	s_cselect_b32 s21, s11, s19
	s_cselect_b32 s20, s10, s18
	s_cselect_b32 s19, s1, s49
	s_cselect_b32 s18, s0, s48
	s_mov_b32 m0, s38
	v_lshl_add_u64 v[126:127], v[112:113], 0, s[16:17]
	ds_read_b128 v[186:189], v118
	ds_read_b128 v[194:197], v118 offset:1024
	ds_read_b128 v[198:201], v118 offset:2048
	ds_read_b128 v[202:205], v118 offset:3072
	ds_read_b128 v[206:209], v118 offset:4096
	ds_read_b128 v[210:213], v118 offset:5120
	ds_read_b128 v[214:217], v118 offset:6144
	ds_read_b128 v[218:221], v118 offset:7168
	global_load_lds_dwordx4 v[126:127], off
	v_lshl_add_u64 v[126:127], v[114:115], 0, s[16:17]
	s_mov_b32 m0, s39
	s_nop 0
	global_load_lds_dwordx4 v[126:127], off
	s_waitcnt vmcnt(8)
	s_waitcnt lgkmcnt(0)
	s_barrier
	s_setprio 1
	s_waitcnt lgkmcnt(0)
	v_mfma_f32_16x16x32_bf16 v[140:143], v[122:125], v[186:189], v[140:143]
	v_mfma_f32_16x16x32_bf16 v[136:139], v[162:165], v[186:189], v[136:139]
	v_mfma_f32_16x16x32_bf16 v[108:111], v[122:125], v[198:201], v[108:111]
	v_mfma_f32_16x16x32_bf16 v[104:107], v[162:165], v[198:201], v[104:107]
	v_mfma_f32_16x16x32_bf16 v[92:95], v[122:125], v[206:209], v[92:95]
	v_mfma_f32_16x16x32_bf16 v[88:91], v[162:165], v[206:209], v[88:91]
	v_mfma_f32_16x16x32_bf16 v[76:79], v[122:125], v[214:217], v[76:79]
	v_mfma_f32_16x16x32_bf16 v[72:75], v[162:165], v[214:217], v[72:75]
	v_mfma_f32_16x16x32_bf16 v[140:143], v[158:161], v[194:197], v[140:143]
	v_mfma_f32_16x16x32_bf16 v[136:139], v[166:169], v[194:197], v[136:139]
	v_mfma_f32_16x16x32_bf16 v[108:111], v[158:161], v[202:205], v[108:111]
	v_mfma_f32_16x16x32_bf16 v[104:107], v[166:169], v[202:205], v[104:107]
	v_mfma_f32_16x16x32_bf16 v[92:95], v[158:161], v[210:213], v[92:95]
	v_mfma_f32_16x16x32_bf16 v[88:91], v[166:169], v[210:213], v[88:91]
	v_mfma_f32_16x16x32_bf16 v[76:79], v[158:161], v[218:221], v[76:79]
	v_mfma_f32_16x16x32_bf16 v[72:75], v[166:169], v[218:221], v[72:75]
	s_setprio 0
	s_setprio 1
	v_mfma_f32_16x16x32_bf16 v[132:135], v[170:173], v[186:189], v[132:135]
	v_mfma_f32_16x16x32_bf16 v[126:129], v[178:181], v[186:189], v[128:131]
	v_mfma_f32_16x16x32_bf16 v[100:103], v[170:173], v[198:201], v[100:103]
	v_mfma_f32_16x16x32_bf16 v[96:99], v[178:181], v[198:201], v[96:99]
	v_mfma_f32_16x16x32_bf16 v[84:87], v[170:173], v[206:209], v[84:87]
	v_mfma_f32_16x16x32_bf16 v[80:83], v[178:181], v[206:209], v[80:83]
	v_mfma_f32_16x16x32_bf16 v[68:71], v[170:173], v[214:217], v[68:71]
	v_mfma_f32_16x16x32_bf16 v[64:67], v[178:181], v[214:217], v[64:67]
	v_mfma_f32_16x16x32_bf16 v[132:135], v[174:177], v[194:197], v[132:135]
	v_mfma_f32_16x16x32_bf16 v[126:129], v[182:185], v[194:197], v[126:129]
	v_mfma_f32_16x16x32_bf16 v[100:103], v[174:177], v[202:205], v[100:103]
	v_mfma_f32_16x16x32_bf16 v[96:99], v[182:185], v[202:205], v[96:99]
	v_mfma_f32_16x16x32_bf16 v[84:87], v[174:177], v[210:213], v[84:87]
	v_mfma_f32_16x16x32_bf16 v[80:83], v[182:185], v[210:213], v[80:83]
	v_mfma_f32_16x16x32_bf16 v[68:71], v[174:177], v[218:221], v[68:71]
	v_mfma_f32_16x16x32_bf16 v[64:67], v[182:185], v[218:221], v[64:67]
	s_setprio 0
	s_barrier
	s_mov_b32 m0, s40
	v_lshl_add_u64 v[154:155], s[18:19], 0, v[146:147]
	s_add_u32 s48, s18, 0xb0000
	ds_read_b128 v[186:189], v118 offset:16384
	ds_read_b128 v[194:197], v118 offset:17408
	ds_read_b128 v[198:201], v118 offset:18432
	ds_read_b128 v[202:205], v118 offset:19456
	ds_read_b128 v[206:209], v118 offset:20480
	ds_read_b128 v[210:213], v118 offset:21504
	ds_read_b128 v[214:217], v118 offset:22528
	ds_read_b128 v[218:221], v118 offset:23552
	global_load_lds_dwordx4 v[154:155], off
	v_lshl_add_u64 v[190:191], s[18:19], 0, v[150:151]
	s_mov_b32 m0, s41
	s_addc_u32 s49, s19, 0
	global_load_lds_dwordx4 v[190:191], off
	s_mov_b32 m0, s42
	v_lshl_add_u64 v[222:223], s[20:21], 0, v[144:145]
	global_load_lds_dwordx4 v146, s[48:49]
	s_mov_b32 m0, s43
	v_lshl_add_u64 v[224:225], s[20:21], 0, v[148:149]
	global_load_lds_dwordx4 v150, s[48:49]
	s_mov_b32 m0, s28
	s_nop 0
	global_load_lds_dwordx4 v[222:223], off
	s_mov_b32 m0, s27
	s_nop 0
	global_load_lds_dwordx4 v[224:225], off
	s_waitcnt vmcnt(8)
	s_waitcnt lgkmcnt(0)
	s_barrier
; #define PG8_STAGE(bufoff, gbase, voff) do { _Pragma("unroll") for (int _i = 0; _i < 2; ++_i) \
;         __builtin_amdgcn_global_load_lds((const unsigned*)((const char*)(gbase) + (voff)[_i]), (PG8_LAS unsigned*)(lds + (bufoff) + ldsw + _i * 8192), 16, 0, 0); } while (0)
; #define PG8_LDA(dst, b, h) do { _Pragma("unroll") for (int m = 0; m < 4; ++m) _Pragma("unroll") for (int k = 0; k < 2; ++k) dst[m][k] = *(const PG8_LAS bf16x8*)(lds + PG8_SA(b, h) + aoff + m * 2048 + k * 1024); } while (0)
; #define PG8_LDB(dst, b, h) do { _Pragma("unroll") for (int n = 0; n < 2; ++n) _Pragma("unroll") for (int k = 0; k < 2; ++k) dst[n][k] = *(const PG8_LAS bf16x8*)(lds + PG8_SB(b, h) + boff + n * 2048 + k * 1024); } while (0)
; #define PG8_MMA(ai, bj, At, Bt) do { __builtin_amdgcn_s_setprio(1); _Pragma("unroll") for (int m = 0; m < 4; ++m) _Pragma("unroll") for (int n = 0; n < 2; ++n) _Pragma("unroll") for (int k = 0; k < 2; ++k) \
;         acc[ai][bj][m][n] = __builtin_amdgcn_mfma_f32_16x16x32_bf16(Bt[n][k], At[m][k], acc[ai][bj][m][n], 0, 0, 0); __builtin_amdgcn_s_setprio(0); } while (0)
; #define PG8_WAIT_V(n) asm volatile("s_waitcnt vmcnt(" #n ")" ::: "memory")
; #define PG8_WAIT_L(n) asm volatile("s_waitcnt lgkmcnt(" #n ")" ::: "memory")
; #define PG8_BAR __builtin_amdgcn_s_barrier()
; #define PG8_SCHED __builtin_amdgcn_sched_barrier(0)
; template <class Epi, class Sched, bool ALIGN_EPI = false, bool SP2 = false>
; __device__ __forceinline__ void gemm_phase(PG8_LAS unsigned char* lds, const Gemm g, const Sched& S, const Epi& E) {
;     ...
;             PG8_WAIT_V(8); PG8_WAIT_L(0); PG8_BAR; PG8_MMA(1, 0, At, B0); PG8_MMA(1, 1, At, B1); PG8_BAR; PG8_SCHED;
;             PG8_LDB(B0, 1, 0); PG8_LDB(B1, 1, 1); PG8_SCHED; PG8_LDA(At, 1, 0); PG8_STAGE(PG8_SA(0, 1), a2 + hstepA, voffA);
;             PG8_WAIT_V(8); PG8_WAIT_L(0); PG8_BAR; PG8_MMA(0, 0, At, B0); PG8_MMA(0, 1, At, B1); PG8_BAR; PG8_SCHED;
	s_setprio 1
	s_waitcnt lgkmcnt(0)
	v_mfma_f32_16x16x32_bf16 v[60:63], v[122:125], v[186:189], v[60:63]
	v_mfma_f32_16x16x32_bf16 v[56:59], v[162:165], v[186:189], v[56:59]
	v_mfma_f32_16x16x32_bf16 v[44:47], v[122:125], v[198:201], v[44:47]
	v_mfma_f32_16x16x32_bf16 v[40:43], v[162:165], v[198:201], v[40:43]
	v_mfma_f32_16x16x32_bf16 v[28:31], v[122:125], v[206:209], v[28:31]
	v_mfma_f32_16x16x32_bf16 v[24:27], v[162:165], v[206:209], v[24:27]
	v_mfma_f32_16x16x32_bf16 v[12:15], v[122:125], v[214:217], v[12:15]
	v_mfma_f32_16x16x32_bf16 v[8:11], v[162:165], v[214:217], v[8:11]
	v_mfma_f32_16x16x32_bf16 v[60:63], v[158:161], v[194:197], v[60:63]
	v_mfma_f32_16x16x32_bf16 v[56:59], v[166:169], v[194:197], v[56:59]
	v_mfma_f32_16x16x32_bf16 v[44:47], v[158:161], v[202:205], v[44:47]
	v_mfma_f32_16x16x32_bf16 v[40:43], v[166:169], v[202:205], v[40:43]
	v_mfma_f32_16x16x32_bf16 v[28:31], v[158:161], v[210:213], v[28:31]
	v_mfma_f32_16x16x32_bf16 v[24:27], v[166:169], v[210:213], v[24:27]
	v_mfma_f32_16x16x32_bf16 v[12:15], v[158:161], v[218:221], v[12:15]
	v_mfma_f32_16x16x32_bf16 v[8:11], v[166:169], v[218:221], v[8:11]
	s_setprio 0
	s_setprio 1
	v_mfma_f32_16x16x32_bf16 v[52:55], v[170:173], v[186:189], v[52:55]
	v_mfma_f32_16x16x32_bf16 v[48:51], v[178:181], v[186:189], v[48:51]
	v_mfma_f32_16x16x32_bf16 v[36:39], v[170:173], v[198:201], v[36:39]
	v_mfma_f32_16x16x32_bf16 v[32:35], v[178:181], v[198:201], v[32:35]
	v_mfma_f32_16x16x32_bf16 v[20:23], v[170:173], v[206:209], v[20:23]
	v_mfma_f32_16x16x32_bf16 v[16:19], v[178:181], v[206:209], v[16:19]
	v_mfma_f32_16x16x32_bf16 v[4:7], v[170:173], v[214:217], v[4:7]
	v_mfma_f32_16x16x32_bf16 v[0:3], v[178:181], v[214:217], v[0:3]
	v_mfma_f32_16x16x32_bf16 v[52:55], v[174:177], v[194:197], v[52:55]
	v_mfma_f32_16x16x32_bf16 v[48:51], v[182:185], v[194:197], v[48:51]
	v_mfma_f32_16x16x32_bf16 v[36:39], v[174:177], v[202:205], v[36:39]
	v_mfma_f32_16x16x32_bf16 v[32:35], v[182:185], v[202:205], v[32:35]
	v_mfma_f32_16x16x32_bf16 v[20:23], v[174:177], v[210:213], v[20:23]
	v_mfma_f32_16x16x32_bf16 v[16:19], v[182:185], v[210:213], v[16:19]
	v_mfma_f32_16x16x32_bf16 v[4:7], v[174:177], v[218:221], v[4:7]
	v_mfma_f32_16x16x32_bf16 v[0:3], v[182:185], v[218:221], v[0:3]
	s_setprio 0
	s_barrier
	ds_read_b128 v[122:125], v119
	ds_read_b128 v[158:161], v119 offset:1024
	ds_read_b128 v[162:165], v119 offset:2048
	ds_read_b128 v[166:169], v119 offset:3072
	ds_read_b128 v[170:173], v120
	ds_read_b128 v[174:177], v120 offset:1024
	ds_read_b128 v[178:181], v120 offset:2048
	ds_read_b128 v[182:185], v120 offset:3072
	s_add_u32 s20, s20, 0xb4000
	s_addc_u32 s21, s21, 0
	s_mov_b32 m0, s29
	v_lshl_add_u64 v[130:131], s[20:21], 0, v[144:145]
	ds_read_b128 v[186:189], v118 offset:32768
	ds_read_b128 v[194:197], v118 offset:33792
	ds_read_b128 v[198:201], v118 offset:34816
	ds_read_b128 v[202:205], v118 offset:35840
	ds_read_b128 v[206:209], v118 offset:36864
	ds_read_b128 v[210:213], v118 offset:37888
	ds_read_b128 v[214:217], v118 offset:38912
	ds_read_b128 v[218:221], v118 offset:39936
	global_load_lds_dwordx4 v[130:131], off
	v_lshl_add_u64 v[130:131], s[20:21], 0, v[148:149]
	s_mov_b32 m0, s31
	s_nop 0
	global_load_lds_dwordx4 v[130:131], off
	s_waitcnt vmcnt(8)
	s_waitcnt lgkmcnt(0)
	s_barrier
	s_setprio 1
	s_waitcnt lgkmcnt(0)
	v_mfma_f32_16x16x32_bf16 v[140:143], v[122:125], v[186:189], v[140:143]
	v_mfma_f32_16x16x32_bf16 v[136:139], v[162:165], v[186:189], v[136:139]
	v_mfma_f32_16x16x32_bf16 v[108:111], v[122:125], v[198:201], v[108:111]
	v_mfma_f32_16x16x32_bf16 v[104:107], v[162:165], v[198:201], v[104:107]
	v_mfma_f32_16x16x32_bf16 v[92:95], v[122:125], v[206:209], v[92:95]
	v_mfma_f32_16x16x32_bf16 v[88:91], v[162:165], v[206:209], v[88:91]
	v_mfma_f32_16x16x32_bf16 v[76:79], v[122:125], v[214:217], v[76:79]
	v_mfma_f32_16x16x32_bf16 v[72:75], v[162:165], v[214:217], v[72:75]
	v_mfma_f32_16x16x32_bf16 v[140:143], v[158:161], v[194:197], v[140:143]
	v_mfma_f32_16x16x32_bf16 v[136:139], v[166:169], v[194:197], v[136:139]
	v_mfma_f32_16x16x32_bf16 v[108:111], v[158:161], v[202:205], v[108:111]
	v_mfma_f32_16x16x32_bf16 v[104:107], v[166:169], v[202:205], v[104:107]
	v_mfma_f32_16x16x32_bf16 v[92:95], v[158:161], v[210:213], v[92:95]
	v_mfma_f32_16x16x32_bf16 v[88:91], v[166:169], v[210:213], v[88:91]
	v_mfma_f32_16x16x32_bf16 v[76:79], v[158:161], v[218:221], v[76:79]
	v_mfma_f32_16x16x32_bf16 v[72:75], v[166:169], v[218:221], v[72:75]
	s_setprio 0
	s_setprio 1
	v_mfma_f32_16x16x32_bf16 v[130:133], v[170:173], v[186:189], v[132:135]
	v_mfma_f32_16x16x32_bf16 v[126:129], v[178:181], v[186:189], v[126:129]
	v_mfma_f32_16x16x32_bf16 v[100:103], v[170:173], v[198:201], v[100:103]
	v_mfma_f32_16x16x32_bf16 v[96:99], v[178:181], v[198:201], v[96:99]
	v_mfma_f32_16x16x32_bf16 v[84:87], v[170:173], v[206:209], v[84:87]
	v_mfma_f32_16x16x32_bf16 v[80:83], v[178:181], v[206:209], v[80:83]
	v_mfma_f32_16x16x32_bf16 v[68:71], v[170:173], v[214:217], v[68:71]
	v_mfma_f32_16x16x32_bf16 v[64:67], v[178:181], v[214:217], v[64:67]
	v_mfma_f32_16x16x32_bf16 v[132:135], v[174:177], v[194:197], v[130:133]
	v_mfma_f32_16x16x32_bf16 v[128:131], v[182:185], v[194:197], v[126:129]
	v_mfma_f32_16x16x32_bf16 v[100:103], v[174:177], v[202:205], v[100:103]
	v_mfma_f32_16x16x32_bf16 v[96:99], v[182:185], v[202:205], v[96:99]
	v_mfma_f32_16x16x32_bf16 v[84:87], v[174:177], v[210:213], v[84:87]
	v_mfma_f32_16x16x32_bf16 v[80:83], v[182:185], v[210:213], v[80:83]
	v_mfma_f32_16x16x32_bf16 v[68:71], v[174:177], v[218:221], v[68:71]
	v_mfma_f32_16x16x32_bf16 v[64:67], v[182:185], v[218:221], v[64:67]
	s_setprio 0
	s_barrier
; #define PG8_STAGE(bufoff, gbase, voff) do { _Pragma("unroll") for (int _i = 0; _i < 2; ++_i) \
;         __builtin_amdgcn_global_load_lds((const unsigned*)((const char*)(gbase) + (voff)[_i]), (PG8_LAS unsigned*)(lds + (bufoff) + ldsw + _i * 8192), 16, 0, 0); } while (0)
; #define PG8_LDA(dst, b, h) do { _Pragma("unroll") for (int m = 0; m < 4; ++m) _Pragma("unroll") for (int k = 0; k < 2; ++k) dst[m][k] = *(const PG8_LAS bf16x8*)(lds + PG8_SA(b, h) + aoff + m * 2048 + k * 1024); } while (0)
; #define PG8_MMA(ai, bj, At, Bt) do { __builtin_amdgcn_s_setprio(1); _Pragma("unroll") for (int m = 0; m < 4; ++m) _Pragma("unroll") for (int n = 0; n < 2; ++n) _Pragma("unroll") for (int k = 0; k < 2; ++k) \
;         acc[ai][bj][m][n] = __builtin_amdgcn_mfma_f32_16x16x32_bf16(Bt[n][k], At[m][k], acc[ai][bj][m][n], 0, 0, 0); __builtin_amdgcn_s_setprio(0); } while (0)
; #define PG8_WAIT_V(n) asm volatile("s_waitcnt vmcnt(" #n ")" ::: "memory")
; #define PG8_WAIT_L(n) asm volatile("s_waitcnt lgkmcnt(" #n ")" ::: "memory")
; #define PG8_BAR __builtin_amdgcn_s_barrier()
; #define PG8_SCHED __builtin_amdgcn_sched_barrier(0)
; template <class Epi, class Sched, bool ALIGN_EPI = false, bool SP2 = false>
; __device__ __forceinline__ void gemm_phase(PG8_LAS unsigned char* lds, const Gemm g, const Sched& S, const Epi& E) {
;     ...
;             PG8_LDA(At, 1, 1); PG8_STAGE(PG8_SB(1, 0), b3, voffB); PG8_STAGE(PG8_SB(1, 1), b3 + hstepB, voffB); PG8_STAGE(PG8_SA(1, 0), a3, voffA);
;             PG8_WAIT_V(8); PG8_WAIT_L(0); PG8_BAR; PG8_MMA(1, 0, At, B0); PG8_MMA(1, 1, At, B1); PG8_BAR; PG8_SCHED;
;     ...
;     PG8_WAIT_V(0);
;     if constexpr (!ALIGN_EPI) { if (wr == 0) PG8_BAR; }
;     PG8_BAR;
	s_mov_b32 m0, s44
	v_lshl_add_u64 v[126:127], v[154:155], 0, s[12:13]
	s_add_u32 s18, s18, 0xb0080
	ds_read_b128 v[186:189], v118 offset:49152
	ds_read_b128 v[194:197], v118 offset:50176
	ds_read_b128 v[198:201], v118 offset:51200
	ds_read_b128 v[202:205], v118 offset:52224
	ds_read_b128 v[206:209], v118 offset:53248
	ds_read_b128 v[210:213], v118 offset:54272
	ds_read_b128 v[214:217], v118 offset:55296
	ds_read_b128 v[218:221], v118 offset:56320
	global_load_lds_dwordx4 v[126:127], off
	v_lshl_add_u64 v[126:127], v[190:191], 0, s[12:13]
	s_mov_b32 m0, s45
	s_addc_u32 s19, s19, 0
	global_load_lds_dwordx4 v[126:127], off
	s_mov_b32 m0, s46
	s_nop 0
	global_load_lds_dwordx4 v146, s[18:19]
	s_mov_b32 m0, s47
	s_nop 0
	global_load_lds_dwordx4 v150, s[18:19]
	v_lshl_add_u64 v[126:127], v[222:223], 0, s[12:13]
	s_mov_b32 m0, s33
	s_nop 0
	global_load_lds_dwordx4 v[126:127], off
	v_lshl_add_u64 v[126:127], v[224:225], 0, s[12:13]
	s_mov_b32 m0, s36
	s_nop 0
	global_load_lds_dwordx4 v[126:127], off
	s_waitcnt vmcnt(8)
	s_waitcnt lgkmcnt(0)
	s_barrier
	s_setprio 1
	s_waitcnt lgkmcnt(0)
	v_mfma_f32_16x16x32_bf16 v[60:63], v[122:125], v[186:189], v[60:63]
	v_mfma_f32_16x16x32_bf16 v[56:59], v[162:165], v[186:189], v[56:59]
	v_mfma_f32_16x16x32_bf16 v[44:47], v[122:125], v[198:201], v[44:47]
	v_mfma_f32_16x16x32_bf16 v[40:43], v[162:165], v[198:201], v[40:43]
	v_mfma_f32_16x16x32_bf16 v[28:31], v[122:125], v[206:209], v[28:31]
	v_mfma_f32_16x16x32_bf16 v[24:27], v[162:165], v[206:209], v[24:27]
	v_mfma_f32_16x16x32_bf16 v[12:15], v[122:125], v[214:217], v[12:15]
	v_mfma_f32_16x16x32_bf16 v[8:11], v[162:165], v[214:217], v[8:11]
	v_mfma_f32_16x16x32_bf16 v[60:63], v[158:161], v[194:197], v[60:63]
	v_mfma_f32_16x16x32_bf16 v[56:59], v[166:169], v[194:197], v[56:59]
	v_mfma_f32_16x16x32_bf16 v[44:47], v[158:161], v[202:205], v[44:47]
	v_mfma_f32_16x16x32_bf16 v[40:43], v[166:169], v[202:205], v[40:43]
	v_mfma_f32_16x16x32_bf16 v[28:31], v[158:161], v[210:213], v[28:31]
	v_mfma_f32_16x16x32_bf16 v[24:27], v[166:169], v[210:213], v[24:27]
	v_mfma_f32_16x16x32_bf16 v[12:15], v[158:161], v[218:221], v[12:15]
	v_mfma_f32_16x16x32_bf16 v[8:11], v[166:169], v[218:221], v[8:11]
	s_setprio 0
	s_setprio 1
	v_mfma_f32_16x16x32_bf16 v[52:55], v[170:173], v[186:189], v[52:55]
	v_mfma_f32_16x16x32_bf16 v[48:51], v[178:181], v[186:189], v[48:51]
	v_mfma_f32_16x16x32_bf16 v[36:39], v[170:173], v[198:201], v[36:39]
	v_mfma_f32_16x16x32_bf16 v[32:35], v[178:181], v[198:201], v[32:35]
	v_mfma_f32_16x16x32_bf16 v[20:23], v[170:173], v[206:209], v[20:23]
	v_mfma_f32_16x16x32_bf16 v[16:19], v[178:181], v[206:209], v[16:19]
	v_mfma_f32_16x16x32_bf16 v[4:7], v[170:173], v[214:217], v[4:7]
	v_mfma_f32_16x16x32_bf16 v[0:3], v[178:181], v[214:217], v[0:3]
	v_mfma_f32_16x16x32_bf16 v[52:55], v[174:177], v[194:197], v[52:55]
	v_mfma_f32_16x16x32_bf16 v[48:51], v[182:185], v[194:197], v[48:51]
	v_mfma_f32_16x16x32_bf16 v[36:39], v[174:177], v[202:205], v[36:39]
	v_mfma_f32_16x16x32_bf16 v[32:35], v[182:185], v[202:205], v[32:35]
	v_mfma_f32_16x16x32_bf16 v[20:23], v[174:177], v[210:213], v[20:23]
	v_mfma_f32_16x16x32_bf16 v[16:19], v[182:185], v[210:213], v[16:19]
	v_mfma_f32_16x16x32_bf16 v[4:7], v[174:177], v[218:221], v[4:7]
	v_mfma_f32_16x16x32_bf16 v[0:3], v[182:185], v[218:221], v[0:3]
	s_setprio 0
	s_barrier
	s_add_i32 s37, s37, 2
	s_add_u32 s16, s16, 0x100
	s_addc_u32 s17, s17, 0
	s_cmp_lt_u32 s37, 42
	s_cbranch_scc1 .LBB0_1640
	s_waitcnt vmcnt(0)
	s_cmpk_gt_u32 s23, 0xff
	s_cbranch_scc1 .LBB0_1643
	s_barrier
